# s_setprio: workgroups >= 256 keep priority 1 for the whole GEMM phase (static raise at entry and no lowering at the stage-top barrier); workgroups < 256 toggle 1 (MFMA groups) / 0 (stage-top wait)
# speedup vs baseline: 1.0171x; 1.0031x over previous
; #define PH(k) case k: if (ONLY_PHASE >= 0 && ONLY_PHASE != k) break;
; template <class Epi>
; DI void gemm_tile(char* smem, const bf16_t* __restrict__ A0, int lda0, int ksplit, const bf16_t* __restrict__ A1, int lda1,
;                   const bf16_t* __restrict__ Bt, int K, int row0, int col0, const Epi& epi, int tid) {
;   constexpr int BK = 32, PITCH = 40, BUF = (256 + 128) * PITCH;
;   bf16_t* sbase = (bf16_t*)smem;
;   const int lane = tid & 63, wid = tid >> 6, wr = wid >> 1, wc = wid & 1, fr = lane & 15, fq = lane >> 4;
;   f32x4 acc[8][4];
; #pragma unroll
;   for (int m = 0; m < 8; ++m)
; #pragma unroll
;     for (int n = 0; n < 4; ++n) acc[m][n] = (f32x4){0.f, 0.f, 0.f, 0.f};
;   u32x4 ra[2][4], rb[2][2];
;   const int nk = K / BK;
;   const int sr = tid >> 2, scv = tid & 3;
; template <int ph> DI void run_phase(const Ctx& c, char* smem) {
;     ...
;     PH(1) gemm_phase(smem, XN, 1024, 1 << 30, XN, 1024, (const bf16_t*)(ws + OFF_WABIN), 1024, 35,
;                        EpiSplit{(bf16_t*)(ws + OFF_R1), 1792, 1792, (bf16_t*)(ws + OFF_R2), 2592, 2592}, TIDX); break;
.LBB0_60:
	s_load_dwordx4 s[52:55], s[74:75], 0x160
	s_load_dwordx8 s[0:7], s[74:75], 0x140
	s_load_dwordx16 s[36:51], s[74:75], 0x80
	s_cmp_gt_i32 s94, 1
	v_mbcnt_lo_u32_b32 v194, -1, 0
	s_waitcnt lgkmcnt(0)
	v_writelane_b32 v253, s0, 48
	s_nop 1
	v_writelane_b32 v253, s1, 49
	v_writelane_b32 v253, s2, 50
	v_writelane_b32 v253, s3, 51
	v_writelane_b32 v253, s4, 52
	v_writelane_b32 v253, s5, 53
	v_writelane_b32 v253, s6, 54
	v_writelane_b32 v253, s7, 55
	s_cselect_b64 s[0:1], -1, 0
	s_cmp_lt_i32 s95, 2
	s_cselect_b64 s[2:3], -1, 0
	s_or_b64 s[0:1], s[0:1], s[2:3]
	s_and_b64 vcc, exec, s[0:1]
	s_cbranch_vccnz .LBB0_344
	s_load_dword s26, s[74:75], 0x180
	s_add_u32 s0, s92, 0x3800000
	s_addc_u32 s1, s93, 0
	s_and_b32 s28, s72, 0xffffffc0
	v_mbcnt_hi_u32_b32 v195, -1, v194
	s_waitcnt lgkmcnt(0)
	s_and_b32 s27, s26, 7
	s_cmp_lg_u32 s27, 0
	v_add_u32_e32 v196, s28, v195
	v_mbcnt_lo_u32_b32 v240, -1, 0
	v_mbcnt_hi_u32_b32 v240, -1, v240
	s_lshr_b32 s23, s72, 6
	s_lshl_b32 s100, s23, 10
	v_and_b32_e32 v241, 15, v240
	v_lshrrev_b32_e32 v242, 4, v240
	v_bfe_u32 v243, v240, 3, 1
	v_mul_u32_u24_e32 v243, 3, v243
	v_xor_b32_e32 v243, v242, v243
	v_lshlrev_b32_e32 v243, 4, v243
	v_lshl_add_u32 v243, v241, 6, v243
	s_lshr_b32 s22, s23, 1
	s_lshl_b32 s22, s22, 13
	v_add_u32_e32 v230, s22, v243
	s_and_b32 s22, s23, 1
	s_lshl_b32 s22, s22, 12
	s_add_u32 s22, s22, 16384
	v_add_u32_e32 v231, s22, v243
	s_lshr_b32 s22, s23, 1
	s_lshl_b32 s22, s22, 7
	v_add_u32_e32 v244, s22, v241
	s_and_b32 s22, s23, 1
	s_lshl_b32 s22, s22, 6
	v_lshl_add_u32 v245, v242, 2, s22
	s_movk_i32 s22, 3584
	v_mul_lo_u32 v246, v244, s22
	v_lshl_add_u32 v234, v245, 1, v246
	s_movk_i32 s22, 5184
	v_mul_lo_u32 v246, v244, s22
	v_lshl_add_u32 v235, v245, 1, v246
	s_mul_i32 s22, s23, 18432
	v_mul_u32_u24_e32 v246, 144, v241
	v_lshl_add_u32 v246, v242, 3, v246
	v_add_u32_e32 v236, s22, v246
	v_lshrrev_b32_e32 v246, 3, v240
	v_mul_u32_u24_e32 v246, 144, v246
	v_and_b32_e32 v247, 7, v240
	v_lshl_add_u32 v246, v247, 4, v246
	v_add_u32_e32 v237, s22, v246
	s_lshr_b32 s22, s23, 1
	s_lshl_b32 s22, s22, 7
	v_lshrrev_b32_e32 v246, 3, v240
	v_add_u32_e32 v246, s22, v246
	s_and_b32 s22, s23, 1
	s_lshl_b32 s22, s22, 6
	v_lshl_add_u32 v248, v247, 3, s22
	s_movk_i32 s22, 3584
	v_mul_lo_u32 v247, v246, s22
	v_lshl_add_u32 v238, v248, 1, v247
	s_movk_i32 s22, 5184
	v_mul_lo_u32 v247, v246, s22
	v_lshl_add_u32 v239, v248, 1, v247
	v_lshrrev_b32_e32 v241, 2, v240
	s_lshl_b32 s22, s23, 4
	v_add_u32_e32 v241, s22, v241
	v_bfe_u32 v242, v240, 5, 1
	v_mul_u32_u24_e32 v242, 3, v242
	v_and_b32_e32 v243, 3, v240
	v_xor_b32_e32 v243, v243, v242
	v_lshlrev_b32_e32 v243, 4, v243
	s_mov_b32 s22, 2048
	v_mad_u32_u24 v224, v241, s22, v243
	v_add_u32_e32 v225, 0x20000, v224
	v_add_u32_e32 v226, 0x40000, v224
	v_add_u32_e32 v227, 0x60000, v224
	s_mov_b32 s22, 2048
	v_mad_u32_u24 v228, v241, s22, v243
	v_add_u32_e32 v229, 0x20000, v228
	s_cmpk_gt_u32 s96, 0xff
	s_cselect_b32 s21, 1, 0
	s_cmpk_gt_u32 s96, 0xff
	s_cbranch_scc0 .Lg1_prio
	s_setprio 1

; #define LWRITE(S, buf) do { bf16_t* sA_ = sbase + (buf) * BUF; bf16_t* sB_ = sA_ + 256 * PITCH; \
;     _Pragma("unroll") for (int i_ = 0; i_ < 4; ++i_) *(u32x4*)(sA_ + (sr + i_ * 64) * PITCH + scv * 8) = ra[S][i_]; \
;     _Pragma("unroll") for (int i_ = 0; i_ < 2; ++i_) *(u32x4*)(sB_ + (sr + i_ * 64) * PITCH + scv * 8) = rb[S][i_]; } while (0)
; template <class Epi>
; DI void gemm_tile(char* smem, const bf16_t* __restrict__ A0, int lda0, int ksplit, const bf16_t* __restrict__ A1, int lda1,
;                   const bf16_t* __restrict__ Bt, int K, int row0, int col0, const Epi& epi, int tid) {
;     ...
;   __syncthreads();
;   {
;     const int last = nk - 1;
;     GLOAD(0, 0);
;     __builtin_amdgcn_sched_barrier(0);
;     GLOAD(1, 1);
;     __builtin_amdgcn_sched_barrier(0);
;     LWRITE(0, 0);
;     __builtin_amdgcn_sched_barrier(0);
;     GLOAD(0, (2 < last ? 2 : last));
;     __builtin_amdgcn_sched_barrier(0);
;     __syncthreads();
;     for (int kt = 0; kt < nk; kt += 2) {
;       LWRITE(1, 1);
;       __builtin_amdgcn_sched_barrier(0);
;       GLOAD(1, (kt + 3 < last ? kt + 3 : last));
;       __builtin_amdgcn_sched_barrier(0);
;       COMPUTE(0);
;       __syncthreads();
;       LWRITE(0, 0);
;       __builtin_amdgcn_sched_barrier(0);
;       GLOAD(0, (kt + 4 < last ? kt + 4 : last));
;       __builtin_amdgcn_sched_barrier(0);
;       COMPUTE(1);
;       __syncthreads();
.Lg1_kloop:
	s_waitcnt vmcnt(6)
	s_waitcnt lgkmcnt(0)
	s_barrier
	v_add_u32_e32 v232, s31, v230
	v_add_u32_e32 v233, s31, v231
	s_add_u32 s22, s30, s100
	s_setprio 1
	v_mfma_f32_16x16x32_bf16 v[0:3], v[128:131], v[144:147], v[0:3]
	v_mfma_f32_16x16x32_bf16 v[4:7], v[132:135], v[144:147], v[4:7]
	v_mfma_f32_16x16x32_bf16 v[8:11], v[136:139], v[144:147], v[8:11]
	v_mfma_f32_16x16x32_bf16 v[12:15], v[140:143], v[144:147], v[12:15]
	ds_read_b128 v[176:179], v233 offset:0
	ds_read_b128 v[180:183], v233 offset:1024
	s_add_u32 m0, s22, 0
	s_nop 0
	global_load_lds_dwordx4 v224, s[0:1]
	v_mfma_f32_16x16x32_bf16 v[16:19], v[128:131], v[148:151], v[16:19]
	v_mfma_f32_16x16x32_bf16 v[20:23], v[132:135], v[148:151], v[20:23]
	v_mfma_f32_16x16x32_bf16 v[24:27], v[136:139], v[148:151], v[24:27]
	v_mfma_f32_16x16x32_bf16 v[28:31], v[140:143], v[148:151], v[28:31]
	ds_read_b128 v[184:187], v233 offset:2048
	ds_read_b128 v[188:191], v233 offset:3072
	s_add_u32 m0, s22, 4096
	s_nop 0
	global_load_lds_dwordx4 v225, s[0:1]
	v_mfma_f32_16x16x32_bf16 v[32:35], v[128:131], v[152:155], v[32:35]
	v_mfma_f32_16x16x32_bf16 v[36:39], v[132:135], v[152:155], v[36:39]
	v_mfma_f32_16x16x32_bf16 v[40:43], v[136:139], v[152:155], v[40:43]
	v_mfma_f32_16x16x32_bf16 v[44:47], v[140:143], v[152:155], v[44:47]
	ds_read_b128 v[192:195], v232 offset:0
	ds_read_b128 v[196:199], v232 offset:1024
	s_add_u32 m0, s22, 8192
	s_nop 0
	global_load_lds_dwordx4 v226, s[0:1]
	v_mfma_f32_16x16x32_bf16 v[48:51], v[128:131], v[156:159], v[48:51]
	v_mfma_f32_16x16x32_bf16 v[52:55], v[132:135], v[156:159], v[52:55]
	v_mfma_f32_16x16x32_bf16 v[56:59], v[136:139], v[156:159], v[56:59]
	v_mfma_f32_16x16x32_bf16 v[60:63], v[140:143], v[156:159], v[60:63]
	ds_read_b128 v[200:203], v232 offset:2048
	ds_read_b128 v[204:207], v232 offset:3072
	s_add_u32 m0, s22, 12288
	s_nop 0
	global_load_lds_dwordx4 v227, s[0:1]
	v_mfma_f32_16x16x32_bf16 v[64:67], v[128:131], v[160:163], v[64:67]
	v_mfma_f32_16x16x32_bf16 v[68:71], v[132:135], v[160:163], v[68:71]
	v_mfma_f32_16x16x32_bf16 v[72:75], v[136:139], v[160:163], v[72:75]
	v_mfma_f32_16x16x32_bf16 v[76:79], v[140:143], v[160:163], v[76:79]
	ds_read_b128 v[208:211], v232 offset:4096
	s_add_u32 m0, s22, 16384
	s_nop 0
	global_load_lds_dwordx4 v228, s[2:3]
	v_mfma_f32_16x16x32_bf16 v[80:83], v[128:131], v[164:167], v[80:83]
	v_mfma_f32_16x16x32_bf16 v[84:87], v[132:135], v[164:167], v[84:87]
	v_mfma_f32_16x16x32_bf16 v[88:91], v[136:139], v[164:167], v[88:91]
	v_mfma_f32_16x16x32_bf16 v[92:95], v[140:143], v[164:167], v[92:95]
	ds_read_b128 v[212:215], v232 offset:5120
	s_add_u32 m0, s22, 20480
	s_nop 0
	global_load_lds_dwordx4 v229, s[2:3]
	v_mfma_f32_16x16x32_bf16 v[96:99], v[128:131], v[168:171], v[96:99]
	v_mfma_f32_16x16x32_bf16 v[100:103], v[132:135], v[168:171], v[100:103]
	v_mfma_f32_16x16x32_bf16 v[104:107], v[136:139], v[168:171], v[104:107]
	v_mfma_f32_16x16x32_bf16 v[108:111], v[140:143], v[168:171], v[108:111]
	ds_read_b128 v[216:219], v232 offset:6144
	s_add_u32 s0, s0, 64
	s_addc_u32 s1, s1, 0
	s_add_u32 s2, s2, 64
	s_addc_u32 s3, s3, 0
	s_add_u32 s99, s99, 1
	s_add_u32 s30, s30, 24576
	s_cmp_eq_u32 s30, 73728
	s_cselect_b32 s30, 0, s30
	s_add_u32 s31, s31, 24576
	s_cmp_eq_u32 s31, 73728
	s_cselect_b32 s31, 0, s31
	v_mfma_f32_16x16x32_bf16 v[112:115], v[128:131], v[172:175], v[112:115]
	v_mfma_f32_16x16x32_bf16 v[116:119], v[132:135], v[172:175], v[116:119]
	v_mfma_f32_16x16x32_bf16 v[120:123], v[136:139], v[172:175], v[120:123]
	v_mfma_f32_16x16x32_bf16 v[124:127], v[140:143], v[172:175], v[124:127]
	ds_read_b128 v[220:223], v232 offset:7168
	s_cmp_eq_u32 s21, 0
	s_cbranch_scc0 .Lg1_hi0
	s_setprio 0
.Lg1_hi0:
	s_waitcnt vmcnt(6)
	s_waitcnt lgkmcnt(0)
	s_barrier
	v_add_u32_e32 v232, s31, v230
	v_add_u32_e32 v233, s31, v231
	s_add_u32 s22, s30, s100
	s_setprio 1
	v_mfma_f32_16x16x32_bf16 v[0:3], v[176:179], v[192:195], v[0:3]
	v_mfma_f32_16x16x32_bf16 v[4:7], v[180:183], v[192:195], v[4:7]
	v_mfma_f32_16x16x32_bf16 v[8:11], v[184:187], v[192:195], v[8:11]
	v_mfma_f32_16x16x32_bf16 v[12:15], v[188:191], v[192:195], v[12:15]
	ds_read_b128 v[128:131], v233 offset:0
	ds_read_b128 v[132:135], v233 offset:1024
	s_add_u32 m0, s22, 0
	s_nop 0
	global_load_lds_dwordx4 v224, s[0:1]
	v_mfma_f32_16x16x32_bf16 v[16:19], v[176:179], v[196:199], v[16:19]
	v_mfma_f32_16x16x32_bf16 v[20:23], v[180:183], v[196:199], v[20:23]
	v_mfma_f32_16x16x32_bf16 v[24:27], v[184:187], v[196:199], v[24:27]
	v_mfma_f32_16x16x32_bf16 v[28:31], v[188:191], v[196:199], v[28:31]
	ds_read_b128 v[136:139], v233 offset:2048
	ds_read_b128 v[140:143], v233 offset:3072
	s_add_u32 m0, s22, 4096
	s_nop 0
	global_load_lds_dwordx4 v225, s[0:1]
	v_mfma_f32_16x16x32_bf16 v[32:35], v[176:179], v[200:203], v[32:35]
	v_mfma_f32_16x16x32_bf16 v[36:39], v[180:183], v[200:203], v[36:39]
	v_mfma_f32_16x16x32_bf16 v[40:43], v[184:187], v[200:203], v[40:43]
	v_mfma_f32_16x16x32_bf16 v[44:47], v[188:191], v[200:203], v[44:47]
	ds_read_b128 v[144:147], v232 offset:0
	ds_read_b128 v[148:151], v232 offset:1024
	s_add_u32 m0, s22, 8192
	s_nop 0
	global_load_lds_dwordx4 v226, s[0:1]
	v_mfma_f32_16x16x32_bf16 v[48:51], v[176:179], v[204:207], v[48:51]
	v_mfma_f32_16x16x32_bf16 v[52:55], v[180:183], v[204:207], v[52:55]
	v_mfma_f32_16x16x32_bf16 v[56:59], v[184:187], v[204:207], v[56:59]
	v_mfma_f32_16x16x32_bf16 v[60:63], v[188:191], v[204:207], v[60:63]
	ds_read_b128 v[152:155], v232 offset:2048
	ds_read_b128 v[156:159], v232 offset:3072
	s_add_u32 m0, s22, 12288
	s_nop 0
	global_load_lds_dwordx4 v227, s[0:1]
	v_mfma_f32_16x16x32_bf16 v[64:67], v[176:179], v[208:211], v[64:67]
; #define LWRITE(S, buf) do { bf16_t* sA_ = sbase + (buf) * BUF; bf16_t* sB_ = sA_ + 256 * PITCH; \
;     _Pragma("unroll") for (int i_ = 0; i_ < 4; ++i_) *(u32x4*)(sA_ + (sr + i_ * 64) * PITCH + scv * 8) = ra[S][i_]; \
;     _Pragma("unroll") for (int i_ = 0; i_ < 2; ++i_) *(u32x4*)(sB_ + (sr + i_ * 64) * PITCH + scv * 8) = rb[S][i_]; } while (0)
; template <class Epi>
; DI void gemm_tile(char* smem, const bf16_t* __restrict__ A0, int lda0, int ksplit, const bf16_t* __restrict__ A1, int lda1,
;                   const bf16_t* __restrict__ Bt, int K, int row0, int col0, const Epi& epi, int tid) {
;     ...
;   __syncthreads();
;   {
;     const int last = nk - 1;
;     GLOAD(0, 0);
;     __builtin_amdgcn_sched_barrier(0);
;     GLOAD(1, 1);
;     __builtin_amdgcn_sched_barrier(0);
;     LWRITE(0, 0);
;     __builtin_amdgcn_sched_barrier(0);
;     GLOAD(0, (2 < last ? 2 : last));
;     __builtin_amdgcn_sched_barrier(0);
;     __syncthreads();
;     for (int kt = 0; kt < nk; kt += 2) {
;       LWRITE(1, 1);
;       __builtin_amdgcn_sched_barrier(0);
;       GLOAD(1, (kt + 3 < last ? kt + 3 : last));
;       __builtin_amdgcn_sched_barrier(0);
;       COMPUTE(0);
;       __syncthreads();
;       LWRITE(0, 0);
;       __builtin_amdgcn_sched_barrier(0);
;       GLOAD(0, (kt + 4 < last ? kt + 4 : last));
;       __builtin_amdgcn_sched_barrier(0);
;       COMPUTE(1);
;       __syncthreads();
;     }
	v_mfma_f32_16x16x32_bf16 v[68:71], v[180:183], v[208:211], v[68:71]
	v_mfma_f32_16x16x32_bf16 v[72:75], v[184:187], v[208:211], v[72:75]
	v_mfma_f32_16x16x32_bf16 v[76:79], v[188:191], v[208:211], v[76:79]
	ds_read_b128 v[160:163], v232 offset:4096
	s_add_u32 m0, s22, 16384
	s_nop 0
	global_load_lds_dwordx4 v228, s[2:3]
	v_mfma_f32_16x16x32_bf16 v[80:83], v[176:179], v[212:215], v[80:83]
	v_mfma_f32_16x16x32_bf16 v[84:87], v[180:183], v[212:215], v[84:87]
	v_mfma_f32_16x16x32_bf16 v[88:91], v[184:187], v[212:215], v[88:91]
	v_mfma_f32_16x16x32_bf16 v[92:95], v[188:191], v[212:215], v[92:95]
	ds_read_b128 v[164:167], v232 offset:5120
	s_add_u32 m0, s22, 20480
	s_nop 0
	global_load_lds_dwordx4 v229, s[2:3]
	v_mfma_f32_16x16x32_bf16 v[96:99], v[176:179], v[216:219], v[96:99]
	v_mfma_f32_16x16x32_bf16 v[100:103], v[180:183], v[216:219], v[100:103]
	v_mfma_f32_16x16x32_bf16 v[104:107], v[184:187], v[216:219], v[104:107]
	v_mfma_f32_16x16x32_bf16 v[108:111], v[188:191], v[216:219], v[108:111]
	ds_read_b128 v[168:171], v232 offset:6144
	s_add_u32 s0, s0, 64
	s_addc_u32 s1, s1, 0
	s_add_u32 s2, s2, 64
	s_addc_u32 s3, s3, 0
	s_add_u32 s99, s99, 1
	s_add_u32 s30, s30, 24576
	s_cmp_eq_u32 s30, 73728
	s_cselect_b32 s30, 0, s30
	s_add_u32 s31, s31, 24576
	s_cmp_eq_u32 s31, 73728
	s_cselect_b32 s31, 0, s31
	v_mfma_f32_16x16x32_bf16 v[112:115], v[176:179], v[220:223], v[112:115]
	v_mfma_f32_16x16x32_bf16 v[116:119], v[180:183], v[220:223], v[116:119]
	v_mfma_f32_16x16x32_bf16 v[120:123], v[184:187], v[220:223], v[120:123]
	v_mfma_f32_16x16x32_bf16 v[124:127], v[188:191], v[220:223], v[124:127]
	ds_read_b128 v[172:175], v232 offset:7168
	s_cmp_eq_u32 s21, 0
	s_cbranch_scc0 .Lg1_hi1
	s_setprio 0
.Lg1_hi1:
	s_add_u32 s98, s98, 2
	s_cmp_lt_u32 s98, 28
	s_cbranch_scc1 .Lg1_kloop
	s_waitcnt vmcnt(6)
	s_waitcnt lgkmcnt(0)
	s_barrier
	v_add_u32_e32 v232, s31, v230
	v_add_u32_e32 v233, s31, v231
	s_add_u32 s22, s30, s100
	s_setprio 1
	v_mfma_f32_16x16x32_bf16 v[0:3], v[128:131], v[144:147], v[0:3]
	v_mfma_f32_16x16x32_bf16 v[4:7], v[132:135], v[144:147], v[4:7]
	v_mfma_f32_16x16x32_bf16 v[8:11], v[136:139], v[144:147], v[8:11]
	v_mfma_f32_16x16x32_bf16 v[12:15], v[140:143], v[144:147], v[12:15]
	ds_read_b128 v[176:179], v233 offset:0
	ds_read_b128 v[180:183], v233 offset:1024
	s_add_u32 m0, s22, 0
	s_nop 0
	global_load_lds_dwordx4 v224, s[0:1]
	v_mfma_f32_16x16x32_bf16 v[16:19], v[128:131], v[148:151], v[16:19]
	v_mfma_f32_16x16x32_bf16 v[20:23], v[132:135], v[148:151], v[20:23]
	v_mfma_f32_16x16x32_bf16 v[24:27], v[136:139], v[148:151], v[24:27]
	v_mfma_f32_16x16x32_bf16 v[28:31], v[140:143], v[148:151], v[28:31]
	ds_read_b128 v[184:187], v233 offset:2048
	ds_read_b128 v[188:191], v233 offset:3072
	s_add_u32 m0, s22, 4096
	s_nop 0
	global_load_lds_dwordx4 v225, s[0:1]
	v_mfma_f32_16x16x32_bf16 v[32:35], v[128:131], v[152:155], v[32:35]
	v_mfma_f32_16x16x32_bf16 v[36:39], v[132:135], v[152:155], v[36:39]
	v_mfma_f32_16x16x32_bf16 v[40:43], v[136:139], v[152:155], v[40:43]
	v_mfma_f32_16x16x32_bf16 v[44:47], v[140:143], v[152:155], v[44:47]
	ds_read_b128 v[192:195], v232 offset:0
	ds_read_b128 v[196:199], v232 offset:1024
	s_add_u32 m0, s22, 8192
	s_nop 0
	global_load_lds_dwordx4 v226, s[0:1]
	v_mfma_f32_16x16x32_bf16 v[48:51], v[128:131], v[156:159], v[48:51]
	v_mfma_f32_16x16x32_bf16 v[52:55], v[132:135], v[156:159], v[52:55]
	v_mfma_f32_16x16x32_bf16 v[56:59], v[136:139], v[156:159], v[56:59]
	v_mfma_f32_16x16x32_bf16 v[60:63], v[140:143], v[156:159], v[60:63]
	ds_read_b128 v[200:203], v232 offset:2048
	ds_read_b128 v[204:207], v232 offset:3072
	s_add_u32 m0, s22, 12288
	s_nop 0
	global_load_lds_dwordx4 v227, s[0:1]
	v_mfma_f32_16x16x32_bf16 v[64:67], v[128:131], v[160:163], v[64:67]
	v_mfma_f32_16x16x32_bf16 v[68:71], v[132:135], v[160:163], v[68:71]
	v_mfma_f32_16x16x32_bf16 v[72:75], v[136:139], v[160:163], v[72:75]
	v_mfma_f32_16x16x32_bf16 v[76:79], v[140:143], v[160:163], v[76:79]
	ds_read_b128 v[208:211], v232 offset:4096
	s_add_u32 m0, s22, 16384
	s_nop 0
	global_load_lds_dwordx4 v228, s[2:3]
	v_mfma_f32_16x16x32_bf16 v[80:83], v[128:131], v[164:167], v[80:83]
	v_mfma_f32_16x16x32_bf16 v[84:87], v[132:135], v[164:167], v[84:87]
	v_mfma_f32_16x16x32_bf16 v[88:91], v[136:139], v[164:167], v[88:91]
	v_mfma_f32_16x16x32_bf16 v[92:95], v[140:143], v[164:167], v[92:95]
	ds_read_b128 v[212:215], v232 offset:5120
	s_add_u32 m0, s22, 20480
	s_nop 0
	global_load_lds_dwordx4 v229, s[2:3]
	v_mfma_f32_16x16x32_bf16 v[96:99], v[128:131], v[168:171], v[96:99]
	v_mfma_f32_16x16x32_bf16 v[100:103], v[132:135], v[168:171], v[100:103]
	v_mfma_f32_16x16x32_bf16 v[104:107], v[136:139], v[168:171], v[104:107]
	v_mfma_f32_16x16x32_bf16 v[108:111], v[140:143], v[168:171], v[108:111]
	ds_read_b128 v[216:219], v232 offset:6144
	s_add_u32 s0, s0, 64
	s_addc_u32 s1, s1, 0
	s_add_u32 s2, s2, 64
	s_addc_u32 s3, s3, 0
	s_add_u32 s99, s99, 1
	s_add_u32 s30, s30, 24576
	s_cmp_eq_u32 s30, 73728
	s_cselect_b32 s30, 0, s30
	s_add_u32 s31, s31, 24576
	s_cmp_eq_u32 s31, 73728
	s_cselect_b32 s31, 0, s31
	v_mfma_f32_16x16x32_bf16 v[112:115], v[128:131], v[172:175], v[112:115]
	v_mfma_f32_16x16x32_bf16 v[116:119], v[132:135], v[172:175], v[116:119]
	v_mfma_f32_16x16x32_bf16 v[120:123], v[136:139], v[172:175], v[120:123]
	v_mfma_f32_16x16x32_bf16 v[124:127], v[140:143], v[172:175], v[124:127]
	ds_read_b128 v[220:223], v232 offset:7168
	s_cmp_eq_u32 s21, 0
	s_cbranch_scc0 .Lg1_hi2
	s_setprio 0
; #define LWRITE(S, buf) do { bf16_t* sA_ = sbase + (buf) * BUF; bf16_t* sB_ = sA_ + 256 * PITCH; \
;     _Pragma("unroll") for (int i_ = 0; i_ < 4; ++i_) *(u32x4*)(sA_ + (sr + i_ * 64) * PITCH + scv * 8) = ra[S][i_]; \
;     _Pragma("unroll") for (int i_ = 0; i_ < 2; ++i_) *(u32x4*)(sB_ + (sr + i_ * 64) * PITCH + scv * 8) = rb[S][i_]; } while (0)
; template <class Epi>
; DI void gemm_tile(char* smem, const bf16_t* __restrict__ A0, int lda0, int ksplit, const bf16_t* __restrict__ A1, int lda1,
;                   const bf16_t* __restrict__ Bt, int K, int row0, int col0, const Epi& epi, int tid) {
;     ...
;   __syncthreads();
;   {
;     const int last = nk - 1;
;     GLOAD(0, 0);
;     __builtin_amdgcn_sched_barrier(0);
;     GLOAD(1, 1);
;     __builtin_amdgcn_sched_barrier(0);
;     LWRITE(0, 0);
;     __builtin_amdgcn_sched_barrier(0);
;     GLOAD(0, (2 < last ? 2 : last));
;     __builtin_amdgcn_sched_barrier(0);
;     __syncthreads();
;     for (int kt = 0; kt < nk; kt += 2) {
;       LWRITE(1, 1);
;       __builtin_amdgcn_sched_barrier(0);
;       GLOAD(1, (kt + 3 < last ? kt + 3 : last));
;       __builtin_amdgcn_sched_barrier(0);
;       COMPUTE(0);
;       __syncthreads();
;       LWRITE(0, 0);
;       __builtin_amdgcn_sched_barrier(0);
;       GLOAD(0, (kt + 4 < last ? kt + 4 : last));
;       __builtin_amdgcn_sched_barrier(0);
;       COMPUTE(1);
;       __syncthreads();
;     }
.Lg1_hi2:
	s_waitcnt vmcnt(6)
	s_waitcnt lgkmcnt(0)
	s_barrier
	v_add_u32_e32 v232, s31, v230
	v_add_u32_e32 v233, s31, v231
	s_setprio 1
	v_mfma_f32_16x16x32_bf16 v[0:3], v[176:179], v[192:195], v[0:3]
	v_mfma_f32_16x16x32_bf16 v[4:7], v[180:183], v[192:195], v[4:7]
	v_mfma_f32_16x16x32_bf16 v[8:11], v[184:187], v[192:195], v[8:11]
	v_mfma_f32_16x16x32_bf16 v[12:15], v[188:191], v[192:195], v[12:15]
	ds_read_b128 v[128:131], v233 offset:0
	ds_read_b128 v[132:135], v233 offset:1024
	v_mfma_f32_16x16x32_bf16 v[16:19], v[176:179], v[196:199], v[16:19]
	v_mfma_f32_16x16x32_bf16 v[20:23], v[180:183], v[196:199], v[20:23]
	v_mfma_f32_16x16x32_bf16 v[24:27], v[184:187], v[196:199], v[24:27]
	v_mfma_f32_16x16x32_bf16 v[28:31], v[188:191], v[196:199], v[28:31]
	ds_read_b128 v[136:139], v233 offset:2048
	ds_read_b128 v[140:143], v233 offset:3072
	v_mfma_f32_16x16x32_bf16 v[32:35], v[176:179], v[200:203], v[32:35]
	v_mfma_f32_16x16x32_bf16 v[36:39], v[180:183], v[200:203], v[36:39]
	v_mfma_f32_16x16x32_bf16 v[40:43], v[184:187], v[200:203], v[40:43]
	v_mfma_f32_16x16x32_bf16 v[44:47], v[188:191], v[200:203], v[44:47]
	ds_read_b128 v[144:147], v232 offset:0
	ds_read_b128 v[148:151], v232 offset:1024
	v_mfma_f32_16x16x32_bf16 v[48:51], v[176:179], v[204:207], v[48:51]
	v_mfma_f32_16x16x32_bf16 v[52:55], v[180:183], v[204:207], v[52:55]
	v_mfma_f32_16x16x32_bf16 v[56:59], v[184:187], v[204:207], v[56:59]
	v_mfma_f32_16x16x32_bf16 v[60:63], v[188:191], v[204:207], v[60:63]
	ds_read_b128 v[152:155], v232 offset:2048
	ds_read_b128 v[156:159], v232 offset:3072
	v_mfma_f32_16x16x32_bf16 v[64:67], v[176:179], v[208:211], v[64:67]
	v_mfma_f32_16x16x32_bf16 v[68:71], v[180:183], v[208:211], v[68:71]
	v_mfma_f32_16x16x32_bf16 v[72:75], v[184:187], v[208:211], v[72:75]
	v_mfma_f32_16x16x32_bf16 v[76:79], v[188:191], v[208:211], v[76:79]
	ds_read_b128 v[160:163], v232 offset:4096
	v_mfma_f32_16x16x32_bf16 v[80:83], v[176:179], v[212:215], v[80:83]
	v_mfma_f32_16x16x32_bf16 v[84:87], v[180:183], v[212:215], v[84:87]
	v_mfma_f32_16x16x32_bf16 v[88:91], v[184:187], v[212:215], v[88:91]
	v_mfma_f32_16x16x32_bf16 v[92:95], v[188:191], v[212:215], v[92:95]
	ds_read_b128 v[164:167], v232 offset:5120
	v_mfma_f32_16x16x32_bf16 v[96:99], v[176:179], v[216:219], v[96:99]
	v_mfma_f32_16x16x32_bf16 v[100:103], v[180:183], v[216:219], v[100:103]
	v_mfma_f32_16x16x32_bf16 v[104:107], v[184:187], v[216:219], v[104:107]
	v_mfma_f32_16x16x32_bf16 v[108:111], v[188:191], v[216:219], v[108:111]
	ds_read_b128 v[168:171], v232 offset:6144
	s_add_u32 s31, s31, 24576
	s_cmp_eq_u32 s31, 73728
	s_cselect_b32 s31, 0, s31
	v_mfma_f32_16x16x32_bf16 v[112:115], v[176:179], v[220:223], v[112:115]
	v_mfma_f32_16x16x32_bf16 v[116:119], v[180:183], v[220:223], v[116:119]
	v_mfma_f32_16x16x32_bf16 v[120:123], v[184:187], v[220:223], v[120:123]
	v_mfma_f32_16x16x32_bf16 v[124:127], v[188:191], v[220:223], v[124:127]
	ds_read_b128 v[172:175], v232 offset:7168
	s_cmp_eq_u32 s21, 0
	s_cbranch_scc0 .Lg1_hi3
	s_setprio 0
.Lg1_hi3:
	s_waitcnt vmcnt(0)
	s_waitcnt lgkmcnt(0)
	s_barrier
	v_add_u32_e32 v232, s31, v230
	v_add_u32_e32 v233, s31, v231
	s_setprio 1
	v_mfma_f32_16x16x32_bf16 v[0:3], v[128:131], v[144:147], v[0:3]
	v_mfma_f32_16x16x32_bf16 v[4:7], v[132:135], v[144:147], v[4:7]
	v_mfma_f32_16x16x32_bf16 v[8:11], v[136:139], v[144:147], v[8:11]
	v_mfma_f32_16x16x32_bf16 v[12:15], v[140:143], v[144:147], v[12:15]
	ds_read_b128 v[176:179], v233 offset:0
	ds_read_b128 v[180:183], v233 offset:1024
	v_mfma_f32_16x16x32_bf16 v[16:19], v[128:131], v[148:151], v[16:19]
	v_mfma_f32_16x16x32_bf16 v[20:23], v[132:135], v[148:151], v[20:23]
	v_mfma_f32_16x16x32_bf16 v[24:27], v[136:139], v[148:151], v[24:27]
	v_mfma_f32_16x16x32_bf16 v[28:31], v[140:143], v[148:151], v[28:31]
	ds_read_b128 v[184:187], v233 offset:2048
	ds_read_b128 v[188:191], v233 offset:3072
	v_mfma_f32_16x16x32_bf16 v[32:35], v[128:131], v[152:155], v[32:35]
	v_mfma_f32_16x16x32_bf16 v[36:39], v[132:135], v[152:155], v[36:39]
	v_mfma_f32_16x16x32_bf16 v[40:43], v[136:139], v[152:155], v[40:43]
	v_mfma_f32_16x16x32_bf16 v[44:47], v[140:143], v[152:155], v[44:47]
	ds_read_b128 v[192:195], v232 offset:0
	ds_read_b128 v[196:199], v232 offset:1024
	v_mfma_f32_16x16x32_bf16 v[48:51], v[128:131], v[156:159], v[48:51]
	v_mfma_f32_16x16x32_bf16 v[52:55], v[132:135], v[156:159], v[52:55]
	v_mfma_f32_16x16x32_bf16 v[56:59], v[136:139], v[156:159], v[56:59]
	v_mfma_f32_16x16x32_bf16 v[60:63], v[140:143], v[156:159], v[60:63]
	ds_read_b128 v[200:203], v232 offset:2048
	ds_read_b128 v[204:207], v232 offset:3072
	v_mfma_f32_16x16x32_bf16 v[64:67], v[128:131], v[160:163], v[64:67]
	v_mfma_f32_16x16x32_bf16 v[68:71], v[132:135], v[160:163], v[68:71]
	v_mfma_f32_16x16x32_bf16 v[72:75], v[136:139], v[160:163], v[72:75]
	v_mfma_f32_16x16x32_bf16 v[76:79], v[140:143], v[160:163], v[76:79]
	ds_read_b128 v[208:211], v232 offset:4096
	v_mfma_f32_16x16x32_bf16 v[80:83], v[128:131], v[164:167], v[80:83]
	v_mfma_f32_16x16x32_bf16 v[84:87], v[132:135], v[164:167], v[84:87]
	v_mfma_f32_16x16x32_bf16 v[88:91], v[136:139], v[164:167], v[88:91]
	v_mfma_f32_16x16x32_bf16 v[92:95], v[140:143], v[164:167], v[92:95]
	ds_read_b128 v[212:215], v232 offset:5120
	v_mfma_f32_16x16x32_bf16 v[96:99], v[128:131], v[168:171], v[96:99]
	v_mfma_f32_16x16x32_bf16 v[100:103], v[132:135], v[168:171], v[100:103]
	v_mfma_f32_16x16x32_bf16 v[104:107], v[136:139], v[168:171], v[104:107]
	v_mfma_f32_16x16x32_bf16 v[108:111], v[140:143], v[168:171], v[108:111]
	ds_read_b128 v[216:219], v232 offset:6144
	s_add_u32 s31, s31, 24576
	s_cmp_eq_u32 s31, 73728
	s_cselect_b32 s31, 0, s31
	v_mfma_f32_16x16x32_bf16 v[112:115], v[128:131], v[172:175], v[112:115]
	v_mfma_f32_16x16x32_bf16 v[116:119], v[132:135], v[172:175], v[116:119]
	v_mfma_f32_16x16x32_bf16 v[120:123], v[136:139], v[172:175], v[120:123]
	v_mfma_f32_16x16x32_bf16 v[124:127], v[140:143], v[172:175], v[124:127]
	ds_read_b128 v[220:223], v232 offset:7168
	s_cmp_eq_u32 s21, 0
	s_cbranch_scc0 .Lg1_hi4
	s_setprio 0
; #define LWRITE(S, buf) do { bf16_t* sA_ = sbase + (buf) * BUF; bf16_t* sB_ = sA_ + 256 * PITCH; \
;     _Pragma("unroll") for (int i_ = 0; i_ < 4; ++i_) *(u32x4*)(sA_ + (sr + i_ * 64) * PITCH + scv * 8) = ra[S][i_]; \
;     _Pragma("unroll") for (int i_ = 0; i_ < 2; ++i_) *(u32x4*)(sB_ + (sr + i_ * 64) * PITCH + scv * 8) = rb[S][i_]; } while (0)
; template <class Epi>
; DI void gemm_tile(char* smem, const bf16_t* __restrict__ A0, int lda0, int ksplit, const bf16_t* __restrict__ A1, int lda1,
;                   const bf16_t* __restrict__ Bt, int K, int row0, int col0, const Epi& epi, int tid) {
;     ...
;   __syncthreads();
;   {
;     const int last = nk - 1;
;     GLOAD(0, 0);
;     __builtin_amdgcn_sched_barrier(0);
;     GLOAD(1, 1);
;     __builtin_amdgcn_sched_barrier(0);
;     LWRITE(0, 0);
;     __builtin_amdgcn_sched_barrier(0);
;     GLOAD(0, (2 < last ? 2 : last));
;     __builtin_amdgcn_sched_barrier(0);
;     __syncthreads();
;     for (int kt = 0; kt < nk; kt += 2) {
;       LWRITE(1, 1);
;       __builtin_amdgcn_sched_barrier(0);
;       GLOAD(1, (kt + 3 < last ? kt + 3 : last));
;       __builtin_amdgcn_sched_barrier(0);
;       COMPUTE(0);
;       __syncthreads();
;       LWRITE(0, 0);
;       __builtin_amdgcn_sched_barrier(0);
;       GLOAD(0, (kt + 4 < last ? kt + 4 : last));
;       __builtin_amdgcn_sched_barrier(0);
;       COMPUTE(1);
;       __syncthreads();
;     }
.Lg1_hi4:
	s_waitcnt lgkmcnt(0)
	s_barrier
	s_setprio 1
	v_mfma_f32_16x16x32_bf16 v[0:3], v[176:179], v[192:195], v[0:3]
	v_mfma_f32_16x16x32_bf16 v[4:7], v[180:183], v[192:195], v[4:7]
	v_mfma_f32_16x16x32_bf16 v[8:11], v[184:187], v[192:195], v[8:11]
	v_mfma_f32_16x16x32_bf16 v[12:15], v[188:191], v[192:195], v[12:15]
	v_mfma_f32_16x16x32_bf16 v[16:19], v[176:179], v[196:199], v[16:19]
	v_mfma_f32_16x16x32_bf16 v[20:23], v[180:183], v[196:199], v[20:23]
	v_mfma_f32_16x16x32_bf16 v[24:27], v[184:187], v[196:199], v[24:27]
	v_mfma_f32_16x16x32_bf16 v[28:31], v[188:191], v[196:199], v[28:31]
	v_mfma_f32_16x16x32_bf16 v[32:35], v[176:179], v[200:203], v[32:35]
	v_mfma_f32_16x16x32_bf16 v[36:39], v[180:183], v[200:203], v[36:39]
	v_mfma_f32_16x16x32_bf16 v[40:43], v[184:187], v[200:203], v[40:43]
	v_mfma_f32_16x16x32_bf16 v[44:47], v[188:191], v[200:203], v[44:47]
	v_mfma_f32_16x16x32_bf16 v[48:51], v[176:179], v[204:207], v[48:51]
	v_mfma_f32_16x16x32_bf16 v[52:55], v[180:183], v[204:207], v[52:55]
	v_mfma_f32_16x16x32_bf16 v[56:59], v[184:187], v[204:207], v[56:59]
	v_mfma_f32_16x16x32_bf16 v[60:63], v[188:191], v[204:207], v[60:63]
	v_mfma_f32_16x16x32_bf16 v[64:67], v[176:179], v[208:211], v[64:67]
	v_mfma_f32_16x16x32_bf16 v[68:71], v[180:183], v[208:211], v[68:71]
	v_mfma_f32_16x16x32_bf16 v[72:75], v[184:187], v[208:211], v[72:75]
	v_mfma_f32_16x16x32_bf16 v[76:79], v[188:191], v[208:211], v[76:79]
	v_mfma_f32_16x16x32_bf16 v[80:83], v[176:179], v[212:215], v[80:83]
	v_mfma_f32_16x16x32_bf16 v[84:87], v[180:183], v[212:215], v[84:87]
	v_mfma_f32_16x16x32_bf16 v[88:91], v[184:187], v[212:215], v[88:91]
	v_mfma_f32_16x16x32_bf16 v[92:95], v[188:191], v[212:215], v[92:95]
	v_mfma_f32_16x16x32_bf16 v[96:99], v[176:179], v[216:219], v[96:99]
	v_mfma_f32_16x16x32_bf16 v[100:103], v[180:183], v[216:219], v[100:103]
	v_mfma_f32_16x16x32_bf16 v[104:107], v[184:187], v[216:219], v[104:107]
	v_mfma_f32_16x16x32_bf16 v[108:111], v[188:191], v[216:219], v[108:111]
	v_mfma_f32_16x16x32_bf16 v[112:115], v[176:179], v[220:223], v[112:115]
	v_mfma_f32_16x16x32_bf16 v[116:119], v[180:183], v[220:223], v[116:119]
	v_mfma_f32_16x16x32_bf16 v[120:123], v[184:187], v[220:223], v[120:123]
	v_mfma_f32_16x16x32_bf16 v[124:127], v[188:191], v[220:223], v[124:127]
	s_cmp_eq_u32 s21, 0
	s_cbranch_scc0 .Lg1_hi5
	s_setprio 0
.Lg1_hi5:
	s_branch .Lg1_epi
; DI unsigned pack2(float lo, float hi) { const f32x2c v = {lo, hi}; return __builtin_bit_cast(unsigned, __builtin_convertvector(v, bf16x2c)); }
; template <class Epi>
; DI void gemm_tile(char* smem, const bf16_t* __restrict__ A0, int lda0, int ksplit, const bf16_t* __restrict__ A1, int lda1,
;                   const bf16_t* __restrict__ Bt, int K, int row0, int col0, const Epi& epi, int tid) {
;     ...
;   for (int m = 0; m < 8; ++m)
; #pragma unroll
;     for (int n = 0; n < 4; ++n) epi(row0 + wr * 128 + m * 16 + fr, col0 + wc * 64 + n * 16 + fq * 4, acc[m][n]);
; }
; DI void st_bf16x4(bf16_t* o, f32x4 v) { u32x2 q; q.x = pack2(v[0], v[1]); q.y = pack2(v[2], v[3]); *(u32x2*)o = q; }
;   DI void operator()(int row, int col, f32x4 v) const {
;     if (col < n0) st_bf16x4(o0 + (size_t)row * ld0 + col, v);
;     else { const int c = col - n0; if (c < n1) st_bf16x4(o1 + (size_t)row * ld1 + c, v); }
;   }
.Lg1_epi:
	s_nop 7
	s_nop 7
	s_cmpk_ge_u32 s24, 1792
	s_cbranch_scc1 .Lg1_eo1
	s_mul_i32 s23, s25, 3584
	s_lshl_b32 s22, s24, 1
	s_add_u32 s23, s23, s22
	s_add_u32 s23, s23, 0x7800000
	s_add_u32 s4, s92, s23
	s_addc_u32 s5, s93, 0
	v_cvt_pk_bf16_f32 v128, v0, v1
	v_cvt_pk_bf16_f32 v129, v2, v3
	ds_write_b64 v236, v[128:129]
	v_cvt_pk_bf16_f32 v130, v4, v5
	v_cvt_pk_bf16_f32 v131, v6, v7
	ds_write_b64 v236, v[130:131] offset:32
	v_cvt_pk_bf16_f32 v132, v8, v9
	v_cvt_pk_bf16_f32 v133, v10, v11
	ds_write_b64 v236, v[132:133] offset:64
	v_cvt_pk_bf16_f32 v134, v12, v13
	v_cvt_pk_bf16_f32 v135, v14, v15
	ds_write_b64 v236, v[134:135] offset:96
	v_cvt_pk_bf16_f32 v136, v16, v17
	v_cvt_pk_bf16_f32 v137, v18, v19
	ds_write_b64 v236, v[136:137] offset:2304
	v_cvt_pk_bf16_f32 v138, v20, v21
	v_cvt_pk_bf16_f32 v139, v22, v23
	ds_write_b64 v236, v[138:139] offset:2336
	v_cvt_pk_bf16_f32 v140, v24, v25
	v_cvt_pk_bf16_f32 v141, v26, v27
	ds_write_b64 v236, v[140:141] offset:2368
	v_cvt_pk_bf16_f32 v142, v28, v29
	v_cvt_pk_bf16_f32 v143, v30, v31
	ds_write_b64 v236, v[142:143] offset:2400
	v_cvt_pk_bf16_f32 v144, v32, v33
	v_cvt_pk_bf16_f32 v145, v34, v35
	ds_write_b64 v236, v[144:145] offset:4608
	v_cvt_pk_bf16_f32 v146, v36, v37
	v_cvt_pk_bf16_f32 v147, v38, v39
	ds_write_b64 v236, v[146:147] offset:4640
	v_cvt_pk_bf16_f32 v148, v40, v41
	v_cvt_pk_bf16_f32 v149, v42, v43
	ds_write_b64 v236, v[148:149] offset:4672
	v_cvt_pk_bf16_f32 v150, v44, v45
	v_cvt_pk_bf16_f32 v151, v46, v47
	ds_write_b64 v236, v[150:151] offset:4704
	v_cvt_pk_bf16_f32 v152, v48, v49
	v_cvt_pk_bf16_f32 v153, v50, v51
	ds_write_b64 v236, v[152:153] offset:6912
	v_cvt_pk_bf16_f32 v154, v52, v53
	v_cvt_pk_bf16_f32 v155, v54, v55
	ds_write_b64 v236, v[154:155] offset:6944
	v_cvt_pk_bf16_f32 v156, v56, v57
	v_cvt_pk_bf16_f32 v157, v58, v59
	ds_write_b64 v236, v[156:157] offset:6976
	v_cvt_pk_bf16_f32 v158, v60, v61
	v_cvt_pk_bf16_f32 v159, v62, v63
	ds_write_b64 v236, v[158:159] offset:7008
	v_cvt_pk_bf16_f32 v128, v64, v65
	v_cvt_pk_bf16_f32 v129, v66, v67
	ds_write_b64 v236, v[128:129] offset:9216
	v_cvt_pk_bf16_f32 v130, v68, v69
	v_cvt_pk_bf16_f32 v131, v70, v71
	ds_write_b64 v236, v[130:131] offset:9248
	v_cvt_pk_bf16_f32 v132, v72, v73
	v_cvt_pk_bf16_f32 v133, v74, v75
	ds_write_b64 v236, v[132:133] offset:9280
	v_cvt_pk_bf16_f32 v134, v76, v77
	v_cvt_pk_bf16_f32 v135, v78, v79
	ds_write_b64 v236, v[134:135] offset:9312
	v_cvt_pk_bf16_f32 v136, v80, v81
	v_cvt_pk_bf16_f32 v137, v82, v83
	ds_write_b64 v236, v[136:137] offset:11520
	v_cvt_pk_bf16_f32 v138, v84, v85
	v_cvt_pk_bf16_f32 v139, v86, v87
	ds_write_b64 v236, v[138:139] offset:11552
	v_cvt_pk_bf16_f32 v140, v88, v89
	v_cvt_pk_bf16_f32 v141, v90, v91
	ds_write_b64 v236, v[140:141] offset:11584
	v_cvt_pk_bf16_f32 v142, v92, v93
	v_cvt_pk_bf16_f32 v143, v94, v95
	ds_write_b64 v236, v[142:143] offset:11616
	v_cvt_pk_bf16_f32 v144, v96, v97
	v_cvt_pk_bf16_f32 v145, v98, v99
	ds_write_b64 v236, v[144:145] offset:13824
	v_cvt_pk_bf16_f32 v146, v100, v101
	v_cvt_pk_bf16_f32 v147, v102, v103
	ds_write_b64 v236, v[146:147] offset:13856
	v_cvt_pk_bf16_f32 v148, v104, v105
	v_cvt_pk_bf16_f32 v149, v106, v107
	ds_write_b64 v236, v[148:149] offset:13888
	v_cvt_pk_bf16_f32 v150, v108, v109
	v_cvt_pk_bf16_f32 v151, v110, v111
	ds_write_b64 v236, v[150:151] offset:13920
	v_cvt_pk_bf16_f32 v152, v112, v113
	v_cvt_pk_bf16_f32 v153, v114, v115
	ds_write_b64 v236, v[152:153] offset:16128
	v_cvt_pk_bf16_f32 v154, v116, v117
	v_cvt_pk_bf16_f32 v155, v118, v119
	ds_write_b64 v236, v[154:155] offset:16160
	v_cvt_pk_bf16_f32 v156, v120, v121
	v_cvt_pk_bf16_f32 v157, v122, v123
	ds_write_b64 v236, v[156:157] offset:16192
	v_cvt_pk_bf16_f32 v158, v124, v125
	v_cvt_pk_bf16_f32 v159, v126, v127
	ds_write_b64 v236, v[158:159] offset:16224
	s_waitcnt lgkmcnt(0)
	ds_read_b128 v[128:131], v237
	ds_read_b128 v[132:135], v237 offset:1152
	ds_read_b128 v[136:139], v237 offset:2304
	ds_read_b128 v[140:143], v237 offset:3456
	ds_read_b128 v[144:147], v237 offset:4608
	ds_read_b128 v[148:151], v237 offset:5760
	ds_read_b128 v[152:155], v237 offset:6912
	ds_read_b128 v[156:159], v237 offset:8064
	ds_read_b128 v[160:163], v237 offset:9216
	ds_read_b128 v[164:167], v237 offset:10368
	ds_read_b128 v[168:171], v237 offset:11520
	ds_read_b128 v[172:175], v237 offset:12672
	ds_read_b128 v[176:179], v237 offset:13824
	ds_read_b128 v[180:183], v237 offset:14976
	ds_read_b128 v[184:187], v237 offset:16128
	ds_read_b128 v[188:191], v237 offset:17280
	s_waitcnt lgkmcnt(15)
	global_store_dwordx4 v238, v[128:131], s[4:5] nt
	s_add_u32 s4, s4, 0x7000
	s_addc_u32 s5, s5, 0
	s_waitcnt lgkmcnt(14)
	global_store_dwordx4 v238, v[132:135], s[4:5] nt
	s_add_u32 s4, s4, 0x7000
	s_addc_u32 s5, s5, 0
	s_waitcnt lgkmcnt(13)
	global_store_dwordx4 v238, v[136:139], s[4:5] nt
	s_add_u32 s4, s4, 0x7000
	s_addc_u32 s5, s5, 0
	s_waitcnt lgkmcnt(12)
	global_store_dwordx4 v238, v[140:143], s[4:5] nt
	s_add_u32 s4, s4, 0x7000
	s_addc_u32 s5, s5, 0
	s_waitcnt lgkmcnt(11)
	global_store_dwordx4 v238, v[144:147], s[4:5] nt
	s_add_u32 s4, s4, 0x7000
	s_addc_u32 s5, s5, 0
	s_waitcnt lgkmcnt(10)
	global_store_dwordx4 v238, v[148:151], s[4:5] nt
	s_add_u32 s4, s4, 0x7000
	s_addc_u32 s5, s5, 0
	s_waitcnt lgkmcnt(9)
	global_store_dwordx4 v238, v[152:155], s[4:5] nt
	s_add_u32 s4, s4, 0x7000
	s_addc_u32 s5, s5, 0
	s_waitcnt lgkmcnt(8)
	global_store_dwordx4 v238, v[156:159], s[4:5] nt
	s_add_u32 s4, s4, 0x7000
	s_addc_u32 s5, s5, 0
	s_waitcnt lgkmcnt(7)
	global_store_dwordx4 v238, v[160:163], s[4:5] nt
	s_add_u32 s4, s4, 0x7000
	s_addc_u32 s5, s5, 0
	s_waitcnt lgkmcnt(6)
	global_store_dwordx4 v238, v[164:167], s[4:5] nt
	s_add_u32 s4, s4, 0x7000
	s_addc_u32 s5, s5, 0
	s_waitcnt lgkmcnt(5)
	global_store_dwordx4 v238, v[168:171], s[4:5] nt
	s_add_u32 s4, s4, 0x7000
	s_addc_u32 s5, s5, 0
	s_waitcnt lgkmcnt(4)
	global_store_dwordx4 v238, v[172:175], s[4:5] nt
	s_add_u32 s4, s4, 0x7000
	s_addc_u32 s5, s5, 0
	s_waitcnt lgkmcnt(3)
	global_store_dwordx4 v238, v[176:179], s[4:5] nt
	s_add_u32 s4, s4, 0x7000
	s_addc_u32 s5, s5, 0
	s_waitcnt lgkmcnt(2)
	global_store_dwordx4 v238, v[180:183], s[4:5] nt
	s_add_u32 s4, s4, 0x7000
	s_addc_u32 s5, s5, 0
	s_waitcnt lgkmcnt(1)
	global_store_dwordx4 v238, v[184:187], s[4:5] nt
	s_add_u32 s4, s4, 0x7000
	s_addc_u32 s5, s5, 0
	s_waitcnt lgkmcnt(0)
	global_store_dwordx4 v238, v[188:191], s[4:5] nt
	s_nop 1
	s_branch .Lg1_enext

; template <class Epi>
; DI void gemm_tile(char* smem, const bf16_t* __restrict__ A0, int lda0, int ksplit, const bf16_t* __restrict__ A1, int lda1,
;                   const bf16_t* __restrict__ Bt, int K, int row0, int col0, const Epi& epi, int tid) {
;   constexpr int BK = 32, PITCH = 40, BUF = (256 + 128) * PITCH;
;   bf16_t* sbase = (bf16_t*)smem;
;   const int lane = tid & 63, wid = tid >> 6, wr = wid >> 1, wc = wid & 1, fr = lane & 15, fq = lane >> 4;
;   f32x4 acc[8][4];
; #pragma unroll
;   for (int m = 0; m < 8; ++m)
; #pragma unroll
;     for (int n = 0; n < 4; ++n) acc[m][n] = (f32x4){0.f, 0.f, 0.f, 0.f};
;   u32x4 ra[2][4], rb[2][2];
;   const int nk = K / BK;
;   const int sr = tid >> 2, scv = tid & 3;
; DI void phase_rw_small_gemms(const Ctx& c, char* smem) {
;   const Params& p = c.p; (void)p;
;   const int tid = TIDX;
;   const bf16_t* sm = (const bf16_t*)(p.ws + OFF_SM);
;   bf16_t* E0 = (bf16_t*)(p.ws + OFF_R1); bf16_t* E1 = E0 + (size_t)NTOK * 512; bf16_t* Ab = E1 + (size_t)NTOK * 512;
;   bf16_t* G = (bf16_t*)(p.ws + OFF_XN);
;   const bf16_t* W2 = (const bf16_t*)(p.ws + OFF_WW2); const bf16_t* A2 = (const bf16_t*)(p.ws + OFF_WA2); const bf16_t* G2 = (const bf16_t*)(p.ws + OFF_WG2);
;   gemm_phase(smem, sm, 256, 1 << 30, sm, 256, W2, 64, 4, EpiSmall{0, p.rw_w0, E0}, tid);
.LBB0_549:
	s_cmp_gt_i32 s94, 3
	s_cselect_b64 s[0:1], -1, 0
	s_cmp_lt_i32 s95, 4
	s_cselect_b64 s[2:3], -1, 0
	s_or_b64 s[0:1], s[0:1], s[2:3]
	s_and_b64 vcc, exec, s[0:1]
	s_cbranch_vccnz .LBB0_600
	s_and_b32 s14, s72, 0xffffffc0
	s_add_u32 s4, s92, 0x1ea00000
	s_load_dword s12, s[74:75], 0x180
	s_addc_u32 s5, s93, 0
	s_add_u32 s0, s92, 0x7800000
	s_addc_u32 s1, s93, 0
	s_add_u32 s6, s92, 0x34a0000
	s_addc_u32 s7, s93, 0
	s_waitcnt lgkmcnt(0)
	s_and_b32 s13, s12, 7
	s_cmp_lg_u32 s13, 0
	s_waitcnt vmcnt(7)
	v_mbcnt_hi_u32_b32 v136, -1, v194
	s_cselect_b64 s[2:3], -1, 0
	v_add_u32_e32 v137, s14, v136
	s_and_b64 vcc, exec, s[2:3]
	v_mbcnt_lo_u32_b32 v240, -1, 0
	v_mbcnt_hi_u32_b32 v240, -1, v240
	s_lshr_b32 s27, s72, 6
	s_lshl_b32 s100, s27, 10
	v_and_b32_e32 v241, 15, v240
	v_lshrrev_b32_e32 v242, 4, v240
	v_bfe_u32 v243, v240, 3, 1
	v_mul_u32_u24_e32 v243, 3, v243
	v_xor_b32_e32 v243, v242, v243
	v_lshlrev_b32_e32 v243, 4, v243
	v_lshl_add_u32 v243, v241, 6, v243
	s_lshr_b32 s26, s27, 1
	s_lshl_b32 s26, s26, 13
	v_add_u32_e32 v230, s26, v243
	s_and_b32 s26, s27, 1
	s_lshl_b32 s26, s26, 12
	s_add_u32 s26, s26, 16384
	v_add_u32_e32 v231, s26, v243
	s_lshr_b32 s26, s27, 1
	s_lshl_b32 s26, s26, 7
	v_add_u32_e32 v244, s26, v241
	s_and_b32 s26, s27, 1
	s_lshl_b32 s26, s26, 6
	v_lshl_add_u32 v245, v242, 2, s26
	v_lshlrev_b32_e32 v235, 2, v245
	s_mul_i32 s26, s27, 18432
	v_mul_u32_u24_e32 v246, 144, v241
	v_lshl_add_u32 v246, v242, 3, v246
	v_add_u32_e32 v236, s26, v246
	v_lshrrev_b32_e32 v246, 3, v240
	v_mul_u32_u24_e32 v246, 144, v246
	v_and_b32_e32 v247, 7, v240
	v_lshl_add_u32 v246, v247, 4, v246
	v_add_u32_e32 v237, s26, v246
	s_lshr_b32 s26, s27, 1
	s_lshl_b32 s26, s26, 7
	v_lshrrev_b32_e32 v246, 3, v240
	v_add_u32_e32 v246, s26, v246
	s_and_b32 s26, s27, 1
	s_lshl_b32 s26, s26, 6
	v_lshl_add_u32 v248, v247, 3, s26
	s_movk_i32 s26, 1024
	v_mul_lo_u32 v247, v246, s26
	v_lshl_add_u32 v238, v248, 1, v247
	v_lshrrev_b32_e32 v241, 2, v240
	s_lshl_b32 s26, s27, 4
	v_add_u32_e32 v241, s26, v241
	v_bfe_u32 v242, v240, 5, 1
	v_mul_u32_u24_e32 v242, 3, v242
	v_and_b32_e32 v243, 3, v240
	v_xor_b32_e32 v243, v243, v242
	v_lshlrev_b32_e32 v243, 4, v243
	s_mov_b32 s26, 512
	v_mad_u32_u24 v224, v241, s26, v243
	v_add_u32_e32 v225, 0x8000, v224
	v_add_u32_e32 v226, 0x10000, v224
	v_add_u32_e32 v227, 0x18000, v224
	s_mov_b32 s26, 128
	v_mad_u32_u24 v228, v241, s26, v243
	v_add_u32_e32 v229, 0x2000, v228
	s_load_dwordx2 s[6:7], s[74:75], 0x48
	s_cmpk_gt_u32 s96, 0xff
	s_cselect_b32 s25, 1, 0
	s_cmpk_gt_u32 s96, 0xff
	s_cbranch_scc0 .Lg3a_prio
	s_setprio 1

; #define LWRITE(S, buf) do { bf16_t* sA_ = sbase + (buf) * BUF; bf16_t* sB_ = sA_ + 256 * PITCH; \
;     _Pragma("unroll") for (int i_ = 0; i_ < 4; ++i_) *(u32x4*)(sA_ + (sr + i_ * 64) * PITCH + scv * 8) = ra[S][i_]; \
;     _Pragma("unroll") for (int i_ = 0; i_ < 2; ++i_) *(u32x4*)(sB_ + (sr + i_ * 64) * PITCH + scv * 8) = rb[S][i_]; } while (0)
; template <class Epi>
; DI void gemm_tile(char* smem, const bf16_t* __restrict__ A0, int lda0, int ksplit, const bf16_t* __restrict__ A1, int lda1,
;                   const bf16_t* __restrict__ Bt, int K, int row0, int col0, const Epi& epi, int tid) {
;     ...
;   const int lane = tid & 63, wid = tid >> 6, wr = wid >> 1, wc = wid & 1, fr = lane & 15, fq = lane >> 4;
;   f32x4 acc[8][4];
; #pragma unroll
;   for (int m = 0; m < 8; ++m)
; #pragma unroll
;     for (int n = 0; n < 4; ++n) acc[m][n] = (f32x4){0.f, 0.f, 0.f, 0.f};
;   u32x4 ra[2][4], rb[2][2];
;   const int nk = K / BK;
;   const int sr = tid >> 2, scv = tid & 3;
;     ...
;   __syncthreads();
;   {
;     const int last = nk - 1;
;     GLOAD(0, 0);
;     __builtin_amdgcn_sched_barrier(0);
;     GLOAD(1, 1);
;     __builtin_amdgcn_sched_barrier(0);
;     LWRITE(0, 0);
;     __builtin_amdgcn_sched_barrier(0);
;     GLOAD(0, (2 < last ? 2 : last));
;     __builtin_amdgcn_sched_barrier(0);
;     __syncthreads();
; template <class Epi>
; DI void gemm_phase(char* smem, const bf16_t* A0, int lda0, int ksplit, const bf16_t* A1, int lda1, const bf16_t* Bt, int K, int nN, const Epi& epi, int tid) {
;     ...
;     const int x = blockIdx.x & 7, l = blockIdx.x >> 3, L = G >> 3, per = 8 * nN, tot = 2 * per;
;     for (int q = l; q < tot; q += L) { const int rgl = q / per, rem = q % per, ct = rem >> 3, rt = (x * 2 + rgl) * 8 + (rem & 7);
;       gemm_tile(smem, A0, lda0, ksplit, A1, lda1, Bt, K, rt * 256, ct * 128, epi, tid); }
.Lg3a_tile:
	s_cmpk_ge_u32 s15, 64
	s_cbranch_scc1 .Lg3a_done
	s_cmpk_ge_u32 s15, 32
	s_cselect_b32 s27, 1, 0
	s_cselect_b32 s26, 32, 0
	s_sub_u32 s26, s15, s26
	s_add_u32 s27, s27, s101
	s_lshl_b32 s27, s27, 3
	s_and_b32 s29, s26, 7
	s_add_u32 s29, s29, s27
	s_lshl_b32 s29, s29, 8
	s_lshr_b32 s28, s26, 3
	s_lshl_b32 s28, s28, 7
	s_mul_i32 s27, s29, 512
	s_add_u32 s27, s27, 0x1ea00000
	s_add_u32 s0, s92, s27
	s_addc_u32 s1, s93, 0
	s_mul_i32 s27, s28, 128
	s_add_u32 s27, s27, 0x34a0000
	s_add_u32 s2, s92, s27
	s_addc_u32 s3, s93, 0
	s_waitcnt lgkmcnt(0)
	s_barrier
	s_mov_b32 s99, 0
	s_mov_b32 s30, 0
	s_add_u32 s26, s30, s100
	s_add_u32 m0, s26, 0
	s_nop 0
	global_load_lds_dwordx4 v224, s[0:1]
	s_add_u32 m0, s26, 4096
	s_nop 0
	global_load_lds_dwordx4 v225, s[0:1]
	s_add_u32 m0, s26, 8192
	s_nop 0
	global_load_lds_dwordx4 v226, s[0:1]
	s_add_u32 m0, s26, 12288
	s_nop 0
	global_load_lds_dwordx4 v227, s[0:1]
	s_add_u32 m0, s26, 16384
	s_nop 0
	global_load_lds_dwordx4 v228, s[2:3]
	s_add_u32 m0, s26, 20480
	s_nop 0
	global_load_lds_dwordx4 v229, s[2:3]
	s_add_u32 s0, s0, 64
	s_addc_u32 s1, s1, 0
	s_add_u32 s2, s2, 64
	s_addc_u32 s3, s3, 0
	s_add_u32 s99, s99, 1
	s_add_u32 s30, s30, 24576
	s_cmp_eq_u32 s30, 73728
	s_cselect_b32 s30, 0, s30
	s_add_u32 s26, s30, s100
	s_add_u32 m0, s26, 0
	s_nop 0
	global_load_lds_dwordx4 v224, s[0:1]
	s_add_u32 m0, s26, 4096
	s_nop 0
	global_load_lds_dwordx4 v225, s[0:1]
	s_add_u32 m0, s26, 8192
	s_nop 0
	global_load_lds_dwordx4 v226, s[0:1]
	s_add_u32 m0, s26, 12288
	s_nop 0
	global_load_lds_dwordx4 v227, s[0:1]
	s_add_u32 m0, s26, 16384
	s_nop 0
	global_load_lds_dwordx4 v228, s[2:3]
	s_add_u32 m0, s26, 20480
	s_nop 0
	global_load_lds_dwordx4 v229, s[2:3]
	s_add_u32 s0, s0, 64
	s_addc_u32 s1, s1, 0
	s_add_u32 s2, s2, 64
	s_addc_u32 s3, s3, 0
	s_add_u32 s99, s99, 1
	s_add_u32 s30, s30, 24576
	s_cmp_eq_u32 s30, 73728
	s_cselect_b32 s30, 0, s30
	v_mov_b32_e32 v0, 0
	v_mov_b32_e32 v1, 0
	v_mov_b32_e32 v2, 0
	v_mov_b32_e32 v3, 0
	v_mov_b32_e32 v4, 0
	v_mov_b32_e32 v5, 0
	v_mov_b32_e32 v6, 0
	v_mov_b32_e32 v7, 0
	v_mov_b32_e32 v8, 0
	v_mov_b32_e32 v9, 0
	v_mov_b32_e32 v10, 0
	v_mov_b32_e32 v11, 0
	v_mov_b32_e32 v12, 0
	v_mov_b32_e32 v13, 0
	v_mov_b32_e32 v14, 0
	v_mov_b32_e32 v15, 0
	v_mov_b32_e32 v16, 0
	v_mov_b32_e32 v17, 0
	v_mov_b32_e32 v18, 0
	v_mov_b32_e32 v19, 0
	v_mov_b32_e32 v20, 0
	v_mov_b32_e32 v21, 0
	v_mov_b32_e32 v22, 0
	v_mov_b32_e32 v23, 0
	v_mov_b32_e32 v24, 0
	v_mov_b32_e32 v25, 0
	v_mov_b32_e32 v26, 0
	v_mov_b32_e32 v27, 0
	v_mov_b32_e32 v28, 0
	v_mov_b32_e32 v29, 0
	v_mov_b32_e32 v30, 0
	v_mov_b32_e32 v31, 0
	v_mov_b32_e32 v32, 0
	v_mov_b32_e32 v33, 0
	v_mov_b32_e32 v34, 0
	v_mov_b32_e32 v35, 0
	v_mov_b32_e32 v36, 0
	v_mov_b32_e32 v37, 0
	v_mov_b32_e32 v38, 0
	v_mov_b32_e32 v39, 0
	v_mov_b32_e32 v40, 0
	v_mov_b32_e32 v41, 0
	v_mov_b32_e32 v42, 0
	v_mov_b32_e32 v43, 0
	v_mov_b32_e32 v44, 0
	v_mov_b32_e32 v45, 0
	v_mov_b32_e32 v46, 0
	v_mov_b32_e32 v47, 0
	v_mov_b32_e32 v48, 0
	v_mov_b32_e32 v49, 0
	v_mov_b32_e32 v50, 0
	v_mov_b32_e32 v51, 0
	v_mov_b32_e32 v52, 0
	v_mov_b32_e32 v53, 0
	v_mov_b32_e32 v54, 0
	v_mov_b32_e32 v55, 0
	v_mov_b32_e32 v56, 0
	v_mov_b32_e32 v57, 0
	v_mov_b32_e32 v58, 0
	v_mov_b32_e32 v59, 0
	v_mov_b32_e32 v60, 0
	v_mov_b32_e32 v61, 0
	v_mov_b32_e32 v62, 0
	v_mov_b32_e32 v63, 0
	v_mov_b32_e32 v64, 0
	v_mov_b32_e32 v65, 0
	v_mov_b32_e32 v66, 0
	v_mov_b32_e32 v67, 0
	v_mov_b32_e32 v68, 0
	v_mov_b32_e32 v69, 0
	v_mov_b32_e32 v70, 0
	v_mov_b32_e32 v71, 0
	v_mov_b32_e32 v72, 0
	v_mov_b32_e32 v73, 0
	v_mov_b32_e32 v74, 0
	v_mov_b32_e32 v75, 0
	v_mov_b32_e32 v76, 0
	v_mov_b32_e32 v77, 0
	v_mov_b32_e32 v78, 0
	v_mov_b32_e32 v79, 0
	v_mov_b32_e32 v80, 0
	v_mov_b32_e32 v81, 0
	v_mov_b32_e32 v82, 0
	v_mov_b32_e32 v83, 0
	v_mov_b32_e32 v84, 0
	v_mov_b32_e32 v85, 0
	v_mov_b32_e32 v86, 0
	v_mov_b32_e32 v87, 0
	v_mov_b32_e32 v88, 0
	v_mov_b32_e32 v89, 0
	v_mov_b32_e32 v90, 0
	v_mov_b32_e32 v91, 0
	v_mov_b32_e32 v92, 0
	v_mov_b32_e32 v93, 0
	v_mov_b32_e32 v94, 0
	v_mov_b32_e32 v95, 0
	v_mov_b32_e32 v96, 0
	v_mov_b32_e32 v97, 0
	v_mov_b32_e32 v98, 0
	v_mov_b32_e32 v99, 0
	v_mov_b32_e32 v100, 0
	v_mov_b32_e32 v101, 0
	v_mov_b32_e32 v102, 0
	v_mov_b32_e32 v103, 0
	v_mov_b32_e32 v104, 0
	v_mov_b32_e32 v105, 0
	v_mov_b32_e32 v106, 0
	v_mov_b32_e32 v107, 0
	v_mov_b32_e32 v108, 0
	v_mov_b32_e32 v109, 0
	v_mov_b32_e32 v110, 0
	v_mov_b32_e32 v111, 0
	v_mov_b32_e32 v112, 0
	v_mov_b32_e32 v113, 0
	v_mov_b32_e32 v114, 0
	v_mov_b32_e32 v115, 0
	v_mov_b32_e32 v116, 0
	v_mov_b32_e32 v117, 0
	v_mov_b32_e32 v118, 0
	v_mov_b32_e32 v119, 0
	v_mov_b32_e32 v120, 0
	v_mov_b32_e32 v121, 0
	v_mov_b32_e32 v122, 0
	v_mov_b32_e32 v123, 0
	v_mov_b32_e32 v124, 0
	v_mov_b32_e32 v125, 0
	v_mov_b32_e32 v126, 0
	v_mov_b32_e32 v127, 0
	s_mov_b32 s98, 0
	s_mov_b32 s31, 24576
	s_waitcnt vmcnt(6)
	s_barrier
	ds_read_b128 v[128:131], v231 offset:0
	ds_read_b128 v[132:135], v231 offset:1024
	ds_read_b128 v[136:139], v231 offset:2048
	ds_read_b128 v[140:143], v231 offset:3072
	ds_read_b128 v[144:147], v230 offset:0
	ds_read_b128 v[148:151], v230 offset:1024
	ds_read_b128 v[152:155], v230 offset:2048
	ds_read_b128 v[156:159], v230 offset:3072
	ds_read_b128 v[160:163], v230 offset:4096
	ds_read_b128 v[164:167], v230 offset:5120
	ds_read_b128 v[168:171], v230 offset:6144
	ds_read_b128 v[172:175], v230 offset:7168
	s_waitcnt vmcnt(0)
	s_waitcnt lgkmcnt(0)
	s_barrier
; #define LWRITE(S, buf) do { bf16_t* sA_ = sbase + (buf) * BUF; bf16_t* sB_ = sA_ + 256 * PITCH; \
;     _Pragma("unroll") for (int i_ = 0; i_ < 4; ++i_) *(u32x4*)(sA_ + (sr + i_ * 64) * PITCH + scv * 8) = ra[S][i_]; \
;     _Pragma("unroll") for (int i_ = 0; i_ < 2; ++i_) *(u32x4*)(sB_ + (sr + i_ * 64) * PITCH + scv * 8) = rb[S][i_]; } while (0)
; template <class Epi>
; DI void gemm_tile(char* smem, const bf16_t* __restrict__ A0, int lda0, int ksplit, const bf16_t* __restrict__ A1, int lda1,
;                   const bf16_t* __restrict__ Bt, int K, int row0, int col0, const Epi& epi, int tid) {
;     ...
;     for (int kt = 0; kt < nk; kt += 2) {
;       LWRITE(1, 1);
;       __builtin_amdgcn_sched_barrier(0);
;       GLOAD(1, (kt + 3 < last ? kt + 3 : last));
;       __builtin_amdgcn_sched_barrier(0);
;       COMPUTE(0);
;       __syncthreads();
;       LWRITE(0, 0);
;       __builtin_amdgcn_sched_barrier(0);
;       GLOAD(0, (kt + 4 < last ? kt + 4 : last));
;       __builtin_amdgcn_sched_barrier(0);
;       COMPUTE(1);
;       __syncthreads();
;     }
	v_add_u32_e32 v232, s31, v230
	v_add_u32_e32 v233, s31, v231
	s_setprio 1
	v_mfma_f32_16x16x32_bf16 v[0:3], v[128:131], v[144:147], v[0:3]
	v_mfma_f32_16x16x32_bf16 v[4:7], v[132:135], v[144:147], v[4:7]
	v_mfma_f32_16x16x32_bf16 v[8:11], v[136:139], v[144:147], v[8:11]
	v_mfma_f32_16x16x32_bf16 v[12:15], v[140:143], v[144:147], v[12:15]
	ds_read_b128 v[176:179], v233 offset:0
	ds_read_b128 v[180:183], v233 offset:1024
	v_mfma_f32_16x16x32_bf16 v[16:19], v[128:131], v[148:151], v[16:19]
	v_mfma_f32_16x16x32_bf16 v[20:23], v[132:135], v[148:151], v[20:23]
	v_mfma_f32_16x16x32_bf16 v[24:27], v[136:139], v[148:151], v[24:27]
	v_mfma_f32_16x16x32_bf16 v[28:31], v[140:143], v[148:151], v[28:31]
	ds_read_b128 v[184:187], v233 offset:2048
	ds_read_b128 v[188:191], v233 offset:3072
	v_mfma_f32_16x16x32_bf16 v[32:35], v[128:131], v[152:155], v[32:35]
	v_mfma_f32_16x16x32_bf16 v[36:39], v[132:135], v[152:155], v[36:39]
	v_mfma_f32_16x16x32_bf16 v[40:43], v[136:139], v[152:155], v[40:43]
	v_mfma_f32_16x16x32_bf16 v[44:47], v[140:143], v[152:155], v[44:47]
	ds_read_b128 v[192:195], v232 offset:0
	ds_read_b128 v[196:199], v232 offset:1024
	v_mfma_f32_16x16x32_bf16 v[48:51], v[128:131], v[156:159], v[48:51]
	v_mfma_f32_16x16x32_bf16 v[52:55], v[132:135], v[156:159], v[52:55]
	v_mfma_f32_16x16x32_bf16 v[56:59], v[136:139], v[156:159], v[56:59]
	v_mfma_f32_16x16x32_bf16 v[60:63], v[140:143], v[156:159], v[60:63]
	ds_read_b128 v[200:203], v232 offset:2048
	ds_read_b128 v[204:207], v232 offset:3072
	v_mfma_f32_16x16x32_bf16 v[64:67], v[128:131], v[160:163], v[64:67]
	v_mfma_f32_16x16x32_bf16 v[68:71], v[132:135], v[160:163], v[68:71]
	v_mfma_f32_16x16x32_bf16 v[72:75], v[136:139], v[160:163], v[72:75]
	v_mfma_f32_16x16x32_bf16 v[76:79], v[140:143], v[160:163], v[76:79]
	ds_read_b128 v[208:211], v232 offset:4096
	v_mfma_f32_16x16x32_bf16 v[80:83], v[128:131], v[164:167], v[80:83]
	v_mfma_f32_16x16x32_bf16 v[84:87], v[132:135], v[164:167], v[84:87]
	v_mfma_f32_16x16x32_bf16 v[88:91], v[136:139], v[164:167], v[88:91]
	v_mfma_f32_16x16x32_bf16 v[92:95], v[140:143], v[164:167], v[92:95]
	ds_read_b128 v[212:215], v232 offset:5120
	v_mfma_f32_16x16x32_bf16 v[96:99], v[128:131], v[168:171], v[96:99]
	v_mfma_f32_16x16x32_bf16 v[100:103], v[132:135], v[168:171], v[100:103]
	v_mfma_f32_16x16x32_bf16 v[104:107], v[136:139], v[168:171], v[104:107]
	v_mfma_f32_16x16x32_bf16 v[108:111], v[140:143], v[168:171], v[108:111]
	ds_read_b128 v[216:219], v232 offset:6144
	s_add_u32 s31, s31, 24576
	s_cmp_eq_u32 s31, 73728
	s_cselect_b32 s31, 0, s31
	v_mfma_f32_16x16x32_bf16 v[112:115], v[128:131], v[172:175], v[112:115]
	v_mfma_f32_16x16x32_bf16 v[116:119], v[132:135], v[172:175], v[116:119]
	v_mfma_f32_16x16x32_bf16 v[120:123], v[136:139], v[172:175], v[120:123]
	v_mfma_f32_16x16x32_bf16 v[124:127], v[140:143], v[172:175], v[124:127]
	ds_read_b128 v[220:223], v232 offset:7168
	s_cmp_eq_u32 s25, 0
	s_cbranch_scc0 .Lg3a_hi0
	s_setprio 0
.Lg3a_hi0:
	s_waitcnt lgkmcnt(0)
	s_barrier
	s_setprio 1
	v_mfma_f32_16x16x32_bf16 v[0:3], v[176:179], v[192:195], v[0:3]
	v_mfma_f32_16x16x32_bf16 v[4:7], v[180:183], v[192:195], v[4:7]
	v_mfma_f32_16x16x32_bf16 v[8:11], v[184:187], v[192:195], v[8:11]
	v_mfma_f32_16x16x32_bf16 v[12:15], v[188:191], v[192:195], v[12:15]
	v_mfma_f32_16x16x32_bf16 v[16:19], v[176:179], v[196:199], v[16:19]
	v_mfma_f32_16x16x32_bf16 v[20:23], v[180:183], v[196:199], v[20:23]
	v_mfma_f32_16x16x32_bf16 v[24:27], v[184:187], v[196:199], v[24:27]
	v_mfma_f32_16x16x32_bf16 v[28:31], v[188:191], v[196:199], v[28:31]
	v_mfma_f32_16x16x32_bf16 v[32:35], v[176:179], v[200:203], v[32:35]
	v_mfma_f32_16x16x32_bf16 v[36:39], v[180:183], v[200:203], v[36:39]
	v_mfma_f32_16x16x32_bf16 v[40:43], v[184:187], v[200:203], v[40:43]
	v_mfma_f32_16x16x32_bf16 v[44:47], v[188:191], v[200:203], v[44:47]
	v_mfma_f32_16x16x32_bf16 v[48:51], v[176:179], v[204:207], v[48:51]
	v_mfma_f32_16x16x32_bf16 v[52:55], v[180:183], v[204:207], v[52:55]
	v_mfma_f32_16x16x32_bf16 v[56:59], v[184:187], v[204:207], v[56:59]
	v_mfma_f32_16x16x32_bf16 v[60:63], v[188:191], v[204:207], v[60:63]
	v_mfma_f32_16x16x32_bf16 v[64:67], v[176:179], v[208:211], v[64:67]
	v_mfma_f32_16x16x32_bf16 v[68:71], v[180:183], v[208:211], v[68:71]
	v_mfma_f32_16x16x32_bf16 v[72:75], v[184:187], v[208:211], v[72:75]
	v_mfma_f32_16x16x32_bf16 v[76:79], v[188:191], v[208:211], v[76:79]
	v_mfma_f32_16x16x32_bf16 v[80:83], v[176:179], v[212:215], v[80:83]
	v_mfma_f32_16x16x32_bf16 v[84:87], v[180:183], v[212:215], v[84:87]
	v_mfma_f32_16x16x32_bf16 v[88:91], v[184:187], v[212:215], v[88:91]
	v_mfma_f32_16x16x32_bf16 v[92:95], v[188:191], v[212:215], v[92:95]
	v_mfma_f32_16x16x32_bf16 v[96:99], v[176:179], v[216:219], v[96:99]
	v_mfma_f32_16x16x32_bf16 v[100:103], v[180:183], v[216:219], v[100:103]
	v_mfma_f32_16x16x32_bf16 v[104:107], v[184:187], v[216:219], v[104:107]
	v_mfma_f32_16x16x32_bf16 v[108:111], v[188:191], v[216:219], v[108:111]
	v_mfma_f32_16x16x32_bf16 v[112:115], v[176:179], v[220:223], v[112:115]
	v_mfma_f32_16x16x32_bf16 v[116:119], v[180:183], v[220:223], v[116:119]
	v_mfma_f32_16x16x32_bf16 v[120:123], v[184:187], v[220:223], v[120:123]
	v_mfma_f32_16x16x32_bf16 v[124:127], v[188:191], v[220:223], v[124:127]
	s_cmp_eq_u32 s25, 0
	s_cbranch_scc0 .Lg3a_hi1
	s_setprio 0
.Lg3a_hi1:
	s_branch .Lg3a_epi
; DI unsigned pack2(float lo, float hi) { const f32x2c v = {lo, hi}; return __builtin_bit_cast(unsigned, __builtin_convertvector(v, bf16x2c)); }
; template <class Epi>
; DI void gemm_tile(char* smem, const bf16_t* __restrict__ A0, int lda0, int ksplit, const bf16_t* __restrict__ A1, int lda1,
;                   const bf16_t* __restrict__ Bt, int K, int row0, int col0, const Epi& epi, int tid) {
;     ...
;   for (int m = 0; m < 8; ++m)
; #pragma unroll
;     for (int n = 0; n < 4; ++n) epi(row0 + wr * 128 + m * 16 + fr, col0 + wc * 64 + n * 16 + fq * 4, acc[m][n]);
; }
; DI void st_bf16x4(bf16_t* o, f32x4 v) { u32x2 q; q.x = pack2(v[0], v[1]); q.y = pack2(v[2], v[3]); *(u32x2*)o = q; }
.Lg3a_epi:
	s_nop 7
	s_nop 7
	s_mul_i32 s27, s29, 1024
	s_lshl_b32 s26, s28, 1
	s_add_u32 s27, s27, s26
	s_add_u32 s27, s27, 0x7800000
	s_add_u32 s4, s92, s27
	s_addc_u32 s5, s93, 0
	s_lshl_b32 s27, s28, 2
	s_add_u32 s27, s27, 0x0
	s_add_u32 s2, s6, s27
	s_addc_u32 s3, s7, 0
	global_load_dwordx4 v[192:195], v235, s[2:3] offset:0
	global_load_dwordx4 v[196:199], v235, s[2:3] offset:64
	global_load_dwordx4 v[200:203], v235, s[2:3] offset:128
	global_load_dwordx4 v[204:207], v235, s[2:3] offset:192
	s_waitcnt vmcnt(0)
	v_add_f32_e32 v0, v0, v192
	v_add_f32_e32 v1, v1, v193
	v_add_f32_e32 v2, v2, v194
	v_add_f32_e32 v3, v3, v195
	v_mul_f32_e32 v0, 0xbfb8aa3b, v0
	v_mul_f32_e32 v1, 0xbfb8aa3b, v1
	v_mul_f32_e32 v2, 0xbfb8aa3b, v2
	v_mul_f32_e32 v3, 0xbfb8aa3b, v3
	v_exp_f32_e32 v0, v0
	v_exp_f32_e32 v1, v1
	v_exp_f32_e32 v2, v2
	v_exp_f32_e32 v3, v3
	s_nop 0
	v_add_f32_e32 v0, 1.0, v0
	v_add_f32_e32 v1, 1.0, v1
	v_add_f32_e32 v2, 1.0, v2
	v_add_f32_e32 v3, 1.0, v3
	v_rcp_f32_e32 v0, v0
	v_rcp_f32_e32 v1, v1
	v_rcp_f32_e32 v2, v2
	v_rcp_f32_e32 v3, v3
	s_nop 0
	v_mul_f32_e32 v0, 0x3f1b4598, v0
	v_mul_f32_e32 v1, 0x3f1b4598, v1
	v_mul_f32_e32 v2, 0x3f1b4598, v2
	v_mul_f32_e32 v3, 0x3f1b4598, v3
	v_cvt_pk_bf16_f32 v128, v0, v1
	v_cvt_pk_bf16_f32 v129, v2, v3
	ds_write_b64 v236, v[128:129]
	v_add_f32_e32 v4, v4, v196
	v_add_f32_e32 v5, v5, v197
	v_add_f32_e32 v6, v6, v198
	v_add_f32_e32 v7, v7, v199
	v_mul_f32_e32 v4, 0xbfb8aa3b, v4
	v_mul_f32_e32 v5, 0xbfb8aa3b, v5
	v_mul_f32_e32 v6, 0xbfb8aa3b, v6
	v_mul_f32_e32 v7, 0xbfb8aa3b, v7
	v_exp_f32_e32 v4, v4
	v_exp_f32_e32 v5, v5
	v_exp_f32_e32 v6, v6
	v_exp_f32_e32 v7, v7
	s_nop 0
	v_add_f32_e32 v4, 1.0, v4
	v_add_f32_e32 v5, 1.0, v5
	v_add_f32_e32 v6, 1.0, v6
	v_add_f32_e32 v7, 1.0, v7
	v_rcp_f32_e32 v4, v4
	v_rcp_f32_e32 v5, v5
	v_rcp_f32_e32 v6, v6
	v_rcp_f32_e32 v7, v7
	s_nop 0
	v_mul_f32_e32 v4, 0x3f1b4598, v4
	v_mul_f32_e32 v5, 0x3f1b4598, v5
	v_mul_f32_e32 v6, 0x3f1b4598, v6
	v_mul_f32_e32 v7, 0x3f1b4598, v7
	v_cvt_pk_bf16_f32 v130, v4, v5
	v_cvt_pk_bf16_f32 v131, v6, v7
	ds_write_b64 v236, v[130:131] offset:32
	v_add_f32_e32 v8, v8, v200
	v_add_f32_e32 v9, v9, v201
	v_add_f32_e32 v10, v10, v202
	v_add_f32_e32 v11, v11, v203
	v_mul_f32_e32 v8, 0xbfb8aa3b, v8
	v_mul_f32_e32 v9, 0xbfb8aa3b, v9
	v_mul_f32_e32 v10, 0xbfb8aa3b, v10
	v_mul_f32_e32 v11, 0xbfb8aa3b, v11
	v_exp_f32_e32 v8, v8
	v_exp_f32_e32 v9, v9
	v_exp_f32_e32 v10, v10
	v_exp_f32_e32 v11, v11
	s_nop 0
	v_add_f32_e32 v8, 1.0, v8
	v_add_f32_e32 v9, 1.0, v9
	v_add_f32_e32 v10, 1.0, v10
	v_add_f32_e32 v11, 1.0, v11
	v_rcp_f32_e32 v8, v8
	v_rcp_f32_e32 v9, v9
	v_rcp_f32_e32 v10, v10
	v_rcp_f32_e32 v11, v11
	s_nop 0
	v_mul_f32_e32 v8, 0x3f1b4598, v8
	v_mul_f32_e32 v9, 0x3f1b4598, v9
	v_mul_f32_e32 v10, 0x3f1b4598, v10
	v_mul_f32_e32 v11, 0x3f1b4598, v11
	v_cvt_pk_bf16_f32 v132, v8, v9
	v_cvt_pk_bf16_f32 v133, v10, v11
	ds_write_b64 v236, v[132:133] offset:64
	v_add_f32_e32 v12, v12, v204
	v_add_f32_e32 v13, v13, v205
	v_add_f32_e32 v14, v14, v206
	v_add_f32_e32 v15, v15, v207
	v_mul_f32_e32 v12, 0xbfb8aa3b, v12
	v_mul_f32_e32 v13, 0xbfb8aa3b, v13
	v_mul_f32_e32 v14, 0xbfb8aa3b, v14
	v_mul_f32_e32 v15, 0xbfb8aa3b, v15
	v_exp_f32_e32 v12, v12
	v_exp_f32_e32 v13, v13
	v_exp_f32_e32 v14, v14
	v_exp_f32_e32 v15, v15
	s_nop 0
	v_add_f32_e32 v12, 1.0, v12
	v_add_f32_e32 v13, 1.0, v13
	v_add_f32_e32 v14, 1.0, v14
	v_add_f32_e32 v15, 1.0, v15
	v_rcp_f32_e32 v12, v12
	v_rcp_f32_e32 v13, v13
	v_rcp_f32_e32 v14, v14
	v_rcp_f32_e32 v15, v15
	s_nop 0
	v_mul_f32_e32 v12, 0x3f1b4598, v12
	v_mul_f32_e32 v13, 0x3f1b4598, v13
	v_mul_f32_e32 v14, 0x3f1b4598, v14
	v_mul_f32_e32 v15, 0x3f1b4598, v15
	v_cvt_pk_bf16_f32 v134, v12, v13
	v_cvt_pk_bf16_f32 v135, v14, v15
	ds_write_b64 v236, v[134:135] offset:96
	v_add_f32_e32 v16, v16, v192
	v_add_f32_e32 v17, v17, v193
	v_add_f32_e32 v18, v18, v194
	v_add_f32_e32 v19, v19, v195
	v_mul_f32_e32 v16, 0xbfb8aa3b, v16
	v_mul_f32_e32 v17, 0xbfb8aa3b, v17
	v_mul_f32_e32 v18, 0xbfb8aa3b, v18
	v_mul_f32_e32 v19, 0xbfb8aa3b, v19
	v_exp_f32_e32 v16, v16
	v_exp_f32_e32 v17, v17
	v_exp_f32_e32 v18, v18
	v_exp_f32_e32 v19, v19
	s_nop 0
	v_add_f32_e32 v16, 1.0, v16
	v_add_f32_e32 v17, 1.0, v17
	v_add_f32_e32 v18, 1.0, v18
	v_add_f32_e32 v19, 1.0, v19
	v_rcp_f32_e32 v16, v16
	v_rcp_f32_e32 v17, v17
	v_rcp_f32_e32 v18, v18
	v_rcp_f32_e32 v19, v19
	s_nop 0
	v_mul_f32_e32 v16, 0x3f1b4598, v16
	v_mul_f32_e32 v17, 0x3f1b4598, v17
	v_mul_f32_e32 v18, 0x3f1b4598, v18
	v_mul_f32_e32 v19, 0x3f1b4598, v19
	v_cvt_pk_bf16_f32 v136, v16, v17
	v_cvt_pk_bf16_f32 v137, v18, v19
	ds_write_b64 v236, v[136:137] offset:2304
	v_add_f32_e32 v20, v20, v196
	v_add_f32_e32 v21, v21, v197
	v_add_f32_e32 v22, v22, v198
	v_add_f32_e32 v23, v23, v199
	v_mul_f32_e32 v20, 0xbfb8aa3b, v20
	v_mul_f32_e32 v21, 0xbfb8aa3b, v21
	v_mul_f32_e32 v22, 0xbfb8aa3b, v22
	v_mul_f32_e32 v23, 0xbfb8aa3b, v23
	v_exp_f32_e32 v20, v20
	v_exp_f32_e32 v21, v21
	v_exp_f32_e32 v22, v22
	v_exp_f32_e32 v23, v23
	s_nop 0
	v_add_f32_e32 v20, 1.0, v20
	v_add_f32_e32 v21, 1.0, v21
	v_add_f32_e32 v22, 1.0, v22
	v_add_f32_e32 v23, 1.0, v23
	v_rcp_f32_e32 v20, v20
	v_rcp_f32_e32 v21, v21
	v_rcp_f32_e32 v22, v22
	v_rcp_f32_e32 v23, v23
	s_nop 0
	v_mul_f32_e32 v20, 0x3f1b4598, v20
	v_mul_f32_e32 v21, 0x3f1b4598, v21
	v_mul_f32_e32 v22, 0x3f1b4598, v22
	v_mul_f32_e32 v23, 0x3f1b4598, v23
	v_cvt_pk_bf16_f32 v138, v20, v21
	v_cvt_pk_bf16_f32 v139, v22, v23
	ds_write_b64 v236, v[138:139] offset:2336
	v_add_f32_e32 v24, v24, v200
	v_add_f32_e32 v25, v25, v201
	v_add_f32_e32 v26, v26, v202
	v_add_f32_e32 v27, v27, v203
	v_mul_f32_e32 v24, 0xbfb8aa3b, v24
	v_mul_f32_e32 v25, 0xbfb8aa3b, v25
	v_mul_f32_e32 v26, 0xbfb8aa3b, v26
	v_mul_f32_e32 v27, 0xbfb8aa3b, v27
	v_exp_f32_e32 v24, v24
	v_exp_f32_e32 v25, v25
	v_exp_f32_e32 v26, v26
	v_exp_f32_e32 v27, v27
	s_nop 0
	v_add_f32_e32 v24, 1.0, v24
	v_add_f32_e32 v25, 1.0, v25
	v_add_f32_e32 v26, 1.0, v26
	v_add_f32_e32 v27, 1.0, v27
	v_rcp_f32_e32 v24, v24
	v_rcp_f32_e32 v25, v25
	v_rcp_f32_e32 v26, v26
	v_rcp_f32_e32 v27, v27
	s_nop 0
	v_mul_f32_e32 v24, 0x3f1b4598, v24
	v_mul_f32_e32 v25, 0x3f1b4598, v25
	v_mul_f32_e32 v26, 0x3f1b4598, v26
	v_mul_f32_e32 v27, 0x3f1b4598, v27
	v_cvt_pk_bf16_f32 v140, v24, v25
	v_cvt_pk_bf16_f32 v141, v26, v27
	ds_write_b64 v236, v[140:141] offset:2368
	v_add_f32_e32 v28, v28, v204
	v_add_f32_e32 v29, v29, v205
	v_add_f32_e32 v30, v30, v206
	v_add_f32_e32 v31, v31, v207
	v_mul_f32_e32 v28, 0xbfb8aa3b, v28
	v_mul_f32_e32 v29, 0xbfb8aa3b, v29
	v_mul_f32_e32 v30, 0xbfb8aa3b, v30
	v_mul_f32_e32 v31, 0xbfb8aa3b, v31
	v_exp_f32_e32 v28, v28
	v_exp_f32_e32 v29, v29
	v_exp_f32_e32 v30, v30
	v_exp_f32_e32 v31, v31
	s_nop 0
	v_add_f32_e32 v28, 1.0, v28
	v_add_f32_e32 v29, 1.0, v29
	v_add_f32_e32 v30, 1.0, v30
	v_add_f32_e32 v31, 1.0, v31
	v_rcp_f32_e32 v28, v28
	v_rcp_f32_e32 v29, v29
	v_rcp_f32_e32 v30, v30
	v_rcp_f32_e32 v31, v31
	s_nop 0
	v_mul_f32_e32 v28, 0x3f1b4598, v28
	v_mul_f32_e32 v29, 0x3f1b4598, v29
	v_mul_f32_e32 v30, 0x3f1b4598, v30
	v_mul_f32_e32 v31, 0x3f1b4598, v31
	v_cvt_pk_bf16_f32 v142, v28, v29
	v_cvt_pk_bf16_f32 v143, v30, v31
	ds_write_b64 v236, v[142:143] offset:2400
	v_add_f32_e32 v32, v32, v192
	v_add_f32_e32 v33, v33, v193
	v_add_f32_e32 v34, v34, v194
	v_add_f32_e32 v35, v35, v195
	v_mul_f32_e32 v32, 0xbfb8aa3b, v32
	v_mul_f32_e32 v33, 0xbfb8aa3b, v33
	v_mul_f32_e32 v34, 0xbfb8aa3b, v34
	v_mul_f32_e32 v35, 0xbfb8aa3b, v35
	v_exp_f32_e32 v32, v32
	v_exp_f32_e32 v33, v33
	v_exp_f32_e32 v34, v34
	v_exp_f32_e32 v35, v35
	s_nop 0
	v_add_f32_e32 v32, 1.0, v32
	v_add_f32_e32 v33, 1.0, v33
	v_add_f32_e32 v34, 1.0, v34
	v_add_f32_e32 v35, 1.0, v35
	v_rcp_f32_e32 v32, v32
	v_rcp_f32_e32 v33, v33
	v_rcp_f32_e32 v34, v34
	v_rcp_f32_e32 v35, v35
	s_nop 0
	v_mul_f32_e32 v32, 0x3f1b4598, v32
	v_mul_f32_e32 v33, 0x3f1b4598, v33
	v_mul_f32_e32 v34, 0x3f1b4598, v34
	v_mul_f32_e32 v35, 0x3f1b4598, v35
	v_cvt_pk_bf16_f32 v144, v32, v33
	v_cvt_pk_bf16_f32 v145, v34, v35
	ds_write_b64 v236, v[144:145] offset:4608
	v_add_f32_e32 v36, v36, v196
	v_add_f32_e32 v37, v37, v197
	v_add_f32_e32 v38, v38, v198
	v_add_f32_e32 v39, v39, v199
	v_mul_f32_e32 v36, 0xbfb8aa3b, v36
	v_mul_f32_e32 v37, 0xbfb8aa3b, v37
	v_mul_f32_e32 v38, 0xbfb8aa3b, v38
	v_mul_f32_e32 v39, 0xbfb8aa3b, v39
	v_exp_f32_e32 v36, v36
	v_exp_f32_e32 v37, v37
	v_exp_f32_e32 v38, v38
	v_exp_f32_e32 v39, v39
	s_nop 0
	v_add_f32_e32 v36, 1.0, v36
	v_add_f32_e32 v37, 1.0, v37
	v_add_f32_e32 v38, 1.0, v38
	v_add_f32_e32 v39, 1.0, v39
	v_rcp_f32_e32 v36, v36
	v_rcp_f32_e32 v37, v37
	v_rcp_f32_e32 v38, v38
	v_rcp_f32_e32 v39, v39
	s_nop 0
	v_mul_f32_e32 v36, 0x3f1b4598, v36
	v_mul_f32_e32 v37, 0x3f1b4598, v37
	v_mul_f32_e32 v38, 0x3f1b4598, v38
	v_mul_f32_e32 v39, 0x3f1b4598, v39
	v_cvt_pk_bf16_f32 v146, v36, v37
	v_cvt_pk_bf16_f32 v147, v38, v39
	ds_write_b64 v236, v[146:147] offset:4640
	v_add_f32_e32 v40, v40, v200
	v_add_f32_e32 v41, v41, v201
	v_add_f32_e32 v42, v42, v202
	v_add_f32_e32 v43, v43, v203
	v_mul_f32_e32 v40, 0xbfb8aa3b, v40
	v_mul_f32_e32 v41, 0xbfb8aa3b, v41
	v_mul_f32_e32 v42, 0xbfb8aa3b, v42
	v_mul_f32_e32 v43, 0xbfb8aa3b, v43
	v_exp_f32_e32 v40, v40
	v_exp_f32_e32 v41, v41
	v_exp_f32_e32 v42, v42
	v_exp_f32_e32 v43, v43
	s_nop 0
	v_add_f32_e32 v40, 1.0, v40
	v_add_f32_e32 v41, 1.0, v41
	v_add_f32_e32 v42, 1.0, v42
	v_add_f32_e32 v43, 1.0, v43
	v_rcp_f32_e32 v40, v40
	v_rcp_f32_e32 v41, v41
	v_rcp_f32_e32 v42, v42
	v_rcp_f32_e32 v43, v43
	s_nop 0
	v_mul_f32_e32 v40, 0x3f1b4598, v40
	v_mul_f32_e32 v41, 0x3f1b4598, v41
	v_mul_f32_e32 v42, 0x3f1b4598, v42
	v_mul_f32_e32 v43, 0x3f1b4598, v43
	v_cvt_pk_bf16_f32 v148, v40, v41
	v_cvt_pk_bf16_f32 v149, v42, v43
	ds_write_b64 v236, v[148:149] offset:4672
	v_add_f32_e32 v44, v44, v204
	v_add_f32_e32 v45, v45, v205
	v_add_f32_e32 v46, v46, v206
	v_add_f32_e32 v47, v47, v207
	v_mul_f32_e32 v44, 0xbfb8aa3b, v44
	v_mul_f32_e32 v45, 0xbfb8aa3b, v45
	v_mul_f32_e32 v46, 0xbfb8aa3b, v46
	v_mul_f32_e32 v47, 0xbfb8aa3b, v47
	v_exp_f32_e32 v44, v44
	v_exp_f32_e32 v45, v45
	v_exp_f32_e32 v46, v46
	v_exp_f32_e32 v47, v47
	s_nop 0
	v_add_f32_e32 v44, 1.0, v44
	v_add_f32_e32 v45, 1.0, v45
	v_add_f32_e32 v46, 1.0, v46
	v_add_f32_e32 v47, 1.0, v47
	v_rcp_f32_e32 v44, v44
	v_rcp_f32_e32 v45, v45
	v_rcp_f32_e32 v46, v46
	v_rcp_f32_e32 v47, v47
	s_nop 0
	v_mul_f32_e32 v44, 0x3f1b4598, v44
	v_mul_f32_e32 v45, 0x3f1b4598, v45
	v_mul_f32_e32 v46, 0x3f1b4598, v46
	v_mul_f32_e32 v47, 0x3f1b4598, v47
	v_cvt_pk_bf16_f32 v150, v44, v45
	v_cvt_pk_bf16_f32 v151, v46, v47
	ds_write_b64 v236, v[150:151] offset:4704
	v_add_f32_e32 v48, v48, v192
	v_add_f32_e32 v49, v49, v193
	v_add_f32_e32 v50, v50, v194
	v_add_f32_e32 v51, v51, v195
	v_mul_f32_e32 v48, 0xbfb8aa3b, v48
	v_mul_f32_e32 v49, 0xbfb8aa3b, v49
	v_mul_f32_e32 v50, 0xbfb8aa3b, v50
	v_mul_f32_e32 v51, 0xbfb8aa3b, v51
	v_exp_f32_e32 v48, v48
	v_exp_f32_e32 v49, v49
	v_exp_f32_e32 v50, v50
	v_exp_f32_e32 v51, v51
	s_nop 0
	v_add_f32_e32 v48, 1.0, v48
	v_add_f32_e32 v49, 1.0, v49
	v_add_f32_e32 v50, 1.0, v50
	v_add_f32_e32 v51, 1.0, v51
	v_rcp_f32_e32 v48, v48
	v_rcp_f32_e32 v49, v49
	v_rcp_f32_e32 v50, v50
	v_rcp_f32_e32 v51, v51
	s_nop 0
	v_mul_f32_e32 v48, 0x3f1b4598, v48
	v_mul_f32_e32 v49, 0x3f1b4598, v49
	v_mul_f32_e32 v50, 0x3f1b4598, v50
	v_mul_f32_e32 v51, 0x3f1b4598, v51
	v_cvt_pk_bf16_f32 v152, v48, v49
	v_cvt_pk_bf16_f32 v153, v50, v51
	ds_write_b64 v236, v[152:153] offset:6912
	v_add_f32_e32 v52, v52, v196
	v_add_f32_e32 v53, v53, v197
	v_add_f32_e32 v54, v54, v198
	v_add_f32_e32 v55, v55, v199
	v_mul_f32_e32 v52, 0xbfb8aa3b, v52
	v_mul_f32_e32 v53, 0xbfb8aa3b, v53
	v_mul_f32_e32 v54, 0xbfb8aa3b, v54
	v_mul_f32_e32 v55, 0xbfb8aa3b, v55
	v_exp_f32_e32 v52, v52
	v_exp_f32_e32 v53, v53
	v_exp_f32_e32 v54, v54
	v_exp_f32_e32 v55, v55
	s_nop 0
	v_add_f32_e32 v52, 1.0, v52
	v_add_f32_e32 v53, 1.0, v53
	v_add_f32_e32 v54, 1.0, v54
	v_add_f32_e32 v55, 1.0, v55
	v_rcp_f32_e32 v52, v52
	v_rcp_f32_e32 v53, v53
	v_rcp_f32_e32 v54, v54
	v_rcp_f32_e32 v55, v55
	s_nop 0
	v_mul_f32_e32 v52, 0x3f1b4598, v52
	v_mul_f32_e32 v53, 0x3f1b4598, v53
	v_mul_f32_e32 v54, 0x3f1b4598, v54
	v_mul_f32_e32 v55, 0x3f1b4598, v55
	v_cvt_pk_bf16_f32 v154, v52, v53
	v_cvt_pk_bf16_f32 v155, v54, v55
	ds_write_b64 v236, v[154:155] offset:6944
	v_add_f32_e32 v56, v56, v200
	v_add_f32_e32 v57, v57, v201
	v_add_f32_e32 v58, v58, v202
	v_add_f32_e32 v59, v59, v203
	v_mul_f32_e32 v56, 0xbfb8aa3b, v56
	v_mul_f32_e32 v57, 0xbfb8aa3b, v57
	v_mul_f32_e32 v58, 0xbfb8aa3b, v58
	v_mul_f32_e32 v59, 0xbfb8aa3b, v59
	v_exp_f32_e32 v56, v56
	v_exp_f32_e32 v57, v57
	v_exp_f32_e32 v58, v58
	v_exp_f32_e32 v59, v59
	s_nop 0
	v_add_f32_e32 v56, 1.0, v56
	v_add_f32_e32 v57, 1.0, v57
	v_add_f32_e32 v58, 1.0, v58
	v_add_f32_e32 v59, 1.0, v59
	v_rcp_f32_e32 v56, v56
	v_rcp_f32_e32 v57, v57
	v_rcp_f32_e32 v58, v58
	v_rcp_f32_e32 v59, v59
	s_nop 0
	v_mul_f32_e32 v56, 0x3f1b4598, v56
	v_mul_f32_e32 v57, 0x3f1b4598, v57
	v_mul_f32_e32 v58, 0x3f1b4598, v58
	v_mul_f32_e32 v59, 0x3f1b4598, v59
	v_cvt_pk_bf16_f32 v156, v56, v57
	v_cvt_pk_bf16_f32 v157, v58, v59
	ds_write_b64 v236, v[156:157] offset:6976
	v_add_f32_e32 v60, v60, v204
	v_add_f32_e32 v61, v61, v205
	v_add_f32_e32 v62, v62, v206
	v_add_f32_e32 v63, v63, v207
	v_mul_f32_e32 v60, 0xbfb8aa3b, v60
	v_mul_f32_e32 v61, 0xbfb8aa3b, v61
	v_mul_f32_e32 v62, 0xbfb8aa3b, v62
	v_mul_f32_e32 v63, 0xbfb8aa3b, v63
	v_exp_f32_e32 v60, v60
	v_exp_f32_e32 v61, v61
	v_exp_f32_e32 v62, v62
	v_exp_f32_e32 v63, v63
	s_nop 0
	v_add_f32_e32 v60, 1.0, v60
	v_add_f32_e32 v61, 1.0, v61
	v_add_f32_e32 v62, 1.0, v62
	v_add_f32_e32 v63, 1.0, v63
	v_rcp_f32_e32 v60, v60
	v_rcp_f32_e32 v61, v61
	v_rcp_f32_e32 v62, v62
	v_rcp_f32_e32 v63, v63
	s_nop 0
	v_mul_f32_e32 v60, 0x3f1b4598, v60
	v_mul_f32_e32 v61, 0x3f1b4598, v61
	v_mul_f32_e32 v62, 0x3f1b4598, v62
	v_mul_f32_e32 v63, 0x3f1b4598, v63
	v_cvt_pk_bf16_f32 v158, v60, v61
	v_cvt_pk_bf16_f32 v159, v62, v63
	ds_write_b64 v236, v[158:159] offset:7008
	v_add_f32_e32 v64, v64, v192
	v_add_f32_e32 v65, v65, v193
	v_add_f32_e32 v66, v66, v194
	v_add_f32_e32 v67, v67, v195
	v_mul_f32_e32 v64, 0xbfb8aa3b, v64
	v_mul_f32_e32 v65, 0xbfb8aa3b, v65
	v_mul_f32_e32 v66, 0xbfb8aa3b, v66
	v_mul_f32_e32 v67, 0xbfb8aa3b, v67
	v_exp_f32_e32 v64, v64
	v_exp_f32_e32 v65, v65
	v_exp_f32_e32 v66, v66
	v_exp_f32_e32 v67, v67
	s_nop 0
	v_add_f32_e32 v64, 1.0, v64
	v_add_f32_e32 v65, 1.0, v65
	v_add_f32_e32 v66, 1.0, v66
	v_add_f32_e32 v67, 1.0, v67
	v_rcp_f32_e32 v64, v64
	v_rcp_f32_e32 v65, v65
	v_rcp_f32_e32 v66, v66
	v_rcp_f32_e32 v67, v67
	s_nop 0
	v_mul_f32_e32 v64, 0x3f1b4598, v64
	v_mul_f32_e32 v65, 0x3f1b4598, v65
	v_mul_f32_e32 v66, 0x3f1b4598, v66
	v_mul_f32_e32 v67, 0x3f1b4598, v67
	v_cvt_pk_bf16_f32 v128, v64, v65
	v_cvt_pk_bf16_f32 v129, v66, v67
	ds_write_b64 v236, v[128:129] offset:9216
	v_add_f32_e32 v68, v68, v196
	v_add_f32_e32 v69, v69, v197
	v_add_f32_e32 v70, v70, v198
	v_add_f32_e32 v71, v71, v199
	v_mul_f32_e32 v68, 0xbfb8aa3b, v68
	v_mul_f32_e32 v69, 0xbfb8aa3b, v69
	v_mul_f32_e32 v70, 0xbfb8aa3b, v70
	v_mul_f32_e32 v71, 0xbfb8aa3b, v71
	v_exp_f32_e32 v68, v68
	v_exp_f32_e32 v69, v69
	v_exp_f32_e32 v70, v70
	v_exp_f32_e32 v71, v71
	s_nop 0
	v_add_f32_e32 v68, 1.0, v68
	v_add_f32_e32 v69, 1.0, v69
	v_add_f32_e32 v70, 1.0, v70
	v_add_f32_e32 v71, 1.0, v71
	v_rcp_f32_e32 v68, v68
	v_rcp_f32_e32 v69, v69
	v_rcp_f32_e32 v70, v70
	v_rcp_f32_e32 v71, v71
	s_nop 0
	v_mul_f32_e32 v68, 0x3f1b4598, v68
	v_mul_f32_e32 v69, 0x3f1b4598, v69
	v_mul_f32_e32 v70, 0x3f1b4598, v70
	v_mul_f32_e32 v71, 0x3f1b4598, v71
	v_cvt_pk_bf16_f32 v130, v68, v69
	v_cvt_pk_bf16_f32 v131, v70, v71
	ds_write_b64 v236, v[130:131] offset:9248
	v_add_f32_e32 v72, v72, v200
	v_add_f32_e32 v73, v73, v201
	v_add_f32_e32 v74, v74, v202
	v_add_f32_e32 v75, v75, v203
	v_mul_f32_e32 v72, 0xbfb8aa3b, v72
	v_mul_f32_e32 v73, 0xbfb8aa3b, v73
	v_mul_f32_e32 v74, 0xbfb8aa3b, v74
	v_mul_f32_e32 v75, 0xbfb8aa3b, v75
	v_exp_f32_e32 v72, v72
	v_exp_f32_e32 v73, v73
	v_exp_f32_e32 v74, v74
	v_exp_f32_e32 v75, v75
	s_nop 0
	v_add_f32_e32 v72, 1.0, v72
	v_add_f32_e32 v73, 1.0, v73
	v_add_f32_e32 v74, 1.0, v74
	v_add_f32_e32 v75, 1.0, v75
	v_rcp_f32_e32 v72, v72
	v_rcp_f32_e32 v73, v73
	v_rcp_f32_e32 v74, v74
	v_rcp_f32_e32 v75, v75
	s_nop 0
	v_mul_f32_e32 v72, 0x3f1b4598, v72
	v_mul_f32_e32 v73, 0x3f1b4598, v73
	v_mul_f32_e32 v74, 0x3f1b4598, v74
	v_mul_f32_e32 v75, 0x3f1b4598, v75
	v_cvt_pk_bf16_f32 v132, v72, v73
	v_cvt_pk_bf16_f32 v133, v74, v75
	ds_write_b64 v236, v[132:133] offset:9280
	v_add_f32_e32 v76, v76, v204
	v_add_f32_e32 v77, v77, v205
	v_add_f32_e32 v78, v78, v206
	v_add_f32_e32 v79, v79, v207
	v_mul_f32_e32 v76, 0xbfb8aa3b, v76
	v_mul_f32_e32 v77, 0xbfb8aa3b, v77
	v_mul_f32_e32 v78, 0xbfb8aa3b, v78
	v_mul_f32_e32 v79, 0xbfb8aa3b, v79
	v_exp_f32_e32 v76, v76
	v_exp_f32_e32 v77, v77
	v_exp_f32_e32 v78, v78
	v_exp_f32_e32 v79, v79
	s_nop 0
	v_add_f32_e32 v76, 1.0, v76
	v_add_f32_e32 v77, 1.0, v77
	v_add_f32_e32 v78, 1.0, v78
	v_add_f32_e32 v79, 1.0, v79
	v_rcp_f32_e32 v76, v76
	v_rcp_f32_e32 v77, v77
	v_rcp_f32_e32 v78, v78
	v_rcp_f32_e32 v79, v79
	s_nop 0
	v_mul_f32_e32 v76, 0x3f1b4598, v76
	v_mul_f32_e32 v77, 0x3f1b4598, v77
	v_mul_f32_e32 v78, 0x3f1b4598, v78
	v_mul_f32_e32 v79, 0x3f1b4598, v79
	v_cvt_pk_bf16_f32 v134, v76, v77
	v_cvt_pk_bf16_f32 v135, v78, v79
	ds_write_b64 v236, v[134:135] offset:9312
	v_add_f32_e32 v80, v80, v192
	v_add_f32_e32 v81, v81, v193
	v_add_f32_e32 v82, v82, v194
	v_add_f32_e32 v83, v83, v195
	v_mul_f32_e32 v80, 0xbfb8aa3b, v80
	v_mul_f32_e32 v81, 0xbfb8aa3b, v81
	v_mul_f32_e32 v82, 0xbfb8aa3b, v82
	v_mul_f32_e32 v83, 0xbfb8aa3b, v83
	v_exp_f32_e32 v80, v80
	v_exp_f32_e32 v81, v81
	v_exp_f32_e32 v82, v82
	v_exp_f32_e32 v83, v83
	s_nop 0
	v_add_f32_e32 v80, 1.0, v80
	v_add_f32_e32 v81, 1.0, v81
	v_add_f32_e32 v82, 1.0, v82
	v_add_f32_e32 v83, 1.0, v83
	v_rcp_f32_e32 v80, v80
	v_rcp_f32_e32 v81, v81
	v_rcp_f32_e32 v82, v82
	v_rcp_f32_e32 v83, v83
	s_nop 0
	v_mul_f32_e32 v80, 0x3f1b4598, v80
	v_mul_f32_e32 v81, 0x3f1b4598, v81
	v_mul_f32_e32 v82, 0x3f1b4598, v82
	v_mul_f32_e32 v83, 0x3f1b4598, v83
	v_cvt_pk_bf16_f32 v136, v80, v81
	v_cvt_pk_bf16_f32 v137, v82, v83
	ds_write_b64 v236, v[136:137] offset:11520
	v_add_f32_e32 v84, v84, v196
	v_add_f32_e32 v85, v85, v197
	v_add_f32_e32 v86, v86, v198
	v_add_f32_e32 v87, v87, v199
	v_mul_f32_e32 v84, 0xbfb8aa3b, v84
	v_mul_f32_e32 v85, 0xbfb8aa3b, v85
	v_mul_f32_e32 v86, 0xbfb8aa3b, v86
	v_mul_f32_e32 v87, 0xbfb8aa3b, v87
	v_exp_f32_e32 v84, v84
	v_exp_f32_e32 v85, v85
	v_exp_f32_e32 v86, v86
	v_exp_f32_e32 v87, v87
	s_nop 0
	v_add_f32_e32 v84, 1.0, v84
	v_add_f32_e32 v85, 1.0, v85
	v_add_f32_e32 v86, 1.0, v86
	v_add_f32_e32 v87, 1.0, v87
	v_rcp_f32_e32 v84, v84
	v_rcp_f32_e32 v85, v85
	v_rcp_f32_e32 v86, v86
	v_rcp_f32_e32 v87, v87
	s_nop 0
	v_mul_f32_e32 v84, 0x3f1b4598, v84
	v_mul_f32_e32 v85, 0x3f1b4598, v85
	v_mul_f32_e32 v86, 0x3f1b4598, v86
	v_mul_f32_e32 v87, 0x3f1b4598, v87
	v_cvt_pk_bf16_f32 v138, v84, v85
	v_cvt_pk_bf16_f32 v139, v86, v87
	ds_write_b64 v236, v[138:139] offset:11552
	v_add_f32_e32 v88, v88, v200
	v_add_f32_e32 v89, v89, v201
	v_add_f32_e32 v90, v90, v202
	v_add_f32_e32 v91, v91, v203
	v_mul_f32_e32 v88, 0xbfb8aa3b, v88
	v_mul_f32_e32 v89, 0xbfb8aa3b, v89
	v_mul_f32_e32 v90, 0xbfb8aa3b, v90
	v_mul_f32_e32 v91, 0xbfb8aa3b, v91
	v_exp_f32_e32 v88, v88
	v_exp_f32_e32 v89, v89
	v_exp_f32_e32 v90, v90
	v_exp_f32_e32 v91, v91
	s_nop 0
	v_add_f32_e32 v88, 1.0, v88
	v_add_f32_e32 v89, 1.0, v89
	v_add_f32_e32 v90, 1.0, v90
	v_add_f32_e32 v91, 1.0, v91
	v_rcp_f32_e32 v88, v88
	v_rcp_f32_e32 v89, v89
	v_rcp_f32_e32 v90, v90
	v_rcp_f32_e32 v91, v91
	s_nop 0
	v_mul_f32_e32 v88, 0x3f1b4598, v88
	v_mul_f32_e32 v89, 0x3f1b4598, v89
	v_mul_f32_e32 v90, 0x3f1b4598, v90
	v_mul_f32_e32 v91, 0x3f1b4598, v91
	v_cvt_pk_bf16_f32 v140, v88, v89
	v_cvt_pk_bf16_f32 v141, v90, v91
	ds_write_b64 v236, v[140:141] offset:11584
	v_add_f32_e32 v92, v92, v204
	v_add_f32_e32 v93, v93, v205
	v_add_f32_e32 v94, v94, v206
	v_add_f32_e32 v95, v95, v207
	v_mul_f32_e32 v92, 0xbfb8aa3b, v92
	v_mul_f32_e32 v93, 0xbfb8aa3b, v93
	v_mul_f32_e32 v94, 0xbfb8aa3b, v94
	v_mul_f32_e32 v95, 0xbfb8aa3b, v95
	v_exp_f32_e32 v92, v92
	v_exp_f32_e32 v93, v93
	v_exp_f32_e32 v94, v94
	v_exp_f32_e32 v95, v95
	s_nop 0
	v_add_f32_e32 v92, 1.0, v92
	v_add_f32_e32 v93, 1.0, v93
	v_add_f32_e32 v94, 1.0, v94
	v_add_f32_e32 v95, 1.0, v95
	v_rcp_f32_e32 v92, v92
	v_rcp_f32_e32 v93, v93
	v_rcp_f32_e32 v94, v94
	v_rcp_f32_e32 v95, v95
	s_nop 0
	v_mul_f32_e32 v92, 0x3f1b4598, v92
	v_mul_f32_e32 v93, 0x3f1b4598, v93
	v_mul_f32_e32 v94, 0x3f1b4598, v94
	v_mul_f32_e32 v95, 0x3f1b4598, v95
	v_cvt_pk_bf16_f32 v142, v92, v93
	v_cvt_pk_bf16_f32 v143, v94, v95
	ds_write_b64 v236, v[142:143] offset:11616
	v_add_f32_e32 v96, v96, v192
	v_add_f32_e32 v97, v97, v193
	v_add_f32_e32 v98, v98, v194
	v_add_f32_e32 v99, v99, v195
	v_mul_f32_e32 v96, 0xbfb8aa3b, v96
	v_mul_f32_e32 v97, 0xbfb8aa3b, v97
	v_mul_f32_e32 v98, 0xbfb8aa3b, v98
	v_mul_f32_e32 v99, 0xbfb8aa3b, v99
	v_exp_f32_e32 v96, v96
	v_exp_f32_e32 v97, v97
	v_exp_f32_e32 v98, v98
	v_exp_f32_e32 v99, v99
	s_nop 0
	v_add_f32_e32 v96, 1.0, v96
	v_add_f32_e32 v97, 1.0, v97
	v_add_f32_e32 v98, 1.0, v98
	v_add_f32_e32 v99, 1.0, v99
	v_rcp_f32_e32 v96, v96
	v_rcp_f32_e32 v97, v97
	v_rcp_f32_e32 v98, v98
	v_rcp_f32_e32 v99, v99
	s_nop 0
	v_mul_f32_e32 v96, 0x3f1b4598, v96
	v_mul_f32_e32 v97, 0x3f1b4598, v97
	v_mul_f32_e32 v98, 0x3f1b4598, v98
	v_mul_f32_e32 v99, 0x3f1b4598, v99
	v_cvt_pk_bf16_f32 v144, v96, v97
	v_cvt_pk_bf16_f32 v145, v98, v99
	ds_write_b64 v236, v[144:145] offset:13824
	v_add_f32_e32 v100, v100, v196
	v_add_f32_e32 v101, v101, v197
	v_add_f32_e32 v102, v102, v198
	v_add_f32_e32 v103, v103, v199
	v_mul_f32_e32 v100, 0xbfb8aa3b, v100
	v_mul_f32_e32 v101, 0xbfb8aa3b, v101
	v_mul_f32_e32 v102, 0xbfb8aa3b, v102
	v_mul_f32_e32 v103, 0xbfb8aa3b, v103
	v_exp_f32_e32 v100, v100
	v_exp_f32_e32 v101, v101
	v_exp_f32_e32 v102, v102
	v_exp_f32_e32 v103, v103
	s_nop 0
	v_add_f32_e32 v100, 1.0, v100
	v_add_f32_e32 v101, 1.0, v101
	v_add_f32_e32 v102, 1.0, v102
	v_add_f32_e32 v103, 1.0, v103
	v_rcp_f32_e32 v100, v100
	v_rcp_f32_e32 v101, v101
	v_rcp_f32_e32 v102, v102
	v_rcp_f32_e32 v103, v103
	s_nop 0
	v_mul_f32_e32 v100, 0x3f1b4598, v100
	v_mul_f32_e32 v101, 0x3f1b4598, v101
	v_mul_f32_e32 v102, 0x3f1b4598, v102
	v_mul_f32_e32 v103, 0x3f1b4598, v103
	v_cvt_pk_bf16_f32 v146, v100, v101
	v_cvt_pk_bf16_f32 v147, v102, v103
	ds_write_b64 v236, v[146:147] offset:13856
	v_add_f32_e32 v104, v104, v200
	v_add_f32_e32 v105, v105, v201
	v_add_f32_e32 v106, v106, v202
	v_add_f32_e32 v107, v107, v203
	v_mul_f32_e32 v104, 0xbfb8aa3b, v104
	v_mul_f32_e32 v105, 0xbfb8aa3b, v105
	v_mul_f32_e32 v106, 0xbfb8aa3b, v106
	v_mul_f32_e32 v107, 0xbfb8aa3b, v107
	v_exp_f32_e32 v104, v104
	v_exp_f32_e32 v105, v105
	v_exp_f32_e32 v106, v106
	v_exp_f32_e32 v107, v107
	s_nop 0
	v_add_f32_e32 v104, 1.0, v104
	v_add_f32_e32 v105, 1.0, v105
	v_add_f32_e32 v106, 1.0, v106
	v_add_f32_e32 v107, 1.0, v107
	v_rcp_f32_e32 v104, v104
	v_rcp_f32_e32 v105, v105
	v_rcp_f32_e32 v106, v106
	v_rcp_f32_e32 v107, v107
	s_nop 0
	v_mul_f32_e32 v104, 0x3f1b4598, v104
	v_mul_f32_e32 v105, 0x3f1b4598, v105
	v_mul_f32_e32 v106, 0x3f1b4598, v106
	v_mul_f32_e32 v107, 0x3f1b4598, v107
	v_cvt_pk_bf16_f32 v148, v104, v105
	v_cvt_pk_bf16_f32 v149, v106, v107
	ds_write_b64 v236, v[148:149] offset:13888
	v_add_f32_e32 v108, v108, v204
	v_add_f32_e32 v109, v109, v205
	v_add_f32_e32 v110, v110, v206
	v_add_f32_e32 v111, v111, v207
	v_mul_f32_e32 v108, 0xbfb8aa3b, v108
	v_mul_f32_e32 v109, 0xbfb8aa3b, v109
	v_mul_f32_e32 v110, 0xbfb8aa3b, v110
	v_mul_f32_e32 v111, 0xbfb8aa3b, v111
	v_exp_f32_e32 v108, v108
	v_exp_f32_e32 v109, v109
	v_exp_f32_e32 v110, v110
	v_exp_f32_e32 v111, v111
	s_nop 0
	v_add_f32_e32 v108, 1.0, v108
	v_add_f32_e32 v109, 1.0, v109
	v_add_f32_e32 v110, 1.0, v110
	v_add_f32_e32 v111, 1.0, v111
	v_rcp_f32_e32 v108, v108
	v_rcp_f32_e32 v109, v109
	v_rcp_f32_e32 v110, v110
	v_rcp_f32_e32 v111, v111
	s_nop 0
	v_mul_f32_e32 v108, 0x3f1b4598, v108
	v_mul_f32_e32 v109, 0x3f1b4598, v109
	v_mul_f32_e32 v110, 0x3f1b4598, v110
	v_mul_f32_e32 v111, 0x3f1b4598, v111
	v_cvt_pk_bf16_f32 v150, v108, v109
	v_cvt_pk_bf16_f32 v151, v110, v111
	ds_write_b64 v236, v[150:151] offset:13920
	v_add_f32_e32 v112, v112, v192
	v_add_f32_e32 v113, v113, v193
	v_add_f32_e32 v114, v114, v194
	v_add_f32_e32 v115, v115, v195
	v_mul_f32_e32 v112, 0xbfb8aa3b, v112
	v_mul_f32_e32 v113, 0xbfb8aa3b, v113
	v_mul_f32_e32 v114, 0xbfb8aa3b, v114
	v_mul_f32_e32 v115, 0xbfb8aa3b, v115
	v_exp_f32_e32 v112, v112
	v_exp_f32_e32 v113, v113
	v_exp_f32_e32 v114, v114
	v_exp_f32_e32 v115, v115
	s_nop 0
	v_add_f32_e32 v112, 1.0, v112
	v_add_f32_e32 v113, 1.0, v113
	v_add_f32_e32 v114, 1.0, v114
	v_add_f32_e32 v115, 1.0, v115
	v_rcp_f32_e32 v112, v112
	v_rcp_f32_e32 v113, v113
	v_rcp_f32_e32 v114, v114
	v_rcp_f32_e32 v115, v115
	s_nop 0
	v_mul_f32_e32 v112, 0x3f1b4598, v112
	v_mul_f32_e32 v113, 0x3f1b4598, v113
	v_mul_f32_e32 v114, 0x3f1b4598, v114
	v_mul_f32_e32 v115, 0x3f1b4598, v115
	v_cvt_pk_bf16_f32 v152, v112, v113
	v_cvt_pk_bf16_f32 v153, v114, v115
	ds_write_b64 v236, v[152:153] offset:16128
	v_add_f32_e32 v116, v116, v196
	v_add_f32_e32 v117, v117, v197
	v_add_f32_e32 v118, v118, v198
	v_add_f32_e32 v119, v119, v199
	v_mul_f32_e32 v116, 0xbfb8aa3b, v116
	v_mul_f32_e32 v117, 0xbfb8aa3b, v117
	v_mul_f32_e32 v118, 0xbfb8aa3b, v118
	v_mul_f32_e32 v119, 0xbfb8aa3b, v119
	v_exp_f32_e32 v116, v116
	v_exp_f32_e32 v117, v117
	v_exp_f32_e32 v118, v118
	v_exp_f32_e32 v119, v119
	s_nop 0
	v_add_f32_e32 v116, 1.0, v116
	v_add_f32_e32 v117, 1.0, v117
	v_add_f32_e32 v118, 1.0, v118
	v_add_f32_e32 v119, 1.0, v119
	v_rcp_f32_e32 v116, v116
	v_rcp_f32_e32 v117, v117
	v_rcp_f32_e32 v118, v118
	v_rcp_f32_e32 v119, v119
	s_nop 0
	v_mul_f32_e32 v116, 0x3f1b4598, v116
	v_mul_f32_e32 v117, 0x3f1b4598, v117
	v_mul_f32_e32 v118, 0x3f1b4598, v118
	v_mul_f32_e32 v119, 0x3f1b4598, v119
	v_cvt_pk_bf16_f32 v154, v116, v117
	v_cvt_pk_bf16_f32 v155, v118, v119
	ds_write_b64 v236, v[154:155] offset:16160
	v_add_f32_e32 v120, v120, v200
	v_add_f32_e32 v121, v121, v201
	v_add_f32_e32 v122, v122, v202
	v_add_f32_e32 v123, v123, v203
	v_mul_f32_e32 v120, 0xbfb8aa3b, v120
	v_mul_f32_e32 v121, 0xbfb8aa3b, v121
	v_mul_f32_e32 v122, 0xbfb8aa3b, v122
	v_mul_f32_e32 v123, 0xbfb8aa3b, v123
	v_exp_f32_e32 v120, v120
	v_exp_f32_e32 v121, v121
	v_exp_f32_e32 v122, v122
	v_exp_f32_e32 v123, v123
	s_nop 0
	v_add_f32_e32 v120, 1.0, v120
	v_add_f32_e32 v121, 1.0, v121
	v_add_f32_e32 v122, 1.0, v122
	v_add_f32_e32 v123, 1.0, v123
	v_rcp_f32_e32 v120, v120
	v_rcp_f32_e32 v121, v121
	v_rcp_f32_e32 v122, v122
	v_rcp_f32_e32 v123, v123
	s_nop 0
	v_mul_f32_e32 v120, 0x3f1b4598, v120
	v_mul_f32_e32 v121, 0x3f1b4598, v121
	v_mul_f32_e32 v122, 0x3f1b4598, v122
	v_mul_f32_e32 v123, 0x3f1b4598, v123
	v_cvt_pk_bf16_f32 v156, v120, v121
	v_cvt_pk_bf16_f32 v157, v122, v123
	ds_write_b64 v236, v[156:157] offset:16192
	v_add_f32_e32 v124, v124, v204
	v_add_f32_e32 v125, v125, v205
	v_add_f32_e32 v126, v126, v206
	v_add_f32_e32 v127, v127, v207
	v_mul_f32_e32 v124, 0xbfb8aa3b, v124
	v_mul_f32_e32 v125, 0xbfb8aa3b, v125
	v_mul_f32_e32 v126, 0xbfb8aa3b, v126
	v_mul_f32_e32 v127, 0xbfb8aa3b, v127
	v_exp_f32_e32 v124, v124
	v_exp_f32_e32 v125, v125
	v_exp_f32_e32 v126, v126
	v_exp_f32_e32 v127, v127
	s_nop 0
	v_add_f32_e32 v124, 1.0, v124
	v_add_f32_e32 v125, 1.0, v125
	v_add_f32_e32 v126, 1.0, v126
	v_add_f32_e32 v127, 1.0, v127
	v_rcp_f32_e32 v124, v124
	v_rcp_f32_e32 v125, v125
	v_rcp_f32_e32 v126, v126
	v_rcp_f32_e32 v127, v127
	s_nop 0
	v_mul_f32_e32 v124, 0x3f1b4598, v124
	v_mul_f32_e32 v125, 0x3f1b4598, v125
	v_mul_f32_e32 v126, 0x3f1b4598, v126
	v_mul_f32_e32 v127, 0x3f1b4598, v127
	v_cvt_pk_bf16_f32 v158, v124, v125
	v_cvt_pk_bf16_f32 v159, v126, v127
	ds_write_b64 v236, v[158:159] offset:16224
	s_waitcnt lgkmcnt(0)
; DI void st_bf16x4(bf16_t* o, f32x4 v) { u32x2 q; q.x = pack2(v[0], v[1]); q.y = pack2(v[2], v[3]); *(u32x2*)o = q; }
; template <class Epi>
; DI void gemm_tile(char* smem, const bf16_t* __restrict__ A0, int lda0, int ksplit, const bf16_t* __restrict__ A1, int lda1,
;                   const bf16_t* __restrict__ Bt, int K, int row0, int col0, const Epi& epi, int tid) {
;   constexpr int BK = 32, PITCH = 40, BUF = (256 + 128) * PITCH;
;   bf16_t* sbase = (bf16_t*)smem;
;   const int lane = tid & 63, wid = tid >> 6, wr = wid >> 1, wc = wid & 1, fr = lane & 15, fq = lane >> 4;
;   f32x4 acc[8][4];
; #pragma unroll
;   for (int m = 0; m < 8; ++m)
; #pragma unroll
;     for (int n = 0; n < 4; ++n) acc[m][n] = (f32x4){0.f, 0.f, 0.f, 0.f};
;   u32x4 ra[2][4], rb[2][2];
;   const int nk = K / BK;
;   const int sr = tid >> 2, scv = tid & 3;
;   DI void operator()(int row, int col, f32x4 v) const {
;     if (col < n0) st_bf16x4(o0 + (size_t)row * ld0 + col, v);
;     else { const int c = col - n0; if (c < n1) st_bf16x4(o1 + (size_t)row * ld1 + c, v); }
;   }
	ds_read_b128 v[128:131], v237
	ds_read_b128 v[132:135], v237 offset:1152
	ds_read_b128 v[136:139], v237 offset:2304
	ds_read_b128 v[140:143], v237 offset:3456
	ds_read_b128 v[144:147], v237 offset:4608
	ds_read_b128 v[148:151], v237 offset:5760
	ds_read_b128 v[152:155], v237 offset:6912
	ds_read_b128 v[156:159], v237 offset:8064
	ds_read_b128 v[160:163], v237 offset:9216
	ds_read_b128 v[164:167], v237 offset:10368
	ds_read_b128 v[168:171], v237 offset:11520
	ds_read_b128 v[172:175], v237 offset:12672
	ds_read_b128 v[176:179], v237 offset:13824
	ds_read_b128 v[180:183], v237 offset:14976
	ds_read_b128 v[184:187], v237 offset:16128
	ds_read_b128 v[188:191], v237 offset:17280
	s_waitcnt lgkmcnt(15)
	global_store_dwordx4 v238, v[128:131], s[4:5] nt
	s_add_u32 s4, s4, 0x2000
	s_addc_u32 s5, s5, 0
	s_waitcnt lgkmcnt(14)
	global_store_dwordx4 v238, v[132:135], s[4:5] nt
	s_add_u32 s4, s4, 0x2000
	s_addc_u32 s5, s5, 0
	s_waitcnt lgkmcnt(13)
	global_store_dwordx4 v238, v[136:139], s[4:5] nt
	s_add_u32 s4, s4, 0x2000
	s_addc_u32 s5, s5, 0
	s_waitcnt lgkmcnt(12)
	global_store_dwordx4 v238, v[140:143], s[4:5] nt
	s_add_u32 s4, s4, 0x2000
	s_addc_u32 s5, s5, 0
	s_waitcnt lgkmcnt(11)
	global_store_dwordx4 v238, v[144:147], s[4:5] nt
	s_add_u32 s4, s4, 0x2000
	s_addc_u32 s5, s5, 0
	s_waitcnt lgkmcnt(10)
	global_store_dwordx4 v238, v[148:151], s[4:5] nt
	s_add_u32 s4, s4, 0x2000
	s_addc_u32 s5, s5, 0
	s_waitcnt lgkmcnt(9)
	global_store_dwordx4 v238, v[152:155], s[4:5] nt
	s_add_u32 s4, s4, 0x2000
	s_addc_u32 s5, s5, 0
	s_waitcnt lgkmcnt(8)
	global_store_dwordx4 v238, v[156:159], s[4:5] nt
	s_add_u32 s4, s4, 0x2000
	s_addc_u32 s5, s5, 0
	s_waitcnt lgkmcnt(7)
	global_store_dwordx4 v238, v[160:163], s[4:5] nt
	s_add_u32 s4, s4, 0x2000
	s_addc_u32 s5, s5, 0
	s_waitcnt lgkmcnt(6)
	global_store_dwordx4 v238, v[164:167], s[4:5] nt
	s_add_u32 s4, s4, 0x2000
	s_addc_u32 s5, s5, 0
	s_waitcnt lgkmcnt(5)
	global_store_dwordx4 v238, v[168:171], s[4:5] nt
	s_add_u32 s4, s4, 0x2000
	s_addc_u32 s5, s5, 0
	s_waitcnt lgkmcnt(4)
	global_store_dwordx4 v238, v[172:175], s[4:5] nt
	s_add_u32 s4, s4, 0x2000
	s_addc_u32 s5, s5, 0
	s_waitcnt lgkmcnt(3)
	global_store_dwordx4 v238, v[176:179], s[4:5] nt
	s_add_u32 s4, s4, 0x2000
	s_addc_u32 s5, s5, 0
	s_waitcnt lgkmcnt(2)
	global_store_dwordx4 v238, v[180:183], s[4:5] nt
	s_add_u32 s4, s4, 0x2000
	s_addc_u32 s5, s5, 0
	s_waitcnt lgkmcnt(1)
	global_store_dwordx4 v238, v[184:187], s[4:5] nt
	s_add_u32 s4, s4, 0x2000
	s_addc_u32 s5, s5, 0
	s_waitcnt lgkmcnt(0)
	global_store_dwordx4 v238, v[188:191], s[4:5] nt
	s_nop 1
	s_add_u32 s15, s15, 64
	s_branch .Lg3a_tile
.Lg3a_done:
	s_setprio 0
	v_mbcnt_lo_u32_b32 v194, -1, 0
	v_mbcnt_hi_u32_b32 v136, -1, v194
	v_mbcnt_lo_u32_b32 v240, -1, 0
	v_mbcnt_hi_u32_b32 v240, -1, v240
	s_lshr_b32 s27, s72, 6
	s_lshl_b32 s100, s27, 10
	v_and_b32_e32 v241, 15, v240
	v_lshrrev_b32_e32 v242, 4, v240
	v_bfe_u32 v243, v240, 3, 1
	v_mul_u32_u24_e32 v243, 3, v243
	v_xor_b32_e32 v243, v242, v243
	v_lshlrev_b32_e32 v243, 4, v243
	v_lshl_add_u32 v243, v241, 6, v243
	s_lshr_b32 s26, s27, 1
	s_lshl_b32 s26, s26, 13
	v_add_u32_e32 v230, s26, v243
	s_and_b32 s26, s27, 1
	s_lshl_b32 s26, s26, 12
	s_add_u32 s26, s26, 16384
	v_add_u32_e32 v231, s26, v243
	s_lshr_b32 s26, s27, 1
	s_lshl_b32 s26, s26, 7
	v_add_u32_e32 v244, s26, v241
	s_and_b32 s26, s27, 1
	s_lshl_b32 s26, s26, 6
	v_lshl_add_u32 v245, v242, 2, s26
	v_lshlrev_b32_e32 v235, 2, v245
	s_mul_i32 s26, s27, 18432
	v_mul_u32_u24_e32 v246, 144, v241
	v_lshl_add_u32 v246, v242, 3, v246
	v_add_u32_e32 v236, s26, v246
	v_lshrrev_b32_e32 v246, 3, v240
	v_mul_u32_u24_e32 v246, 144, v246
	v_and_b32_e32 v247, 7, v240
	v_lshl_add_u32 v246, v247, 4, v246
	v_add_u32_e32 v237, s26, v246
	s_lshr_b32 s26, s27, 1
	s_lshl_b32 s26, s26, 7
	v_lshrrev_b32_e32 v246, 3, v240
	v_add_u32_e32 v246, s26, v246
	s_and_b32 s26, s27, 1
	s_lshl_b32 s26, s26, 6
	v_lshl_add_u32 v248, v247, 3, s26
	s_movk_i32 s26, 1024
	v_mul_lo_u32 v247, v246, s26
	v_lshl_add_u32 v238, v248, 1, v247
	v_lshrrev_b32_e32 v241, 2, v240
	s_lshl_b32 s26, s27, 4
	v_add_u32_e32 v241, s26, v241
	v_bfe_u32 v242, v240, 5, 1
	v_mul_u32_u24_e32 v242, 3, v242
	v_and_b32_e32 v243, 3, v240
	v_xor_b32_e32 v243, v243, v242
	v_lshlrev_b32_e32 v243, 4, v243
	s_mov_b32 s26, 512
	v_mad_u32_u24 v224, v241, s26, v243
	v_add_u32_e32 v225, 0x8000, v224
	v_add_u32_e32 v226, 0x10000, v224
	v_add_u32_e32 v227, 0x18000, v224
	s_mov_b32 s26, 128
	v_mad_u32_u24 v228, v241, s26, v243
	v_add_u32_e32 v229, 0x2000, v228
	s_load_dwordx2 s[6:7], s[74:75], 0x48
	s_cmpk_gt_u32 s96, 0xff
	s_cselect_b32 s25, 1, 0
	s_cmpk_gt_u32 s96, 0xff
	s_cbranch_scc0 .Lg3b_prio
	s_setprio 1

; #define LWRITE(S, buf) do { bf16_t* sA_ = sbase + (buf) * BUF; bf16_t* sB_ = sA_ + 256 * PITCH; \
;     _Pragma("unroll") for (int i_ = 0; i_ < 4; ++i_) *(u32x4*)(sA_ + (sr + i_ * 64) * PITCH + scv * 8) = ra[S][i_]; \
;     _Pragma("unroll") for (int i_ = 0; i_ < 2; ++i_) *(u32x4*)(sB_ + (sr + i_ * 64) * PITCH + scv * 8) = rb[S][i_]; } while (0)
; template <class Epi>
; DI void gemm_tile(char* smem, const bf16_t* __restrict__ A0, int lda0, int ksplit, const bf16_t* __restrict__ A1, int lda1,
;                   const bf16_t* __restrict__ Bt, int K, int row0, int col0, const Epi& epi, int tid) {
;     ...
;   f32x4 acc[8][4];
; #pragma unroll
;   for (int m = 0; m < 8; ++m)
; #pragma unroll
;     for (int n = 0; n < 4; ++n) acc[m][n] = (f32x4){0.f, 0.f, 0.f, 0.f};
;   u32x4 ra[2][4], rb[2][2];
;   const int nk = K / BK;
;   const int sr = tid >> 2, scv = tid & 3;
;     ...
;   __syncthreads();
;   {
;     const int last = nk - 1;
;     GLOAD(0, 0);
;     __builtin_amdgcn_sched_barrier(0);
;     GLOAD(1, 1);
;     __builtin_amdgcn_sched_barrier(0);
;     LWRITE(0, 0);
;     __builtin_amdgcn_sched_barrier(0);
;     GLOAD(0, (2 < last ? 2 : last));
;     __builtin_amdgcn_sched_barrier(0);
;     __syncthreads();
; template <class Epi>
; DI void gemm_phase(char* smem, const bf16_t* A0, int lda0, int ksplit, const bf16_t* A1, int lda1, const bf16_t* Bt, int K, int nN, const Epi& epi, int tid) {
;     ...
;     const int x = blockIdx.x & 7, l = blockIdx.x >> 3, L = G >> 3, per = 8 * nN, tot = 2 * per;
;     for (int q = l; q < tot; q += L) { const int rgl = q / per, rem = q % per, ct = rem >> 3, rt = (x * 2 + rgl) * 8 + (rem & 7);
;       gemm_tile(smem, A0, lda0, ksplit, A1, lda1, Bt, K, rt * 256, ct * 128, epi, tid); }
.Lg3b_tile:
	s_cmpk_ge_u32 s15, 64
	s_cbranch_scc1 .Lg3b_done
	s_cmpk_ge_u32 s15, 32
	s_cselect_b32 s27, 1, 0
	s_cselect_b32 s26, 32, 0
	s_sub_u32 s26, s15, s26
	s_add_u32 s27, s27, s101
	s_lshl_b32 s27, s27, 3
	s_and_b32 s29, s26, 7
	s_add_u32 s29, s29, s27
	s_lshl_b32 s29, s29, 8
	s_lshr_b32 s28, s26, 3
	s_lshl_b32 s28, s28, 7
	s_mul_i32 s27, s29, 512
	s_add_u32 s27, s27, 0x1ea00000
	s_add_u32 s0, s92, s27
	s_addc_u32 s1, s93, 0
	s_mul_i32 s27, s28, 128
	s_add_u32 s27, s27, 0x34b0000
	s_add_u32 s2, s92, s27
	s_addc_u32 s3, s93, 0
	s_waitcnt lgkmcnt(0)
	s_barrier
	s_mov_b32 s99, 0
	s_mov_b32 s30, 0
	s_add_u32 s26, s30, s100
	s_add_u32 m0, s26, 0
	s_nop 0
	global_load_lds_dwordx4 v224, s[0:1]
	s_add_u32 m0, s26, 4096
	s_nop 0
	global_load_lds_dwordx4 v225, s[0:1]
	s_add_u32 m0, s26, 8192
	s_nop 0
	global_load_lds_dwordx4 v226, s[0:1]
	s_add_u32 m0, s26, 12288
	s_nop 0
	global_load_lds_dwordx4 v227, s[0:1]
	s_add_u32 m0, s26, 16384
	s_nop 0
	global_load_lds_dwordx4 v228, s[2:3]
	s_add_u32 m0, s26, 20480
	s_nop 0
	global_load_lds_dwordx4 v229, s[2:3]
	s_add_u32 s0, s0, 64
	s_addc_u32 s1, s1, 0
	s_add_u32 s2, s2, 64
	s_addc_u32 s3, s3, 0
	s_add_u32 s99, s99, 1
	s_add_u32 s30, s30, 24576
	s_cmp_eq_u32 s30, 73728
	s_cselect_b32 s30, 0, s30
	s_add_u32 s26, s30, s100
	s_add_u32 m0, s26, 0
	s_nop 0
	global_load_lds_dwordx4 v224, s[0:1]
	s_add_u32 m0, s26, 4096
	s_nop 0
	global_load_lds_dwordx4 v225, s[0:1]
	s_add_u32 m0, s26, 8192
	s_nop 0
	global_load_lds_dwordx4 v226, s[0:1]
	s_add_u32 m0, s26, 12288
	s_nop 0
	global_load_lds_dwordx4 v227, s[0:1]
	s_add_u32 m0, s26, 16384
	s_nop 0
	global_load_lds_dwordx4 v228, s[2:3]
	s_add_u32 m0, s26, 20480
	s_nop 0
	global_load_lds_dwordx4 v229, s[2:3]
	s_add_u32 s0, s0, 64
	s_addc_u32 s1, s1, 0
	s_add_u32 s2, s2, 64
	s_addc_u32 s3, s3, 0
	s_add_u32 s99, s99, 1
	s_add_u32 s30, s30, 24576
	s_cmp_eq_u32 s30, 73728
	s_cselect_b32 s30, 0, s30
	v_mov_b32_e32 v0, 0
	v_mov_b32_e32 v1, 0
	v_mov_b32_e32 v2, 0
	v_mov_b32_e32 v3, 0
	v_mov_b32_e32 v4, 0
	v_mov_b32_e32 v5, 0
	v_mov_b32_e32 v6, 0
	v_mov_b32_e32 v7, 0
	v_mov_b32_e32 v8, 0
	v_mov_b32_e32 v9, 0
	v_mov_b32_e32 v10, 0
	v_mov_b32_e32 v11, 0
	v_mov_b32_e32 v12, 0
	v_mov_b32_e32 v13, 0
	v_mov_b32_e32 v14, 0
	v_mov_b32_e32 v15, 0
	v_mov_b32_e32 v16, 0
	v_mov_b32_e32 v17, 0
	v_mov_b32_e32 v18, 0
	v_mov_b32_e32 v19, 0
	v_mov_b32_e32 v20, 0
	v_mov_b32_e32 v21, 0
	v_mov_b32_e32 v22, 0
	v_mov_b32_e32 v23, 0
	v_mov_b32_e32 v24, 0
	v_mov_b32_e32 v25, 0
	v_mov_b32_e32 v26, 0
	v_mov_b32_e32 v27, 0
	v_mov_b32_e32 v28, 0
	v_mov_b32_e32 v29, 0
	v_mov_b32_e32 v30, 0
	v_mov_b32_e32 v31, 0
	v_mov_b32_e32 v32, 0
	v_mov_b32_e32 v33, 0
	v_mov_b32_e32 v34, 0
	v_mov_b32_e32 v35, 0
	v_mov_b32_e32 v36, 0
	v_mov_b32_e32 v37, 0
	v_mov_b32_e32 v38, 0
	v_mov_b32_e32 v39, 0
	v_mov_b32_e32 v40, 0
	v_mov_b32_e32 v41, 0
	v_mov_b32_e32 v42, 0
	v_mov_b32_e32 v43, 0
	v_mov_b32_e32 v44, 0
	v_mov_b32_e32 v45, 0
	v_mov_b32_e32 v46, 0
	v_mov_b32_e32 v47, 0
	v_mov_b32_e32 v48, 0
	v_mov_b32_e32 v49, 0
	v_mov_b32_e32 v50, 0
	v_mov_b32_e32 v51, 0
	v_mov_b32_e32 v52, 0
	v_mov_b32_e32 v53, 0
	v_mov_b32_e32 v54, 0
	v_mov_b32_e32 v55, 0
	v_mov_b32_e32 v56, 0
	v_mov_b32_e32 v57, 0
	v_mov_b32_e32 v58, 0
	v_mov_b32_e32 v59, 0
	v_mov_b32_e32 v60, 0
	v_mov_b32_e32 v61, 0
	v_mov_b32_e32 v62, 0
	v_mov_b32_e32 v63, 0
	v_mov_b32_e32 v64, 0
	v_mov_b32_e32 v65, 0
	v_mov_b32_e32 v66, 0
	v_mov_b32_e32 v67, 0
	v_mov_b32_e32 v68, 0
	v_mov_b32_e32 v69, 0
	v_mov_b32_e32 v70, 0
	v_mov_b32_e32 v71, 0
	v_mov_b32_e32 v72, 0
	v_mov_b32_e32 v73, 0
	v_mov_b32_e32 v74, 0
	v_mov_b32_e32 v75, 0
	v_mov_b32_e32 v76, 0
	v_mov_b32_e32 v77, 0
	v_mov_b32_e32 v78, 0
	v_mov_b32_e32 v79, 0
	v_mov_b32_e32 v80, 0
	v_mov_b32_e32 v81, 0
	v_mov_b32_e32 v82, 0
	v_mov_b32_e32 v83, 0
	v_mov_b32_e32 v84, 0
	v_mov_b32_e32 v85, 0
	v_mov_b32_e32 v86, 0
	v_mov_b32_e32 v87, 0
	v_mov_b32_e32 v88, 0
	v_mov_b32_e32 v89, 0
	v_mov_b32_e32 v90, 0
	v_mov_b32_e32 v91, 0
	v_mov_b32_e32 v92, 0
	v_mov_b32_e32 v93, 0
	v_mov_b32_e32 v94, 0
	v_mov_b32_e32 v95, 0
	v_mov_b32_e32 v96, 0
	v_mov_b32_e32 v97, 0
	v_mov_b32_e32 v98, 0
	v_mov_b32_e32 v99, 0
	v_mov_b32_e32 v100, 0
	v_mov_b32_e32 v101, 0
	v_mov_b32_e32 v102, 0
	v_mov_b32_e32 v103, 0
	v_mov_b32_e32 v104, 0
	v_mov_b32_e32 v105, 0
	v_mov_b32_e32 v106, 0
	v_mov_b32_e32 v107, 0
	v_mov_b32_e32 v108, 0
	v_mov_b32_e32 v109, 0
	v_mov_b32_e32 v110, 0
	v_mov_b32_e32 v111, 0
	v_mov_b32_e32 v112, 0
	v_mov_b32_e32 v113, 0
	v_mov_b32_e32 v114, 0
	v_mov_b32_e32 v115, 0
	v_mov_b32_e32 v116, 0
	v_mov_b32_e32 v117, 0
	v_mov_b32_e32 v118, 0
	v_mov_b32_e32 v119, 0
	v_mov_b32_e32 v120, 0
	v_mov_b32_e32 v121, 0
	v_mov_b32_e32 v122, 0
	v_mov_b32_e32 v123, 0
	v_mov_b32_e32 v124, 0
	v_mov_b32_e32 v125, 0
	v_mov_b32_e32 v126, 0
	v_mov_b32_e32 v127, 0
	s_mov_b32 s98, 0
	s_mov_b32 s31, 24576
	s_waitcnt vmcnt(6)
	s_barrier
	ds_read_b128 v[128:131], v231 offset:0
	ds_read_b128 v[132:135], v231 offset:1024
	ds_read_b128 v[136:139], v231 offset:2048
	ds_read_b128 v[140:143], v231 offset:3072
	ds_read_b128 v[144:147], v230 offset:0
	ds_read_b128 v[148:151], v230 offset:1024
	ds_read_b128 v[152:155], v230 offset:2048
	ds_read_b128 v[156:159], v230 offset:3072
	ds_read_b128 v[160:163], v230 offset:4096
	ds_read_b128 v[164:167], v230 offset:5120
	ds_read_b128 v[168:171], v230 offset:6144
	ds_read_b128 v[172:175], v230 offset:7168
	s_waitcnt vmcnt(0)
	s_waitcnt lgkmcnt(0)
	s_barrier
	v_add_u32_e32 v232, s31, v230
	v_add_u32_e32 v233, s31, v231
	s_setprio 1
	v_mfma_f32_16x16x32_bf16 v[0:3], v[128:131], v[144:147], v[0:3]
	v_mfma_f32_16x16x32_bf16 v[4:7], v[132:135], v[144:147], v[4:7]
	v_mfma_f32_16x16x32_bf16 v[8:11], v[136:139], v[144:147], v[8:11]
	v_mfma_f32_16x16x32_bf16 v[12:15], v[140:143], v[144:147], v[12:15]
	ds_read_b128 v[176:179], v233 offset:0
	ds_read_b128 v[180:183], v233 offset:1024
	v_mfma_f32_16x16x32_bf16 v[16:19], v[128:131], v[148:151], v[16:19]
	v_mfma_f32_16x16x32_bf16 v[20:23], v[132:135], v[148:151], v[20:23]
	v_mfma_f32_16x16x32_bf16 v[24:27], v[136:139], v[148:151], v[24:27]
	v_mfma_f32_16x16x32_bf16 v[28:31], v[140:143], v[148:151], v[28:31]
	ds_read_b128 v[184:187], v233 offset:2048
	ds_read_b128 v[188:191], v233 offset:3072
	v_mfma_f32_16x16x32_bf16 v[32:35], v[128:131], v[152:155], v[32:35]
	v_mfma_f32_16x16x32_bf16 v[36:39], v[132:135], v[152:155], v[36:39]
	v_mfma_f32_16x16x32_bf16 v[40:43], v[136:139], v[152:155], v[40:43]
	v_mfma_f32_16x16x32_bf16 v[44:47], v[140:143], v[152:155], v[44:47]
	ds_read_b128 v[192:195], v232 offset:0
	ds_read_b128 v[196:199], v232 offset:1024
	v_mfma_f32_16x16x32_bf16 v[48:51], v[128:131], v[156:159], v[48:51]
	v_mfma_f32_16x16x32_bf16 v[52:55], v[132:135], v[156:159], v[52:55]
	v_mfma_f32_16x16x32_bf16 v[56:59], v[136:139], v[156:159], v[56:59]
	v_mfma_f32_16x16x32_bf16 v[60:63], v[140:143], v[156:159], v[60:63]
	ds_read_b128 v[200:203], v232 offset:2048
	ds_read_b128 v[204:207], v232 offset:3072
	v_mfma_f32_16x16x32_bf16 v[64:67], v[128:131], v[160:163], v[64:67]
	v_mfma_f32_16x16x32_bf16 v[68:71], v[132:135], v[160:163], v[68:71]
	v_mfma_f32_16x16x32_bf16 v[72:75], v[136:139], v[160:163], v[72:75]
	v_mfma_f32_16x16x32_bf16 v[76:79], v[140:143], v[160:163], v[76:79]
	ds_read_b128 v[208:211], v232 offset:4096
	v_mfma_f32_16x16x32_bf16 v[80:83], v[128:131], v[164:167], v[80:83]
	v_mfma_f32_16x16x32_bf16 v[84:87], v[132:135], v[164:167], v[84:87]
	v_mfma_f32_16x16x32_bf16 v[88:91], v[136:139], v[164:167], v[88:91]
	v_mfma_f32_16x16x32_bf16 v[92:95], v[140:143], v[164:167], v[92:95]
	ds_read_b128 v[212:215], v232 offset:5120
	v_mfma_f32_16x16x32_bf16 v[96:99], v[128:131], v[168:171], v[96:99]
	v_mfma_f32_16x16x32_bf16 v[100:103], v[132:135], v[168:171], v[100:103]
	v_mfma_f32_16x16x32_bf16 v[104:107], v[136:139], v[168:171], v[104:107]
	v_mfma_f32_16x16x32_bf16 v[108:111], v[140:143], v[168:171], v[108:111]
	ds_read_b128 v[216:219], v232 offset:6144
	s_add_u32 s31, s31, 24576
	s_cmp_eq_u32 s31, 73728
	s_cselect_b32 s31, 0, s31
	v_mfma_f32_16x16x32_bf16 v[112:115], v[128:131], v[172:175], v[112:115]
	v_mfma_f32_16x16x32_bf16 v[116:119], v[132:135], v[172:175], v[116:119]
	v_mfma_f32_16x16x32_bf16 v[120:123], v[136:139], v[172:175], v[120:123]
	v_mfma_f32_16x16x32_bf16 v[124:127], v[140:143], v[172:175], v[124:127]
	ds_read_b128 v[220:223], v232 offset:7168
	s_cmp_eq_u32 s25, 0
	s_cbranch_scc0 .Lg3b_hi0
	s_setprio 0

; template <class Epi>
; DI void gemm_tile(char* smem, const bf16_t* __restrict__ A0, int lda0, int ksplit, const bf16_t* __restrict__ A1, int lda1,
;                   const bf16_t* __restrict__ Bt, int K, int row0, int col0, const Epi& epi, int tid) {
;     ...
;     for (int n = 0; n < 4; ++n) epi(row0 + wr * 128 + m * 16 + fr, col0 + wc * 64 + n * 16 + fq * 4, acc[m][n]);
.Lg3b_hi1:
	s_branch .Lg3b_epi
.Lg3b_epi:
	s_nop 7
	s_nop 7
	s_mul_i32 s27, s29, 1024
	s_lshl_b32 s26, s28, 1
	s_add_u32 s27, s27, s26
	s_add_u32 s27, s27, 0x9800000
	s_add_u32 s4, s92, s27
	s_addc_u32 s5, s93, 0
	s_lshl_b32 s27, s28, 2
	s_add_u32 s27, s27, 0x800
	s_add_u32 s2, s6, s27
	s_addc_u32 s3, s7, 0
	global_load_dwordx4 v[192:195], v235, s[2:3] offset:0
	global_load_dwordx4 v[196:199], v235, s[2:3] offset:64
	global_load_dwordx4 v[200:203], v235, s[2:3] offset:128
	global_load_dwordx4 v[204:207], v235, s[2:3] offset:192
	s_waitcnt vmcnt(0)
	v_add_f32_e32 v0, v0, v192
	v_add_f32_e32 v1, v1, v193
	v_add_f32_e32 v2, v2, v194
	v_add_f32_e32 v3, v3, v195
	v_mul_f32_e32 v0, 0xbfb8aa3b, v0
	v_mul_f32_e32 v1, 0xbfb8aa3b, v1
	v_mul_f32_e32 v2, 0xbfb8aa3b, v2
	v_mul_f32_e32 v3, 0xbfb8aa3b, v3
	v_exp_f32_e32 v0, v0
	v_exp_f32_e32 v1, v1
	v_exp_f32_e32 v2, v2
	v_exp_f32_e32 v3, v3
	s_nop 0
	v_add_f32_e32 v0, 1.0, v0
	v_add_f32_e32 v1, 1.0, v1
	v_add_f32_e32 v2, 1.0, v2
	v_add_f32_e32 v3, 1.0, v3
	v_rcp_f32_e32 v0, v0
	v_rcp_f32_e32 v1, v1
	v_rcp_f32_e32 v2, v2
	v_rcp_f32_e32 v3, v3
	s_nop 0
	v_mul_f32_e32 v0, 0x3f1b4598, v0
	v_mul_f32_e32 v1, 0x3f1b4598, v1
	v_mul_f32_e32 v2, 0x3f1b4598, v2
	v_mul_f32_e32 v3, 0x3f1b4598, v3
	v_cvt_pk_bf16_f32 v128, v0, v1
	v_cvt_pk_bf16_f32 v129, v2, v3
	ds_write_b64 v236, v[128:129]
	v_add_f32_e32 v4, v4, v196
	v_add_f32_e32 v5, v5, v197
	v_add_f32_e32 v6, v6, v198
	v_add_f32_e32 v7, v7, v199
	v_mul_f32_e32 v4, 0xbfb8aa3b, v4
	v_mul_f32_e32 v5, 0xbfb8aa3b, v5
	v_mul_f32_e32 v6, 0xbfb8aa3b, v6
	v_mul_f32_e32 v7, 0xbfb8aa3b, v7
	v_exp_f32_e32 v4, v4
	v_exp_f32_e32 v5, v5
	v_exp_f32_e32 v6, v6
	v_exp_f32_e32 v7, v7
	s_nop 0
	v_add_f32_e32 v4, 1.0, v4
	v_add_f32_e32 v5, 1.0, v5
	v_add_f32_e32 v6, 1.0, v6
	v_add_f32_e32 v7, 1.0, v7
	v_rcp_f32_e32 v4, v4
	v_rcp_f32_e32 v5, v5
	v_rcp_f32_e32 v6, v6
	v_rcp_f32_e32 v7, v7
	s_nop 0
	v_mul_f32_e32 v4, 0x3f1b4598, v4
	v_mul_f32_e32 v5, 0x3f1b4598, v5
	v_mul_f32_e32 v6, 0x3f1b4598, v6
	v_mul_f32_e32 v7, 0x3f1b4598, v7
	v_cvt_pk_bf16_f32 v130, v4, v5
	v_cvt_pk_bf16_f32 v131, v6, v7
	ds_write_b64 v236, v[130:131] offset:32
	v_add_f32_e32 v8, v8, v200
	v_add_f32_e32 v9, v9, v201
	v_add_f32_e32 v10, v10, v202
	v_add_f32_e32 v11, v11, v203
	v_mul_f32_e32 v8, 0xbfb8aa3b, v8
	v_mul_f32_e32 v9, 0xbfb8aa3b, v9
	v_mul_f32_e32 v10, 0xbfb8aa3b, v10
	v_mul_f32_e32 v11, 0xbfb8aa3b, v11
	v_exp_f32_e32 v8, v8
	v_exp_f32_e32 v9, v9
	v_exp_f32_e32 v10, v10
	v_exp_f32_e32 v11, v11
	s_nop 0
	v_add_f32_e32 v8, 1.0, v8
	v_add_f32_e32 v9, 1.0, v9
	v_add_f32_e32 v10, 1.0, v10
	v_add_f32_e32 v11, 1.0, v11
	v_rcp_f32_e32 v8, v8
	v_rcp_f32_e32 v9, v9
	v_rcp_f32_e32 v10, v10
	v_rcp_f32_e32 v11, v11
	s_nop 0
	v_mul_f32_e32 v8, 0x3f1b4598, v8
	v_mul_f32_e32 v9, 0x3f1b4598, v9
	v_mul_f32_e32 v10, 0x3f1b4598, v10
	v_mul_f32_e32 v11, 0x3f1b4598, v11
	v_cvt_pk_bf16_f32 v132, v8, v9
	v_cvt_pk_bf16_f32 v133, v10, v11
	ds_write_b64 v236, v[132:133] offset:64
	v_add_f32_e32 v12, v12, v204
	v_add_f32_e32 v13, v13, v205
	v_add_f32_e32 v14, v14, v206
	v_add_f32_e32 v15, v15, v207
	v_mul_f32_e32 v12, 0xbfb8aa3b, v12
	v_mul_f32_e32 v13, 0xbfb8aa3b, v13
	v_mul_f32_e32 v14, 0xbfb8aa3b, v14
	v_mul_f32_e32 v15, 0xbfb8aa3b, v15
	v_exp_f32_e32 v12, v12
	v_exp_f32_e32 v13, v13
	v_exp_f32_e32 v14, v14
	v_exp_f32_e32 v15, v15
	s_nop 0
	v_add_f32_e32 v12, 1.0, v12
	v_add_f32_e32 v13, 1.0, v13
	v_add_f32_e32 v14, 1.0, v14
	v_add_f32_e32 v15, 1.0, v15
	v_rcp_f32_e32 v12, v12
	v_rcp_f32_e32 v13, v13
	v_rcp_f32_e32 v14, v14
	v_rcp_f32_e32 v15, v15
	s_nop 0
	v_mul_f32_e32 v12, 0x3f1b4598, v12
	v_mul_f32_e32 v13, 0x3f1b4598, v13
	v_mul_f32_e32 v14, 0x3f1b4598, v14
	v_mul_f32_e32 v15, 0x3f1b4598, v15
	v_cvt_pk_bf16_f32 v134, v12, v13
	v_cvt_pk_bf16_f32 v135, v14, v15
	ds_write_b64 v236, v[134:135] offset:96
	v_add_f32_e32 v16, v16, v192
	v_add_f32_e32 v17, v17, v193
	v_add_f32_e32 v18, v18, v194
	v_add_f32_e32 v19, v19, v195
	v_mul_f32_e32 v16, 0xbfb8aa3b, v16
	v_mul_f32_e32 v17, 0xbfb8aa3b, v17
	v_mul_f32_e32 v18, 0xbfb8aa3b, v18
	v_mul_f32_e32 v19, 0xbfb8aa3b, v19
	v_exp_f32_e32 v16, v16
	v_exp_f32_e32 v17, v17
	v_exp_f32_e32 v18, v18
	v_exp_f32_e32 v19, v19
	s_nop 0
	v_add_f32_e32 v16, 1.0, v16
	v_add_f32_e32 v17, 1.0, v17
	v_add_f32_e32 v18, 1.0, v18
	v_add_f32_e32 v19, 1.0, v19
	v_rcp_f32_e32 v16, v16
	v_rcp_f32_e32 v17, v17
	v_rcp_f32_e32 v18, v18
	v_rcp_f32_e32 v19, v19
	s_nop 0
	v_mul_f32_e32 v16, 0x3f1b4598, v16
	v_mul_f32_e32 v17, 0x3f1b4598, v17
	v_mul_f32_e32 v18, 0x3f1b4598, v18
	v_mul_f32_e32 v19, 0x3f1b4598, v19
	v_cvt_pk_bf16_f32 v136, v16, v17
	v_cvt_pk_bf16_f32 v137, v18, v19
	ds_write_b64 v236, v[136:137] offset:2304
	v_add_f32_e32 v20, v20, v196
	v_add_f32_e32 v21, v21, v197
	v_add_f32_e32 v22, v22, v198
	v_add_f32_e32 v23, v23, v199
	v_mul_f32_e32 v20, 0xbfb8aa3b, v20
	v_mul_f32_e32 v21, 0xbfb8aa3b, v21
	v_mul_f32_e32 v22, 0xbfb8aa3b, v22
	v_mul_f32_e32 v23, 0xbfb8aa3b, v23
	v_exp_f32_e32 v20, v20
	v_exp_f32_e32 v21, v21
	v_exp_f32_e32 v22, v22
	v_exp_f32_e32 v23, v23
	s_nop 0
	v_add_f32_e32 v20, 1.0, v20
	v_add_f32_e32 v21, 1.0, v21
	v_add_f32_e32 v22, 1.0, v22
	v_add_f32_e32 v23, 1.0, v23
	v_rcp_f32_e32 v20, v20
	v_rcp_f32_e32 v21, v21
	v_rcp_f32_e32 v22, v22
	v_rcp_f32_e32 v23, v23
	s_nop 0
	v_mul_f32_e32 v20, 0x3f1b4598, v20
	v_mul_f32_e32 v21, 0x3f1b4598, v21
	v_mul_f32_e32 v22, 0x3f1b4598, v22
	v_mul_f32_e32 v23, 0x3f1b4598, v23
	v_cvt_pk_bf16_f32 v138, v20, v21
	v_cvt_pk_bf16_f32 v139, v22, v23
	ds_write_b64 v236, v[138:139] offset:2336
	v_add_f32_e32 v24, v24, v200
	v_add_f32_e32 v25, v25, v201
	v_add_f32_e32 v26, v26, v202
	v_add_f32_e32 v27, v27, v203
	v_mul_f32_e32 v24, 0xbfb8aa3b, v24
	v_mul_f32_e32 v25, 0xbfb8aa3b, v25
	v_mul_f32_e32 v26, 0xbfb8aa3b, v26
	v_mul_f32_e32 v27, 0xbfb8aa3b, v27
	v_exp_f32_e32 v24, v24
	v_exp_f32_e32 v25, v25
	v_exp_f32_e32 v26, v26
	v_exp_f32_e32 v27, v27
	s_nop 0
	v_add_f32_e32 v24, 1.0, v24
	v_add_f32_e32 v25, 1.0, v25
	v_add_f32_e32 v26, 1.0, v26
	v_add_f32_e32 v27, 1.0, v27
	v_rcp_f32_e32 v24, v24
	v_rcp_f32_e32 v25, v25
	v_rcp_f32_e32 v26, v26
	v_rcp_f32_e32 v27, v27
	s_nop 0
	v_mul_f32_e32 v24, 0x3f1b4598, v24
	v_mul_f32_e32 v25, 0x3f1b4598, v25
	v_mul_f32_e32 v26, 0x3f1b4598, v26
	v_mul_f32_e32 v27, 0x3f1b4598, v27
	v_cvt_pk_bf16_f32 v140, v24, v25
	v_cvt_pk_bf16_f32 v141, v26, v27
	ds_write_b64 v236, v[140:141] offset:2368
	v_add_f32_e32 v28, v28, v204
	v_add_f32_e32 v29, v29, v205
	v_add_f32_e32 v30, v30, v206
	v_add_f32_e32 v31, v31, v207
	v_mul_f32_e32 v28, 0xbfb8aa3b, v28
	v_mul_f32_e32 v29, 0xbfb8aa3b, v29
	v_mul_f32_e32 v30, 0xbfb8aa3b, v30
	v_mul_f32_e32 v31, 0xbfb8aa3b, v31
	v_exp_f32_e32 v28, v28
	v_exp_f32_e32 v29, v29
	v_exp_f32_e32 v30, v30
	v_exp_f32_e32 v31, v31
	s_nop 0
	v_add_f32_e32 v28, 1.0, v28
	v_add_f32_e32 v29, 1.0, v29
	v_add_f32_e32 v30, 1.0, v30
	v_add_f32_e32 v31, 1.0, v31
	v_rcp_f32_e32 v28, v28
	v_rcp_f32_e32 v29, v29
	v_rcp_f32_e32 v30, v30
	v_rcp_f32_e32 v31, v31
	s_nop 0
	v_mul_f32_e32 v28, 0x3f1b4598, v28
	v_mul_f32_e32 v29, 0x3f1b4598, v29
	v_mul_f32_e32 v30, 0x3f1b4598, v30
	v_mul_f32_e32 v31, 0x3f1b4598, v31
	v_cvt_pk_bf16_f32 v142, v28, v29
	v_cvt_pk_bf16_f32 v143, v30, v31
	ds_write_b64 v236, v[142:143] offset:2400
	v_add_f32_e32 v32, v32, v192
	v_add_f32_e32 v33, v33, v193
	v_add_f32_e32 v34, v34, v194
	v_add_f32_e32 v35, v35, v195
	v_mul_f32_e32 v32, 0xbfb8aa3b, v32
	v_mul_f32_e32 v33, 0xbfb8aa3b, v33
	v_mul_f32_e32 v34, 0xbfb8aa3b, v34
	v_mul_f32_e32 v35, 0xbfb8aa3b, v35
	v_exp_f32_e32 v32, v32
	v_exp_f32_e32 v33, v33
	v_exp_f32_e32 v34, v34
	v_exp_f32_e32 v35, v35
	s_nop 0
	v_add_f32_e32 v32, 1.0, v32
	v_add_f32_e32 v33, 1.0, v33
	v_add_f32_e32 v34, 1.0, v34
	v_add_f32_e32 v35, 1.0, v35
	v_rcp_f32_e32 v32, v32
	v_rcp_f32_e32 v33, v33
	v_rcp_f32_e32 v34, v34
	v_rcp_f32_e32 v35, v35
	s_nop 0
	v_mul_f32_e32 v32, 0x3f1b4598, v32
	v_mul_f32_e32 v33, 0x3f1b4598, v33
	v_mul_f32_e32 v34, 0x3f1b4598, v34
	v_mul_f32_e32 v35, 0x3f1b4598, v35
	v_cvt_pk_bf16_f32 v144, v32, v33
	v_cvt_pk_bf16_f32 v145, v34, v35
	ds_write_b64 v236, v[144:145] offset:4608
	v_add_f32_e32 v36, v36, v196
	v_add_f32_e32 v37, v37, v197
	v_add_f32_e32 v38, v38, v198
	v_add_f32_e32 v39, v39, v199
	v_mul_f32_e32 v36, 0xbfb8aa3b, v36
	v_mul_f32_e32 v37, 0xbfb8aa3b, v37
	v_mul_f32_e32 v38, 0xbfb8aa3b, v38
	v_mul_f32_e32 v39, 0xbfb8aa3b, v39
	v_exp_f32_e32 v36, v36
	v_exp_f32_e32 v37, v37
	v_exp_f32_e32 v38, v38
	v_exp_f32_e32 v39, v39
	s_nop 0
	v_add_f32_e32 v36, 1.0, v36
	v_add_f32_e32 v37, 1.0, v37
	v_add_f32_e32 v38, 1.0, v38
	v_add_f32_e32 v39, 1.0, v39
	v_rcp_f32_e32 v36, v36
	v_rcp_f32_e32 v37, v37
	v_rcp_f32_e32 v38, v38
	v_rcp_f32_e32 v39, v39
	s_nop 0
	v_mul_f32_e32 v36, 0x3f1b4598, v36
	v_mul_f32_e32 v37, 0x3f1b4598, v37
	v_mul_f32_e32 v38, 0x3f1b4598, v38
	v_mul_f32_e32 v39, 0x3f1b4598, v39
	v_cvt_pk_bf16_f32 v146, v36, v37
	v_cvt_pk_bf16_f32 v147, v38, v39
	ds_write_b64 v236, v[146:147] offset:4640
	v_add_f32_e32 v40, v40, v200
	v_add_f32_e32 v41, v41, v201
	v_add_f32_e32 v42, v42, v202
	v_add_f32_e32 v43, v43, v203
	v_mul_f32_e32 v40, 0xbfb8aa3b, v40
	v_mul_f32_e32 v41, 0xbfb8aa3b, v41
	v_mul_f32_e32 v42, 0xbfb8aa3b, v42
	v_mul_f32_e32 v43, 0xbfb8aa3b, v43
	v_exp_f32_e32 v40, v40
	v_exp_f32_e32 v41, v41
	v_exp_f32_e32 v42, v42
	v_exp_f32_e32 v43, v43
	s_nop 0
	v_add_f32_e32 v40, 1.0, v40
	v_add_f32_e32 v41, 1.0, v41
	v_add_f32_e32 v42, 1.0, v42
	v_add_f32_e32 v43, 1.0, v43
	v_rcp_f32_e32 v40, v40
	v_rcp_f32_e32 v41, v41
	v_rcp_f32_e32 v42, v42
	v_rcp_f32_e32 v43, v43
	s_nop 0
	v_mul_f32_e32 v40, 0x3f1b4598, v40
	v_mul_f32_e32 v41, 0x3f1b4598, v41
	v_mul_f32_e32 v42, 0x3f1b4598, v42
	v_mul_f32_e32 v43, 0x3f1b4598, v43
	v_cvt_pk_bf16_f32 v148, v40, v41
	v_cvt_pk_bf16_f32 v149, v42, v43
	ds_write_b64 v236, v[148:149] offset:4672
	v_add_f32_e32 v44, v44, v204
	v_add_f32_e32 v45, v45, v205
	v_add_f32_e32 v46, v46, v206
	v_add_f32_e32 v47, v47, v207
	v_mul_f32_e32 v44, 0xbfb8aa3b, v44
	v_mul_f32_e32 v45, 0xbfb8aa3b, v45
	v_mul_f32_e32 v46, 0xbfb8aa3b, v46
	v_mul_f32_e32 v47, 0xbfb8aa3b, v47
	v_exp_f32_e32 v44, v44
	v_exp_f32_e32 v45, v45
	v_exp_f32_e32 v46, v46
	v_exp_f32_e32 v47, v47
	s_nop 0
	v_add_f32_e32 v44, 1.0, v44
	v_add_f32_e32 v45, 1.0, v45
	v_add_f32_e32 v46, 1.0, v46
	v_add_f32_e32 v47, 1.0, v47
	v_rcp_f32_e32 v44, v44
	v_rcp_f32_e32 v45, v45
	v_rcp_f32_e32 v46, v46
	v_rcp_f32_e32 v47, v47
	s_nop 0
	v_mul_f32_e32 v44, 0x3f1b4598, v44
	v_mul_f32_e32 v45, 0x3f1b4598, v45
	v_mul_f32_e32 v46, 0x3f1b4598, v46
	v_mul_f32_e32 v47, 0x3f1b4598, v47
	v_cvt_pk_bf16_f32 v150, v44, v45
	v_cvt_pk_bf16_f32 v151, v46, v47
	ds_write_b64 v236, v[150:151] offset:4704
	v_add_f32_e32 v48, v48, v192
	v_add_f32_e32 v49, v49, v193
	v_add_f32_e32 v50, v50, v194
	v_add_f32_e32 v51, v51, v195
	v_mul_f32_e32 v48, 0xbfb8aa3b, v48
	v_mul_f32_e32 v49, 0xbfb8aa3b, v49
	v_mul_f32_e32 v50, 0xbfb8aa3b, v50
	v_mul_f32_e32 v51, 0xbfb8aa3b, v51
	v_exp_f32_e32 v48, v48
	v_exp_f32_e32 v49, v49
	v_exp_f32_e32 v50, v50
	v_exp_f32_e32 v51, v51
	s_nop 0
	v_add_f32_e32 v48, 1.0, v48
	v_add_f32_e32 v49, 1.0, v49
	v_add_f32_e32 v50, 1.0, v50
	v_add_f32_e32 v51, 1.0, v51
	v_rcp_f32_e32 v48, v48
	v_rcp_f32_e32 v49, v49
	v_rcp_f32_e32 v50, v50
	v_rcp_f32_e32 v51, v51
	s_nop 0
	v_mul_f32_e32 v48, 0x3f1b4598, v48
	v_mul_f32_e32 v49, 0x3f1b4598, v49
	v_mul_f32_e32 v50, 0x3f1b4598, v50
	v_mul_f32_e32 v51, 0x3f1b4598, v51
	v_cvt_pk_bf16_f32 v152, v48, v49
	v_cvt_pk_bf16_f32 v153, v50, v51
	ds_write_b64 v236, v[152:153] offset:6912
	v_add_f32_e32 v52, v52, v196
	v_add_f32_e32 v53, v53, v197
	v_add_f32_e32 v54, v54, v198
	v_add_f32_e32 v55, v55, v199
	v_mul_f32_e32 v52, 0xbfb8aa3b, v52
	v_mul_f32_e32 v53, 0xbfb8aa3b, v53
	v_mul_f32_e32 v54, 0xbfb8aa3b, v54
	v_mul_f32_e32 v55, 0xbfb8aa3b, v55
	v_exp_f32_e32 v52, v52
	v_exp_f32_e32 v53, v53
	v_exp_f32_e32 v54, v54
	v_exp_f32_e32 v55, v55
	s_nop 0
	v_add_f32_e32 v52, 1.0, v52
	v_add_f32_e32 v53, 1.0, v53
	v_add_f32_e32 v54, 1.0, v54
	v_add_f32_e32 v55, 1.0, v55
	v_rcp_f32_e32 v52, v52
	v_rcp_f32_e32 v53, v53
	v_rcp_f32_e32 v54, v54
	v_rcp_f32_e32 v55, v55
	s_nop 0
	v_mul_f32_e32 v52, 0x3f1b4598, v52
	v_mul_f32_e32 v53, 0x3f1b4598, v53
	v_mul_f32_e32 v54, 0x3f1b4598, v54
	v_mul_f32_e32 v55, 0x3f1b4598, v55
	v_cvt_pk_bf16_f32 v154, v52, v53
	v_cvt_pk_bf16_f32 v155, v54, v55
	ds_write_b64 v236, v[154:155] offset:6944
	v_add_f32_e32 v56, v56, v200
	v_add_f32_e32 v57, v57, v201
	v_add_f32_e32 v58, v58, v202
	v_add_f32_e32 v59, v59, v203
	v_mul_f32_e32 v56, 0xbfb8aa3b, v56
	v_mul_f32_e32 v57, 0xbfb8aa3b, v57
	v_mul_f32_e32 v58, 0xbfb8aa3b, v58
	v_mul_f32_e32 v59, 0xbfb8aa3b, v59
	v_exp_f32_e32 v56, v56
	v_exp_f32_e32 v57, v57
	v_exp_f32_e32 v58, v58
	v_exp_f32_e32 v59, v59
	s_nop 0
	v_add_f32_e32 v56, 1.0, v56
	v_add_f32_e32 v57, 1.0, v57
	v_add_f32_e32 v58, 1.0, v58
	v_add_f32_e32 v59, 1.0, v59
	v_rcp_f32_e32 v56, v56
	v_rcp_f32_e32 v57, v57
	v_rcp_f32_e32 v58, v58
	v_rcp_f32_e32 v59, v59
	s_nop 0
	v_mul_f32_e32 v56, 0x3f1b4598, v56
	v_mul_f32_e32 v57, 0x3f1b4598, v57
	v_mul_f32_e32 v58, 0x3f1b4598, v58
	v_mul_f32_e32 v59, 0x3f1b4598, v59
	v_cvt_pk_bf16_f32 v156, v56, v57
	v_cvt_pk_bf16_f32 v157, v58, v59
	ds_write_b64 v236, v[156:157] offset:6976
	v_add_f32_e32 v60, v60, v204
	v_add_f32_e32 v61, v61, v205
	v_add_f32_e32 v62, v62, v206
	v_add_f32_e32 v63, v63, v207
	v_mul_f32_e32 v60, 0xbfb8aa3b, v60
	v_mul_f32_e32 v61, 0xbfb8aa3b, v61
	v_mul_f32_e32 v62, 0xbfb8aa3b, v62
	v_mul_f32_e32 v63, 0xbfb8aa3b, v63
	v_exp_f32_e32 v60, v60
	v_exp_f32_e32 v61, v61
	v_exp_f32_e32 v62, v62
	v_exp_f32_e32 v63, v63
	s_nop 0
	v_add_f32_e32 v60, 1.0, v60
	v_add_f32_e32 v61, 1.0, v61
	v_add_f32_e32 v62, 1.0, v62
	v_add_f32_e32 v63, 1.0, v63
	v_rcp_f32_e32 v60, v60
	v_rcp_f32_e32 v61, v61
	v_rcp_f32_e32 v62, v62
	v_rcp_f32_e32 v63, v63
	s_nop 0
	v_mul_f32_e32 v60, 0x3f1b4598, v60
	v_mul_f32_e32 v61, 0x3f1b4598, v61
	v_mul_f32_e32 v62, 0x3f1b4598, v62
	v_mul_f32_e32 v63, 0x3f1b4598, v63
	v_cvt_pk_bf16_f32 v158, v60, v61
	v_cvt_pk_bf16_f32 v159, v62, v63
	ds_write_b64 v236, v[158:159] offset:7008
	v_add_f32_e32 v64, v64, v192
	v_add_f32_e32 v65, v65, v193
	v_add_f32_e32 v66, v66, v194
	v_add_f32_e32 v67, v67, v195
	v_mul_f32_e32 v64, 0xbfb8aa3b, v64
	v_mul_f32_e32 v65, 0xbfb8aa3b, v65
	v_mul_f32_e32 v66, 0xbfb8aa3b, v66
	v_mul_f32_e32 v67, 0xbfb8aa3b, v67
	v_exp_f32_e32 v64, v64
	v_exp_f32_e32 v65, v65
	v_exp_f32_e32 v66, v66
	v_exp_f32_e32 v67, v67
	s_nop 0
	v_add_f32_e32 v64, 1.0, v64
	v_add_f32_e32 v65, 1.0, v65
	v_add_f32_e32 v66, 1.0, v66
	v_add_f32_e32 v67, 1.0, v67
	v_rcp_f32_e32 v64, v64
	v_rcp_f32_e32 v65, v65
	v_rcp_f32_e32 v66, v66
	v_rcp_f32_e32 v67, v67
	s_nop 0
	v_mul_f32_e32 v64, 0x3f1b4598, v64
	v_mul_f32_e32 v65, 0x3f1b4598, v65
	v_mul_f32_e32 v66, 0x3f1b4598, v66
	v_mul_f32_e32 v67, 0x3f1b4598, v67
	v_cvt_pk_bf16_f32 v128, v64, v65
	v_cvt_pk_bf16_f32 v129, v66, v67
	ds_write_b64 v236, v[128:129] offset:9216
	v_add_f32_e32 v68, v68, v196
	v_add_f32_e32 v69, v69, v197
	v_add_f32_e32 v70, v70, v198
	v_add_f32_e32 v71, v71, v199
	v_mul_f32_e32 v68, 0xbfb8aa3b, v68
	v_mul_f32_e32 v69, 0xbfb8aa3b, v69
	v_mul_f32_e32 v70, 0xbfb8aa3b, v70
	v_mul_f32_e32 v71, 0xbfb8aa3b, v71
	v_exp_f32_e32 v68, v68
	v_exp_f32_e32 v69, v69
	v_exp_f32_e32 v70, v70
	v_exp_f32_e32 v71, v71
	s_nop 0
	v_add_f32_e32 v68, 1.0, v68
	v_add_f32_e32 v69, 1.0, v69
	v_add_f32_e32 v70, 1.0, v70
	v_add_f32_e32 v71, 1.0, v71
	v_rcp_f32_e32 v68, v68
	v_rcp_f32_e32 v69, v69
	v_rcp_f32_e32 v70, v70
	v_rcp_f32_e32 v71, v71
	s_nop 0
	v_mul_f32_e32 v68, 0x3f1b4598, v68
	v_mul_f32_e32 v69, 0x3f1b4598, v69
	v_mul_f32_e32 v70, 0x3f1b4598, v70
	v_mul_f32_e32 v71, 0x3f1b4598, v71
	v_cvt_pk_bf16_f32 v130, v68, v69
	v_cvt_pk_bf16_f32 v131, v70, v71
	ds_write_b64 v236, v[130:131] offset:9248
	v_add_f32_e32 v72, v72, v200
	v_add_f32_e32 v73, v73, v201
	v_add_f32_e32 v74, v74, v202
	v_add_f32_e32 v75, v75, v203
	v_mul_f32_e32 v72, 0xbfb8aa3b, v72
	v_mul_f32_e32 v73, 0xbfb8aa3b, v73
	v_mul_f32_e32 v74, 0xbfb8aa3b, v74
	v_mul_f32_e32 v75, 0xbfb8aa3b, v75
	v_exp_f32_e32 v72, v72
	v_exp_f32_e32 v73, v73
	v_exp_f32_e32 v74, v74
	v_exp_f32_e32 v75, v75
	s_nop 0
	v_add_f32_e32 v72, 1.0, v72
	v_add_f32_e32 v73, 1.0, v73
	v_add_f32_e32 v74, 1.0, v74
	v_add_f32_e32 v75, 1.0, v75
	v_rcp_f32_e32 v72, v72
	v_rcp_f32_e32 v73, v73
	v_rcp_f32_e32 v74, v74
	v_rcp_f32_e32 v75, v75
	s_nop 0
	v_mul_f32_e32 v72, 0x3f1b4598, v72
	v_mul_f32_e32 v73, 0x3f1b4598, v73
	v_mul_f32_e32 v74, 0x3f1b4598, v74
	v_mul_f32_e32 v75, 0x3f1b4598, v75
	v_cvt_pk_bf16_f32 v132, v72, v73
	v_cvt_pk_bf16_f32 v133, v74, v75
	ds_write_b64 v236, v[132:133] offset:9280
	v_add_f32_e32 v76, v76, v204
	v_add_f32_e32 v77, v77, v205
	v_add_f32_e32 v78, v78, v206
	v_add_f32_e32 v79, v79, v207
	v_mul_f32_e32 v76, 0xbfb8aa3b, v76
	v_mul_f32_e32 v77, 0xbfb8aa3b, v77
	v_mul_f32_e32 v78, 0xbfb8aa3b, v78
	v_mul_f32_e32 v79, 0xbfb8aa3b, v79
	v_exp_f32_e32 v76, v76
	v_exp_f32_e32 v77, v77
	v_exp_f32_e32 v78, v78
	v_exp_f32_e32 v79, v79
	s_nop 0
	v_add_f32_e32 v76, 1.0, v76
	v_add_f32_e32 v77, 1.0, v77
	v_add_f32_e32 v78, 1.0, v78
	v_add_f32_e32 v79, 1.0, v79
	v_rcp_f32_e32 v76, v76
	v_rcp_f32_e32 v77, v77
	v_rcp_f32_e32 v78, v78
	v_rcp_f32_e32 v79, v79
	s_nop 0
	v_mul_f32_e32 v76, 0x3f1b4598, v76
	v_mul_f32_e32 v77, 0x3f1b4598, v77
	v_mul_f32_e32 v78, 0x3f1b4598, v78
	v_mul_f32_e32 v79, 0x3f1b4598, v79
	v_cvt_pk_bf16_f32 v134, v76, v77
	v_cvt_pk_bf16_f32 v135, v78, v79
	ds_write_b64 v236, v[134:135] offset:9312
	v_add_f32_e32 v80, v80, v192
	v_add_f32_e32 v81, v81, v193
	v_add_f32_e32 v82, v82, v194
	v_add_f32_e32 v83, v83, v195
	v_mul_f32_e32 v80, 0xbfb8aa3b, v80
	v_mul_f32_e32 v81, 0xbfb8aa3b, v81
	v_mul_f32_e32 v82, 0xbfb8aa3b, v82
	v_mul_f32_e32 v83, 0xbfb8aa3b, v83
	v_exp_f32_e32 v80, v80
	v_exp_f32_e32 v81, v81
	v_exp_f32_e32 v82, v82
	v_exp_f32_e32 v83, v83
	s_nop 0
	v_add_f32_e32 v80, 1.0, v80
	v_add_f32_e32 v81, 1.0, v81
	v_add_f32_e32 v82, 1.0, v82
	v_add_f32_e32 v83, 1.0, v83
	v_rcp_f32_e32 v80, v80
	v_rcp_f32_e32 v81, v81
	v_rcp_f32_e32 v82, v82
	v_rcp_f32_e32 v83, v83
	s_nop 0
	v_mul_f32_e32 v80, 0x3f1b4598, v80
	v_mul_f32_e32 v81, 0x3f1b4598, v81
	v_mul_f32_e32 v82, 0x3f1b4598, v82
	v_mul_f32_e32 v83, 0x3f1b4598, v83
	v_cvt_pk_bf16_f32 v136, v80, v81
	v_cvt_pk_bf16_f32 v137, v82, v83
	ds_write_b64 v236, v[136:137] offset:11520
	v_add_f32_e32 v84, v84, v196
	v_add_f32_e32 v85, v85, v197
	v_add_f32_e32 v86, v86, v198
	v_add_f32_e32 v87, v87, v199
	v_mul_f32_e32 v84, 0xbfb8aa3b, v84
	v_mul_f32_e32 v85, 0xbfb8aa3b, v85
	v_mul_f32_e32 v86, 0xbfb8aa3b, v86
	v_mul_f32_e32 v87, 0xbfb8aa3b, v87
	v_exp_f32_e32 v84, v84
	v_exp_f32_e32 v85, v85
	v_exp_f32_e32 v86, v86
	v_exp_f32_e32 v87, v87
	s_nop 0
	v_add_f32_e32 v84, 1.0, v84
	v_add_f32_e32 v85, 1.0, v85
	v_add_f32_e32 v86, 1.0, v86
	v_add_f32_e32 v87, 1.0, v87
	v_rcp_f32_e32 v84, v84
	v_rcp_f32_e32 v85, v85
	v_rcp_f32_e32 v86, v86
	v_rcp_f32_e32 v87, v87
	s_nop 0
	v_mul_f32_e32 v84, 0x3f1b4598, v84
	v_mul_f32_e32 v85, 0x3f1b4598, v85
	v_mul_f32_e32 v86, 0x3f1b4598, v86
	v_mul_f32_e32 v87, 0x3f1b4598, v87
	v_cvt_pk_bf16_f32 v138, v84, v85
	v_cvt_pk_bf16_f32 v139, v86, v87
	ds_write_b64 v236, v[138:139] offset:11552
	v_add_f32_e32 v88, v88, v200
	v_add_f32_e32 v89, v89, v201
	v_add_f32_e32 v90, v90, v202
	v_add_f32_e32 v91, v91, v203
	v_mul_f32_e32 v88, 0xbfb8aa3b, v88
	v_mul_f32_e32 v89, 0xbfb8aa3b, v89
	v_mul_f32_e32 v90, 0xbfb8aa3b, v90
	v_mul_f32_e32 v91, 0xbfb8aa3b, v91
	v_exp_f32_e32 v88, v88
	v_exp_f32_e32 v89, v89
	v_exp_f32_e32 v90, v90
	v_exp_f32_e32 v91, v91
	s_nop 0
	v_add_f32_e32 v88, 1.0, v88
	v_add_f32_e32 v89, 1.0, v89
	v_add_f32_e32 v90, 1.0, v90
	v_add_f32_e32 v91, 1.0, v91
	v_rcp_f32_e32 v88, v88
	v_rcp_f32_e32 v89, v89
	v_rcp_f32_e32 v90, v90
	v_rcp_f32_e32 v91, v91
	s_nop 0
	v_mul_f32_e32 v88, 0x3f1b4598, v88
	v_mul_f32_e32 v89, 0x3f1b4598, v89
	v_mul_f32_e32 v90, 0x3f1b4598, v90
	v_mul_f32_e32 v91, 0x3f1b4598, v91
	v_cvt_pk_bf16_f32 v140, v88, v89
	v_cvt_pk_bf16_f32 v141, v90, v91
	ds_write_b64 v236, v[140:141] offset:11584
	v_add_f32_e32 v92, v92, v204
	v_add_f32_e32 v93, v93, v205
	v_add_f32_e32 v94, v94, v206
	v_add_f32_e32 v95, v95, v207
	v_mul_f32_e32 v92, 0xbfb8aa3b, v92
	v_mul_f32_e32 v93, 0xbfb8aa3b, v93
	v_mul_f32_e32 v94, 0xbfb8aa3b, v94
	v_mul_f32_e32 v95, 0xbfb8aa3b, v95
	v_exp_f32_e32 v92, v92
	v_exp_f32_e32 v93, v93
	v_exp_f32_e32 v94, v94
	v_exp_f32_e32 v95, v95
	s_nop 0
	v_add_f32_e32 v92, 1.0, v92
	v_add_f32_e32 v93, 1.0, v93
	v_add_f32_e32 v94, 1.0, v94
	v_add_f32_e32 v95, 1.0, v95
	v_rcp_f32_e32 v92, v92
	v_rcp_f32_e32 v93, v93
	v_rcp_f32_e32 v94, v94
	v_rcp_f32_e32 v95, v95
	s_nop 0
	v_mul_f32_e32 v92, 0x3f1b4598, v92
	v_mul_f32_e32 v93, 0x3f1b4598, v93
	v_mul_f32_e32 v94, 0x3f1b4598, v94
	v_mul_f32_e32 v95, 0x3f1b4598, v95
	v_cvt_pk_bf16_f32 v142, v92, v93
	v_cvt_pk_bf16_f32 v143, v94, v95
	ds_write_b64 v236, v[142:143] offset:11616
	v_add_f32_e32 v96, v96, v192
	v_add_f32_e32 v97, v97, v193
	v_add_f32_e32 v98, v98, v194
	v_add_f32_e32 v99, v99, v195
	v_mul_f32_e32 v96, 0xbfb8aa3b, v96
	v_mul_f32_e32 v97, 0xbfb8aa3b, v97
	v_mul_f32_e32 v98, 0xbfb8aa3b, v98
	v_mul_f32_e32 v99, 0xbfb8aa3b, v99
	v_exp_f32_e32 v96, v96
	v_exp_f32_e32 v97, v97
	v_exp_f32_e32 v98, v98
	v_exp_f32_e32 v99, v99
	s_nop 0
	v_add_f32_e32 v96, 1.0, v96
	v_add_f32_e32 v97, 1.0, v97
	v_add_f32_e32 v98, 1.0, v98
	v_add_f32_e32 v99, 1.0, v99
	v_rcp_f32_e32 v96, v96
	v_rcp_f32_e32 v97, v97
	v_rcp_f32_e32 v98, v98
	v_rcp_f32_e32 v99, v99
	s_nop 0
	v_mul_f32_e32 v96, 0x3f1b4598, v96
	v_mul_f32_e32 v97, 0x3f1b4598, v97
	v_mul_f32_e32 v98, 0x3f1b4598, v98
	v_mul_f32_e32 v99, 0x3f1b4598, v99
	v_cvt_pk_bf16_f32 v144, v96, v97
	v_cvt_pk_bf16_f32 v145, v98, v99
	ds_write_b64 v236, v[144:145] offset:13824
	v_add_f32_e32 v100, v100, v196
	v_add_f32_e32 v101, v101, v197
	v_add_f32_e32 v102, v102, v198
	v_add_f32_e32 v103, v103, v199
	v_mul_f32_e32 v100, 0xbfb8aa3b, v100
	v_mul_f32_e32 v101, 0xbfb8aa3b, v101
	v_mul_f32_e32 v102, 0xbfb8aa3b, v102
	v_mul_f32_e32 v103, 0xbfb8aa3b, v103
	v_exp_f32_e32 v100, v100
	v_exp_f32_e32 v101, v101
	v_exp_f32_e32 v102, v102
	v_exp_f32_e32 v103, v103
	s_nop 0
	v_add_f32_e32 v100, 1.0, v100
	v_add_f32_e32 v101, 1.0, v101
	v_add_f32_e32 v102, 1.0, v102
	v_add_f32_e32 v103, 1.0, v103
	v_rcp_f32_e32 v100, v100
	v_rcp_f32_e32 v101, v101
	v_rcp_f32_e32 v102, v102
	v_rcp_f32_e32 v103, v103
	s_nop 0
	v_mul_f32_e32 v100, 0x3f1b4598, v100
	v_mul_f32_e32 v101, 0x3f1b4598, v101
	v_mul_f32_e32 v102, 0x3f1b4598, v102
	v_mul_f32_e32 v103, 0x3f1b4598, v103
	v_cvt_pk_bf16_f32 v146, v100, v101
	v_cvt_pk_bf16_f32 v147, v102, v103
	ds_write_b64 v236, v[146:147] offset:13856
	v_add_f32_e32 v104, v104, v200
	v_add_f32_e32 v105, v105, v201
	v_add_f32_e32 v106, v106, v202
	v_add_f32_e32 v107, v107, v203
	v_mul_f32_e32 v104, 0xbfb8aa3b, v104
	v_mul_f32_e32 v105, 0xbfb8aa3b, v105
	v_mul_f32_e32 v106, 0xbfb8aa3b, v106
	v_mul_f32_e32 v107, 0xbfb8aa3b, v107
	v_exp_f32_e32 v104, v104
	v_exp_f32_e32 v105, v105
	v_exp_f32_e32 v106, v106
	v_exp_f32_e32 v107, v107
	s_nop 0
	v_add_f32_e32 v104, 1.0, v104
	v_add_f32_e32 v105, 1.0, v105
	v_add_f32_e32 v106, 1.0, v106
	v_add_f32_e32 v107, 1.0, v107
	v_rcp_f32_e32 v104, v104
	v_rcp_f32_e32 v105, v105
	v_rcp_f32_e32 v106, v106
	v_rcp_f32_e32 v107, v107
	s_nop 0
	v_mul_f32_e32 v104, 0x3f1b4598, v104
	v_mul_f32_e32 v105, 0x3f1b4598, v105
	v_mul_f32_e32 v106, 0x3f1b4598, v106
	v_mul_f32_e32 v107, 0x3f1b4598, v107
	v_cvt_pk_bf16_f32 v148, v104, v105
	v_cvt_pk_bf16_f32 v149, v106, v107
	ds_write_b64 v236, v[148:149] offset:13888
	v_add_f32_e32 v108, v108, v204
	v_add_f32_e32 v109, v109, v205
	v_add_f32_e32 v110, v110, v206
	v_add_f32_e32 v111, v111, v207
	v_mul_f32_e32 v108, 0xbfb8aa3b, v108
	v_mul_f32_e32 v109, 0xbfb8aa3b, v109
	v_mul_f32_e32 v110, 0xbfb8aa3b, v110
	v_mul_f32_e32 v111, 0xbfb8aa3b, v111
	v_exp_f32_e32 v108, v108
	v_exp_f32_e32 v109, v109
	v_exp_f32_e32 v110, v110
	v_exp_f32_e32 v111, v111
	s_nop 0
	v_add_f32_e32 v108, 1.0, v108
	v_add_f32_e32 v109, 1.0, v109
	v_add_f32_e32 v110, 1.0, v110
	v_add_f32_e32 v111, 1.0, v111
	v_rcp_f32_e32 v108, v108
	v_rcp_f32_e32 v109, v109
	v_rcp_f32_e32 v110, v110
	v_rcp_f32_e32 v111, v111
	s_nop 0
	v_mul_f32_e32 v108, 0x3f1b4598, v108
	v_mul_f32_e32 v109, 0x3f1b4598, v109
	v_mul_f32_e32 v110, 0x3f1b4598, v110
	v_mul_f32_e32 v111, 0x3f1b4598, v111
	v_cvt_pk_bf16_f32 v150, v108, v109
	v_cvt_pk_bf16_f32 v151, v110, v111
	ds_write_b64 v236, v[150:151] offset:13920
	v_add_f32_e32 v112, v112, v192
	v_add_f32_e32 v113, v113, v193
	v_add_f32_e32 v114, v114, v194
	v_add_f32_e32 v115, v115, v195
	v_mul_f32_e32 v112, 0xbfb8aa3b, v112
	v_mul_f32_e32 v113, 0xbfb8aa3b, v113
	v_mul_f32_e32 v114, 0xbfb8aa3b, v114
	v_mul_f32_e32 v115, 0xbfb8aa3b, v115
	v_exp_f32_e32 v112, v112
	v_exp_f32_e32 v113, v113
	v_exp_f32_e32 v114, v114
	v_exp_f32_e32 v115, v115
	s_nop 0
	v_add_f32_e32 v112, 1.0, v112
	v_add_f32_e32 v113, 1.0, v113
	v_add_f32_e32 v114, 1.0, v114
	v_add_f32_e32 v115, 1.0, v115
	v_rcp_f32_e32 v112, v112
	v_rcp_f32_e32 v113, v113
	v_rcp_f32_e32 v114, v114
	v_rcp_f32_e32 v115, v115
	s_nop 0
	v_mul_f32_e32 v112, 0x3f1b4598, v112
	v_mul_f32_e32 v113, 0x3f1b4598, v113
	v_mul_f32_e32 v114, 0x3f1b4598, v114
	v_mul_f32_e32 v115, 0x3f1b4598, v115
	v_cvt_pk_bf16_f32 v152, v112, v113
	v_cvt_pk_bf16_f32 v153, v114, v115
	ds_write_b64 v236, v[152:153] offset:16128
	v_add_f32_e32 v116, v116, v196
	v_add_f32_e32 v117, v117, v197
	v_add_f32_e32 v118, v118, v198
	v_add_f32_e32 v119, v119, v199
	v_mul_f32_e32 v116, 0xbfb8aa3b, v116
	v_mul_f32_e32 v117, 0xbfb8aa3b, v117
	v_mul_f32_e32 v118, 0xbfb8aa3b, v118
	v_mul_f32_e32 v119, 0xbfb8aa3b, v119
	v_exp_f32_e32 v116, v116
	v_exp_f32_e32 v117, v117
	v_exp_f32_e32 v118, v118
	v_exp_f32_e32 v119, v119
	s_nop 0
	v_add_f32_e32 v116, 1.0, v116
	v_add_f32_e32 v117, 1.0, v117
	v_add_f32_e32 v118, 1.0, v118
	v_add_f32_e32 v119, 1.0, v119
	v_rcp_f32_e32 v116, v116
	v_rcp_f32_e32 v117, v117
	v_rcp_f32_e32 v118, v118
	v_rcp_f32_e32 v119, v119
	s_nop 0
	v_mul_f32_e32 v116, 0x3f1b4598, v116
	v_mul_f32_e32 v117, 0x3f1b4598, v117
	v_mul_f32_e32 v118, 0x3f1b4598, v118
	v_mul_f32_e32 v119, 0x3f1b4598, v119
	v_cvt_pk_bf16_f32 v154, v116, v117
	v_cvt_pk_bf16_f32 v155, v118, v119
	ds_write_b64 v236, v[154:155] offset:16160
	v_add_f32_e32 v120, v120, v200
	v_add_f32_e32 v121, v121, v201
	v_add_f32_e32 v122, v122, v202
	v_add_f32_e32 v123, v123, v203
	v_mul_f32_e32 v120, 0xbfb8aa3b, v120
	v_mul_f32_e32 v121, 0xbfb8aa3b, v121
	v_mul_f32_e32 v122, 0xbfb8aa3b, v122
	v_mul_f32_e32 v123, 0xbfb8aa3b, v123
	v_exp_f32_e32 v120, v120
	v_exp_f32_e32 v121, v121
	v_exp_f32_e32 v122, v122
	v_exp_f32_e32 v123, v123
	s_nop 0
	v_add_f32_e32 v120, 1.0, v120
	v_add_f32_e32 v121, 1.0, v121
	v_add_f32_e32 v122, 1.0, v122
	v_add_f32_e32 v123, 1.0, v123
	v_rcp_f32_e32 v120, v120
	v_rcp_f32_e32 v121, v121
	v_rcp_f32_e32 v122, v122
	v_rcp_f32_e32 v123, v123
	s_nop 0
	v_mul_f32_e32 v120, 0x3f1b4598, v120
	v_mul_f32_e32 v121, 0x3f1b4598, v121
	v_mul_f32_e32 v122, 0x3f1b4598, v122
	v_mul_f32_e32 v123, 0x3f1b4598, v123
	v_cvt_pk_bf16_f32 v156, v120, v121
	v_cvt_pk_bf16_f32 v157, v122, v123
	ds_write_b64 v236, v[156:157] offset:16192
	v_add_f32_e32 v124, v124, v204
	v_add_f32_e32 v125, v125, v205
	v_add_f32_e32 v126, v126, v206
	v_add_f32_e32 v127, v127, v207
	v_mul_f32_e32 v124, 0xbfb8aa3b, v124
	v_mul_f32_e32 v125, 0xbfb8aa3b, v125
	v_mul_f32_e32 v126, 0xbfb8aa3b, v126
	v_mul_f32_e32 v127, 0xbfb8aa3b, v127
	v_exp_f32_e32 v124, v124
	v_exp_f32_e32 v125, v125
	v_exp_f32_e32 v126, v126
	v_exp_f32_e32 v127, v127
	s_nop 0
	v_add_f32_e32 v124, 1.0, v124
	v_add_f32_e32 v125, 1.0, v125
	v_add_f32_e32 v126, 1.0, v126
	v_add_f32_e32 v127, 1.0, v127
	v_rcp_f32_e32 v124, v124
	v_rcp_f32_e32 v125, v125
	v_rcp_f32_e32 v126, v126
	v_rcp_f32_e32 v127, v127
	s_nop 0
	v_mul_f32_e32 v124, 0x3f1b4598, v124
	v_mul_f32_e32 v125, 0x3f1b4598, v125
	v_mul_f32_e32 v126, 0x3f1b4598, v126
	v_mul_f32_e32 v127, 0x3f1b4598, v127
	v_cvt_pk_bf16_f32 v158, v124, v125
	v_cvt_pk_bf16_f32 v159, v126, v127
	ds_write_b64 v236, v[158:159] offset:16224
	s_waitcnt lgkmcnt(0)
; DI void st_bf16x4(bf16_t* o, f32x4 v) { u32x2 q; q.x = pack2(v[0], v[1]); q.y = pack2(v[2], v[3]); *(u32x2*)o = q; }
; template <class Epi>
; DI void gemm_tile(char* smem, const bf16_t* __restrict__ A0, int lda0, int ksplit, const bf16_t* __restrict__ A1, int lda1,
;                   const bf16_t* __restrict__ Bt, int K, int row0, int col0, const Epi& epi, int tid) {
;   constexpr int BK = 32, PITCH = 40, BUF = (256 + 128) * PITCH;
;   bf16_t* sbase = (bf16_t*)smem;
;   const int lane = tid & 63, wid = tid >> 6, wr = wid >> 1, wc = wid & 1, fr = lane & 15, fq = lane >> 4;
;   f32x4 acc[8][4];
; #pragma unroll
;   for (int m = 0; m < 8; ++m)
; #pragma unroll
;     for (int n = 0; n < 4; ++n) acc[m][n] = (f32x4){0.f, 0.f, 0.f, 0.f};
;   u32x4 ra[2][4], rb[2][2];
;   const int nk = K / BK;
;   const int sr = tid >> 2, scv = tid & 3;
;   DI void operator()(int row, int col, f32x4 v) const {
;     if (col < n0) st_bf16x4(o0 + (size_t)row * ld0 + col, v);
;     else { const int c = col - n0; if (c < n1) st_bf16x4(o1 + (size_t)row * ld1 + c, v); }
;   }
	ds_read_b128 v[128:131], v237
	ds_read_b128 v[132:135], v237 offset:1152
	ds_read_b128 v[136:139], v237 offset:2304
	ds_read_b128 v[140:143], v237 offset:3456
	ds_read_b128 v[144:147], v237 offset:4608
	ds_read_b128 v[148:151], v237 offset:5760
	ds_read_b128 v[152:155], v237 offset:6912
	ds_read_b128 v[156:159], v237 offset:8064
	ds_read_b128 v[160:163], v237 offset:9216
	ds_read_b128 v[164:167], v237 offset:10368
	ds_read_b128 v[168:171], v237 offset:11520
	ds_read_b128 v[172:175], v237 offset:12672
	ds_read_b128 v[176:179], v237 offset:13824
	ds_read_b128 v[180:183], v237 offset:14976
	ds_read_b128 v[184:187], v237 offset:16128
	ds_read_b128 v[188:191], v237 offset:17280
	s_waitcnt lgkmcnt(15)
	global_store_dwordx4 v238, v[128:131], s[4:5] nt
	s_add_u32 s4, s4, 0x2000
	s_addc_u32 s5, s5, 0
	s_waitcnt lgkmcnt(14)
	global_store_dwordx4 v238, v[132:135], s[4:5] nt
	s_add_u32 s4, s4, 0x2000
	s_addc_u32 s5, s5, 0
	s_waitcnt lgkmcnt(13)
	global_store_dwordx4 v238, v[136:139], s[4:5] nt
	s_add_u32 s4, s4, 0x2000
	s_addc_u32 s5, s5, 0
	s_waitcnt lgkmcnt(12)
	global_store_dwordx4 v238, v[140:143], s[4:5] nt
	s_add_u32 s4, s4, 0x2000
	s_addc_u32 s5, s5, 0
	s_waitcnt lgkmcnt(11)
	global_store_dwordx4 v238, v[144:147], s[4:5] nt
	s_add_u32 s4, s4, 0x2000
	s_addc_u32 s5, s5, 0
	s_waitcnt lgkmcnt(10)
	global_store_dwordx4 v238, v[148:151], s[4:5] nt
	s_add_u32 s4, s4, 0x2000
	s_addc_u32 s5, s5, 0
	s_waitcnt lgkmcnt(9)
	global_store_dwordx4 v238, v[152:155], s[4:5] nt
	s_add_u32 s4, s4, 0x2000
	s_addc_u32 s5, s5, 0
	s_waitcnt lgkmcnt(8)
	global_store_dwordx4 v238, v[156:159], s[4:5] nt
	s_add_u32 s4, s4, 0x2000
	s_addc_u32 s5, s5, 0
	s_waitcnt lgkmcnt(7)
	global_store_dwordx4 v238, v[160:163], s[4:5] nt
	s_add_u32 s4, s4, 0x2000
	s_addc_u32 s5, s5, 0
	s_waitcnt lgkmcnt(6)
	global_store_dwordx4 v238, v[164:167], s[4:5] nt
	s_add_u32 s4, s4, 0x2000
	s_addc_u32 s5, s5, 0
	s_waitcnt lgkmcnt(5)
	global_store_dwordx4 v238, v[168:171], s[4:5] nt
	s_add_u32 s4, s4, 0x2000
	s_addc_u32 s5, s5, 0
	s_waitcnt lgkmcnt(4)
	global_store_dwordx4 v238, v[172:175], s[4:5] nt
	s_add_u32 s4, s4, 0x2000
	s_addc_u32 s5, s5, 0
	s_waitcnt lgkmcnt(3)
	global_store_dwordx4 v238, v[176:179], s[4:5] nt
	s_add_u32 s4, s4, 0x2000
	s_addc_u32 s5, s5, 0
	s_waitcnt lgkmcnt(2)
	global_store_dwordx4 v238, v[180:183], s[4:5] nt
	s_add_u32 s4, s4, 0x2000
	s_addc_u32 s5, s5, 0
	s_waitcnt lgkmcnt(1)
	global_store_dwordx4 v238, v[184:187], s[4:5] nt
	s_add_u32 s4, s4, 0x2000
	s_addc_u32 s5, s5, 0
	s_waitcnt lgkmcnt(0)
	global_store_dwordx4 v238, v[188:191], s[4:5] nt
	s_nop 1
	s_add_u32 s15, s15, 64
	s_branch .Lg3b_tile
.Lg3b_done:
	s_setprio 0
	v_mbcnt_lo_u32_b32 v194, -1, 0
	v_mbcnt_hi_u32_b32 v136, -1, v194
	v_mbcnt_lo_u32_b32 v240, -1, 0
	v_mbcnt_hi_u32_b32 v240, -1, v240
	s_lshr_b32 s27, s72, 6
	s_lshl_b32 s100, s27, 10
	v_and_b32_e32 v241, 15, v240
	v_lshrrev_b32_e32 v242, 4, v240
	v_bfe_u32 v243, v240, 3, 1
	v_mul_u32_u24_e32 v243, 3, v243
	v_xor_b32_e32 v243, v242, v243
	v_lshlrev_b32_e32 v243, 4, v243
	v_lshl_add_u32 v243, v241, 6, v243
	s_lshr_b32 s26, s27, 1
	s_lshl_b32 s26, s26, 13
	v_add_u32_e32 v230, s26, v243
	s_and_b32 s26, s27, 1
	s_lshl_b32 s26, s26, 12
	s_add_u32 s26, s26, 16384
	v_add_u32_e32 v231, s26, v243
	s_lshr_b32 s26, s27, 1
	s_lshl_b32 s26, s26, 7
	v_add_u32_e32 v244, s26, v241
	s_and_b32 s26, s27, 1
	s_lshl_b32 s26, s26, 6
	v_lshl_add_u32 v245, v242, 2, s26
	v_lshlrev_b32_e32 v235, 2, v245
	s_mul_i32 s26, s27, 18432
	v_mul_u32_u24_e32 v246, 144, v241
	v_lshl_add_u32 v246, v242, 3, v246
	v_add_u32_e32 v236, s26, v246
	v_lshrrev_b32_e32 v246, 3, v240
	v_mul_u32_u24_e32 v246, 144, v246
	v_and_b32_e32 v247, 7, v240
	v_lshl_add_u32 v246, v247, 4, v246
	v_add_u32_e32 v237, s26, v246
	s_lshr_b32 s26, s27, 1
	s_lshl_b32 s26, s26, 7
	v_lshrrev_b32_e32 v246, 3, v240
	v_add_u32_e32 v246, s26, v246
	s_and_b32 s26, s27, 1
	s_lshl_b32 s26, s26, 6
	v_lshl_add_u32 v248, v247, 3, s26
	s_movk_i32 s26, 1024
	v_mul_lo_u32 v247, v246, s26
	v_lshl_add_u32 v238, v248, 1, v247
	v_lshrrev_b32_e32 v241, 2, v240
	s_lshl_b32 s26, s27, 4
	v_add_u32_e32 v241, s26, v241
	v_bfe_u32 v242, v240, 5, 1
	v_mul_u32_u24_e32 v242, 3, v242
	v_and_b32_e32 v243, 3, v240
	v_xor_b32_e32 v243, v243, v242
	v_lshlrev_b32_e32 v243, 4, v243
	s_mov_b32 s26, 512
	v_mad_u32_u24 v224, v241, s26, v243
	v_add_u32_e32 v225, 0x8000, v224
	v_add_u32_e32 v226, 0x10000, v224
	v_add_u32_e32 v227, 0x18000, v224
	s_mov_b32 s26, 128
	v_mad_u32_u24 v228, v241, s26, v243
	v_add_u32_e32 v229, 0x2000, v228
	s_load_dwordx2 s[6:7], s[74:75], 0x58
	s_cmpk_gt_u32 s96, 0xff
	s_cselect_b32 s25, 1, 0
	s_cmpk_gt_u32 s96, 0xff
	s_cbranch_scc0 .Lg3c_prio
	s_setprio 1

; #define LWRITE(S, buf) do { bf16_t* sA_ = sbase + (buf) * BUF; bf16_t* sB_ = sA_ + 256 * PITCH; \
;     _Pragma("unroll") for (int i_ = 0; i_ < 4; ++i_) *(u32x4*)(sA_ + (sr + i_ * 64) * PITCH + scv * 8) = ra[S][i_]; \
;     _Pragma("unroll") for (int i_ = 0; i_ < 2; ++i_) *(u32x4*)(sB_ + (sr + i_ * 64) * PITCH + scv * 8) = rb[S][i_]; } while (0)
; template <class Epi>
; DI void gemm_tile(char* smem, const bf16_t* __restrict__ A0, int lda0, int ksplit, const bf16_t* __restrict__ A1, int lda1,
;                   const bf16_t* __restrict__ Bt, int K, int row0, int col0, const Epi& epi, int tid) {
;     ...
;   f32x4 acc[8][4];
; #pragma unroll
;   for (int m = 0; m < 8; ++m)
; #pragma unroll
;     for (int n = 0; n < 4; ++n) acc[m][n] = (f32x4){0.f, 0.f, 0.f, 0.f};
;   u32x4 ra[2][4], rb[2][2];
;   const int nk = K / BK;
;   const int sr = tid >> 2, scv = tid & 3;
;     ...
;   __syncthreads();
;   {
;     const int last = nk - 1;
;     GLOAD(0, 0);
;     __builtin_amdgcn_sched_barrier(0);
;     GLOAD(1, 1);
;     __builtin_amdgcn_sched_barrier(0);
;     LWRITE(0, 0);
;     __builtin_amdgcn_sched_barrier(0);
;     GLOAD(0, (2 < last ? 2 : last));
;     __builtin_amdgcn_sched_barrier(0);
;     __syncthreads();
; template <class Epi>
; DI void gemm_phase(char* smem, const bf16_t* A0, int lda0, int ksplit, const bf16_t* A1, int lda1, const bf16_t* Bt, int K, int nN, const Epi& epi, int tid) {
;     ...
;     const int x = blockIdx.x & 7, l = blockIdx.x >> 3, L = G >> 3, per = 8 * nN, tot = 2 * per;
;     for (int q = l; q < tot; q += L) { const int rgl = q / per, rem = q % per, ct = rem >> 3, rt = (x * 2 + rgl) * 8 + (rem & 7);
;       gemm_tile(smem, A0, lda0, ksplit, A1, lda1, Bt, K, rt * 256, ct * 128, epi, tid); }
.Lg3c_tile:
	s_cmpk_ge_u32 s15, 64
	s_cbranch_scc1 .Lg3c_done
	s_cmpk_ge_u32 s15, 32
	s_cselect_b32 s27, 1, 0
	s_cselect_b32 s26, 32, 0
	s_sub_u32 s26, s15, s26
	s_add_u32 s27, s27, s101
	s_lshl_b32 s27, s27, 3
	s_and_b32 s29, s26, 7
	s_add_u32 s29, s29, s27
	s_lshl_b32 s29, s29, 8
	s_lshr_b32 s28, s26, 3
	s_lshl_b32 s28, s28, 7
	s_mul_i32 s27, s29, 512
	s_add_u32 s27, s27, 0x1ea00080
	s_add_u32 s0, s92, s27
	s_addc_u32 s1, s93, 0
	s_mul_i32 s27, s28, 128
	s_add_u32 s27, s27, 0x34c0000
	s_add_u32 s2, s92, s27
	s_addc_u32 s3, s93, 0
	s_waitcnt lgkmcnt(0)
	s_barrier
	s_mov_b32 s99, 0
	s_mov_b32 s30, 0
	s_add_u32 s26, s30, s100
	s_add_u32 m0, s26, 0
	s_nop 0
	global_load_lds_dwordx4 v224, s[0:1]
	s_add_u32 m0, s26, 4096
	s_nop 0
	global_load_lds_dwordx4 v225, s[0:1]
	s_add_u32 m0, s26, 8192
	s_nop 0
	global_load_lds_dwordx4 v226, s[0:1]
	s_add_u32 m0, s26, 12288
	s_nop 0
	global_load_lds_dwordx4 v227, s[0:1]
	s_add_u32 m0, s26, 16384
	s_nop 0
	global_load_lds_dwordx4 v228, s[2:3]
	s_add_u32 m0, s26, 20480
	s_nop 0
	global_load_lds_dwordx4 v229, s[2:3]
	s_add_u32 s0, s0, 64
	s_addc_u32 s1, s1, 0
	s_add_u32 s2, s2, 64
	s_addc_u32 s3, s3, 0
	s_add_u32 s99, s99, 1
	s_add_u32 s30, s30, 24576
	s_cmp_eq_u32 s30, 73728
	s_cselect_b32 s30, 0, s30
	s_add_u32 s26, s30, s100
	s_add_u32 m0, s26, 0
	s_nop 0
	global_load_lds_dwordx4 v224, s[0:1]
	s_add_u32 m0, s26, 4096
	s_nop 0
	global_load_lds_dwordx4 v225, s[0:1]
	s_add_u32 m0, s26, 8192
	s_nop 0
	global_load_lds_dwordx4 v226, s[0:1]
	s_add_u32 m0, s26, 12288
	s_nop 0
	global_load_lds_dwordx4 v227, s[0:1]
	s_add_u32 m0, s26, 16384
	s_nop 0
	global_load_lds_dwordx4 v228, s[2:3]
	s_add_u32 m0, s26, 20480
	s_nop 0
	global_load_lds_dwordx4 v229, s[2:3]
	s_add_u32 s0, s0, 64
	s_addc_u32 s1, s1, 0
	s_add_u32 s2, s2, 64
	s_addc_u32 s3, s3, 0
	s_add_u32 s99, s99, 1
	s_add_u32 s30, s30, 24576
	s_cmp_eq_u32 s30, 73728
	s_cselect_b32 s30, 0, s30
	v_mov_b32_e32 v0, 0
	v_mov_b32_e32 v1, 0
	v_mov_b32_e32 v2, 0
	v_mov_b32_e32 v3, 0
	v_mov_b32_e32 v4, 0
	v_mov_b32_e32 v5, 0
	v_mov_b32_e32 v6, 0
	v_mov_b32_e32 v7, 0
	v_mov_b32_e32 v8, 0
	v_mov_b32_e32 v9, 0
	v_mov_b32_e32 v10, 0
	v_mov_b32_e32 v11, 0
	v_mov_b32_e32 v12, 0
	v_mov_b32_e32 v13, 0
	v_mov_b32_e32 v14, 0
	v_mov_b32_e32 v15, 0
	v_mov_b32_e32 v16, 0
	v_mov_b32_e32 v17, 0
	v_mov_b32_e32 v18, 0
	v_mov_b32_e32 v19, 0
	v_mov_b32_e32 v20, 0
	v_mov_b32_e32 v21, 0
	v_mov_b32_e32 v22, 0
	v_mov_b32_e32 v23, 0
	v_mov_b32_e32 v24, 0
	v_mov_b32_e32 v25, 0
	v_mov_b32_e32 v26, 0
	v_mov_b32_e32 v27, 0
	v_mov_b32_e32 v28, 0
	v_mov_b32_e32 v29, 0
	v_mov_b32_e32 v30, 0
	v_mov_b32_e32 v31, 0
	v_mov_b32_e32 v32, 0
	v_mov_b32_e32 v33, 0
	v_mov_b32_e32 v34, 0
	v_mov_b32_e32 v35, 0
	v_mov_b32_e32 v36, 0
	v_mov_b32_e32 v37, 0
	v_mov_b32_e32 v38, 0
	v_mov_b32_e32 v39, 0
	v_mov_b32_e32 v40, 0
	v_mov_b32_e32 v41, 0
	v_mov_b32_e32 v42, 0
	v_mov_b32_e32 v43, 0
	v_mov_b32_e32 v44, 0
	v_mov_b32_e32 v45, 0
	v_mov_b32_e32 v46, 0
	v_mov_b32_e32 v47, 0
	v_mov_b32_e32 v48, 0
	v_mov_b32_e32 v49, 0
	v_mov_b32_e32 v50, 0
	v_mov_b32_e32 v51, 0
	v_mov_b32_e32 v52, 0
	v_mov_b32_e32 v53, 0
	v_mov_b32_e32 v54, 0
	v_mov_b32_e32 v55, 0
	v_mov_b32_e32 v56, 0
	v_mov_b32_e32 v57, 0
	v_mov_b32_e32 v58, 0
	v_mov_b32_e32 v59, 0
	v_mov_b32_e32 v60, 0
	v_mov_b32_e32 v61, 0
	v_mov_b32_e32 v62, 0
	v_mov_b32_e32 v63, 0
	v_mov_b32_e32 v64, 0
	v_mov_b32_e32 v65, 0
	v_mov_b32_e32 v66, 0
	v_mov_b32_e32 v67, 0
	v_mov_b32_e32 v68, 0
	v_mov_b32_e32 v69, 0
	v_mov_b32_e32 v70, 0
	v_mov_b32_e32 v71, 0
	v_mov_b32_e32 v72, 0
	v_mov_b32_e32 v73, 0
	v_mov_b32_e32 v74, 0
	v_mov_b32_e32 v75, 0
	v_mov_b32_e32 v76, 0
	v_mov_b32_e32 v77, 0
	v_mov_b32_e32 v78, 0
	v_mov_b32_e32 v79, 0
	v_mov_b32_e32 v80, 0
	v_mov_b32_e32 v81, 0
	v_mov_b32_e32 v82, 0
	v_mov_b32_e32 v83, 0
	v_mov_b32_e32 v84, 0
	v_mov_b32_e32 v85, 0
	v_mov_b32_e32 v86, 0
	v_mov_b32_e32 v87, 0
	v_mov_b32_e32 v88, 0
	v_mov_b32_e32 v89, 0
	v_mov_b32_e32 v90, 0
	v_mov_b32_e32 v91, 0
	v_mov_b32_e32 v92, 0
	v_mov_b32_e32 v93, 0
	v_mov_b32_e32 v94, 0
	v_mov_b32_e32 v95, 0
	v_mov_b32_e32 v96, 0
	v_mov_b32_e32 v97, 0
	v_mov_b32_e32 v98, 0
	v_mov_b32_e32 v99, 0
	v_mov_b32_e32 v100, 0
	v_mov_b32_e32 v101, 0
	v_mov_b32_e32 v102, 0
	v_mov_b32_e32 v103, 0
	v_mov_b32_e32 v104, 0
	v_mov_b32_e32 v105, 0
	v_mov_b32_e32 v106, 0
	v_mov_b32_e32 v107, 0
	v_mov_b32_e32 v108, 0
	v_mov_b32_e32 v109, 0
	v_mov_b32_e32 v110, 0
	v_mov_b32_e32 v111, 0
	v_mov_b32_e32 v112, 0
	v_mov_b32_e32 v113, 0
	v_mov_b32_e32 v114, 0
	v_mov_b32_e32 v115, 0
	v_mov_b32_e32 v116, 0
	v_mov_b32_e32 v117, 0
	v_mov_b32_e32 v118, 0
	v_mov_b32_e32 v119, 0
	v_mov_b32_e32 v120, 0
	v_mov_b32_e32 v121, 0
	v_mov_b32_e32 v122, 0
	v_mov_b32_e32 v123, 0
	v_mov_b32_e32 v124, 0
	v_mov_b32_e32 v125, 0
	v_mov_b32_e32 v126, 0
	v_mov_b32_e32 v127, 0
	s_mov_b32 s98, 0
	s_mov_b32 s31, 24576
	s_waitcnt vmcnt(6)
	s_barrier
	ds_read_b128 v[128:131], v231 offset:0
	ds_read_b128 v[132:135], v231 offset:1024
	ds_read_b128 v[136:139], v231 offset:2048
	ds_read_b128 v[140:143], v231 offset:3072
	ds_read_b128 v[144:147], v230 offset:0
	ds_read_b128 v[148:151], v230 offset:1024
	ds_read_b128 v[152:155], v230 offset:2048
	ds_read_b128 v[156:159], v230 offset:3072
	ds_read_b128 v[160:163], v230 offset:4096
	ds_read_b128 v[164:167], v230 offset:5120
	ds_read_b128 v[168:171], v230 offset:6144
	ds_read_b128 v[172:175], v230 offset:7168
	s_waitcnt vmcnt(0)
	s_waitcnt lgkmcnt(0)
	s_barrier
	v_add_u32_e32 v232, s31, v230
	v_add_u32_e32 v233, s31, v231
	s_setprio 1
	v_mfma_f32_16x16x32_bf16 v[0:3], v[128:131], v[144:147], v[0:3]
	v_mfma_f32_16x16x32_bf16 v[4:7], v[132:135], v[144:147], v[4:7]
	v_mfma_f32_16x16x32_bf16 v[8:11], v[136:139], v[144:147], v[8:11]
	v_mfma_f32_16x16x32_bf16 v[12:15], v[140:143], v[144:147], v[12:15]
	ds_read_b128 v[176:179], v233 offset:0
	ds_read_b128 v[180:183], v233 offset:1024
	v_mfma_f32_16x16x32_bf16 v[16:19], v[128:131], v[148:151], v[16:19]
	v_mfma_f32_16x16x32_bf16 v[20:23], v[132:135], v[148:151], v[20:23]
	v_mfma_f32_16x16x32_bf16 v[24:27], v[136:139], v[148:151], v[24:27]
	v_mfma_f32_16x16x32_bf16 v[28:31], v[140:143], v[148:151], v[28:31]
	ds_read_b128 v[184:187], v233 offset:2048
	ds_read_b128 v[188:191], v233 offset:3072
	v_mfma_f32_16x16x32_bf16 v[32:35], v[128:131], v[152:155], v[32:35]
	v_mfma_f32_16x16x32_bf16 v[36:39], v[132:135], v[152:155], v[36:39]
	v_mfma_f32_16x16x32_bf16 v[40:43], v[136:139], v[152:155], v[40:43]
	v_mfma_f32_16x16x32_bf16 v[44:47], v[140:143], v[152:155], v[44:47]
	ds_read_b128 v[192:195], v232 offset:0
	ds_read_b128 v[196:199], v232 offset:1024
	v_mfma_f32_16x16x32_bf16 v[48:51], v[128:131], v[156:159], v[48:51]
	v_mfma_f32_16x16x32_bf16 v[52:55], v[132:135], v[156:159], v[52:55]
	v_mfma_f32_16x16x32_bf16 v[56:59], v[136:139], v[156:159], v[56:59]
	v_mfma_f32_16x16x32_bf16 v[60:63], v[140:143], v[156:159], v[60:63]
	ds_read_b128 v[200:203], v232 offset:2048
	ds_read_b128 v[204:207], v232 offset:3072
	v_mfma_f32_16x16x32_bf16 v[64:67], v[128:131], v[160:163], v[64:67]
	v_mfma_f32_16x16x32_bf16 v[68:71], v[132:135], v[160:163], v[68:71]
	v_mfma_f32_16x16x32_bf16 v[72:75], v[136:139], v[160:163], v[72:75]
	v_mfma_f32_16x16x32_bf16 v[76:79], v[140:143], v[160:163], v[76:79]
	ds_read_b128 v[208:211], v232 offset:4096
	v_mfma_f32_16x16x32_bf16 v[80:83], v[128:131], v[164:167], v[80:83]
	v_mfma_f32_16x16x32_bf16 v[84:87], v[132:135], v[164:167], v[84:87]
	v_mfma_f32_16x16x32_bf16 v[88:91], v[136:139], v[164:167], v[88:91]
	v_mfma_f32_16x16x32_bf16 v[92:95], v[140:143], v[164:167], v[92:95]
	ds_read_b128 v[212:215], v232 offset:5120
	v_mfma_f32_16x16x32_bf16 v[96:99], v[128:131], v[168:171], v[96:99]
	v_mfma_f32_16x16x32_bf16 v[100:103], v[132:135], v[168:171], v[100:103]
	v_mfma_f32_16x16x32_bf16 v[104:107], v[136:139], v[168:171], v[104:107]
	v_mfma_f32_16x16x32_bf16 v[108:111], v[140:143], v[168:171], v[108:111]
	ds_read_b128 v[216:219], v232 offset:6144
	s_add_u32 s31, s31, 24576
	s_cmp_eq_u32 s31, 73728
	s_cselect_b32 s31, 0, s31
	v_mfma_f32_16x16x32_bf16 v[112:115], v[128:131], v[172:175], v[112:115]
	v_mfma_f32_16x16x32_bf16 v[116:119], v[132:135], v[172:175], v[116:119]
	v_mfma_f32_16x16x32_bf16 v[120:123], v[136:139], v[172:175], v[120:123]
	v_mfma_f32_16x16x32_bf16 v[124:127], v[140:143], v[172:175], v[124:127]
	ds_read_b128 v[220:223], v232 offset:7168
	s_cmp_eq_u32 s25, 0
	s_cbranch_scc0 .Lg3c_hi0
	s_setprio 0

; template <class Epi>
; DI void gemm_tile(char* smem, const bf16_t* __restrict__ A0, int lda0, int ksplit, const bf16_t* __restrict__ A1, int lda1,
;                   const bf16_t* __restrict__ Bt, int K, int row0, int col0, const Epi& epi, int tid) {
;     ...
;     for (int n = 0; n < 4; ++n) epi(row0 + wr * 128 + m * 16 + fr, col0 + wc * 64 + n * 16 + fq * 4, acc[m][n]);
.Lg3c_hi1:
	s_branch .Lg3c_epi
.Lg3c_epi:
	s_nop 7
	s_nop 7
	s_mul_i32 s27, s29, 1024
	s_lshl_b32 s26, s28, 1
	s_add_u32 s27, s27, s26
	s_add_u32 s27, s27, 0xb800000
	s_add_u32 s4, s92, s27
	s_addc_u32 s5, s93, 0
	s_lshl_b32 s27, s28, 2
	s_add_u32 s27, s27, 0x0
	s_add_u32 s2, s6, s27
	s_addc_u32 s3, s7, 0
	global_load_dwordx4 v[192:195], v235, s[2:3] offset:0
	global_load_dwordx4 v[196:199], v235, s[2:3] offset:64
	global_load_dwordx4 v[200:203], v235, s[2:3] offset:128
	global_load_dwordx4 v[204:207], v235, s[2:3] offset:192
	s_waitcnt vmcnt(0)
	v_add_f32_e32 v0, v0, v192
	v_add_f32_e32 v1, v1, v193
	v_add_f32_e32 v2, v2, v194
	v_add_f32_e32 v3, v3, v195
	v_mul_f32_e32 v0, 0xbfb8aa3b, v0
	v_mul_f32_e32 v1, 0xbfb8aa3b, v1
	v_mul_f32_e32 v2, 0xbfb8aa3b, v2
	v_mul_f32_e32 v3, 0xbfb8aa3b, v3
	v_exp_f32_e32 v0, v0
	v_exp_f32_e32 v1, v1
	v_exp_f32_e32 v2, v2
	v_exp_f32_e32 v3, v3
	s_nop 0
	v_add_f32_e32 v0, 1.0, v0
	v_add_f32_e32 v1, 1.0, v1
	v_add_f32_e32 v2, 1.0, v2
	v_add_f32_e32 v3, 1.0, v3
	v_rcp_f32_e32 v0, v0
	v_rcp_f32_e32 v1, v1
	v_rcp_f32_e32 v2, v2
	v_rcp_f32_e32 v3, v3
	s_nop 0
	v_cvt_pk_bf16_f32 v128, v0, v1
	v_cvt_pk_bf16_f32 v129, v2, v3
	ds_write_b64 v236, v[128:129]
	v_add_f32_e32 v4, v4, v196
	v_add_f32_e32 v5, v5, v197
	v_add_f32_e32 v6, v6, v198
	v_add_f32_e32 v7, v7, v199
	v_mul_f32_e32 v4, 0xbfb8aa3b, v4
	v_mul_f32_e32 v5, 0xbfb8aa3b, v5
	v_mul_f32_e32 v6, 0xbfb8aa3b, v6
	v_mul_f32_e32 v7, 0xbfb8aa3b, v7
	v_exp_f32_e32 v4, v4
	v_exp_f32_e32 v5, v5
	v_exp_f32_e32 v6, v6
	v_exp_f32_e32 v7, v7
	s_nop 0
	v_add_f32_e32 v4, 1.0, v4
	v_add_f32_e32 v5, 1.0, v5
	v_add_f32_e32 v6, 1.0, v6
	v_add_f32_e32 v7, 1.0, v7
	v_rcp_f32_e32 v4, v4
	v_rcp_f32_e32 v5, v5
	v_rcp_f32_e32 v6, v6
	v_rcp_f32_e32 v7, v7
	s_nop 0
	v_cvt_pk_bf16_f32 v130, v4, v5
	v_cvt_pk_bf16_f32 v131, v6, v7
	ds_write_b64 v236, v[130:131] offset:32
	v_add_f32_e32 v8, v8, v200
	v_add_f32_e32 v9, v9, v201
	v_add_f32_e32 v10, v10, v202
	v_add_f32_e32 v11, v11, v203
	v_mul_f32_e32 v8, 0xbfb8aa3b, v8
	v_mul_f32_e32 v9, 0xbfb8aa3b, v9
	v_mul_f32_e32 v10, 0xbfb8aa3b, v10
	v_mul_f32_e32 v11, 0xbfb8aa3b, v11
	v_exp_f32_e32 v8, v8
	v_exp_f32_e32 v9, v9
	v_exp_f32_e32 v10, v10
	v_exp_f32_e32 v11, v11
	s_nop 0
	v_add_f32_e32 v8, 1.0, v8
	v_add_f32_e32 v9, 1.0, v9
	v_add_f32_e32 v10, 1.0, v10
	v_add_f32_e32 v11, 1.0, v11
	v_rcp_f32_e32 v8, v8
	v_rcp_f32_e32 v9, v9
	v_rcp_f32_e32 v10, v10
	v_rcp_f32_e32 v11, v11
	s_nop 0
	v_cvt_pk_bf16_f32 v132, v8, v9
	v_cvt_pk_bf16_f32 v133, v10, v11
	ds_write_b64 v236, v[132:133] offset:64
	v_add_f32_e32 v12, v12, v204
	v_add_f32_e32 v13, v13, v205
	v_add_f32_e32 v14, v14, v206
	v_add_f32_e32 v15, v15, v207
	v_mul_f32_e32 v12, 0xbfb8aa3b, v12
	v_mul_f32_e32 v13, 0xbfb8aa3b, v13
	v_mul_f32_e32 v14, 0xbfb8aa3b, v14
	v_mul_f32_e32 v15, 0xbfb8aa3b, v15
	v_exp_f32_e32 v12, v12
	v_exp_f32_e32 v13, v13
	v_exp_f32_e32 v14, v14
	v_exp_f32_e32 v15, v15
	s_nop 0
	v_add_f32_e32 v12, 1.0, v12
	v_add_f32_e32 v13, 1.0, v13
	v_add_f32_e32 v14, 1.0, v14
	v_add_f32_e32 v15, 1.0, v15
	v_rcp_f32_e32 v12, v12
	v_rcp_f32_e32 v13, v13
	v_rcp_f32_e32 v14, v14
	v_rcp_f32_e32 v15, v15
	s_nop 0
	v_cvt_pk_bf16_f32 v134, v12, v13
	v_cvt_pk_bf16_f32 v135, v14, v15
	ds_write_b64 v236, v[134:135] offset:96
	v_add_f32_e32 v16, v16, v192
	v_add_f32_e32 v17, v17, v193
	v_add_f32_e32 v18, v18, v194
	v_add_f32_e32 v19, v19, v195
	v_mul_f32_e32 v16, 0xbfb8aa3b, v16
	v_mul_f32_e32 v17, 0xbfb8aa3b, v17
	v_mul_f32_e32 v18, 0xbfb8aa3b, v18
	v_mul_f32_e32 v19, 0xbfb8aa3b, v19
	v_exp_f32_e32 v16, v16
	v_exp_f32_e32 v17, v17
	v_exp_f32_e32 v18, v18
	v_exp_f32_e32 v19, v19
	s_nop 0
	v_add_f32_e32 v16, 1.0, v16
	v_add_f32_e32 v17, 1.0, v17
	v_add_f32_e32 v18, 1.0, v18
	v_add_f32_e32 v19, 1.0, v19
	v_rcp_f32_e32 v16, v16
	v_rcp_f32_e32 v17, v17
	v_rcp_f32_e32 v18, v18
	v_rcp_f32_e32 v19, v19
	s_nop 0
	v_cvt_pk_bf16_f32 v136, v16, v17
	v_cvt_pk_bf16_f32 v137, v18, v19
	ds_write_b64 v236, v[136:137] offset:2304
	v_add_f32_e32 v20, v20, v196
	v_add_f32_e32 v21, v21, v197
	v_add_f32_e32 v22, v22, v198
	v_add_f32_e32 v23, v23, v199
	v_mul_f32_e32 v20, 0xbfb8aa3b, v20
	v_mul_f32_e32 v21, 0xbfb8aa3b, v21
	v_mul_f32_e32 v22, 0xbfb8aa3b, v22
	v_mul_f32_e32 v23, 0xbfb8aa3b, v23
	v_exp_f32_e32 v20, v20
	v_exp_f32_e32 v21, v21
	v_exp_f32_e32 v22, v22
	v_exp_f32_e32 v23, v23
	s_nop 0
	v_add_f32_e32 v20, 1.0, v20
	v_add_f32_e32 v21, 1.0, v21
	v_add_f32_e32 v22, 1.0, v22
	v_add_f32_e32 v23, 1.0, v23
	v_rcp_f32_e32 v20, v20
	v_rcp_f32_e32 v21, v21
	v_rcp_f32_e32 v22, v22
	v_rcp_f32_e32 v23, v23
	s_nop 0
	v_cvt_pk_bf16_f32 v138, v20, v21
	v_cvt_pk_bf16_f32 v139, v22, v23
	ds_write_b64 v236, v[138:139] offset:2336
	v_add_f32_e32 v24, v24, v200
	v_add_f32_e32 v25, v25, v201
	v_add_f32_e32 v26, v26, v202
	v_add_f32_e32 v27, v27, v203
	v_mul_f32_e32 v24, 0xbfb8aa3b, v24
	v_mul_f32_e32 v25, 0xbfb8aa3b, v25
	v_mul_f32_e32 v26, 0xbfb8aa3b, v26
	v_mul_f32_e32 v27, 0xbfb8aa3b, v27
	v_exp_f32_e32 v24, v24
	v_exp_f32_e32 v25, v25
	v_exp_f32_e32 v26, v26
	v_exp_f32_e32 v27, v27
	s_nop 0
	v_add_f32_e32 v24, 1.0, v24
	v_add_f32_e32 v25, 1.0, v25
	v_add_f32_e32 v26, 1.0, v26
	v_add_f32_e32 v27, 1.0, v27
	v_rcp_f32_e32 v24, v24
	v_rcp_f32_e32 v25, v25
	v_rcp_f32_e32 v26, v26
	v_rcp_f32_e32 v27, v27
	s_nop 0
	v_cvt_pk_bf16_f32 v140, v24, v25
	v_cvt_pk_bf16_f32 v141, v26, v27
	ds_write_b64 v236, v[140:141] offset:2368
	v_add_f32_e32 v28, v28, v204
	v_add_f32_e32 v29, v29, v205
	v_add_f32_e32 v30, v30, v206
	v_add_f32_e32 v31, v31, v207
	v_mul_f32_e32 v28, 0xbfb8aa3b, v28
	v_mul_f32_e32 v29, 0xbfb8aa3b, v29
	v_mul_f32_e32 v30, 0xbfb8aa3b, v30
	v_mul_f32_e32 v31, 0xbfb8aa3b, v31
	v_exp_f32_e32 v28, v28
	v_exp_f32_e32 v29, v29
	v_exp_f32_e32 v30, v30
	v_exp_f32_e32 v31, v31
	s_nop 0
	v_add_f32_e32 v28, 1.0, v28
	v_add_f32_e32 v29, 1.0, v29
	v_add_f32_e32 v30, 1.0, v30
	v_add_f32_e32 v31, 1.0, v31
	v_rcp_f32_e32 v28, v28
	v_rcp_f32_e32 v29, v29
	v_rcp_f32_e32 v30, v30
	v_rcp_f32_e32 v31, v31
	s_nop 0
	v_cvt_pk_bf16_f32 v142, v28, v29
	v_cvt_pk_bf16_f32 v143, v30, v31
	ds_write_b64 v236, v[142:143] offset:2400
	v_add_f32_e32 v32, v32, v192
	v_add_f32_e32 v33, v33, v193
	v_add_f32_e32 v34, v34, v194
	v_add_f32_e32 v35, v35, v195
	v_mul_f32_e32 v32, 0xbfb8aa3b, v32
	v_mul_f32_e32 v33, 0xbfb8aa3b, v33
	v_mul_f32_e32 v34, 0xbfb8aa3b, v34
	v_mul_f32_e32 v35, 0xbfb8aa3b, v35
	v_exp_f32_e32 v32, v32
	v_exp_f32_e32 v33, v33
	v_exp_f32_e32 v34, v34
	v_exp_f32_e32 v35, v35
	s_nop 0
	v_add_f32_e32 v32, 1.0, v32
	v_add_f32_e32 v33, 1.0, v33
	v_add_f32_e32 v34, 1.0, v34
	v_add_f32_e32 v35, 1.0, v35
	v_rcp_f32_e32 v32, v32
	v_rcp_f32_e32 v33, v33
	v_rcp_f32_e32 v34, v34
	v_rcp_f32_e32 v35, v35
	s_nop 0
	v_cvt_pk_bf16_f32 v144, v32, v33
	v_cvt_pk_bf16_f32 v145, v34, v35
	ds_write_b64 v236, v[144:145] offset:4608
	v_add_f32_e32 v36, v36, v196
	v_add_f32_e32 v37, v37, v197
	v_add_f32_e32 v38, v38, v198
	v_add_f32_e32 v39, v39, v199
	v_mul_f32_e32 v36, 0xbfb8aa3b, v36
	v_mul_f32_e32 v37, 0xbfb8aa3b, v37
	v_mul_f32_e32 v38, 0xbfb8aa3b, v38
	v_mul_f32_e32 v39, 0xbfb8aa3b, v39
	v_exp_f32_e32 v36, v36
	v_exp_f32_e32 v37, v37
	v_exp_f32_e32 v38, v38
	v_exp_f32_e32 v39, v39
	s_nop 0
	v_add_f32_e32 v36, 1.0, v36
	v_add_f32_e32 v37, 1.0, v37
	v_add_f32_e32 v38, 1.0, v38
	v_add_f32_e32 v39, 1.0, v39
	v_rcp_f32_e32 v36, v36
	v_rcp_f32_e32 v37, v37
	v_rcp_f32_e32 v38, v38
	v_rcp_f32_e32 v39, v39
	s_nop 0
	v_cvt_pk_bf16_f32 v146, v36, v37
	v_cvt_pk_bf16_f32 v147, v38, v39
	ds_write_b64 v236, v[146:147] offset:4640
	v_add_f32_e32 v40, v40, v200
	v_add_f32_e32 v41, v41, v201
	v_add_f32_e32 v42, v42, v202
	v_add_f32_e32 v43, v43, v203
	v_mul_f32_e32 v40, 0xbfb8aa3b, v40
	v_mul_f32_e32 v41, 0xbfb8aa3b, v41
	v_mul_f32_e32 v42, 0xbfb8aa3b, v42
	v_mul_f32_e32 v43, 0xbfb8aa3b, v43
	v_exp_f32_e32 v40, v40
	v_exp_f32_e32 v41, v41
	v_exp_f32_e32 v42, v42
	v_exp_f32_e32 v43, v43
	s_nop 0
	v_add_f32_e32 v40, 1.0, v40
	v_add_f32_e32 v41, 1.0, v41
	v_add_f32_e32 v42, 1.0, v42
	v_add_f32_e32 v43, 1.0, v43
	v_rcp_f32_e32 v40, v40
	v_rcp_f32_e32 v41, v41
	v_rcp_f32_e32 v42, v42
	v_rcp_f32_e32 v43, v43
	s_nop 0
	v_cvt_pk_bf16_f32 v148, v40, v41
	v_cvt_pk_bf16_f32 v149, v42, v43
	ds_write_b64 v236, v[148:149] offset:4672
	v_add_f32_e32 v44, v44, v204
	v_add_f32_e32 v45, v45, v205
	v_add_f32_e32 v46, v46, v206
	v_add_f32_e32 v47, v47, v207
	v_mul_f32_e32 v44, 0xbfb8aa3b, v44
	v_mul_f32_e32 v45, 0xbfb8aa3b, v45
	v_mul_f32_e32 v46, 0xbfb8aa3b, v46
	v_mul_f32_e32 v47, 0xbfb8aa3b, v47
	v_exp_f32_e32 v44, v44
	v_exp_f32_e32 v45, v45
	v_exp_f32_e32 v46, v46
	v_exp_f32_e32 v47, v47
	s_nop 0
	v_add_f32_e32 v44, 1.0, v44
	v_add_f32_e32 v45, 1.0, v45
	v_add_f32_e32 v46, 1.0, v46
	v_add_f32_e32 v47, 1.0, v47
	v_rcp_f32_e32 v44, v44
	v_rcp_f32_e32 v45, v45
	v_rcp_f32_e32 v46, v46
	v_rcp_f32_e32 v47, v47
	s_nop 0
	v_cvt_pk_bf16_f32 v150, v44, v45
	v_cvt_pk_bf16_f32 v151, v46, v47
	ds_write_b64 v236, v[150:151] offset:4704
	v_add_f32_e32 v48, v48, v192
	v_add_f32_e32 v49, v49, v193
	v_add_f32_e32 v50, v50, v194
	v_add_f32_e32 v51, v51, v195
	v_mul_f32_e32 v48, 0xbfb8aa3b, v48
	v_mul_f32_e32 v49, 0xbfb8aa3b, v49
	v_mul_f32_e32 v50, 0xbfb8aa3b, v50
	v_mul_f32_e32 v51, 0xbfb8aa3b, v51
	v_exp_f32_e32 v48, v48
	v_exp_f32_e32 v49, v49
	v_exp_f32_e32 v50, v50
	v_exp_f32_e32 v51, v51
	s_nop 0
	v_add_f32_e32 v48, 1.0, v48
	v_add_f32_e32 v49, 1.0, v49
	v_add_f32_e32 v50, 1.0, v50
	v_add_f32_e32 v51, 1.0, v51
	v_rcp_f32_e32 v48, v48
	v_rcp_f32_e32 v49, v49
	v_rcp_f32_e32 v50, v50
	v_rcp_f32_e32 v51, v51
	s_nop 0
	v_cvt_pk_bf16_f32 v152, v48, v49
	v_cvt_pk_bf16_f32 v153, v50, v51
	ds_write_b64 v236, v[152:153] offset:6912
	v_add_f32_e32 v52, v52, v196
	v_add_f32_e32 v53, v53, v197
	v_add_f32_e32 v54, v54, v198
	v_add_f32_e32 v55, v55, v199
	v_mul_f32_e32 v52, 0xbfb8aa3b, v52
	v_mul_f32_e32 v53, 0xbfb8aa3b, v53
	v_mul_f32_e32 v54, 0xbfb8aa3b, v54
	v_mul_f32_e32 v55, 0xbfb8aa3b, v55
	v_exp_f32_e32 v52, v52
	v_exp_f32_e32 v53, v53
	v_exp_f32_e32 v54, v54
	v_exp_f32_e32 v55, v55
	s_nop 0
	v_add_f32_e32 v52, 1.0, v52
	v_add_f32_e32 v53, 1.0, v53
	v_add_f32_e32 v54, 1.0, v54
	v_add_f32_e32 v55, 1.0, v55
	v_rcp_f32_e32 v52, v52
	v_rcp_f32_e32 v53, v53
	v_rcp_f32_e32 v54, v54
	v_rcp_f32_e32 v55, v55
	s_nop 0
	v_cvt_pk_bf16_f32 v154, v52, v53
	v_cvt_pk_bf16_f32 v155, v54, v55
	ds_write_b64 v236, v[154:155] offset:6944
	v_add_f32_e32 v56, v56, v200
	v_add_f32_e32 v57, v57, v201
	v_add_f32_e32 v58, v58, v202
	v_add_f32_e32 v59, v59, v203
	v_mul_f32_e32 v56, 0xbfb8aa3b, v56
	v_mul_f32_e32 v57, 0xbfb8aa3b, v57
	v_mul_f32_e32 v58, 0xbfb8aa3b, v58
	v_mul_f32_e32 v59, 0xbfb8aa3b, v59
	v_exp_f32_e32 v56, v56
	v_exp_f32_e32 v57, v57
	v_exp_f32_e32 v58, v58
	v_exp_f32_e32 v59, v59
	s_nop 0
	v_add_f32_e32 v56, 1.0, v56
	v_add_f32_e32 v57, 1.0, v57
	v_add_f32_e32 v58, 1.0, v58
	v_add_f32_e32 v59, 1.0, v59
	v_rcp_f32_e32 v56, v56
	v_rcp_f32_e32 v57, v57
	v_rcp_f32_e32 v58, v58
	v_rcp_f32_e32 v59, v59
	s_nop 0
	v_cvt_pk_bf16_f32 v156, v56, v57
	v_cvt_pk_bf16_f32 v157, v58, v59
	ds_write_b64 v236, v[156:157] offset:6976
	v_add_f32_e32 v60, v60, v204
	v_add_f32_e32 v61, v61, v205
	v_add_f32_e32 v62, v62, v206
	v_add_f32_e32 v63, v63, v207
	v_mul_f32_e32 v60, 0xbfb8aa3b, v60
	v_mul_f32_e32 v61, 0xbfb8aa3b, v61
	v_mul_f32_e32 v62, 0xbfb8aa3b, v62
	v_mul_f32_e32 v63, 0xbfb8aa3b, v63
	v_exp_f32_e32 v60, v60
	v_exp_f32_e32 v61, v61
	v_exp_f32_e32 v62, v62
	v_exp_f32_e32 v63, v63
	s_nop 0
	v_add_f32_e32 v60, 1.0, v60
	v_add_f32_e32 v61, 1.0, v61
	v_add_f32_e32 v62, 1.0, v62
	v_add_f32_e32 v63, 1.0, v63
	v_rcp_f32_e32 v60, v60
	v_rcp_f32_e32 v61, v61
	v_rcp_f32_e32 v62, v62
	v_rcp_f32_e32 v63, v63
	s_nop 0
	v_cvt_pk_bf16_f32 v158, v60, v61
	v_cvt_pk_bf16_f32 v159, v62, v63
	ds_write_b64 v236, v[158:159] offset:7008
	v_add_f32_e32 v64, v64, v192
	v_add_f32_e32 v65, v65, v193
	v_add_f32_e32 v66, v66, v194
	v_add_f32_e32 v67, v67, v195
	v_mul_f32_e32 v64, 0xbfb8aa3b, v64
	v_mul_f32_e32 v65, 0xbfb8aa3b, v65
	v_mul_f32_e32 v66, 0xbfb8aa3b, v66
	v_mul_f32_e32 v67, 0xbfb8aa3b, v67
	v_exp_f32_e32 v64, v64
	v_exp_f32_e32 v65, v65
	v_exp_f32_e32 v66, v66
	v_exp_f32_e32 v67, v67
	s_nop 0
	v_add_f32_e32 v64, 1.0, v64
	v_add_f32_e32 v65, 1.0, v65
	v_add_f32_e32 v66, 1.0, v66
	v_add_f32_e32 v67, 1.0, v67
	v_rcp_f32_e32 v64, v64
	v_rcp_f32_e32 v65, v65
	v_rcp_f32_e32 v66, v66
	v_rcp_f32_e32 v67, v67
	s_nop 0
	v_cvt_pk_bf16_f32 v128, v64, v65
	v_cvt_pk_bf16_f32 v129, v66, v67
	ds_write_b64 v236, v[128:129] offset:9216
	v_add_f32_e32 v68, v68, v196
	v_add_f32_e32 v69, v69, v197
	v_add_f32_e32 v70, v70, v198
	v_add_f32_e32 v71, v71, v199
	v_mul_f32_e32 v68, 0xbfb8aa3b, v68
	v_mul_f32_e32 v69, 0xbfb8aa3b, v69
	v_mul_f32_e32 v70, 0xbfb8aa3b, v70
	v_mul_f32_e32 v71, 0xbfb8aa3b, v71
	v_exp_f32_e32 v68, v68
	v_exp_f32_e32 v69, v69
	v_exp_f32_e32 v70, v70
	v_exp_f32_e32 v71, v71
	s_nop 0
	v_add_f32_e32 v68, 1.0, v68
	v_add_f32_e32 v69, 1.0, v69
	v_add_f32_e32 v70, 1.0, v70
	v_add_f32_e32 v71, 1.0, v71
	v_rcp_f32_e32 v68, v68
	v_rcp_f32_e32 v69, v69
	v_rcp_f32_e32 v70, v70
	v_rcp_f32_e32 v71, v71
	s_nop 0
	v_cvt_pk_bf16_f32 v130, v68, v69
	v_cvt_pk_bf16_f32 v131, v70, v71
	ds_write_b64 v236, v[130:131] offset:9248
	v_add_f32_e32 v72, v72, v200
	v_add_f32_e32 v73, v73, v201
	v_add_f32_e32 v74, v74, v202
	v_add_f32_e32 v75, v75, v203
	v_mul_f32_e32 v72, 0xbfb8aa3b, v72
	v_mul_f32_e32 v73, 0xbfb8aa3b, v73
	v_mul_f32_e32 v74, 0xbfb8aa3b, v74
	v_mul_f32_e32 v75, 0xbfb8aa3b, v75
	v_exp_f32_e32 v72, v72
	v_exp_f32_e32 v73, v73
	v_exp_f32_e32 v74, v74
	v_exp_f32_e32 v75, v75
	s_nop 0
	v_add_f32_e32 v72, 1.0, v72
	v_add_f32_e32 v73, 1.0, v73
	v_add_f32_e32 v74, 1.0, v74
	v_add_f32_e32 v75, 1.0, v75
	v_rcp_f32_e32 v72, v72
	v_rcp_f32_e32 v73, v73
	v_rcp_f32_e32 v74, v74
	v_rcp_f32_e32 v75, v75
	s_nop 0
	v_cvt_pk_bf16_f32 v132, v72, v73
	v_cvt_pk_bf16_f32 v133, v74, v75
	ds_write_b64 v236, v[132:133] offset:9280
	v_add_f32_e32 v76, v76, v204
	v_add_f32_e32 v77, v77, v205
	v_add_f32_e32 v78, v78, v206
	v_add_f32_e32 v79, v79, v207
	v_mul_f32_e32 v76, 0xbfb8aa3b, v76
	v_mul_f32_e32 v77, 0xbfb8aa3b, v77
	v_mul_f32_e32 v78, 0xbfb8aa3b, v78
	v_mul_f32_e32 v79, 0xbfb8aa3b, v79
	v_exp_f32_e32 v76, v76
	v_exp_f32_e32 v77, v77
	v_exp_f32_e32 v78, v78
	v_exp_f32_e32 v79, v79
	s_nop 0
	v_add_f32_e32 v76, 1.0, v76
	v_add_f32_e32 v77, 1.0, v77
	v_add_f32_e32 v78, 1.0, v78
	v_add_f32_e32 v79, 1.0, v79
	v_rcp_f32_e32 v76, v76
	v_rcp_f32_e32 v77, v77
	v_rcp_f32_e32 v78, v78
	v_rcp_f32_e32 v79, v79
	s_nop 0
	v_cvt_pk_bf16_f32 v134, v76, v77
	v_cvt_pk_bf16_f32 v135, v78, v79
	ds_write_b64 v236, v[134:135] offset:9312
	v_add_f32_e32 v80, v80, v192
	v_add_f32_e32 v81, v81, v193
	v_add_f32_e32 v82, v82, v194
	v_add_f32_e32 v83, v83, v195
	v_mul_f32_e32 v80, 0xbfb8aa3b, v80
	v_mul_f32_e32 v81, 0xbfb8aa3b, v81
	v_mul_f32_e32 v82, 0xbfb8aa3b, v82
	v_mul_f32_e32 v83, 0xbfb8aa3b, v83
	v_exp_f32_e32 v80, v80
	v_exp_f32_e32 v81, v81
	v_exp_f32_e32 v82, v82
	v_exp_f32_e32 v83, v83
	s_nop 0
	v_add_f32_e32 v80, 1.0, v80
	v_add_f32_e32 v81, 1.0, v81
	v_add_f32_e32 v82, 1.0, v82
	v_add_f32_e32 v83, 1.0, v83
	v_rcp_f32_e32 v80, v80
	v_rcp_f32_e32 v81, v81
	v_rcp_f32_e32 v82, v82
	v_rcp_f32_e32 v83, v83
	s_nop 0
	v_cvt_pk_bf16_f32 v136, v80, v81
	v_cvt_pk_bf16_f32 v137, v82, v83
	ds_write_b64 v236, v[136:137] offset:11520
	v_add_f32_e32 v84, v84, v196
	v_add_f32_e32 v85, v85, v197
	v_add_f32_e32 v86, v86, v198
	v_add_f32_e32 v87, v87, v199
	v_mul_f32_e32 v84, 0xbfb8aa3b, v84
	v_mul_f32_e32 v85, 0xbfb8aa3b, v85
	v_mul_f32_e32 v86, 0xbfb8aa3b, v86
	v_mul_f32_e32 v87, 0xbfb8aa3b, v87
	v_exp_f32_e32 v84, v84
	v_exp_f32_e32 v85, v85
	v_exp_f32_e32 v86, v86
	v_exp_f32_e32 v87, v87
	s_nop 0
	v_add_f32_e32 v84, 1.0, v84
	v_add_f32_e32 v85, 1.0, v85
	v_add_f32_e32 v86, 1.0, v86
	v_add_f32_e32 v87, 1.0, v87
	v_rcp_f32_e32 v84, v84
	v_rcp_f32_e32 v85, v85
	v_rcp_f32_e32 v86, v86
	v_rcp_f32_e32 v87, v87
	s_nop 0
	v_cvt_pk_bf16_f32 v138, v84, v85
	v_cvt_pk_bf16_f32 v139, v86, v87
	ds_write_b64 v236, v[138:139] offset:11552
	v_add_f32_e32 v88, v88, v200
	v_add_f32_e32 v89, v89, v201
	v_add_f32_e32 v90, v90, v202
	v_add_f32_e32 v91, v91, v203
	v_mul_f32_e32 v88, 0xbfb8aa3b, v88
	v_mul_f32_e32 v89, 0xbfb8aa3b, v89
	v_mul_f32_e32 v90, 0xbfb8aa3b, v90
	v_mul_f32_e32 v91, 0xbfb8aa3b, v91
	v_exp_f32_e32 v88, v88
	v_exp_f32_e32 v89, v89
	v_exp_f32_e32 v90, v90
	v_exp_f32_e32 v91, v91
	s_nop 0
	v_add_f32_e32 v88, 1.0, v88
	v_add_f32_e32 v89, 1.0, v89
	v_add_f32_e32 v90, 1.0, v90
	v_add_f32_e32 v91, 1.0, v91
	v_rcp_f32_e32 v88, v88
	v_rcp_f32_e32 v89, v89
	v_rcp_f32_e32 v90, v90
	v_rcp_f32_e32 v91, v91
	s_nop 0
	v_cvt_pk_bf16_f32 v140, v88, v89
	v_cvt_pk_bf16_f32 v141, v90, v91
	ds_write_b64 v236, v[140:141] offset:11584
	v_add_f32_e32 v92, v92, v204
	v_add_f32_e32 v93, v93, v205
	v_add_f32_e32 v94, v94, v206
	v_add_f32_e32 v95, v95, v207
	v_mul_f32_e32 v92, 0xbfb8aa3b, v92
	v_mul_f32_e32 v93, 0xbfb8aa3b, v93
	v_mul_f32_e32 v94, 0xbfb8aa3b, v94
	v_mul_f32_e32 v95, 0xbfb8aa3b, v95
	v_exp_f32_e32 v92, v92
	v_exp_f32_e32 v93, v93
	v_exp_f32_e32 v94, v94
	v_exp_f32_e32 v95, v95
	s_nop 0
	v_add_f32_e32 v92, 1.0, v92
	v_add_f32_e32 v93, 1.0, v93
	v_add_f32_e32 v94, 1.0, v94
	v_add_f32_e32 v95, 1.0, v95
	v_rcp_f32_e32 v92, v92
	v_rcp_f32_e32 v93, v93
	v_rcp_f32_e32 v94, v94
	v_rcp_f32_e32 v95, v95
	s_nop 0
	v_cvt_pk_bf16_f32 v142, v92, v93
	v_cvt_pk_bf16_f32 v143, v94, v95
	ds_write_b64 v236, v[142:143] offset:11616
	v_add_f32_e32 v96, v96, v192
	v_add_f32_e32 v97, v97, v193
	v_add_f32_e32 v98, v98, v194
	v_add_f32_e32 v99, v99, v195
	v_mul_f32_e32 v96, 0xbfb8aa3b, v96
	v_mul_f32_e32 v97, 0xbfb8aa3b, v97
	v_mul_f32_e32 v98, 0xbfb8aa3b, v98
	v_mul_f32_e32 v99, 0xbfb8aa3b, v99
	v_exp_f32_e32 v96, v96
	v_exp_f32_e32 v97, v97
	v_exp_f32_e32 v98, v98
	v_exp_f32_e32 v99, v99
	s_nop 0
	v_add_f32_e32 v96, 1.0, v96
	v_add_f32_e32 v97, 1.0, v97
	v_add_f32_e32 v98, 1.0, v98
	v_add_f32_e32 v99, 1.0, v99
	v_rcp_f32_e32 v96, v96
	v_rcp_f32_e32 v97, v97
	v_rcp_f32_e32 v98, v98
	v_rcp_f32_e32 v99, v99
	s_nop 0
	v_cvt_pk_bf16_f32 v144, v96, v97
	v_cvt_pk_bf16_f32 v145, v98, v99
	ds_write_b64 v236, v[144:145] offset:13824
	v_add_f32_e32 v100, v100, v196
	v_add_f32_e32 v101, v101, v197
	v_add_f32_e32 v102, v102, v198
	v_add_f32_e32 v103, v103, v199
	v_mul_f32_e32 v100, 0xbfb8aa3b, v100
	v_mul_f32_e32 v101, 0xbfb8aa3b, v101
	v_mul_f32_e32 v102, 0xbfb8aa3b, v102
	v_mul_f32_e32 v103, 0xbfb8aa3b, v103
	v_exp_f32_e32 v100, v100
	v_exp_f32_e32 v101, v101
	v_exp_f32_e32 v102, v102
	v_exp_f32_e32 v103, v103
	s_nop 0
	v_add_f32_e32 v100, 1.0, v100
	v_add_f32_e32 v101, 1.0, v101
	v_add_f32_e32 v102, 1.0, v102
	v_add_f32_e32 v103, 1.0, v103
	v_rcp_f32_e32 v100, v100
	v_rcp_f32_e32 v101, v101
	v_rcp_f32_e32 v102, v102
	v_rcp_f32_e32 v103, v103
	s_nop 0
	v_cvt_pk_bf16_f32 v146, v100, v101
	v_cvt_pk_bf16_f32 v147, v102, v103
	ds_write_b64 v236, v[146:147] offset:13856
	v_add_f32_e32 v104, v104, v200
	v_add_f32_e32 v105, v105, v201
	v_add_f32_e32 v106, v106, v202
	v_add_f32_e32 v107, v107, v203
	v_mul_f32_e32 v104, 0xbfb8aa3b, v104
	v_mul_f32_e32 v105, 0xbfb8aa3b, v105
	v_mul_f32_e32 v106, 0xbfb8aa3b, v106
	v_mul_f32_e32 v107, 0xbfb8aa3b, v107
	v_exp_f32_e32 v104, v104
	v_exp_f32_e32 v105, v105
	v_exp_f32_e32 v106, v106
	v_exp_f32_e32 v107, v107
	s_nop 0
	v_add_f32_e32 v104, 1.0, v104
	v_add_f32_e32 v105, 1.0, v105
	v_add_f32_e32 v106, 1.0, v106
	v_add_f32_e32 v107, 1.0, v107
	v_rcp_f32_e32 v104, v104
	v_rcp_f32_e32 v105, v105
	v_rcp_f32_e32 v106, v106
	v_rcp_f32_e32 v107, v107
	s_nop 0
	v_cvt_pk_bf16_f32 v148, v104, v105
	v_cvt_pk_bf16_f32 v149, v106, v107
	ds_write_b64 v236, v[148:149] offset:13888
	v_add_f32_e32 v108, v108, v204
	v_add_f32_e32 v109, v109, v205
	v_add_f32_e32 v110, v110, v206
	v_add_f32_e32 v111, v111, v207
	v_mul_f32_e32 v108, 0xbfb8aa3b, v108
	v_mul_f32_e32 v109, 0xbfb8aa3b, v109
	v_mul_f32_e32 v110, 0xbfb8aa3b, v110
	v_mul_f32_e32 v111, 0xbfb8aa3b, v111
	v_exp_f32_e32 v108, v108
	v_exp_f32_e32 v109, v109
	v_exp_f32_e32 v110, v110
	v_exp_f32_e32 v111, v111
	s_nop 0
	v_add_f32_e32 v108, 1.0, v108
	v_add_f32_e32 v109, 1.0, v109
	v_add_f32_e32 v110, 1.0, v110
	v_add_f32_e32 v111, 1.0, v111
	v_rcp_f32_e32 v108, v108
	v_rcp_f32_e32 v109, v109
	v_rcp_f32_e32 v110, v110
	v_rcp_f32_e32 v111, v111
	s_nop 0
	v_cvt_pk_bf16_f32 v150, v108, v109
	v_cvt_pk_bf16_f32 v151, v110, v111
	ds_write_b64 v236, v[150:151] offset:13920
	v_add_f32_e32 v112, v112, v192
	v_add_f32_e32 v113, v113, v193
	v_add_f32_e32 v114, v114, v194
	v_add_f32_e32 v115, v115, v195
	v_mul_f32_e32 v112, 0xbfb8aa3b, v112
	v_mul_f32_e32 v113, 0xbfb8aa3b, v113
	v_mul_f32_e32 v114, 0xbfb8aa3b, v114
	v_mul_f32_e32 v115, 0xbfb8aa3b, v115
	v_exp_f32_e32 v112, v112
	v_exp_f32_e32 v113, v113
	v_exp_f32_e32 v114, v114
	v_exp_f32_e32 v115, v115
	s_nop 0
	v_add_f32_e32 v112, 1.0, v112
	v_add_f32_e32 v113, 1.0, v113
	v_add_f32_e32 v114, 1.0, v114
	v_add_f32_e32 v115, 1.0, v115
	v_rcp_f32_e32 v112, v112
	v_rcp_f32_e32 v113, v113
	v_rcp_f32_e32 v114, v114
	v_rcp_f32_e32 v115, v115
	s_nop 0
	v_cvt_pk_bf16_f32 v152, v112, v113
	v_cvt_pk_bf16_f32 v153, v114, v115
	ds_write_b64 v236, v[152:153] offset:16128
	v_add_f32_e32 v116, v116, v196
	v_add_f32_e32 v117, v117, v197
	v_add_f32_e32 v118, v118, v198
	v_add_f32_e32 v119, v119, v199
	v_mul_f32_e32 v116, 0xbfb8aa3b, v116
	v_mul_f32_e32 v117, 0xbfb8aa3b, v117
	v_mul_f32_e32 v118, 0xbfb8aa3b, v118
	v_mul_f32_e32 v119, 0xbfb8aa3b, v119
	v_exp_f32_e32 v116, v116
	v_exp_f32_e32 v117, v117
	v_exp_f32_e32 v118, v118
	v_exp_f32_e32 v119, v119
	s_nop 0
	v_add_f32_e32 v116, 1.0, v116
	v_add_f32_e32 v117, 1.0, v117
	v_add_f32_e32 v118, 1.0, v118
	v_add_f32_e32 v119, 1.0, v119
	v_rcp_f32_e32 v116, v116
	v_rcp_f32_e32 v117, v117
	v_rcp_f32_e32 v118, v118
	v_rcp_f32_e32 v119, v119
	s_nop 0
	v_cvt_pk_bf16_f32 v154, v116, v117
	v_cvt_pk_bf16_f32 v155, v118, v119
	ds_write_b64 v236, v[154:155] offset:16160
	v_add_f32_e32 v120, v120, v200
	v_add_f32_e32 v121, v121, v201
	v_add_f32_e32 v122, v122, v202
	v_add_f32_e32 v123, v123, v203
	v_mul_f32_e32 v120, 0xbfb8aa3b, v120
	v_mul_f32_e32 v121, 0xbfb8aa3b, v121
	v_mul_f32_e32 v122, 0xbfb8aa3b, v122
	v_mul_f32_e32 v123, 0xbfb8aa3b, v123
	v_exp_f32_e32 v120, v120
	v_exp_f32_e32 v121, v121
	v_exp_f32_e32 v122, v122
	v_exp_f32_e32 v123, v123
	s_nop 0
	v_add_f32_e32 v120, 1.0, v120
	v_add_f32_e32 v121, 1.0, v121
	v_add_f32_e32 v122, 1.0, v122
	v_add_f32_e32 v123, 1.0, v123
	v_rcp_f32_e32 v120, v120
	v_rcp_f32_e32 v121, v121
	v_rcp_f32_e32 v122, v122
	v_rcp_f32_e32 v123, v123
	s_nop 0
	v_cvt_pk_bf16_f32 v156, v120, v121
	v_cvt_pk_bf16_f32 v157, v122, v123
	ds_write_b64 v236, v[156:157] offset:16192
	v_add_f32_e32 v124, v124, v204
	v_add_f32_e32 v125, v125, v205
	v_add_f32_e32 v126, v126, v206
	v_add_f32_e32 v127, v127, v207
	v_mul_f32_e32 v124, 0xbfb8aa3b, v124
	v_mul_f32_e32 v125, 0xbfb8aa3b, v125
	v_mul_f32_e32 v126, 0xbfb8aa3b, v126
	v_mul_f32_e32 v127, 0xbfb8aa3b, v127
	v_exp_f32_e32 v124, v124
	v_exp_f32_e32 v125, v125
	v_exp_f32_e32 v126, v126
	v_exp_f32_e32 v127, v127
	s_nop 0
	v_add_f32_e32 v124, 1.0, v124
	v_add_f32_e32 v125, 1.0, v125
	v_add_f32_e32 v126, 1.0, v126
	v_add_f32_e32 v127, 1.0, v127
	v_rcp_f32_e32 v124, v124
	v_rcp_f32_e32 v125, v125
	v_rcp_f32_e32 v126, v126
	v_rcp_f32_e32 v127, v127
	s_nop 0
	v_cvt_pk_bf16_f32 v158, v124, v125
	v_cvt_pk_bf16_f32 v159, v126, v127
	ds_write_b64 v236, v[158:159] offset:16224
	s_waitcnt lgkmcnt(0)
; DI void st_bf16x4(bf16_t* o, f32x4 v) { u32x2 q; q.x = pack2(v[0], v[1]); q.y = pack2(v[2], v[3]); *(u32x2*)o = q; }
; template <class Epi>
; DI void gemm_tile(char* smem, const bf16_t* __restrict__ A0, int lda0, int ksplit, const bf16_t* __restrict__ A1, int lda1,
;                   const bf16_t* __restrict__ Bt, int K, int row0, int col0, const Epi& epi, int tid) {
;   constexpr int BK = 32, PITCH = 40, BUF = (256 + 128) * PITCH;
;   bf16_t* sbase = (bf16_t*)smem;
;   const int lane = tid & 63, wid = tid >> 6, wr = wid >> 1, wc = wid & 1, fr = lane & 15, fq = lane >> 4;
;   f32x4 acc[8][4];
; #pragma unroll
;   for (int m = 0; m < 8; ++m)
; #pragma unroll
;     for (int n = 0; n < 4; ++n) acc[m][n] = (f32x4){0.f, 0.f, 0.f, 0.f};
;   u32x4 ra[2][4], rb[2][2];
;   const int nk = K / BK;
;   const int sr = tid >> 2, scv = tid & 3;
;   DI void operator()(int row, int col, f32x4 v) const {
;     if (col < n0) st_bf16x4(o0 + (size_t)row * ld0 + col, v);
;     else { const int c = col - n0; if (c < n1) st_bf16x4(o1 + (size_t)row * ld1 + c, v); }
;   }
	ds_read_b128 v[128:131], v237
	ds_read_b128 v[132:135], v237 offset:1152
	ds_read_b128 v[136:139], v237 offset:2304
	ds_read_b128 v[140:143], v237 offset:3456
	ds_read_b128 v[144:147], v237 offset:4608
	ds_read_b128 v[148:151], v237 offset:5760
	ds_read_b128 v[152:155], v237 offset:6912
	ds_read_b128 v[156:159], v237 offset:8064
	ds_read_b128 v[160:163], v237 offset:9216
	ds_read_b128 v[164:167], v237 offset:10368
	ds_read_b128 v[168:171], v237 offset:11520
	ds_read_b128 v[172:175], v237 offset:12672
	ds_read_b128 v[176:179], v237 offset:13824
	ds_read_b128 v[180:183], v237 offset:14976
	ds_read_b128 v[184:187], v237 offset:16128
	ds_read_b128 v[188:191], v237 offset:17280
	s_waitcnt lgkmcnt(15)
	global_store_dwordx4 v238, v[128:131], s[4:5] nt
	s_add_u32 s4, s4, 0x2000
	s_addc_u32 s5, s5, 0
	s_waitcnt lgkmcnt(14)
	global_store_dwordx4 v238, v[132:135], s[4:5] nt
	s_add_u32 s4, s4, 0x2000
	s_addc_u32 s5, s5, 0
	s_waitcnt lgkmcnt(13)
	global_store_dwordx4 v238, v[136:139], s[4:5] nt
	s_add_u32 s4, s4, 0x2000
	s_addc_u32 s5, s5, 0
	s_waitcnt lgkmcnt(12)
	global_store_dwordx4 v238, v[140:143], s[4:5] nt
	s_add_u32 s4, s4, 0x2000
	s_addc_u32 s5, s5, 0
	s_waitcnt lgkmcnt(11)
	global_store_dwordx4 v238, v[144:147], s[4:5] nt
	s_add_u32 s4, s4, 0x2000
	s_addc_u32 s5, s5, 0
	s_waitcnt lgkmcnt(10)
	global_store_dwordx4 v238, v[148:151], s[4:5] nt
	s_add_u32 s4, s4, 0x2000
	s_addc_u32 s5, s5, 0
	s_waitcnt lgkmcnt(9)
	global_store_dwordx4 v238, v[152:155], s[4:5] nt
	s_add_u32 s4, s4, 0x2000
	s_addc_u32 s5, s5, 0
	s_waitcnt lgkmcnt(8)
	global_store_dwordx4 v238, v[156:159], s[4:5] nt
	s_add_u32 s4, s4, 0x2000
	s_addc_u32 s5, s5, 0
	s_waitcnt lgkmcnt(7)
	global_store_dwordx4 v238, v[160:163], s[4:5] nt
	s_add_u32 s4, s4, 0x2000
	s_addc_u32 s5, s5, 0
	s_waitcnt lgkmcnt(6)
	global_store_dwordx4 v238, v[164:167], s[4:5] nt
	s_add_u32 s4, s4, 0x2000
	s_addc_u32 s5, s5, 0
	s_waitcnt lgkmcnt(5)
	global_store_dwordx4 v238, v[168:171], s[4:5] nt
	s_add_u32 s4, s4, 0x2000
	s_addc_u32 s5, s5, 0
	s_waitcnt lgkmcnt(4)
	global_store_dwordx4 v238, v[172:175], s[4:5] nt
	s_add_u32 s4, s4, 0x2000
	s_addc_u32 s5, s5, 0
	s_waitcnt lgkmcnt(3)
	global_store_dwordx4 v238, v[176:179], s[4:5] nt
	s_add_u32 s4, s4, 0x2000
	s_addc_u32 s5, s5, 0
	s_waitcnt lgkmcnt(2)
	global_store_dwordx4 v238, v[180:183], s[4:5] nt
	s_add_u32 s4, s4, 0x2000
	s_addc_u32 s5, s5, 0
	s_waitcnt lgkmcnt(1)
	global_store_dwordx4 v238, v[184:187], s[4:5] nt
	s_add_u32 s4, s4, 0x2000
	s_addc_u32 s5, s5, 0
	s_waitcnt lgkmcnt(0)
	global_store_dwordx4 v238, v[188:191], s[4:5] nt
	s_nop 1
	s_add_u32 s15, s15, 64
	s_branch .Lg3c_tile
.Lg3c_done:
	s_setprio 0
	v_mbcnt_lo_u32_b32 v194, -1, 0
	v_mbcnt_hi_u32_b32 v136, -1, v194
	v_mbcnt_lo_u32_b32 v240, -1, 0
	v_mbcnt_hi_u32_b32 v240, -1, v240
	s_lshr_b32 s27, s72, 6
	s_lshl_b32 s100, s27, 10
	v_and_b32_e32 v241, 15, v240
	v_lshrrev_b32_e32 v242, 4, v240
	v_bfe_u32 v243, v240, 3, 1
	v_mul_u32_u24_e32 v243, 3, v243
	v_xor_b32_e32 v243, v242, v243
	v_lshlrev_b32_e32 v243, 4, v243
	v_lshl_add_u32 v243, v241, 6, v243
	s_lshr_b32 s26, s27, 1
	s_lshl_b32 s26, s26, 13
	v_add_u32_e32 v230, s26, v243
	s_and_b32 s26, s27, 1
	s_lshl_b32 s26, s26, 12
	s_add_u32 s26, s26, 16384
	v_add_u32_e32 v231, s26, v243
	s_lshr_b32 s26, s27, 1
	s_lshl_b32 s26, s26, 7
	v_add_u32_e32 v244, s26, v241
	s_and_b32 s26, s27, 1
	s_lshl_b32 s26, s26, 6
	v_lshl_add_u32 v245, v242, 2, s26
	v_lshlrev_b32_e32 v235, 2, v245
	s_mul_i32 s26, s27, 18432
	v_mul_u32_u24_e32 v246, 144, v241
	v_lshl_add_u32 v246, v242, 3, v246
	v_add_u32_e32 v236, s26, v246
	v_lshrrev_b32_e32 v246, 3, v240
	v_mul_u32_u24_e32 v246, 144, v246
	v_and_b32_e32 v247, 7, v240
	v_lshl_add_u32 v246, v247, 4, v246
	v_add_u32_e32 v237, s26, v246
	s_lshr_b32 s26, s27, 1
	s_lshl_b32 s26, s26, 7
	v_lshrrev_b32_e32 v246, 3, v240
	v_add_u32_e32 v246, s26, v246
	s_and_b32 s26, s27, 1
	s_lshl_b32 s26, s26, 6
	v_lshl_add_u32 v248, v247, 3, s26
	s_movk_i32 s26, 1024
	v_mul_lo_u32 v247, v246, s26
	v_lshl_add_u32 v238, v248, 1, v247
	v_lshrrev_b32_e32 v241, 2, v240
	s_lshl_b32 s26, s27, 4
	v_add_u32_e32 v241, s26, v241
	v_bfe_u32 v242, v240, 5, 1
	v_mul_u32_u24_e32 v242, 3, v242
	v_and_b32_e32 v243, 3, v240
	v_xor_b32_e32 v243, v243, v242
	v_lshlrev_b32_e32 v243, 4, v243
	s_mov_b32 s26, 512
	v_mad_u32_u24 v224, v241, s26, v243
	v_add_u32_e32 v225, 0x8000, v224
	v_add_u32_e32 v226, 0x10000, v224
	v_add_u32_e32 v227, 0x18000, v224
	s_mov_b32 s26, 256
	v_mad_u32_u24 v228, v241, s26, v243
	v_add_u32_e32 v229, 0x4000, v228
	s_cmpk_gt_u32 s96, 0xff
	s_cselect_b32 s25, 1, 0
	s_cmpk_gt_u32 s96, 0xff
	s_cbranch_scc0 .Lg3d_prio
	s_setprio 1

; #define LWRITE(S, buf) do { bf16_t* sA_ = sbase + (buf) * BUF; bf16_t* sB_ = sA_ + 256 * PITCH; \
;     _Pragma("unroll") for (int i_ = 0; i_ < 4; ++i_) *(u32x4*)(sA_ + (sr + i_ * 64) * PITCH + scv * 8) = ra[S][i_]; \
;     _Pragma("unroll") for (int i_ = 0; i_ < 2; ++i_) *(u32x4*)(sB_ + (sr + i_ * 64) * PITCH + scv * 8) = rb[S][i_]; } while (0)
; template <class Epi>
; DI void gemm_tile(char* smem, const bf16_t* __restrict__ A0, int lda0, int ksplit, const bf16_t* __restrict__ A1, int lda1,
;                   const bf16_t* __restrict__ Bt, int K, int row0, int col0, const Epi& epi, int tid) {
;     ...
;   f32x4 acc[8][4];
; #pragma unroll
;   for (int m = 0; m < 8; ++m)
; #pragma unroll
;     for (int n = 0; n < 4; ++n) acc[m][n] = (f32x4){0.f, 0.f, 0.f, 0.f};
;   u32x4 ra[2][4], rb[2][2];
;   const int nk = K / BK;
;   const int sr = tid >> 2, scv = tid & 3;
;     ...
;   __syncthreads();
;   {
;     const int last = nk - 1;
;     GLOAD(0, 0);
;     __builtin_amdgcn_sched_barrier(0);
;     GLOAD(1, 1);
;     __builtin_amdgcn_sched_barrier(0);
;     LWRITE(0, 0);
;     __builtin_amdgcn_sched_barrier(0);
;     GLOAD(0, (2 < last ? 2 : last));
;     __builtin_amdgcn_sched_barrier(0);
;     __syncthreads();
; template <class Epi>
; DI void gemm_phase(char* smem, const bf16_t* A0, int lda0, int ksplit, const bf16_t* A1, int lda1, const bf16_t* Bt, int K, int nN, const Epi& epi, int tid) {
;     ...
;     const int x = blockIdx.x & 7, l = blockIdx.x >> 3, L = G >> 3, per = 8 * nN, tot = 2 * per;
;     for (int q = l; q < tot; q += L) { const int rgl = q / per, rem = q % per, ct = rem >> 3, rt = (x * 2 + rgl) * 8 + (rem & 7);
;       gemm_tile(smem, A0, lda0, ksplit, A1, lda1, Bt, K, rt * 256, ct * 128, epi, tid); }
.Lg3d_tile:
	s_cmpk_ge_u32 s15, 64
	s_cbranch_scc1 .Lg3d_done
	s_cmpk_ge_u32 s15, 32
	s_cselect_b32 s27, 1, 0
	s_cselect_b32 s26, 32, 0
	s_sub_u32 s26, s15, s26
	s_add_u32 s27, s27, s101
	s_lshl_b32 s27, s27, 3
	s_and_b32 s29, s26, 7
	s_add_u32 s29, s29, s27
	s_lshl_b32 s29, s29, 8
	s_lshr_b32 s28, s26, 3
	s_lshl_b32 s28, s28, 7
	s_mul_i32 s27, s29, 512
	s_add_u32 s27, s27, 0x1ea00100
	s_add_u32 s0, s92, s27
	s_addc_u32 s1, s93, 0
	s_mul_i32 s27, s28, 256
	s_add_u32 s27, s27, 0x3480000
	s_add_u32 s2, s92, s27
	s_addc_u32 s3, s93, 0
	s_waitcnt lgkmcnt(0)
	s_barrier
	s_mov_b32 s99, 0
	s_mov_b32 s30, 0
	s_add_u32 s26, s30, s100
	s_add_u32 m0, s26, 0
	s_nop 0
	global_load_lds_dwordx4 v224, s[0:1]
	s_add_u32 m0, s26, 4096
	s_nop 0
	global_load_lds_dwordx4 v225, s[0:1]
	s_add_u32 m0, s26, 8192
	s_nop 0
	global_load_lds_dwordx4 v226, s[0:1]
	s_add_u32 m0, s26, 12288
	s_nop 0
	global_load_lds_dwordx4 v227, s[0:1]
	s_add_u32 m0, s26, 16384
	s_nop 0
	global_load_lds_dwordx4 v228, s[2:3]
	s_add_u32 m0, s26, 20480
	s_nop 0
	global_load_lds_dwordx4 v229, s[2:3]
	s_add_u32 s0, s0, 64
	s_addc_u32 s1, s1, 0
	s_add_u32 s2, s2, 64
	s_addc_u32 s3, s3, 0
	s_add_u32 s99, s99, 1
	s_add_u32 s30, s30, 24576
	s_cmp_eq_u32 s30, 73728
	s_cselect_b32 s30, 0, s30
	s_add_u32 s26, s30, s100
	s_add_u32 m0, s26, 0
	s_nop 0
	global_load_lds_dwordx4 v224, s[0:1]
	s_add_u32 m0, s26, 4096
	s_nop 0
	global_load_lds_dwordx4 v225, s[0:1]
	s_add_u32 m0, s26, 8192
	s_nop 0
	global_load_lds_dwordx4 v226, s[0:1]
	s_add_u32 m0, s26, 12288
	s_nop 0
	global_load_lds_dwordx4 v227, s[0:1]
	s_add_u32 m0, s26, 16384
	s_nop 0
	global_load_lds_dwordx4 v228, s[2:3]
	s_add_u32 m0, s26, 20480
	s_nop 0
	global_load_lds_dwordx4 v229, s[2:3]
	s_add_u32 s0, s0, 64
	s_addc_u32 s1, s1, 0
	s_add_u32 s2, s2, 64
	s_addc_u32 s3, s3, 0
	s_add_u32 s99, s99, 1
	s_add_u32 s30, s30, 24576
	s_cmp_eq_u32 s30, 73728
	s_cselect_b32 s30, 0, s30
	s_add_u32 s26, s30, s100
	s_add_u32 m0, s26, 0
	s_nop 0
	global_load_lds_dwordx4 v224, s[0:1]
	s_add_u32 m0, s26, 4096
	s_nop 0
	global_load_lds_dwordx4 v225, s[0:1]
	s_add_u32 m0, s26, 8192
	s_nop 0
	global_load_lds_dwordx4 v226, s[0:1]
	s_add_u32 m0, s26, 12288
	s_nop 0
	global_load_lds_dwordx4 v227, s[0:1]
	s_add_u32 m0, s26, 16384
	s_nop 0
	global_load_lds_dwordx4 v228, s[2:3]
	s_add_u32 m0, s26, 20480
	s_nop 0
	global_load_lds_dwordx4 v229, s[2:3]
	s_add_u32 s0, s0, 64
	s_addc_u32 s1, s1, 0
	s_add_u32 s2, s2, 64
	s_addc_u32 s3, s3, 0
	s_add_u32 s99, s99, 1
	s_add_u32 s30, s30, 24576
	s_cmp_eq_u32 s30, 73728
	s_cselect_b32 s30, 0, s30
	v_mov_b32_e32 v0, 0
	v_mov_b32_e32 v1, 0
	v_mov_b32_e32 v2, 0
	v_mov_b32_e32 v3, 0
	v_mov_b32_e32 v4, 0
	v_mov_b32_e32 v5, 0
	v_mov_b32_e32 v6, 0
	v_mov_b32_e32 v7, 0
	v_mov_b32_e32 v8, 0
	v_mov_b32_e32 v9, 0
	v_mov_b32_e32 v10, 0
	v_mov_b32_e32 v11, 0
	v_mov_b32_e32 v12, 0
	v_mov_b32_e32 v13, 0
	v_mov_b32_e32 v14, 0
	v_mov_b32_e32 v15, 0
	v_mov_b32_e32 v16, 0
	v_mov_b32_e32 v17, 0
	v_mov_b32_e32 v18, 0
	v_mov_b32_e32 v19, 0
	v_mov_b32_e32 v20, 0
	v_mov_b32_e32 v21, 0
	v_mov_b32_e32 v22, 0
	v_mov_b32_e32 v23, 0
	v_mov_b32_e32 v24, 0
	v_mov_b32_e32 v25, 0
	v_mov_b32_e32 v26, 0
	v_mov_b32_e32 v27, 0
	v_mov_b32_e32 v28, 0
	v_mov_b32_e32 v29, 0
	v_mov_b32_e32 v30, 0
	v_mov_b32_e32 v31, 0
	v_mov_b32_e32 v32, 0
	v_mov_b32_e32 v33, 0
	v_mov_b32_e32 v34, 0
	v_mov_b32_e32 v35, 0
	v_mov_b32_e32 v36, 0
	v_mov_b32_e32 v37, 0
	v_mov_b32_e32 v38, 0
	v_mov_b32_e32 v39, 0
	v_mov_b32_e32 v40, 0
	v_mov_b32_e32 v41, 0
	v_mov_b32_e32 v42, 0
	v_mov_b32_e32 v43, 0
	v_mov_b32_e32 v44, 0
	v_mov_b32_e32 v45, 0
	v_mov_b32_e32 v46, 0
	v_mov_b32_e32 v47, 0
	v_mov_b32_e32 v48, 0
	v_mov_b32_e32 v49, 0
	v_mov_b32_e32 v50, 0
	v_mov_b32_e32 v51, 0
	v_mov_b32_e32 v52, 0
	v_mov_b32_e32 v53, 0
	v_mov_b32_e32 v54, 0
	v_mov_b32_e32 v55, 0
	v_mov_b32_e32 v56, 0
	v_mov_b32_e32 v57, 0
	v_mov_b32_e32 v58, 0
	v_mov_b32_e32 v59, 0
	v_mov_b32_e32 v60, 0
	v_mov_b32_e32 v61, 0
	v_mov_b32_e32 v62, 0
	v_mov_b32_e32 v63, 0
	v_mov_b32_e32 v64, 0
	v_mov_b32_e32 v65, 0
	v_mov_b32_e32 v66, 0
	v_mov_b32_e32 v67, 0
	v_mov_b32_e32 v68, 0
	v_mov_b32_e32 v69, 0
	v_mov_b32_e32 v70, 0
	v_mov_b32_e32 v71, 0
	v_mov_b32_e32 v72, 0
	v_mov_b32_e32 v73, 0
	v_mov_b32_e32 v74, 0
	v_mov_b32_e32 v75, 0
	v_mov_b32_e32 v76, 0
	v_mov_b32_e32 v77, 0
	v_mov_b32_e32 v78, 0
	v_mov_b32_e32 v79, 0
	v_mov_b32_e32 v80, 0
	v_mov_b32_e32 v81, 0
	v_mov_b32_e32 v82, 0
	v_mov_b32_e32 v83, 0
	v_mov_b32_e32 v84, 0
	v_mov_b32_e32 v85, 0
	v_mov_b32_e32 v86, 0
	v_mov_b32_e32 v87, 0
	v_mov_b32_e32 v88, 0
	v_mov_b32_e32 v89, 0
	v_mov_b32_e32 v90, 0
	v_mov_b32_e32 v91, 0
	v_mov_b32_e32 v92, 0
	v_mov_b32_e32 v93, 0
	v_mov_b32_e32 v94, 0
	v_mov_b32_e32 v95, 0
	v_mov_b32_e32 v96, 0
	v_mov_b32_e32 v97, 0
	v_mov_b32_e32 v98, 0
	v_mov_b32_e32 v99, 0
	v_mov_b32_e32 v100, 0
	v_mov_b32_e32 v101, 0
	v_mov_b32_e32 v102, 0
	v_mov_b32_e32 v103, 0
	v_mov_b32_e32 v104, 0
	v_mov_b32_e32 v105, 0
	v_mov_b32_e32 v106, 0
	v_mov_b32_e32 v107, 0
	v_mov_b32_e32 v108, 0
	v_mov_b32_e32 v109, 0
	v_mov_b32_e32 v110, 0
	v_mov_b32_e32 v111, 0
	v_mov_b32_e32 v112, 0
	v_mov_b32_e32 v113, 0
	v_mov_b32_e32 v114, 0
	v_mov_b32_e32 v115, 0
	v_mov_b32_e32 v116, 0
	v_mov_b32_e32 v117, 0
	v_mov_b32_e32 v118, 0
	v_mov_b32_e32 v119, 0
	v_mov_b32_e32 v120, 0
	v_mov_b32_e32 v121, 0
	v_mov_b32_e32 v122, 0
	v_mov_b32_e32 v123, 0
	v_mov_b32_e32 v124, 0
	v_mov_b32_e32 v125, 0
	v_mov_b32_e32 v126, 0
	v_mov_b32_e32 v127, 0
	s_mov_b32 s98, 0
	s_mov_b32 s31, 24576
	s_waitcnt vmcnt(12)
	s_barrier
; #define LWRITE(S, buf) do { bf16_t* sA_ = sbase + (buf) * BUF; bf16_t* sB_ = sA_ + 256 * PITCH; \
;     _Pragma("unroll") for (int i_ = 0; i_ < 4; ++i_) *(u32x4*)(sA_ + (sr + i_ * 64) * PITCH + scv * 8) = ra[S][i_]; \
;     _Pragma("unroll") for (int i_ = 0; i_ < 2; ++i_) *(u32x4*)(sB_ + (sr + i_ * 64) * PITCH + scv * 8) = rb[S][i_]; } while (0)
; template <class Epi>
; DI void gemm_tile(char* smem, const bf16_t* __restrict__ A0, int lda0, int ksplit, const bf16_t* __restrict__ A1, int lda1,
;                   const bf16_t* __restrict__ Bt, int K, int row0, int col0, const Epi& epi, int tid) {
;     ...
;   __syncthreads();
;   {
;     const int last = nk - 1;
;     GLOAD(0, 0);
;     __builtin_amdgcn_sched_barrier(0);
;     GLOAD(1, 1);
;     __builtin_amdgcn_sched_barrier(0);
;     LWRITE(0, 0);
;     __builtin_amdgcn_sched_barrier(0);
;     GLOAD(0, (2 < last ? 2 : last));
;     __builtin_amdgcn_sched_barrier(0);
;     __syncthreads();
;     for (int kt = 0; kt < nk; kt += 2) {
;       LWRITE(1, 1);
;       __builtin_amdgcn_sched_barrier(0);
;       GLOAD(1, (kt + 3 < last ? kt + 3 : last));
;       __builtin_amdgcn_sched_barrier(0);
;       COMPUTE(0);
;       __syncthreads();
;       LWRITE(0, 0);
;       __builtin_amdgcn_sched_barrier(0);
;       GLOAD(0, (kt + 4 < last ? kt + 4 : last));
;       __builtin_amdgcn_sched_barrier(0);
;       COMPUTE(1);
	ds_read_b128 v[128:131], v231 offset:0
	ds_read_b128 v[132:135], v231 offset:1024
	ds_read_b128 v[136:139], v231 offset:2048
	ds_read_b128 v[140:143], v231 offset:3072
	ds_read_b128 v[144:147], v230 offset:0
	ds_read_b128 v[148:151], v230 offset:1024
	ds_read_b128 v[152:155], v230 offset:2048
	ds_read_b128 v[156:159], v230 offset:3072
	ds_read_b128 v[160:163], v230 offset:4096
	ds_read_b128 v[164:167], v230 offset:5120
	ds_read_b128 v[168:171], v230 offset:6144
	ds_read_b128 v[172:175], v230 offset:7168
	s_waitcnt vmcnt(6)
	s_waitcnt lgkmcnt(0)
	s_barrier
	v_add_u32_e32 v232, s31, v230
	v_add_u32_e32 v233, s31, v231
	s_add_u32 s26, s30, s100
	s_setprio 1
	v_mfma_f32_16x16x32_bf16 v[0:3], v[128:131], v[144:147], v[0:3]
	v_mfma_f32_16x16x32_bf16 v[4:7], v[132:135], v[144:147], v[4:7]
	v_mfma_f32_16x16x32_bf16 v[8:11], v[136:139], v[144:147], v[8:11]
	v_mfma_f32_16x16x32_bf16 v[12:15], v[140:143], v[144:147], v[12:15]
	ds_read_b128 v[176:179], v233 offset:0
	ds_read_b128 v[180:183], v233 offset:1024
	s_add_u32 m0, s26, 0
	s_nop 0
	global_load_lds_dwordx4 v224, s[0:1]
	v_mfma_f32_16x16x32_bf16 v[16:19], v[128:131], v[148:151], v[16:19]
	v_mfma_f32_16x16x32_bf16 v[20:23], v[132:135], v[148:151], v[20:23]
	v_mfma_f32_16x16x32_bf16 v[24:27], v[136:139], v[148:151], v[24:27]
	v_mfma_f32_16x16x32_bf16 v[28:31], v[140:143], v[148:151], v[28:31]
	ds_read_b128 v[184:187], v233 offset:2048
	ds_read_b128 v[188:191], v233 offset:3072
	s_add_u32 m0, s26, 4096
	s_nop 0
	global_load_lds_dwordx4 v225, s[0:1]
	v_mfma_f32_16x16x32_bf16 v[32:35], v[128:131], v[152:155], v[32:35]
	v_mfma_f32_16x16x32_bf16 v[36:39], v[132:135], v[152:155], v[36:39]
	v_mfma_f32_16x16x32_bf16 v[40:43], v[136:139], v[152:155], v[40:43]
	v_mfma_f32_16x16x32_bf16 v[44:47], v[140:143], v[152:155], v[44:47]
	ds_read_b128 v[192:195], v232 offset:0
	ds_read_b128 v[196:199], v232 offset:1024
	s_add_u32 m0, s26, 8192
	s_nop 0
	global_load_lds_dwordx4 v226, s[0:1]
	v_mfma_f32_16x16x32_bf16 v[48:51], v[128:131], v[156:159], v[48:51]
	v_mfma_f32_16x16x32_bf16 v[52:55], v[132:135], v[156:159], v[52:55]
	v_mfma_f32_16x16x32_bf16 v[56:59], v[136:139], v[156:159], v[56:59]
	v_mfma_f32_16x16x32_bf16 v[60:63], v[140:143], v[156:159], v[60:63]
	ds_read_b128 v[200:203], v232 offset:2048
	ds_read_b128 v[204:207], v232 offset:3072
	s_add_u32 m0, s26, 12288
	s_nop 0
	global_load_lds_dwordx4 v227, s[0:1]
	v_mfma_f32_16x16x32_bf16 v[64:67], v[128:131], v[160:163], v[64:67]
	v_mfma_f32_16x16x32_bf16 v[68:71], v[132:135], v[160:163], v[68:71]
	v_mfma_f32_16x16x32_bf16 v[72:75], v[136:139], v[160:163], v[72:75]
	v_mfma_f32_16x16x32_bf16 v[76:79], v[140:143], v[160:163], v[76:79]
	ds_read_b128 v[208:211], v232 offset:4096
	s_add_u32 m0, s26, 16384
	s_nop 0
	global_load_lds_dwordx4 v228, s[2:3]
	v_mfma_f32_16x16x32_bf16 v[80:83], v[128:131], v[164:167], v[80:83]
	v_mfma_f32_16x16x32_bf16 v[84:87], v[132:135], v[164:167], v[84:87]
	v_mfma_f32_16x16x32_bf16 v[88:91], v[136:139], v[164:167], v[88:91]
	v_mfma_f32_16x16x32_bf16 v[92:95], v[140:143], v[164:167], v[92:95]
	ds_read_b128 v[212:215], v232 offset:5120
	s_add_u32 m0, s26, 20480
	s_nop 0
	global_load_lds_dwordx4 v229, s[2:3]
	v_mfma_f32_16x16x32_bf16 v[96:99], v[128:131], v[168:171], v[96:99]
	v_mfma_f32_16x16x32_bf16 v[100:103], v[132:135], v[168:171], v[100:103]
	v_mfma_f32_16x16x32_bf16 v[104:107], v[136:139], v[168:171], v[104:107]
	v_mfma_f32_16x16x32_bf16 v[108:111], v[140:143], v[168:171], v[108:111]
	ds_read_b128 v[216:219], v232 offset:6144
	s_add_u32 s0, s0, 64
	s_addc_u32 s1, s1, 0
	s_add_u32 s2, s2, 64
	s_addc_u32 s3, s3, 0
	s_add_u32 s99, s99, 1
	s_add_u32 s30, s30, 24576
	s_cmp_eq_u32 s30, 73728
	s_cselect_b32 s30, 0, s30
	s_add_u32 s31, s31, 24576
	s_cmp_eq_u32 s31, 73728
	s_cselect_b32 s31, 0, s31
	v_mfma_f32_16x16x32_bf16 v[112:115], v[128:131], v[172:175], v[112:115]
	v_mfma_f32_16x16x32_bf16 v[116:119], v[132:135], v[172:175], v[116:119]
	v_mfma_f32_16x16x32_bf16 v[120:123], v[136:139], v[172:175], v[120:123]
	v_mfma_f32_16x16x32_bf16 v[124:127], v[140:143], v[172:175], v[124:127]
	ds_read_b128 v[220:223], v232 offset:7168
	s_cmp_eq_u32 s25, 0
	s_cbranch_scc0 .Lg3d_hi0
	s_setprio 0
; #define LWRITE(S, buf) do { bf16_t* sA_ = sbase + (buf) * BUF; bf16_t* sB_ = sA_ + 256 * PITCH; \
;     _Pragma("unroll") for (int i_ = 0; i_ < 4; ++i_) *(u32x4*)(sA_ + (sr + i_ * 64) * PITCH + scv * 8) = ra[S][i_]; \
;     _Pragma("unroll") for (int i_ = 0; i_ < 2; ++i_) *(u32x4*)(sB_ + (sr + i_ * 64) * PITCH + scv * 8) = rb[S][i_]; } while (0)
; template <class Epi>
; DI void gemm_tile(char* smem, const bf16_t* __restrict__ A0, int lda0, int ksplit, const bf16_t* __restrict__ A1, int lda1,
;                   const bf16_t* __restrict__ Bt, int K, int row0, int col0, const Epi& epi, int tid) {
;     ...
;   __syncthreads();
;   {
;     const int last = nk - 1;
;     GLOAD(0, 0);
;     __builtin_amdgcn_sched_barrier(0);
;     GLOAD(1, 1);
;     __builtin_amdgcn_sched_barrier(0);
;     LWRITE(0, 0);
;     __builtin_amdgcn_sched_barrier(0);
;     GLOAD(0, (2 < last ? 2 : last));
;     __builtin_amdgcn_sched_barrier(0);
;     __syncthreads();
;     for (int kt = 0; kt < nk; kt += 2) {
;       LWRITE(1, 1);
;       __builtin_amdgcn_sched_barrier(0);
;       GLOAD(1, (kt + 3 < last ? kt + 3 : last));
;       __builtin_amdgcn_sched_barrier(0);
;       COMPUTE(0);
;       __syncthreads();
;       LWRITE(0, 0);
;       __builtin_amdgcn_sched_barrier(0);
;       GLOAD(0, (kt + 4 < last ? kt + 4 : last));
;       __builtin_amdgcn_sched_barrier(0);
;       COMPUTE(1);
.Lg3d_hi0:
	s_waitcnt vmcnt(6)
	s_waitcnt lgkmcnt(0)
	s_barrier
	v_add_u32_e32 v232, s31, v230
	v_add_u32_e32 v233, s31, v231
	s_setprio 1
	v_mfma_f32_16x16x32_bf16 v[0:3], v[176:179], v[192:195], v[0:3]
	v_mfma_f32_16x16x32_bf16 v[4:7], v[180:183], v[192:195], v[4:7]
	v_mfma_f32_16x16x32_bf16 v[8:11], v[184:187], v[192:195], v[8:11]
	v_mfma_f32_16x16x32_bf16 v[12:15], v[188:191], v[192:195], v[12:15]
	ds_read_b128 v[128:131], v233 offset:0
	ds_read_b128 v[132:135], v233 offset:1024
	v_mfma_f32_16x16x32_bf16 v[16:19], v[176:179], v[196:199], v[16:19]
	v_mfma_f32_16x16x32_bf16 v[20:23], v[180:183], v[196:199], v[20:23]
	v_mfma_f32_16x16x32_bf16 v[24:27], v[184:187], v[196:199], v[24:27]
	v_mfma_f32_16x16x32_bf16 v[28:31], v[188:191], v[196:199], v[28:31]
	ds_read_b128 v[136:139], v233 offset:2048
	ds_read_b128 v[140:143], v233 offset:3072
	v_mfma_f32_16x16x32_bf16 v[32:35], v[176:179], v[200:203], v[32:35]
	v_mfma_f32_16x16x32_bf16 v[36:39], v[180:183], v[200:203], v[36:39]
	v_mfma_f32_16x16x32_bf16 v[40:43], v[184:187], v[200:203], v[40:43]
	v_mfma_f32_16x16x32_bf16 v[44:47], v[188:191], v[200:203], v[44:47]
	ds_read_b128 v[144:147], v232 offset:0
	ds_read_b128 v[148:151], v232 offset:1024
	v_mfma_f32_16x16x32_bf16 v[48:51], v[176:179], v[204:207], v[48:51]
	v_mfma_f32_16x16x32_bf16 v[52:55], v[180:183], v[204:207], v[52:55]
	v_mfma_f32_16x16x32_bf16 v[56:59], v[184:187], v[204:207], v[56:59]
	v_mfma_f32_16x16x32_bf16 v[60:63], v[188:191], v[204:207], v[60:63]
	ds_read_b128 v[152:155], v232 offset:2048
	ds_read_b128 v[156:159], v232 offset:3072
	v_mfma_f32_16x16x32_bf16 v[64:67], v[176:179], v[208:211], v[64:67]
	v_mfma_f32_16x16x32_bf16 v[68:71], v[180:183], v[208:211], v[68:71]
	v_mfma_f32_16x16x32_bf16 v[72:75], v[184:187], v[208:211], v[72:75]
	v_mfma_f32_16x16x32_bf16 v[76:79], v[188:191], v[208:211], v[76:79]
	ds_read_b128 v[160:163], v232 offset:4096
	v_mfma_f32_16x16x32_bf16 v[80:83], v[176:179], v[212:215], v[80:83]
	v_mfma_f32_16x16x32_bf16 v[84:87], v[180:183], v[212:215], v[84:87]
	v_mfma_f32_16x16x32_bf16 v[88:91], v[184:187], v[212:215], v[88:91]
	v_mfma_f32_16x16x32_bf16 v[92:95], v[188:191], v[212:215], v[92:95]
	ds_read_b128 v[164:167], v232 offset:5120
	v_mfma_f32_16x16x32_bf16 v[96:99], v[176:179], v[216:219], v[96:99]
	v_mfma_f32_16x16x32_bf16 v[100:103], v[180:183], v[216:219], v[100:103]
	v_mfma_f32_16x16x32_bf16 v[104:107], v[184:187], v[216:219], v[104:107]
	v_mfma_f32_16x16x32_bf16 v[108:111], v[188:191], v[216:219], v[108:111]
	ds_read_b128 v[168:171], v232 offset:6144
	s_add_u32 s31, s31, 24576
	s_cmp_eq_u32 s31, 73728
	s_cselect_b32 s31, 0, s31
	v_mfma_f32_16x16x32_bf16 v[112:115], v[176:179], v[220:223], v[112:115]
	v_mfma_f32_16x16x32_bf16 v[116:119], v[180:183], v[220:223], v[116:119]
	v_mfma_f32_16x16x32_bf16 v[120:123], v[184:187], v[220:223], v[120:123]
	v_mfma_f32_16x16x32_bf16 v[124:127], v[188:191], v[220:223], v[124:127]
	ds_read_b128 v[172:175], v232 offset:7168
	s_cmp_eq_u32 s25, 0
	s_cbranch_scc0 .Lg3d_hi1
	s_setprio 0
.Lg3d_hi1:
	s_waitcnt vmcnt(0)
	s_waitcnt lgkmcnt(0)
	s_barrier
	v_add_u32_e32 v232, s31, v230
	v_add_u32_e32 v233, s31, v231
	s_setprio 1
	v_mfma_f32_16x16x32_bf16 v[0:3], v[128:131], v[144:147], v[0:3]
	v_mfma_f32_16x16x32_bf16 v[4:7], v[132:135], v[144:147], v[4:7]
	v_mfma_f32_16x16x32_bf16 v[8:11], v[136:139], v[144:147], v[8:11]
	v_mfma_f32_16x16x32_bf16 v[12:15], v[140:143], v[144:147], v[12:15]
	ds_read_b128 v[176:179], v233 offset:0
	ds_read_b128 v[180:183], v233 offset:1024
	v_mfma_f32_16x16x32_bf16 v[16:19], v[128:131], v[148:151], v[16:19]
	v_mfma_f32_16x16x32_bf16 v[20:23], v[132:135], v[148:151], v[20:23]
	v_mfma_f32_16x16x32_bf16 v[24:27], v[136:139], v[148:151], v[24:27]
	v_mfma_f32_16x16x32_bf16 v[28:31], v[140:143], v[148:151], v[28:31]
	ds_read_b128 v[184:187], v233 offset:2048
	ds_read_b128 v[188:191], v233 offset:3072
	v_mfma_f32_16x16x32_bf16 v[32:35], v[128:131], v[152:155], v[32:35]
	v_mfma_f32_16x16x32_bf16 v[36:39], v[132:135], v[152:155], v[36:39]
	v_mfma_f32_16x16x32_bf16 v[40:43], v[136:139], v[152:155], v[40:43]
	v_mfma_f32_16x16x32_bf16 v[44:47], v[140:143], v[152:155], v[44:47]
	ds_read_b128 v[192:195], v232 offset:0
	ds_read_b128 v[196:199], v232 offset:1024
	v_mfma_f32_16x16x32_bf16 v[48:51], v[128:131], v[156:159], v[48:51]
	v_mfma_f32_16x16x32_bf16 v[52:55], v[132:135], v[156:159], v[52:55]
	v_mfma_f32_16x16x32_bf16 v[56:59], v[136:139], v[156:159], v[56:59]
	v_mfma_f32_16x16x32_bf16 v[60:63], v[140:143], v[156:159], v[60:63]
	ds_read_b128 v[200:203], v232 offset:2048
	ds_read_b128 v[204:207], v232 offset:3072
	v_mfma_f32_16x16x32_bf16 v[64:67], v[128:131], v[160:163], v[64:67]
	v_mfma_f32_16x16x32_bf16 v[68:71], v[132:135], v[160:163], v[68:71]
	v_mfma_f32_16x16x32_bf16 v[72:75], v[136:139], v[160:163], v[72:75]
	v_mfma_f32_16x16x32_bf16 v[76:79], v[140:143], v[160:163], v[76:79]
	ds_read_b128 v[208:211], v232 offset:4096
	v_mfma_f32_16x16x32_bf16 v[80:83], v[128:131], v[164:167], v[80:83]
	v_mfma_f32_16x16x32_bf16 v[84:87], v[132:135], v[164:167], v[84:87]
	v_mfma_f32_16x16x32_bf16 v[88:91], v[136:139], v[164:167], v[88:91]
	v_mfma_f32_16x16x32_bf16 v[92:95], v[140:143], v[164:167], v[92:95]
	ds_read_b128 v[212:215], v232 offset:5120
	v_mfma_f32_16x16x32_bf16 v[96:99], v[128:131], v[168:171], v[96:99]
	v_mfma_f32_16x16x32_bf16 v[100:103], v[132:135], v[168:171], v[100:103]
	v_mfma_f32_16x16x32_bf16 v[104:107], v[136:139], v[168:171], v[104:107]
	v_mfma_f32_16x16x32_bf16 v[108:111], v[140:143], v[168:171], v[108:111]
	ds_read_b128 v[216:219], v232 offset:6144
	s_add_u32 s31, s31, 24576
	s_cmp_eq_u32 s31, 73728
	s_cselect_b32 s31, 0, s31
	v_mfma_f32_16x16x32_bf16 v[112:115], v[128:131], v[172:175], v[112:115]
	v_mfma_f32_16x16x32_bf16 v[116:119], v[132:135], v[172:175], v[116:119]
	v_mfma_f32_16x16x32_bf16 v[120:123], v[136:139], v[172:175], v[120:123]
	v_mfma_f32_16x16x32_bf16 v[124:127], v[140:143], v[172:175], v[124:127]
	ds_read_b128 v[220:223], v232 offset:7168
	s_cmp_eq_u32 s25, 0
	s_cbranch_scc0 .Lg3d_hi2
	s_setprio 0

; template <class Epi>
; DI void gemm_tile(char* smem, const bf16_t* __restrict__ A0, int lda0, int ksplit, const bf16_t* __restrict__ A1, int lda1,
;                   const bf16_t* __restrict__ Bt, int K, int row0, int col0, const Epi& epi, int tid) {
;     ...
; #pragma unroll
;   for (int m = 0; m < 8; ++m)
; #pragma unroll
;     for (int n = 0; n < 4; ++n) epi(row0 + wr * 128 + m * 16 + fr, col0 + wc * 64 + n * 16 + fq * 4, acc[m][n]);
.Lg3d_hi3:
	s_branch .Lg3d_epi
.Lg3d_epi:
	s_nop 7
	s_nop 7
	s_mul_i32 s27, s29, 1024
	s_lshl_b32 s26, s28, 1
	s_add_u32 s27, s27, s26
	s_add_u32 s27, s27, 0x3800000
	s_add_u32 s4, s92, s27
	s_addc_u32 s5, s93, 0
	v_cvt_pk_bf16_f32 v128, v0, v1
	v_cvt_pk_bf16_f32 v129, v2, v3
	ds_write_b64 v236, v[128:129]
	v_cvt_pk_bf16_f32 v130, v4, v5
	v_cvt_pk_bf16_f32 v131, v6, v7
	ds_write_b64 v236, v[130:131] offset:32
	v_cvt_pk_bf16_f32 v132, v8, v9
	v_cvt_pk_bf16_f32 v133, v10, v11
	ds_write_b64 v236, v[132:133] offset:64
	v_cvt_pk_bf16_f32 v134, v12, v13
	v_cvt_pk_bf16_f32 v135, v14, v15
	ds_write_b64 v236, v[134:135] offset:96
	v_cvt_pk_bf16_f32 v136, v16, v17
	v_cvt_pk_bf16_f32 v137, v18, v19
	ds_write_b64 v236, v[136:137] offset:2304
	v_cvt_pk_bf16_f32 v138, v20, v21
	v_cvt_pk_bf16_f32 v139, v22, v23
	ds_write_b64 v236, v[138:139] offset:2336
	v_cvt_pk_bf16_f32 v140, v24, v25
	v_cvt_pk_bf16_f32 v141, v26, v27
	ds_write_b64 v236, v[140:141] offset:2368
	v_cvt_pk_bf16_f32 v142, v28, v29
	v_cvt_pk_bf16_f32 v143, v30, v31
	ds_write_b64 v236, v[142:143] offset:2400
	v_cvt_pk_bf16_f32 v144, v32, v33
	v_cvt_pk_bf16_f32 v145, v34, v35
	ds_write_b64 v236, v[144:145] offset:4608
	v_cvt_pk_bf16_f32 v146, v36, v37
	v_cvt_pk_bf16_f32 v147, v38, v39
	ds_write_b64 v236, v[146:147] offset:4640
	v_cvt_pk_bf16_f32 v148, v40, v41
	v_cvt_pk_bf16_f32 v149, v42, v43
	ds_write_b64 v236, v[148:149] offset:4672
	v_cvt_pk_bf16_f32 v150, v44, v45
	v_cvt_pk_bf16_f32 v151, v46, v47
	ds_write_b64 v236, v[150:151] offset:4704
	v_cvt_pk_bf16_f32 v152, v48, v49
	v_cvt_pk_bf16_f32 v153, v50, v51
	ds_write_b64 v236, v[152:153] offset:6912
	v_cvt_pk_bf16_f32 v154, v52, v53
	v_cvt_pk_bf16_f32 v155, v54, v55
	ds_write_b64 v236, v[154:155] offset:6944
	v_cvt_pk_bf16_f32 v156, v56, v57
	v_cvt_pk_bf16_f32 v157, v58, v59
	ds_write_b64 v236, v[156:157] offset:6976
	v_cvt_pk_bf16_f32 v158, v60, v61
	v_cvt_pk_bf16_f32 v159, v62, v63
	ds_write_b64 v236, v[158:159] offset:7008
	v_cvt_pk_bf16_f32 v128, v64, v65
	v_cvt_pk_bf16_f32 v129, v66, v67
	ds_write_b64 v236, v[128:129] offset:9216
	v_cvt_pk_bf16_f32 v130, v68, v69
	v_cvt_pk_bf16_f32 v131, v70, v71
	ds_write_b64 v236, v[130:131] offset:9248
	v_cvt_pk_bf16_f32 v132, v72, v73
	v_cvt_pk_bf16_f32 v133, v74, v75
	ds_write_b64 v236, v[132:133] offset:9280
	v_cvt_pk_bf16_f32 v134, v76, v77
	v_cvt_pk_bf16_f32 v135, v78, v79
	ds_write_b64 v236, v[134:135] offset:9312
	v_cvt_pk_bf16_f32 v136, v80, v81
	v_cvt_pk_bf16_f32 v137, v82, v83
	ds_write_b64 v236, v[136:137] offset:11520
	v_cvt_pk_bf16_f32 v138, v84, v85
	v_cvt_pk_bf16_f32 v139, v86, v87
	ds_write_b64 v236, v[138:139] offset:11552
	v_cvt_pk_bf16_f32 v140, v88, v89
	v_cvt_pk_bf16_f32 v141, v90, v91
	ds_write_b64 v236, v[140:141] offset:11584
	v_cvt_pk_bf16_f32 v142, v92, v93
	v_cvt_pk_bf16_f32 v143, v94, v95
	ds_write_b64 v236, v[142:143] offset:11616
	v_cvt_pk_bf16_f32 v144, v96, v97
	v_cvt_pk_bf16_f32 v145, v98, v99
	ds_write_b64 v236, v[144:145] offset:13824
	v_cvt_pk_bf16_f32 v146, v100, v101
	v_cvt_pk_bf16_f32 v147, v102, v103
	ds_write_b64 v236, v[146:147] offset:13856
	v_cvt_pk_bf16_f32 v148, v104, v105
	v_cvt_pk_bf16_f32 v149, v106, v107
	ds_write_b64 v236, v[148:149] offset:13888
	v_cvt_pk_bf16_f32 v150, v108, v109
	v_cvt_pk_bf16_f32 v151, v110, v111
	ds_write_b64 v236, v[150:151] offset:13920
	v_cvt_pk_bf16_f32 v152, v112, v113
	v_cvt_pk_bf16_f32 v153, v114, v115
	ds_write_b64 v236, v[152:153] offset:16128
	v_cvt_pk_bf16_f32 v154, v116, v117
	v_cvt_pk_bf16_f32 v155, v118, v119
	ds_write_b64 v236, v[154:155] offset:16160
	v_cvt_pk_bf16_f32 v156, v120, v121
	v_cvt_pk_bf16_f32 v157, v122, v123
	ds_write_b64 v236, v[156:157] offset:16192
	v_cvt_pk_bf16_f32 v158, v124, v125
	v_cvt_pk_bf16_f32 v159, v126, v127
	ds_write_b64 v236, v[158:159] offset:16224
	s_waitcnt lgkmcnt(0)
	ds_read_b128 v[128:131], v237
	ds_read_b128 v[132:135], v237 offset:1152
	ds_read_b128 v[136:139], v237 offset:2304
	ds_read_b128 v[140:143], v237 offset:3456
	ds_read_b128 v[144:147], v237 offset:4608
	ds_read_b128 v[148:151], v237 offset:5760
	ds_read_b128 v[152:155], v237 offset:6912
	ds_read_b128 v[156:159], v237 offset:8064
	ds_read_b128 v[160:163], v237 offset:9216
	ds_read_b128 v[164:167], v237 offset:10368
	ds_read_b128 v[168:171], v237 offset:11520
	ds_read_b128 v[172:175], v237 offset:12672
	ds_read_b128 v[176:179], v237 offset:13824
	ds_read_b128 v[180:183], v237 offset:14976
	ds_read_b128 v[184:187], v237 offset:16128
	ds_read_b128 v[188:191], v237 offset:17280
	s_waitcnt lgkmcnt(15)
	global_store_dwordx4 v238, v[128:131], s[4:5] nt
	s_add_u32 s4, s4, 0x2000
	s_addc_u32 s5, s5, 0
	s_waitcnt lgkmcnt(14)
	global_store_dwordx4 v238, v[132:135], s[4:5] nt
	s_add_u32 s4, s4, 0x2000
	s_addc_u32 s5, s5, 0
	s_waitcnt lgkmcnt(13)
	global_store_dwordx4 v238, v[136:139], s[4:5] nt
	s_add_u32 s4, s4, 0x2000
	s_addc_u32 s5, s5, 0
	s_waitcnt lgkmcnt(12)
	global_store_dwordx4 v238, v[140:143], s[4:5] nt
	s_add_u32 s4, s4, 0x2000
	s_addc_u32 s5, s5, 0
	s_waitcnt lgkmcnt(11)
	global_store_dwordx4 v238, v[144:147], s[4:5] nt
	s_add_u32 s4, s4, 0x2000
	s_addc_u32 s5, s5, 0
	s_waitcnt lgkmcnt(10)
	global_store_dwordx4 v238, v[148:151], s[4:5] nt
	s_add_u32 s4, s4, 0x2000
	s_addc_u32 s5, s5, 0
	s_waitcnt lgkmcnt(9)
	global_store_dwordx4 v238, v[152:155], s[4:5] nt
	s_add_u32 s4, s4, 0x2000
	s_addc_u32 s5, s5, 0
	s_waitcnt lgkmcnt(8)
	global_store_dwordx4 v238, v[156:159], s[4:5] nt
	s_add_u32 s4, s4, 0x2000
	s_addc_u32 s5, s5, 0
	s_waitcnt lgkmcnt(7)
	global_store_dwordx4 v238, v[160:163], s[4:5] nt
	s_add_u32 s4, s4, 0x2000
	s_addc_u32 s5, s5, 0
	s_waitcnt lgkmcnt(6)
	global_store_dwordx4 v238, v[164:167], s[4:5] nt
	s_add_u32 s4, s4, 0x2000
	s_addc_u32 s5, s5, 0
	s_waitcnt lgkmcnt(5)
	global_store_dwordx4 v238, v[168:171], s[4:5] nt
	s_add_u32 s4, s4, 0x2000
	s_addc_u32 s5, s5, 0
	s_waitcnt lgkmcnt(4)
	global_store_dwordx4 v238, v[172:175], s[4:5] nt
	s_add_u32 s4, s4, 0x2000
	s_addc_u32 s5, s5, 0
	s_waitcnt lgkmcnt(3)
	global_store_dwordx4 v238, v[176:179], s[4:5] nt
	s_add_u32 s4, s4, 0x2000
	s_addc_u32 s5, s5, 0
	s_waitcnt lgkmcnt(2)
	global_store_dwordx4 v238, v[180:183], s[4:5] nt
	s_add_u32 s4, s4, 0x2000
	s_addc_u32 s5, s5, 0
	s_waitcnt lgkmcnt(1)
	global_store_dwordx4 v238, v[184:187], s[4:5] nt
	s_add_u32 s4, s4, 0x2000
	s_addc_u32 s5, s5, 0
	s_waitcnt lgkmcnt(0)
	global_store_dwordx4 v238, v[188:191], s[4:5] nt
	s_nop 1
	s_add_u32 s15, s15, 64
	s_branch .Lg3d_tile

; template <class Epi>
; DI void gemm_tile(char* smem, const bf16_t* __restrict__ A0, int lda0, int ksplit, const bf16_t* __restrict__ A1, int lda1,
;                   const bf16_t* __restrict__ Bt, int K, int row0, int col0, const Epi& epi, int tid) {
;   constexpr int BK = 32, PITCH = 40, BUF = (256 + 128) * PITCH;
;   bf16_t* sbase = (bf16_t*)smem;
;   const int lane = tid & 63, wid = tid >> 6, wr = wid >> 1, wc = wid & 1, fr = lane & 15, fq = lane >> 4;
;   f32x4 acc[8][4];
; #pragma unroll
;   for (int m = 0; m < 8; ++m)
; #pragma unroll
;     for (int n = 0; n < 4; ++n) acc[m][n] = (f32x4){0.f, 0.f, 0.f, 0.f};
;   u32x4 ra[2][4], rb[2][2];
;   const int nk = K / BK;
;   const int sr = tid >> 2, scv = tid & 3;
; template <class Epi>
; DI void gemm_phase(char* smem, const bf16_t* A0, int lda0, int ksplit, const bf16_t* A1, int lda1, const bf16_t* Bt, int K, int nN, const Epi& epi, int tid) {
;   const int G = gridDim.x;
;   if ((G & 7) == 0) {
;     const int x = blockIdx.x & 7, l = blockIdx.x >> 3, L = G >> 3, per = 8 * nN, tot = 2 * per;
;     for (int q = l; q < tot; q += L) { const int rgl = q / per, rem = q % per, ct = rem >> 3, rt = (x * 2 + rgl) * 8 + (rem & 7);
;       gemm_tile(smem, A0, lda0, ksplit, A1, lda1, Bt, K, rt * 256, ct * 128, epi, tid); }
.LBB0_855:
	s_cmp_gt_i32 s94, 6
	s_cselect_b64 s[0:1], -1, 0
	s_cmp_lt_i32 s95, 7
	s_cselect_b64 s[2:3], -1, 0
	s_or_b64 s[0:1], s[0:1], s[2:3]
	s_and_b64 vcc, exec, s[0:1]
	s_cbranch_vccnz .LBB0_883
	s_add_u32 s0, s92, 0x7800000
	s_load_dword s12, s[74:75], 0x180
	s_addc_u32 s1, s93, 0
	s_add_u32 s6, s92, 0xe800000
	s_addc_u32 s7, s93, 0
	s_add_u32 s2, s92, 0x8c0000
	s_addc_u32 s3, s93, 0
	s_and_b32 s8, s72, 0xffffffc0
	v_mbcnt_hi_u32_b32 v195, -1, v194
	s_waitcnt lgkmcnt(0)
	s_and_b32 s10, s12, 7
	s_cmp_lg_u32 s10, 0
	s_waitcnt vmcnt(16)
	v_add_u32_e32 v196, s8, v195
	v_mbcnt_lo_u32_b32 v240, -1, 0
	v_mbcnt_hi_u32_b32 v240, -1, v240
	s_lshr_b32 s20, s72, 6
	s_lshl_b32 s13, s20, 10
	v_and_b32_e32 v241, 15, v240
	v_lshrrev_b32_e32 v242, 4, v240
	v_bfe_u32 v243, v240, 3, 1
	v_mul_u32_u24_e32 v243, 3, v243
	v_xor_b32_e32 v243, v242, v243
	v_lshlrev_b32_e32 v243, 4, v243
	v_lshl_add_u32 v243, v241, 6, v243
	s_lshr_b32 s19, s20, 1
	s_lshl_b32 s19, s19, 13
	v_add_u32_e32 v230, s19, v243
	s_and_b32 s19, s20, 1
	s_lshl_b32 s19, s19, 12
	s_add_u32 s19, s19, 16384
	v_add_u32_e32 v231, s19, v243
	s_lshr_b32 s19, s20, 1
	s_lshl_b32 s19, s19, 7
	v_add_u32_e32 v244, s19, v241
	s_and_b32 s19, s20, 1
	s_lshl_b32 s19, s19, 6
	v_lshl_add_u32 v245, v242, 2, s19
	s_movk_i32 s19, 0x1000
	v_mul_lo_u32 v246, v244, s19
	v_lshl_add_u32 v234, v245, 2, v246
	v_lshrrev_b32_e32 v241, 2, v240
	s_lshl_b32 s19, s20, 4
	v_add_u32_e32 v241, s19, v241
	v_bfe_u32 v242, v240, 5, 1
	v_mul_u32_u24_e32 v242, 3, v242
	v_and_b32_e32 v243, 3, v240
	v_xor_b32_e32 v243, v243, v242
	v_lshlrev_b32_e32 v243, 4, v243
	s_mov_b32 s19, 1024
	v_mad_u32_u24 v224, v241, s19, v243
	v_add_u32_e32 v225, 0x10000, v224
	v_add_u32_e32 v226, 0x20000, v224
	v_add_u32_e32 v227, 0x30000, v224
	s_mov_b32 s19, 5184
	v_mad_u32_u24 v236, v241, s19, v243
	v_add_u32_e32 v237, 0x51000, v236
	v_add_u32_e32 v238, 0xa2000, v236
	v_add_u32_e32 v239, 0xf3000, v236
	v_mov_b32_e32 v248, v224
	v_mov_b32_e32 v249, v225
	v_mov_b32_e32 v250, v226
	v_mov_b32_e32 v251, v227
	s_mov_b32 s19, 3072
	v_mad_u32_u24 v228, v241, s19, v243
	v_add_u32_e32 v229, 0x30000, v228
	s_load_dwordx2 s[6:7], s[74:75], 0x168
	s_load_dwordx2 s[14:15], s[74:75], 0x0
	v_mbcnt_lo_u32_b32 v240, -1, 0
	v_mbcnt_hi_u32_b32 v240, -1, v240
	s_lshr_b32 s20, s72, 6
	s_mul_i32 s19, s20, 17408
	v_and_b32_e32 v241, 15, v240
	v_lshrrev_b32_e32 v242, 4, v240
	v_mul_u32_u24_e32 v243, 0x110, v241
	v_lshl_add_u32 v243, v242, 4, v243
	v_add_u32_e32 v245, s19, v243
	v_mul_u32_u24_e32 v243, 0x110, v242
	v_lshl_add_u32 v243, v241, 4, v243
	v_add_u32_e32 v246, s19, v243
	s_lshr_b32 s19, s20, 1
	s_lshl_b32 s19, s19, 7
	v_add_u32_e32 v243, s19, v242
	v_lshlrev_b32_e32 v243, 12, v243
	s_and_b32 s19, s20, 1
	s_lshl_b32 s19, s19, 8
	v_lshl_add_u32 v244, v241, 4, s19
	v_add_u32_e32 v247, v243, v244
	s_cmpk_gt_u32 s96, 0xff
	s_cselect_b32 s18, 1, 0
	s_cmpk_gt_u32 s96, 0xff
	s_cbranch_scc0 .Lg6_prio
	s_setprio 1

; #define LWRITE(S, buf) do { bf16_t* sA_ = sbase + (buf) * BUF; bf16_t* sB_ = sA_ + 256 * PITCH; \
;     _Pragma("unroll") for (int i_ = 0; i_ < 4; ++i_) *(u32x4*)(sA_ + (sr + i_ * 64) * PITCH + scv * 8) = ra[S][i_]; \
;     _Pragma("unroll") for (int i_ = 0; i_ < 2; ++i_) *(u32x4*)(sB_ + (sr + i_ * 64) * PITCH + scv * 8) = rb[S][i_]; } while (0)
; template <class Epi>
; DI void gemm_tile(char* smem, const bf16_t* __restrict__ A0, int lda0, int ksplit, const bf16_t* __restrict__ A1, int lda1,
;                   const bf16_t* __restrict__ Bt, int K, int row0, int col0, const Epi& epi, int tid) {
;     ...
;   __syncthreads();
;   {
;     const int last = nk - 1;
;     GLOAD(0, 0);
;     __builtin_amdgcn_sched_barrier(0);
;     GLOAD(1, 1);
;     __builtin_amdgcn_sched_barrier(0);
;     LWRITE(0, 0);
;     __builtin_amdgcn_sched_barrier(0);
;     GLOAD(0, (2 < last ? 2 : last));
;     __builtin_amdgcn_sched_barrier(0);
;     __syncthreads();
;     for (int kt = 0; kt < nk; kt += 2) {
;       LWRITE(1, 1);
;       __builtin_amdgcn_sched_barrier(0);
;       GLOAD(1, (kt + 3 < last ? kt + 3 : last));
;       __builtin_amdgcn_sched_barrier(0);
;       COMPUTE(0);
;       __syncthreads();
;       LWRITE(0, 0);
;       __builtin_amdgcn_sched_barrier(0);
;       GLOAD(0, (kt + 4 < last ? kt + 4 : last));
;       __builtin_amdgcn_sched_barrier(0);
;       COMPUTE(1);
;       __syncthreads();
;     }
.Lg6_swb0:
	s_waitcnt vmcnt(6)
	s_waitcnt lgkmcnt(0)
	s_barrier
	v_add_u32_e32 v232, s100, v230
	v_add_u32_e32 v233, s100, v231
	s_add_u32 s19, s99, s13
	s_setprio 1
	v_mfma_f32_16x16x32_bf16 v[0:3], v[128:131], v[144:147], v[0:3]
	v_mfma_f32_16x16x32_bf16 v[4:7], v[132:135], v[144:147], v[4:7]
	v_mfma_f32_16x16x32_bf16 v[8:11], v[136:139], v[144:147], v[8:11]
	v_mfma_f32_16x16x32_bf16 v[12:15], v[140:143], v[144:147], v[12:15]
	ds_read_b128 v[176:179], v233 offset:0
	ds_read_b128 v[180:183], v233 offset:1024
	s_add_u32 m0, s19, 0
	s_nop 0
	global_load_lds_dwordx4 v224, s[0:1]
	v_mfma_f32_16x16x32_bf16 v[16:19], v[128:131], v[148:151], v[16:19]
	v_mfma_f32_16x16x32_bf16 v[20:23], v[132:135], v[148:151], v[20:23]
	v_mfma_f32_16x16x32_bf16 v[24:27], v[136:139], v[148:151], v[24:27]
	v_mfma_f32_16x16x32_bf16 v[28:31], v[140:143], v[148:151], v[28:31]
	ds_read_b128 v[184:187], v233 offset:2048
	ds_read_b128 v[188:191], v233 offset:3072
	s_add_u32 m0, s19, 4096
	s_nop 0
	global_load_lds_dwordx4 v225, s[0:1]
	v_mfma_f32_16x16x32_bf16 v[32:35], v[128:131], v[152:155], v[32:35]
	v_mfma_f32_16x16x32_bf16 v[36:39], v[132:135], v[152:155], v[36:39]
	v_mfma_f32_16x16x32_bf16 v[40:43], v[136:139], v[152:155], v[40:43]
	v_mfma_f32_16x16x32_bf16 v[44:47], v[140:143], v[152:155], v[44:47]
	ds_read_b128 v[192:195], v232 offset:0
	ds_read_b128 v[196:199], v232 offset:1024
	s_add_u32 m0, s19, 8192
	s_nop 0
	global_load_lds_dwordx4 v226, s[0:1]
	v_mfma_f32_16x16x32_bf16 v[48:51], v[128:131], v[156:159], v[48:51]
	v_mfma_f32_16x16x32_bf16 v[52:55], v[132:135], v[156:159], v[52:55]
	v_mfma_f32_16x16x32_bf16 v[56:59], v[136:139], v[156:159], v[56:59]
	v_mfma_f32_16x16x32_bf16 v[60:63], v[140:143], v[156:159], v[60:63]
	ds_read_b128 v[200:203], v232 offset:2048
	ds_read_b128 v[204:207], v232 offset:3072
	s_add_u32 m0, s19, 12288
	s_nop 0
	global_load_lds_dwordx4 v227, s[0:1]
	v_mfma_f32_16x16x32_bf16 v[64:67], v[128:131], v[160:163], v[64:67]
	v_mfma_f32_16x16x32_bf16 v[68:71], v[132:135], v[160:163], v[68:71]
	v_mfma_f32_16x16x32_bf16 v[72:75], v[136:139], v[160:163], v[72:75]
	v_mfma_f32_16x16x32_bf16 v[76:79], v[140:143], v[160:163], v[76:79]
	ds_read_b128 v[208:211], v232 offset:4096
	s_add_u32 m0, s19, 16384
	s_nop 0
	global_load_lds_dwordx4 v228, s[2:3]
	v_mfma_f32_16x16x32_bf16 v[80:83], v[128:131], v[164:167], v[80:83]
	v_mfma_f32_16x16x32_bf16 v[84:87], v[132:135], v[164:167], v[84:87]
	v_mfma_f32_16x16x32_bf16 v[88:91], v[136:139], v[164:167], v[88:91]
	v_mfma_f32_16x16x32_bf16 v[92:95], v[140:143], v[164:167], v[92:95]
	ds_read_b128 v[212:215], v232 offset:5120
	s_add_u32 m0, s19, 20480
	s_nop 0
	global_load_lds_dwordx4 v229, s[2:3]
	v_mfma_f32_16x16x32_bf16 v[96:99], v[128:131], v[168:171], v[96:99]
	v_mfma_f32_16x16x32_bf16 v[100:103], v[132:135], v[168:171], v[100:103]
	v_mfma_f32_16x16x32_bf16 v[104:107], v[136:139], v[168:171], v[104:107]
	v_mfma_f32_16x16x32_bf16 v[108:111], v[140:143], v[168:171], v[108:111]
	ds_read_b128 v[216:219], v232 offset:6144
	s_add_u32 s0, s0, 64
	s_addc_u32 s1, s1, 0
	s_add_u32 s2, s2, 64
	s_addc_u32 s3, s3, 0
	s_add_u32 s22, s22, 1
	s_add_u32 s99, s99, 24576
	s_cmp_eq_u32 s99, 73728
	s_cselect_b32 s99, 0, s99
	s_add_u32 s100, s100, 24576
	s_cmp_eq_u32 s100, 73728
	s_cselect_b32 s100, 0, s100
	v_mfma_f32_16x16x32_bf16 v[112:115], v[128:131], v[172:175], v[112:115]
	v_mfma_f32_16x16x32_bf16 v[116:119], v[132:135], v[172:175], v[116:119]
	v_mfma_f32_16x16x32_bf16 v[120:123], v[136:139], v[172:175], v[120:123]
	v_mfma_f32_16x16x32_bf16 v[124:127], v[140:143], v[172:175], v[124:127]
	ds_read_b128 v[220:223], v232 offset:7168
	s_cmp_eq_u32 s18, 0
	s_cbranch_scc0 .Lg6_hi0
	s_setprio 0

; #define LWRITE(S, buf) do { bf16_t* sA_ = sbase + (buf) * BUF; bf16_t* sB_ = sA_ + 256 * PITCH; \
;     _Pragma("unroll") for (int i_ = 0; i_ < 4; ++i_) *(u32x4*)(sA_ + (sr + i_ * 64) * PITCH + scv * 8) = ra[S][i_]; \
;     _Pragma("unroll") for (int i_ = 0; i_ < 2; ++i_) *(u32x4*)(sB_ + (sr + i_ * 64) * PITCH + scv * 8) = rb[S][i_]; } while (0)
; template <class Epi>
; DI void gemm_tile(char* smem, const bf16_t* __restrict__ A0, int lda0, int ksplit, const bf16_t* __restrict__ A1, int lda1,
;                   const bf16_t* __restrict__ Bt, int K, int row0, int col0, const Epi& epi, int tid) {
;     ...
;   __syncthreads();
;   {
;     const int last = nk - 1;
;     GLOAD(0, 0);
;     __builtin_amdgcn_sched_barrier(0);
;     GLOAD(1, 1);
;     __builtin_amdgcn_sched_barrier(0);
;     LWRITE(0, 0);
;     __builtin_amdgcn_sched_barrier(0);
;     GLOAD(0, (2 < last ? 2 : last));
;     __builtin_amdgcn_sched_barrier(0);
;     __syncthreads();
;     for (int kt = 0; kt < nk; kt += 2) {
;       LWRITE(1, 1);
;       __builtin_amdgcn_sched_barrier(0);
;       GLOAD(1, (kt + 3 < last ? kt + 3 : last));
;       __builtin_amdgcn_sched_barrier(0);
;       COMPUTE(0);
;       __syncthreads();
;       LWRITE(0, 0);
;       __builtin_amdgcn_sched_barrier(0);
;       GLOAD(0, (kt + 4 < last ? kt + 4 : last));
;       __builtin_amdgcn_sched_barrier(0);
;       COMPUTE(1);
;       __syncthreads();
;     }
.Lg6_swb1:
	s_waitcnt vmcnt(6)
	s_waitcnt lgkmcnt(0)
	s_barrier
	v_add_u32_e32 v232, s100, v230
	v_add_u32_e32 v233, s100, v231
	s_add_u32 s19, s99, s13
	s_setprio 1
	v_mfma_f32_16x16x32_bf16 v[0:3], v[176:179], v[192:195], v[0:3]
	v_mfma_f32_16x16x32_bf16 v[4:7], v[180:183], v[192:195], v[4:7]
	v_mfma_f32_16x16x32_bf16 v[8:11], v[184:187], v[192:195], v[8:11]
	v_mfma_f32_16x16x32_bf16 v[12:15], v[188:191], v[192:195], v[12:15]
	ds_read_b128 v[128:131], v233 offset:0
	ds_read_b128 v[132:135], v233 offset:1024
	s_add_u32 m0, s19, 0
	s_nop 0
	global_load_lds_dwordx4 v224, s[0:1]
	v_mfma_f32_16x16x32_bf16 v[16:19], v[176:179], v[196:199], v[16:19]
	v_mfma_f32_16x16x32_bf16 v[20:23], v[180:183], v[196:199], v[20:23]
	v_mfma_f32_16x16x32_bf16 v[24:27], v[184:187], v[196:199], v[24:27]
	v_mfma_f32_16x16x32_bf16 v[28:31], v[188:191], v[196:199], v[28:31]
	ds_read_b128 v[136:139], v233 offset:2048
	ds_read_b128 v[140:143], v233 offset:3072
	s_add_u32 m0, s19, 4096
	s_nop 0
	global_load_lds_dwordx4 v225, s[0:1]
	v_mfma_f32_16x16x32_bf16 v[32:35], v[176:179], v[200:203], v[32:35]
	v_mfma_f32_16x16x32_bf16 v[36:39], v[180:183], v[200:203], v[36:39]
	v_mfma_f32_16x16x32_bf16 v[40:43], v[184:187], v[200:203], v[40:43]
	v_mfma_f32_16x16x32_bf16 v[44:47], v[188:191], v[200:203], v[44:47]
	ds_read_b128 v[144:147], v232 offset:0
	ds_read_b128 v[148:151], v232 offset:1024
	s_add_u32 m0, s19, 8192
	s_nop 0
	global_load_lds_dwordx4 v226, s[0:1]
	v_mfma_f32_16x16x32_bf16 v[48:51], v[176:179], v[204:207], v[48:51]
	v_mfma_f32_16x16x32_bf16 v[52:55], v[180:183], v[204:207], v[52:55]
	v_mfma_f32_16x16x32_bf16 v[56:59], v[184:187], v[204:207], v[56:59]
	v_mfma_f32_16x16x32_bf16 v[60:63], v[188:191], v[204:207], v[60:63]
	ds_read_b128 v[152:155], v232 offset:2048
	ds_read_b128 v[156:159], v232 offset:3072
	s_add_u32 m0, s19, 12288
	s_nop 0
	global_load_lds_dwordx4 v227, s[0:1]
	v_mfma_f32_16x16x32_bf16 v[64:67], v[176:179], v[208:211], v[64:67]
	v_mfma_f32_16x16x32_bf16 v[68:71], v[180:183], v[208:211], v[68:71]
	v_mfma_f32_16x16x32_bf16 v[72:75], v[184:187], v[208:211], v[72:75]
	v_mfma_f32_16x16x32_bf16 v[76:79], v[188:191], v[208:211], v[76:79]
	ds_read_b128 v[160:163], v232 offset:4096
	s_add_u32 m0, s19, 16384
	s_nop 0
	global_load_lds_dwordx4 v228, s[2:3]
	v_mfma_f32_16x16x32_bf16 v[80:83], v[176:179], v[212:215], v[80:83]
	v_mfma_f32_16x16x32_bf16 v[84:87], v[180:183], v[212:215], v[84:87]
	v_mfma_f32_16x16x32_bf16 v[88:91], v[184:187], v[212:215], v[88:91]
	v_mfma_f32_16x16x32_bf16 v[92:95], v[188:191], v[212:215], v[92:95]
	ds_read_b128 v[164:167], v232 offset:5120
	s_add_u32 m0, s19, 20480
	s_nop 0
	global_load_lds_dwordx4 v229, s[2:3]
	v_mfma_f32_16x16x32_bf16 v[96:99], v[176:179], v[216:219], v[96:99]
	v_mfma_f32_16x16x32_bf16 v[100:103], v[180:183], v[216:219], v[100:103]
	v_mfma_f32_16x16x32_bf16 v[104:107], v[184:187], v[216:219], v[104:107]
	v_mfma_f32_16x16x32_bf16 v[108:111], v[188:191], v[216:219], v[108:111]
	ds_read_b128 v[168:171], v232 offset:6144
	s_add_u32 s0, s0, 64
	s_addc_u32 s1, s1, 0
	s_add_u32 s2, s2, 64
	s_addc_u32 s3, s3, 0
	s_add_u32 s22, s22, 1
	s_add_u32 s99, s99, 24576
	s_cmp_eq_u32 s99, 73728
	s_cselect_b32 s99, 0, s99
	s_add_u32 s100, s100, 24576
	s_cmp_eq_u32 s100, 73728
	s_cselect_b32 s100, 0, s100
	v_mfma_f32_16x16x32_bf16 v[112:115], v[176:179], v[220:223], v[112:115]
	v_mfma_f32_16x16x32_bf16 v[116:119], v[180:183], v[220:223], v[116:119]
	v_mfma_f32_16x16x32_bf16 v[120:123], v[184:187], v[220:223], v[120:123]
	v_mfma_f32_16x16x32_bf16 v[124:127], v[188:191], v[220:223], v[124:127]
	ds_read_b128 v[172:175], v232 offset:7168
	s_cmp_eq_u32 s18, 0
	s_cbranch_scc0 .Lg6_hi1
	s_setprio 0
.Lg6_hi1:
	s_add_u32 s101, s101, 2
	s_cmp_lt_u32 s101, 44
	s_cbranch_scc1 .Lg6_kloop
	s_cmp_eq_u32 s22, 16
	s_cbranch_scc1 .Lg6_sw2

; #define LWRITE(S, buf) do { bf16_t* sA_ = sbase + (buf) * BUF; bf16_t* sB_ = sA_ + 256 * PITCH; \
;     _Pragma("unroll") for (int i_ = 0; i_ < 4; ++i_) *(u32x4*)(sA_ + (sr + i_ * 64) * PITCH + scv * 8) = ra[S][i_]; \
;     _Pragma("unroll") for (int i_ = 0; i_ < 2; ++i_) *(u32x4*)(sB_ + (sr + i_ * 64) * PITCH + scv * 8) = rb[S][i_]; } while (0)
; template <class Epi>
; DI void gemm_tile(char* smem, const bf16_t* __restrict__ A0, int lda0, int ksplit, const bf16_t* __restrict__ A1, int lda1,
;                   const bf16_t* __restrict__ Bt, int K, int row0, int col0, const Epi& epi, int tid) {
;     ...
;     for (int kt = 0; kt < nk; kt += 2) {
;       LWRITE(1, 1);
;       __builtin_amdgcn_sched_barrier(0);
;       GLOAD(1, (kt + 3 < last ? kt + 3 : last));
;       __builtin_amdgcn_sched_barrier(0);
;       COMPUTE(0);
;       __syncthreads();
;       LWRITE(0, 0);
;       __builtin_amdgcn_sched_barrier(0);
;       GLOAD(0, (kt + 4 < last ? kt + 4 : last));
;       __builtin_amdgcn_sched_barrier(0);
;       COMPUTE(1);
;       __syncthreads();
;     }
.Lg6_hi2:
	s_waitcnt vmcnt(6)
	s_waitcnt lgkmcnt(0)
	s_barrier
	v_add_u32_e32 v232, s100, v230
	v_add_u32_e32 v233, s100, v231
	s_setprio 1
	v_mfma_f32_16x16x32_bf16 v[0:3], v[176:179], v[192:195], v[0:3]
	v_mfma_f32_16x16x32_bf16 v[4:7], v[180:183], v[192:195], v[4:7]
	v_mfma_f32_16x16x32_bf16 v[8:11], v[184:187], v[192:195], v[8:11]
	v_mfma_f32_16x16x32_bf16 v[12:15], v[188:191], v[192:195], v[12:15]
	ds_read_b128 v[128:131], v233 offset:0
	ds_read_b128 v[132:135], v233 offset:1024
	v_mfma_f32_16x16x32_bf16 v[16:19], v[176:179], v[196:199], v[16:19]
	v_mfma_f32_16x16x32_bf16 v[20:23], v[180:183], v[196:199], v[20:23]
	v_mfma_f32_16x16x32_bf16 v[24:27], v[184:187], v[196:199], v[24:27]
	v_mfma_f32_16x16x32_bf16 v[28:31], v[188:191], v[196:199], v[28:31]
	ds_read_b128 v[136:139], v233 offset:2048
	ds_read_b128 v[140:143], v233 offset:3072
	v_mfma_f32_16x16x32_bf16 v[32:35], v[176:179], v[200:203], v[32:35]
	v_mfma_f32_16x16x32_bf16 v[36:39], v[180:183], v[200:203], v[36:39]
	v_mfma_f32_16x16x32_bf16 v[40:43], v[184:187], v[200:203], v[40:43]
	v_mfma_f32_16x16x32_bf16 v[44:47], v[188:191], v[200:203], v[44:47]
	ds_read_b128 v[144:147], v232 offset:0
	ds_read_b128 v[148:151], v232 offset:1024
	v_mfma_f32_16x16x32_bf16 v[48:51], v[176:179], v[204:207], v[48:51]
	v_mfma_f32_16x16x32_bf16 v[52:55], v[180:183], v[204:207], v[52:55]
	v_mfma_f32_16x16x32_bf16 v[56:59], v[184:187], v[204:207], v[56:59]
	v_mfma_f32_16x16x32_bf16 v[60:63], v[188:191], v[204:207], v[60:63]
	ds_read_b128 v[152:155], v232 offset:2048
	ds_read_b128 v[156:159], v232 offset:3072
	v_mfma_f32_16x16x32_bf16 v[64:67], v[176:179], v[208:211], v[64:67]
	v_mfma_f32_16x16x32_bf16 v[68:71], v[180:183], v[208:211], v[68:71]
	v_mfma_f32_16x16x32_bf16 v[72:75], v[184:187], v[208:211], v[72:75]
	v_mfma_f32_16x16x32_bf16 v[76:79], v[188:191], v[208:211], v[76:79]
	ds_read_b128 v[160:163], v232 offset:4096
	v_mfma_f32_16x16x32_bf16 v[80:83], v[176:179], v[212:215], v[80:83]
	v_mfma_f32_16x16x32_bf16 v[84:87], v[180:183], v[212:215], v[84:87]
	v_mfma_f32_16x16x32_bf16 v[88:91], v[184:187], v[212:215], v[88:91]
	v_mfma_f32_16x16x32_bf16 v[92:95], v[188:191], v[212:215], v[92:95]
	ds_read_b128 v[164:167], v232 offset:5120
	v_mfma_f32_16x16x32_bf16 v[96:99], v[176:179], v[216:219], v[96:99]
	v_mfma_f32_16x16x32_bf16 v[100:103], v[180:183], v[216:219], v[100:103]
	v_mfma_f32_16x16x32_bf16 v[104:107], v[184:187], v[216:219], v[104:107]
	v_mfma_f32_16x16x32_bf16 v[108:111], v[188:191], v[216:219], v[108:111]
	ds_read_b128 v[168:171], v232 offset:6144
	s_add_u32 s100, s100, 24576
	s_cmp_eq_u32 s100, 73728
	s_cselect_b32 s100, 0, s100
	v_mfma_f32_16x16x32_bf16 v[112:115], v[176:179], v[220:223], v[112:115]
	v_mfma_f32_16x16x32_bf16 v[116:119], v[180:183], v[220:223], v[116:119]
	v_mfma_f32_16x16x32_bf16 v[120:123], v[184:187], v[220:223], v[120:123]
	v_mfma_f32_16x16x32_bf16 v[124:127], v[188:191], v[220:223], v[124:127]
	ds_read_b128 v[172:175], v232 offset:7168
	s_cmp_eq_u32 s18, 0
	s_cbranch_scc0 .Lg6_hi3
	s_setprio 0
; #define LWRITE(S, buf) do { bf16_t* sA_ = sbase + (buf) * BUF; bf16_t* sB_ = sA_ + 256 * PITCH; \
;     _Pragma("unroll") for (int i_ = 0; i_ < 4; ++i_) *(u32x4*)(sA_ + (sr + i_ * 64) * PITCH + scv * 8) = ra[S][i_]; \
;     _Pragma("unroll") for (int i_ = 0; i_ < 2; ++i_) *(u32x4*)(sB_ + (sr + i_ * 64) * PITCH + scv * 8) = rb[S][i_]; } while (0)
; template <class Epi>
; DI void gemm_tile(char* smem, const bf16_t* __restrict__ A0, int lda0, int ksplit, const bf16_t* __restrict__ A1, int lda1,
;                   const bf16_t* __restrict__ Bt, int K, int row0, int col0, const Epi& epi, int tid) {
;     ...
;     for (int kt = 0; kt < nk; kt += 2) {
;       LWRITE(1, 1);
;       __builtin_amdgcn_sched_barrier(0);
;       GLOAD(1, (kt + 3 < last ? kt + 3 : last));
;       __builtin_amdgcn_sched_barrier(0);
;       COMPUTE(0);
;       __syncthreads();
;       LWRITE(0, 0);
;       __builtin_amdgcn_sched_barrier(0);
;       GLOAD(0, (kt + 4 < last ? kt + 4 : last));
;       __builtin_amdgcn_sched_barrier(0);
;       COMPUTE(1);
;       __syncthreads();
;     }
.Lg6_hi3:
	s_waitcnt vmcnt(0)
	s_waitcnt lgkmcnt(0)
	s_barrier
	v_add_u32_e32 v232, s100, v230
	v_add_u32_e32 v233, s100, v231
	s_setprio 1
	v_mfma_f32_16x16x32_bf16 v[0:3], v[128:131], v[144:147], v[0:3]
	v_mfma_f32_16x16x32_bf16 v[4:7], v[132:135], v[144:147], v[4:7]
	v_mfma_f32_16x16x32_bf16 v[8:11], v[136:139], v[144:147], v[8:11]
	v_mfma_f32_16x16x32_bf16 v[12:15], v[140:143], v[144:147], v[12:15]
	ds_read_b128 v[176:179], v233 offset:0
	ds_read_b128 v[180:183], v233 offset:1024
	v_mfma_f32_16x16x32_bf16 v[16:19], v[128:131], v[148:151], v[16:19]
	v_mfma_f32_16x16x32_bf16 v[20:23], v[132:135], v[148:151], v[20:23]
	v_mfma_f32_16x16x32_bf16 v[24:27], v[136:139], v[148:151], v[24:27]
	v_mfma_f32_16x16x32_bf16 v[28:31], v[140:143], v[148:151], v[28:31]
	ds_read_b128 v[184:187], v233 offset:2048
	ds_read_b128 v[188:191], v233 offset:3072
	v_mfma_f32_16x16x32_bf16 v[32:35], v[128:131], v[152:155], v[32:35]
	v_mfma_f32_16x16x32_bf16 v[36:39], v[132:135], v[152:155], v[36:39]
	v_mfma_f32_16x16x32_bf16 v[40:43], v[136:139], v[152:155], v[40:43]
	v_mfma_f32_16x16x32_bf16 v[44:47], v[140:143], v[152:155], v[44:47]
	ds_read_b128 v[192:195], v232 offset:0
	ds_read_b128 v[196:199], v232 offset:1024
	v_mfma_f32_16x16x32_bf16 v[48:51], v[128:131], v[156:159], v[48:51]
	v_mfma_f32_16x16x32_bf16 v[52:55], v[132:135], v[156:159], v[52:55]
	v_mfma_f32_16x16x32_bf16 v[56:59], v[136:139], v[156:159], v[56:59]
	v_mfma_f32_16x16x32_bf16 v[60:63], v[140:143], v[156:159], v[60:63]
	ds_read_b128 v[200:203], v232 offset:2048
	ds_read_b128 v[204:207], v232 offset:3072
	v_mfma_f32_16x16x32_bf16 v[64:67], v[128:131], v[160:163], v[64:67]
	v_mfma_f32_16x16x32_bf16 v[68:71], v[132:135], v[160:163], v[68:71]
	v_mfma_f32_16x16x32_bf16 v[72:75], v[136:139], v[160:163], v[72:75]
	v_mfma_f32_16x16x32_bf16 v[76:79], v[140:143], v[160:163], v[76:79]
	ds_read_b128 v[208:211], v232 offset:4096
	v_mfma_f32_16x16x32_bf16 v[80:83], v[128:131], v[164:167], v[80:83]
	v_mfma_f32_16x16x32_bf16 v[84:87], v[132:135], v[164:167], v[84:87]
	v_mfma_f32_16x16x32_bf16 v[88:91], v[136:139], v[164:167], v[88:91]
	v_mfma_f32_16x16x32_bf16 v[92:95], v[140:143], v[164:167], v[92:95]
	ds_read_b128 v[212:215], v232 offset:5120
	v_mfma_f32_16x16x32_bf16 v[96:99], v[128:131], v[168:171], v[96:99]
	v_mfma_f32_16x16x32_bf16 v[100:103], v[132:135], v[168:171], v[100:103]
	v_mfma_f32_16x16x32_bf16 v[104:107], v[136:139], v[168:171], v[104:107]
	v_mfma_f32_16x16x32_bf16 v[108:111], v[140:143], v[168:171], v[108:111]
	ds_read_b128 v[216:219], v232 offset:6144
	s_add_u32 s100, s100, 24576
	s_cmp_eq_u32 s100, 73728
	s_cselect_b32 s100, 0, s100
	v_mfma_f32_16x16x32_bf16 v[112:115], v[128:131], v[172:175], v[112:115]
	v_mfma_f32_16x16x32_bf16 v[116:119], v[132:135], v[172:175], v[116:119]
	v_mfma_f32_16x16x32_bf16 v[120:123], v[136:139], v[172:175], v[120:123]
	v_mfma_f32_16x16x32_bf16 v[124:127], v[140:143], v[172:175], v[124:127]
	ds_read_b128 v[220:223], v232 offset:7168
	s_cmp_eq_u32 s18, 0
	s_cbranch_scc0 .Lg6_hi4
	s_setprio 0
.Lg6_hi4:
	s_waitcnt lgkmcnt(0)
	s_barrier
	s_setprio 1
	v_mfma_f32_16x16x32_bf16 v[0:3], v[176:179], v[192:195], v[0:3]
	v_mfma_f32_16x16x32_bf16 v[4:7], v[180:183], v[192:195], v[4:7]
	v_mfma_f32_16x16x32_bf16 v[8:11], v[184:187], v[192:195], v[8:11]
	v_mfma_f32_16x16x32_bf16 v[12:15], v[188:191], v[192:195], v[12:15]
	v_mfma_f32_16x16x32_bf16 v[16:19], v[176:179], v[196:199], v[16:19]
	v_mfma_f32_16x16x32_bf16 v[20:23], v[180:183], v[196:199], v[20:23]
	v_mfma_f32_16x16x32_bf16 v[24:27], v[184:187], v[196:199], v[24:27]
	v_mfma_f32_16x16x32_bf16 v[28:31], v[188:191], v[196:199], v[28:31]
	v_mfma_f32_16x16x32_bf16 v[32:35], v[176:179], v[200:203], v[32:35]
	v_mfma_f32_16x16x32_bf16 v[36:39], v[180:183], v[200:203], v[36:39]
	v_mfma_f32_16x16x32_bf16 v[40:43], v[184:187], v[200:203], v[40:43]
	v_mfma_f32_16x16x32_bf16 v[44:47], v[188:191], v[200:203], v[44:47]
	v_mfma_f32_16x16x32_bf16 v[48:51], v[176:179], v[204:207], v[48:51]
	v_mfma_f32_16x16x32_bf16 v[52:55], v[180:183], v[204:207], v[52:55]
	v_mfma_f32_16x16x32_bf16 v[56:59], v[184:187], v[204:207], v[56:59]
	v_mfma_f32_16x16x32_bf16 v[60:63], v[188:191], v[204:207], v[60:63]
	v_mfma_f32_16x16x32_bf16 v[64:67], v[176:179], v[208:211], v[64:67]
	v_mfma_f32_16x16x32_bf16 v[68:71], v[180:183], v[208:211], v[68:71]
	v_mfma_f32_16x16x32_bf16 v[72:75], v[184:187], v[208:211], v[72:75]
	v_mfma_f32_16x16x32_bf16 v[76:79], v[188:191], v[208:211], v[76:79]
	v_mfma_f32_16x16x32_bf16 v[80:83], v[176:179], v[212:215], v[80:83]
	v_mfma_f32_16x16x32_bf16 v[84:87], v[180:183], v[212:215], v[84:87]
	v_mfma_f32_16x16x32_bf16 v[88:91], v[184:187], v[212:215], v[88:91]
	v_mfma_f32_16x16x32_bf16 v[92:95], v[188:191], v[212:215], v[92:95]
	v_mfma_f32_16x16x32_bf16 v[96:99], v[176:179], v[216:219], v[96:99]
	v_mfma_f32_16x16x32_bf16 v[100:103], v[180:183], v[216:219], v[100:103]
	v_mfma_f32_16x16x32_bf16 v[104:107], v[184:187], v[216:219], v[104:107]
	v_mfma_f32_16x16x32_bf16 v[108:111], v[188:191], v[216:219], v[108:111]
	v_mfma_f32_16x16x32_bf16 v[112:115], v[176:179], v[220:223], v[112:115]
	v_mfma_f32_16x16x32_bf16 v[116:119], v[180:183], v[220:223], v[116:119]
	v_mfma_f32_16x16x32_bf16 v[120:123], v[184:187], v[220:223], v[120:123]
	v_mfma_f32_16x16x32_bf16 v[124:127], v[188:191], v[220:223], v[124:127]
	s_cmp_eq_u32 s18, 0
	s_cbranch_scc0 .Lg6_hi5
	s_setprio 0
.Lg6_hi5:
	s_branch .Lg6_epi
.Lg6_sw0:
	s_mul_i32 s20, s98, 5184
	s_add_u32 s20, s20, 0xe800000
	s_add_u32 s0, s92, s20
	s_addc_u32 s1, s93, 0
	v_mov_b32_e32 v224, v236
	v_mov_b32_e32 v225, v237
	v_mov_b32_e32 v226, v238
	v_mov_b32_e32 v227, v239
	s_branch .Lg6_swb0

; template <class Epi>
; DI void gemm_tile(char* smem, const bf16_t* __restrict__ A0, int lda0, int ksplit, const bf16_t* __restrict__ A1, int lda1,
;                   const bf16_t* __restrict__ Bt, int K, int row0, int col0, const Epi& epi, int tid) {
;   constexpr int BK = 32, PITCH = 40, BUF = (256 + 128) * PITCH;
;   bf16_t* sbase = (bf16_t*)smem;
;   const int lane = tid & 63, wid = tid >> 6, wr = wid >> 1, wc = wid & 1, fr = lane & 15, fq = lane >> 4;
;   f32x4 acc[8][4];
; #pragma unroll
;   for (int m = 0; m < 8; ++m)
; #pragma unroll
;     for (int n = 0; n < 4; ++n) acc[m][n] = (f32x4){0.f, 0.f, 0.f, 0.f};
;   u32x4 ra[2][4], rb[2][2];
;   const int nk = K / BK;
;   const int sr = tid >> 2, scv = tid & 3;
; template <class Epi>
; DI void gemm_phase(char* smem, const bf16_t* A0, int lda0, int ksplit, const bf16_t* A1, int lda1, const bf16_t* Bt, int K, int nN, const Epi& epi, int tid) {
;   const int G = gridDim.x;
;   if ((G & 7) == 0) {
;     const int x = blockIdx.x & 7, l = blockIdx.x >> 3, L = G >> 3, per = 8 * nN, tot = 2 * per;
;     for (int q = l; q < tot; q += L) { const int rgl = q / per, rem = q % per, ct = rem >> 3, rt = (x * 2 + rgl) * 8 + (rem & 7);
;       gemm_tile(smem, A0, lda0, ksplit, A1, lda1, Bt, K, rt * 256, ct * 128, epi, tid); }
.LBB0_901:
	s_cmp_gt_i32 s94, 8
	s_cselect_b64 s[0:1], -1, 0
	s_cmp_lt_i32 s95, 9
	s_cselect_b64 s[2:3], -1, 0
	s_or_b64 s[0:1], s[0:1], s[2:3]
	s_and_b64 vcc, exec, s[0:1]
	s_cbranch_vccnz .LBB0_929
	s_add_u32 s2, s92, 0x3800000
	s_waitcnt lgkmcnt(0)
	s_load_dword s14, s[74:75], 0x180
	s_addc_u32 s3, s93, 0
	s_add_u32 s4, s92, 0xbc0000
	s_addc_u32 s5, s93, 0
	s_add_u32 s0, s92, 0x7800000
	s_addc_u32 s1, s93, 0
	s_and_b32 s16, s72, 0xffffffc0
	v_mbcnt_hi_u32_b32 v195, -1, v194
	s_waitcnt lgkmcnt(0)
	s_and_b32 s15, s14, 7
	s_cmp_lg_u32 s15, 0
	s_waitcnt vmcnt(16)
	v_add_u32_e32 v196, s16, v195
	v_mbcnt_lo_u32_b32 v240, -1, 0
	v_mbcnt_hi_u32_b32 v240, -1, v240
	s_lshr_b32 s12, s72, 6
	s_lshl_b32 s101, s12, 10
	v_and_b32_e32 v241, 15, v240
	v_lshrrev_b32_e32 v242, 4, v240
	v_bfe_u32 v243, v240, 3, 1
	v_mul_u32_u24_e32 v243, 3, v243
	v_xor_b32_e32 v243, v242, v243
	v_lshlrev_b32_e32 v243, 4, v243
	v_lshl_add_u32 v243, v241, 6, v243
	s_lshr_b32 s11, s12, 1
	s_lshl_b32 s11, s11, 13
	v_add_u32_e32 v230, s11, v243
	s_and_b32 s11, s12, 1
	s_lshl_b32 s11, s11, 12
	s_add_u32 s11, s11, 16384
	v_add_u32_e32 v231, s11, v243
	s_lshr_b32 s11, s12, 1
	s_lshl_b32 s11, s11, 7
	v_add_u32_e32 v244, s11, v241
	s_and_b32 s11, s12, 1
	s_lshl_b32 s11, s11, 6
	v_lshl_add_u32 v245, v242, 2, s11
	s_movk_i32 s11, 0x2000
	v_mul_lo_u32 v246, v244, s11
	v_lshl_add_u32 v234, v245, 1, v246
	s_mul_i32 s11, s12, 18432
	v_mul_u32_u24_e32 v246, 144, v241
	v_lshl_add_u32 v246, v242, 3, v246
	v_add_u32_e32 v236, s11, v246
	v_lshrrev_b32_e32 v246, 3, v240
	v_mul_u32_u24_e32 v246, 144, v246
	v_and_b32_e32 v247, 7, v240
	v_lshl_add_u32 v246, v247, 4, v246
	v_add_u32_e32 v237, s11, v246
	s_lshr_b32 s11, s12, 1
	s_lshl_b32 s11, s11, 7
	v_lshrrev_b32_e32 v246, 3, v240
	v_add_u32_e32 v246, s11, v246
	s_and_b32 s11, s12, 1
	s_lshl_b32 s11, s11, 6
	v_lshl_add_u32 v248, v247, 3, s11
	s_movk_i32 s11, 8192
	v_mul_lo_u32 v247, v246, s11
	v_lshl_add_u32 v238, v248, 1, v247
	v_lshrrev_b32_e32 v241, 2, v240
	s_lshl_b32 s11, s12, 4
	v_add_u32_e32 v241, s11, v241
	v_bfe_u32 v242, v240, 5, 1
	v_mul_u32_u24_e32 v242, 3, v242
	v_and_b32_e32 v243, 3, v240
	v_xor_b32_e32 v243, v243, v242
	v_lshlrev_b32_e32 v243, 4, v243
	s_mov_b32 s11, 2048
	v_mad_u32_u24 v224, v241, s11, v243
	v_add_u32_e32 v225, 0x20000, v224
	v_add_u32_e32 v226, 0x40000, v224
	v_add_u32_e32 v227, 0x60000, v224
	s_mov_b32 s11, 2048
	v_mad_u32_u24 v228, v241, s11, v243
	v_add_u32_e32 v229, 0x20000, v228
	s_cmpk_gt_u32 s96, 0xff
	s_cselect_b32 s10, 1, 0
	s_cmpk_gt_u32 s96, 0xff
	s_cbranch_scc0 .Lg8_prio
	s_setprio 1

; #define LWRITE(S, buf) do { bf16_t* sA_ = sbase + (buf) * BUF; bf16_t* sB_ = sA_ + 256 * PITCH; \
;     _Pragma("unroll") for (int i_ = 0; i_ < 4; ++i_) *(u32x4*)(sA_ + (sr + i_ * 64) * PITCH + scv * 8) = ra[S][i_]; \
;     _Pragma("unroll") for (int i_ = 0; i_ < 2; ++i_) *(u32x4*)(sB_ + (sr + i_ * 64) * PITCH + scv * 8) = rb[S][i_]; } while (0)
; template <class Epi>
; DI void gemm_tile(char* smem, const bf16_t* __restrict__ A0, int lda0, int ksplit, const bf16_t* __restrict__ A1, int lda1,
;                   const bf16_t* __restrict__ Bt, int K, int row0, int col0, const Epi& epi, int tid) {
;     ...
;   __syncthreads();
;   {
;     const int last = nk - 1;
;     GLOAD(0, 0);
;     __builtin_amdgcn_sched_barrier(0);
;     GLOAD(1, 1);
;     __builtin_amdgcn_sched_barrier(0);
;     LWRITE(0, 0);
;     __builtin_amdgcn_sched_barrier(0);
;     GLOAD(0, (2 < last ? 2 : last));
;     __builtin_amdgcn_sched_barrier(0);
;     __syncthreads();
;     for (int kt = 0; kt < nk; kt += 2) {
;       LWRITE(1, 1);
;       __builtin_amdgcn_sched_barrier(0);
;       GLOAD(1, (kt + 3 < last ? kt + 3 : last));
;       __builtin_amdgcn_sched_barrier(0);
;       COMPUTE(0);
;       __syncthreads();
;       LWRITE(0, 0);
;       __builtin_amdgcn_sched_barrier(0);
;       GLOAD(0, (kt + 4 < last ? kt + 4 : last));
;       __builtin_amdgcn_sched_barrier(0);
;       COMPUTE(1);
;       __syncthreads();
;     }
.Lg8_kloop:
	s_waitcnt vmcnt(6)
	s_waitcnt lgkmcnt(0)
	s_barrier
	v_add_u32_e32 v232, s98, v230
	v_add_u32_e32 v233, s98, v231
	s_add_u32 s11, s19, s101
	s_setprio 1
	v_mfma_f32_16x16x32_bf16 v[0:3], v[128:131], v[144:147], v[0:3]
	v_mfma_f32_16x16x32_bf16 v[4:7], v[132:135], v[144:147], v[4:7]
	v_mfma_f32_16x16x32_bf16 v[8:11], v[136:139], v[144:147], v[8:11]
	v_mfma_f32_16x16x32_bf16 v[12:15], v[140:143], v[144:147], v[12:15]
	ds_read_b128 v[176:179], v233 offset:0
	ds_read_b128 v[180:183], v233 offset:1024
	s_add_u32 m0, s11, 0
	s_nop 0
	global_load_lds_dwordx4 v224, s[0:1]
	v_mfma_f32_16x16x32_bf16 v[16:19], v[128:131], v[148:151], v[16:19]
	v_mfma_f32_16x16x32_bf16 v[20:23], v[132:135], v[148:151], v[20:23]
	v_mfma_f32_16x16x32_bf16 v[24:27], v[136:139], v[148:151], v[24:27]
	v_mfma_f32_16x16x32_bf16 v[28:31], v[140:143], v[148:151], v[28:31]
	ds_read_b128 v[184:187], v233 offset:2048
	ds_read_b128 v[188:191], v233 offset:3072
	s_add_u32 m0, s11, 4096
	s_nop 0
	global_load_lds_dwordx4 v225, s[0:1]
	v_mfma_f32_16x16x32_bf16 v[32:35], v[128:131], v[152:155], v[32:35]
	v_mfma_f32_16x16x32_bf16 v[36:39], v[132:135], v[152:155], v[36:39]
	v_mfma_f32_16x16x32_bf16 v[40:43], v[136:139], v[152:155], v[40:43]
	v_mfma_f32_16x16x32_bf16 v[44:47], v[140:143], v[152:155], v[44:47]
	ds_read_b128 v[192:195], v232 offset:0
	ds_read_b128 v[196:199], v232 offset:1024
	s_add_u32 m0, s11, 8192
	s_nop 0
	global_load_lds_dwordx4 v226, s[0:1]
	v_mfma_f32_16x16x32_bf16 v[48:51], v[128:131], v[156:159], v[48:51]
	v_mfma_f32_16x16x32_bf16 v[52:55], v[132:135], v[156:159], v[52:55]
	v_mfma_f32_16x16x32_bf16 v[56:59], v[136:139], v[156:159], v[56:59]
	v_mfma_f32_16x16x32_bf16 v[60:63], v[140:143], v[156:159], v[60:63]
	ds_read_b128 v[200:203], v232 offset:2048
	ds_read_b128 v[204:207], v232 offset:3072
	s_add_u32 m0, s11, 12288
	s_nop 0
	global_load_lds_dwordx4 v227, s[0:1]
	v_mfma_f32_16x16x32_bf16 v[64:67], v[128:131], v[160:163], v[64:67]
	v_mfma_f32_16x16x32_bf16 v[68:71], v[132:135], v[160:163], v[68:71]
	v_mfma_f32_16x16x32_bf16 v[72:75], v[136:139], v[160:163], v[72:75]
	v_mfma_f32_16x16x32_bf16 v[76:79], v[140:143], v[160:163], v[76:79]
	ds_read_b128 v[208:211], v232 offset:4096
	s_add_u32 m0, s11, 16384
	s_nop 0
	global_load_lds_dwordx4 v228, s[2:3]
	v_mfma_f32_16x16x32_bf16 v[80:83], v[128:131], v[164:167], v[80:83]
	v_mfma_f32_16x16x32_bf16 v[84:87], v[132:135], v[164:167], v[84:87]
	v_mfma_f32_16x16x32_bf16 v[88:91], v[136:139], v[164:167], v[88:91]
	v_mfma_f32_16x16x32_bf16 v[92:95], v[140:143], v[164:167], v[92:95]
	ds_read_b128 v[212:215], v232 offset:5120
	s_add_u32 m0, s11, 20480
	s_nop 0
	global_load_lds_dwordx4 v229, s[2:3]
	v_mfma_f32_16x16x32_bf16 v[96:99], v[128:131], v[168:171], v[96:99]
	v_mfma_f32_16x16x32_bf16 v[100:103], v[132:135], v[168:171], v[100:103]
	v_mfma_f32_16x16x32_bf16 v[104:107], v[136:139], v[168:171], v[104:107]
	v_mfma_f32_16x16x32_bf16 v[108:111], v[140:143], v[168:171], v[108:111]
	ds_read_b128 v[216:219], v232 offset:6144
	s_add_u32 s0, s0, 64
	s_addc_u32 s1, s1, 0
	s_add_u32 s2, s2, 64
	s_addc_u32 s3, s3, 0
	s_add_u32 s100, s100, 1
	s_add_u32 s19, s19, 24576
	s_cmp_eq_u32 s19, 73728
	s_cselect_b32 s19, 0, s19
	s_add_u32 s98, s98, 24576
	s_cmp_eq_u32 s98, 73728
	s_cselect_b32 s98, 0, s98
	v_mfma_f32_16x16x32_bf16 v[112:115], v[128:131], v[172:175], v[112:115]
	v_mfma_f32_16x16x32_bf16 v[116:119], v[132:135], v[172:175], v[116:119]
	v_mfma_f32_16x16x32_bf16 v[120:123], v[136:139], v[172:175], v[120:123]
	v_mfma_f32_16x16x32_bf16 v[124:127], v[140:143], v[172:175], v[124:127]
	ds_read_b128 v[220:223], v232 offset:7168
	s_cmp_eq_u32 s10, 0
	s_cbranch_scc0 .Lg8_hi0
	s_setprio 0
.Lg8_hi0:
	s_waitcnt vmcnt(6)
	s_waitcnt lgkmcnt(0)
	s_barrier
	v_add_u32_e32 v232, s98, v230
	v_add_u32_e32 v233, s98, v231
	s_add_u32 s11, s19, s101
	s_setprio 1
	v_mfma_f32_16x16x32_bf16 v[0:3], v[176:179], v[192:195], v[0:3]
	v_mfma_f32_16x16x32_bf16 v[4:7], v[180:183], v[192:195], v[4:7]
	v_mfma_f32_16x16x32_bf16 v[8:11], v[184:187], v[192:195], v[8:11]
	v_mfma_f32_16x16x32_bf16 v[12:15], v[188:191], v[192:195], v[12:15]
	ds_read_b128 v[128:131], v233 offset:0
	ds_read_b128 v[132:135], v233 offset:1024
	s_add_u32 m0, s11, 0
	s_nop 0
	global_load_lds_dwordx4 v224, s[0:1]
	v_mfma_f32_16x16x32_bf16 v[16:19], v[176:179], v[196:199], v[16:19]
	v_mfma_f32_16x16x32_bf16 v[20:23], v[180:183], v[196:199], v[20:23]
	v_mfma_f32_16x16x32_bf16 v[24:27], v[184:187], v[196:199], v[24:27]
	v_mfma_f32_16x16x32_bf16 v[28:31], v[188:191], v[196:199], v[28:31]
	ds_read_b128 v[136:139], v233 offset:2048
	ds_read_b128 v[140:143], v233 offset:3072
	s_add_u32 m0, s11, 4096
	s_nop 0
	global_load_lds_dwordx4 v225, s[0:1]
	v_mfma_f32_16x16x32_bf16 v[32:35], v[176:179], v[200:203], v[32:35]
	v_mfma_f32_16x16x32_bf16 v[36:39], v[180:183], v[200:203], v[36:39]
	v_mfma_f32_16x16x32_bf16 v[40:43], v[184:187], v[200:203], v[40:43]
	v_mfma_f32_16x16x32_bf16 v[44:47], v[188:191], v[200:203], v[44:47]
	ds_read_b128 v[144:147], v232 offset:0
	ds_read_b128 v[148:151], v232 offset:1024
	s_add_u32 m0, s11, 8192
	s_nop 0
	global_load_lds_dwordx4 v226, s[0:1]
	v_mfma_f32_16x16x32_bf16 v[48:51], v[176:179], v[204:207], v[48:51]
	v_mfma_f32_16x16x32_bf16 v[52:55], v[180:183], v[204:207], v[52:55]
	v_mfma_f32_16x16x32_bf16 v[56:59], v[184:187], v[204:207], v[56:59]
	v_mfma_f32_16x16x32_bf16 v[60:63], v[188:191], v[204:207], v[60:63]
	ds_read_b128 v[152:155], v232 offset:2048
	ds_read_b128 v[156:159], v232 offset:3072
	s_add_u32 m0, s11, 12288
	s_nop 0
	global_load_lds_dwordx4 v227, s[0:1]
	v_mfma_f32_16x16x32_bf16 v[64:67], v[176:179], v[208:211], v[64:67]
; #define LWRITE(S, buf) do { bf16_t* sA_ = sbase + (buf) * BUF; bf16_t* sB_ = sA_ + 256 * PITCH; \
;     _Pragma("unroll") for (int i_ = 0; i_ < 4; ++i_) *(u32x4*)(sA_ + (sr + i_ * 64) * PITCH + scv * 8) = ra[S][i_]; \
;     _Pragma("unroll") for (int i_ = 0; i_ < 2; ++i_) *(u32x4*)(sB_ + (sr + i_ * 64) * PITCH + scv * 8) = rb[S][i_]; } while (0)
; template <class Epi>
; DI void gemm_tile(char* smem, const bf16_t* __restrict__ A0, int lda0, int ksplit, const bf16_t* __restrict__ A1, int lda1,
;                   const bf16_t* __restrict__ Bt, int K, int row0, int col0, const Epi& epi, int tid) {
;     ...
;   __syncthreads();
;   {
;     const int last = nk - 1;
;     GLOAD(0, 0);
;     __builtin_amdgcn_sched_barrier(0);
;     GLOAD(1, 1);
;     __builtin_amdgcn_sched_barrier(0);
;     LWRITE(0, 0);
;     __builtin_amdgcn_sched_barrier(0);
;     GLOAD(0, (2 < last ? 2 : last));
;     __builtin_amdgcn_sched_barrier(0);
;     __syncthreads();
;     for (int kt = 0; kt < nk; kt += 2) {
;       LWRITE(1, 1);
;       __builtin_amdgcn_sched_barrier(0);
;       GLOAD(1, (kt + 3 < last ? kt + 3 : last));
;       __builtin_amdgcn_sched_barrier(0);
;       COMPUTE(0);
;       __syncthreads();
;       LWRITE(0, 0);
;       __builtin_amdgcn_sched_barrier(0);
;       GLOAD(0, (kt + 4 < last ? kt + 4 : last));
;       __builtin_amdgcn_sched_barrier(0);
;       COMPUTE(1);
;       __syncthreads();
;     }
	v_mfma_f32_16x16x32_bf16 v[68:71], v[180:183], v[208:211], v[68:71]
	v_mfma_f32_16x16x32_bf16 v[72:75], v[184:187], v[208:211], v[72:75]
	v_mfma_f32_16x16x32_bf16 v[76:79], v[188:191], v[208:211], v[76:79]
	ds_read_b128 v[160:163], v232 offset:4096
	s_add_u32 m0, s11, 16384
	s_nop 0
	global_load_lds_dwordx4 v228, s[2:3]
	v_mfma_f32_16x16x32_bf16 v[80:83], v[176:179], v[212:215], v[80:83]
	v_mfma_f32_16x16x32_bf16 v[84:87], v[180:183], v[212:215], v[84:87]
	v_mfma_f32_16x16x32_bf16 v[88:91], v[184:187], v[212:215], v[88:91]
	v_mfma_f32_16x16x32_bf16 v[92:95], v[188:191], v[212:215], v[92:95]
	ds_read_b128 v[164:167], v232 offset:5120
	s_add_u32 m0, s11, 20480
	s_nop 0
	global_load_lds_dwordx4 v229, s[2:3]
	v_mfma_f32_16x16x32_bf16 v[96:99], v[176:179], v[216:219], v[96:99]
	v_mfma_f32_16x16x32_bf16 v[100:103], v[180:183], v[216:219], v[100:103]
	v_mfma_f32_16x16x32_bf16 v[104:107], v[184:187], v[216:219], v[104:107]
	v_mfma_f32_16x16x32_bf16 v[108:111], v[188:191], v[216:219], v[108:111]
	ds_read_b128 v[168:171], v232 offset:6144
	s_add_u32 s0, s0, 64
	s_addc_u32 s1, s1, 0
	s_add_u32 s2, s2, 64
	s_addc_u32 s3, s3, 0
	s_add_u32 s100, s100, 1
	s_add_u32 s19, s19, 24576
	s_cmp_eq_u32 s19, 73728
	s_cselect_b32 s19, 0, s19
	s_add_u32 s98, s98, 24576
	s_cmp_eq_u32 s98, 73728
	s_cselect_b32 s98, 0, s98
	v_mfma_f32_16x16x32_bf16 v[112:115], v[176:179], v[220:223], v[112:115]
	v_mfma_f32_16x16x32_bf16 v[116:119], v[180:183], v[220:223], v[116:119]
	v_mfma_f32_16x16x32_bf16 v[120:123], v[184:187], v[220:223], v[120:123]
	v_mfma_f32_16x16x32_bf16 v[124:127], v[188:191], v[220:223], v[124:127]
	ds_read_b128 v[172:175], v232 offset:7168
	s_cmp_eq_u32 s10, 0
	s_cbranch_scc0 .Lg8_hi1
	s_setprio 0
.Lg8_hi1:
	s_add_u32 s99, s99, 2
	s_cmp_lt_u32 s99, 28
	s_cbranch_scc1 .Lg8_kloop
	s_waitcnt vmcnt(6)
	s_waitcnt lgkmcnt(0)
	s_barrier
	v_add_u32_e32 v232, s98, v230
	v_add_u32_e32 v233, s98, v231
	s_add_u32 s11, s19, s101
	s_setprio 1
	v_mfma_f32_16x16x32_bf16 v[0:3], v[128:131], v[144:147], v[0:3]
	v_mfma_f32_16x16x32_bf16 v[4:7], v[132:135], v[144:147], v[4:7]
	v_mfma_f32_16x16x32_bf16 v[8:11], v[136:139], v[144:147], v[8:11]
	v_mfma_f32_16x16x32_bf16 v[12:15], v[140:143], v[144:147], v[12:15]
	ds_read_b128 v[176:179], v233 offset:0
	ds_read_b128 v[180:183], v233 offset:1024
	s_add_u32 m0, s11, 0
	s_nop 0
	global_load_lds_dwordx4 v224, s[0:1]
	v_mfma_f32_16x16x32_bf16 v[16:19], v[128:131], v[148:151], v[16:19]
	v_mfma_f32_16x16x32_bf16 v[20:23], v[132:135], v[148:151], v[20:23]
	v_mfma_f32_16x16x32_bf16 v[24:27], v[136:139], v[148:151], v[24:27]
	v_mfma_f32_16x16x32_bf16 v[28:31], v[140:143], v[148:151], v[28:31]
	ds_read_b128 v[184:187], v233 offset:2048
	ds_read_b128 v[188:191], v233 offset:3072
	s_add_u32 m0, s11, 4096
	s_nop 0
	global_load_lds_dwordx4 v225, s[0:1]
	v_mfma_f32_16x16x32_bf16 v[32:35], v[128:131], v[152:155], v[32:35]
	v_mfma_f32_16x16x32_bf16 v[36:39], v[132:135], v[152:155], v[36:39]
	v_mfma_f32_16x16x32_bf16 v[40:43], v[136:139], v[152:155], v[40:43]
	v_mfma_f32_16x16x32_bf16 v[44:47], v[140:143], v[152:155], v[44:47]
	ds_read_b128 v[192:195], v232 offset:0
	ds_read_b128 v[196:199], v232 offset:1024
	s_add_u32 m0, s11, 8192
	s_nop 0
	global_load_lds_dwordx4 v226, s[0:1]
	v_mfma_f32_16x16x32_bf16 v[48:51], v[128:131], v[156:159], v[48:51]
	v_mfma_f32_16x16x32_bf16 v[52:55], v[132:135], v[156:159], v[52:55]
	v_mfma_f32_16x16x32_bf16 v[56:59], v[136:139], v[156:159], v[56:59]
	v_mfma_f32_16x16x32_bf16 v[60:63], v[140:143], v[156:159], v[60:63]
	ds_read_b128 v[200:203], v232 offset:2048
	ds_read_b128 v[204:207], v232 offset:3072
	s_add_u32 m0, s11, 12288
	s_nop 0
	global_load_lds_dwordx4 v227, s[0:1]
	v_mfma_f32_16x16x32_bf16 v[64:67], v[128:131], v[160:163], v[64:67]
	v_mfma_f32_16x16x32_bf16 v[68:71], v[132:135], v[160:163], v[68:71]
	v_mfma_f32_16x16x32_bf16 v[72:75], v[136:139], v[160:163], v[72:75]
	v_mfma_f32_16x16x32_bf16 v[76:79], v[140:143], v[160:163], v[76:79]
	ds_read_b128 v[208:211], v232 offset:4096
	s_add_u32 m0, s11, 16384
	s_nop 0
	global_load_lds_dwordx4 v228, s[2:3]
	v_mfma_f32_16x16x32_bf16 v[80:83], v[128:131], v[164:167], v[80:83]
	v_mfma_f32_16x16x32_bf16 v[84:87], v[132:135], v[164:167], v[84:87]
	v_mfma_f32_16x16x32_bf16 v[88:91], v[136:139], v[164:167], v[88:91]
	v_mfma_f32_16x16x32_bf16 v[92:95], v[140:143], v[164:167], v[92:95]
	ds_read_b128 v[212:215], v232 offset:5120
	s_add_u32 m0, s11, 20480
	s_nop 0
	global_load_lds_dwordx4 v229, s[2:3]
	v_mfma_f32_16x16x32_bf16 v[96:99], v[128:131], v[168:171], v[96:99]
	v_mfma_f32_16x16x32_bf16 v[100:103], v[132:135], v[168:171], v[100:103]
	v_mfma_f32_16x16x32_bf16 v[104:107], v[136:139], v[168:171], v[104:107]
	v_mfma_f32_16x16x32_bf16 v[108:111], v[140:143], v[168:171], v[108:111]
	ds_read_b128 v[216:219], v232 offset:6144
	s_add_u32 s0, s0, 64
	s_addc_u32 s1, s1, 0
	s_add_u32 s2, s2, 64
	s_addc_u32 s3, s3, 0
	s_add_u32 s100, s100, 1
	s_add_u32 s19, s19, 24576
	s_cmp_eq_u32 s19, 73728
	s_cselect_b32 s19, 0, s19
	s_add_u32 s98, s98, 24576
	s_cmp_eq_u32 s98, 73728
	s_cselect_b32 s98, 0, s98
	v_mfma_f32_16x16x32_bf16 v[112:115], v[128:131], v[172:175], v[112:115]
	v_mfma_f32_16x16x32_bf16 v[116:119], v[132:135], v[172:175], v[116:119]
	v_mfma_f32_16x16x32_bf16 v[120:123], v[136:139], v[172:175], v[120:123]
	v_mfma_f32_16x16x32_bf16 v[124:127], v[140:143], v[172:175], v[124:127]
	ds_read_b128 v[220:223], v232 offset:7168
	s_cmp_eq_u32 s10, 0
	s_cbranch_scc0 .Lg8_hi2
	s_setprio 0
; #define LWRITE(S, buf) do { bf16_t* sA_ = sbase + (buf) * BUF; bf16_t* sB_ = sA_ + 256 * PITCH; \
;     _Pragma("unroll") for (int i_ = 0; i_ < 4; ++i_) *(u32x4*)(sA_ + (sr + i_ * 64) * PITCH + scv * 8) = ra[S][i_]; \
;     _Pragma("unroll") for (int i_ = 0; i_ < 2; ++i_) *(u32x4*)(sB_ + (sr + i_ * 64) * PITCH + scv * 8) = rb[S][i_]; } while (0)
; template <class Epi>
; DI void gemm_tile(char* smem, const bf16_t* __restrict__ A0, int lda0, int ksplit, const bf16_t* __restrict__ A1, int lda1,
;                   const bf16_t* __restrict__ Bt, int K, int row0, int col0, const Epi& epi, int tid) {
;     ...
;   __syncthreads();
;   {
;     const int last = nk - 1;
;     GLOAD(0, 0);
;     __builtin_amdgcn_sched_barrier(0);
;     GLOAD(1, 1);
;     __builtin_amdgcn_sched_barrier(0);
;     LWRITE(0, 0);
;     __builtin_amdgcn_sched_barrier(0);
;     GLOAD(0, (2 < last ? 2 : last));
;     __builtin_amdgcn_sched_barrier(0);
;     __syncthreads();
;     for (int kt = 0; kt < nk; kt += 2) {
;       LWRITE(1, 1);
;       __builtin_amdgcn_sched_barrier(0);
;       GLOAD(1, (kt + 3 < last ? kt + 3 : last));
;       __builtin_amdgcn_sched_barrier(0);
;       COMPUTE(0);
;       __syncthreads();
;       LWRITE(0, 0);
;       __builtin_amdgcn_sched_barrier(0);
;       GLOAD(0, (kt + 4 < last ? kt + 4 : last));
;       __builtin_amdgcn_sched_barrier(0);
;       COMPUTE(1);
;       __syncthreads();
;     }
.Lg8_hi2:
	s_waitcnt vmcnt(6)
	s_waitcnt lgkmcnt(0)
	s_barrier
	v_add_u32_e32 v232, s98, v230
	v_add_u32_e32 v233, s98, v231
	s_setprio 1
	v_mfma_f32_16x16x32_bf16 v[0:3], v[176:179], v[192:195], v[0:3]
	v_mfma_f32_16x16x32_bf16 v[4:7], v[180:183], v[192:195], v[4:7]
	v_mfma_f32_16x16x32_bf16 v[8:11], v[184:187], v[192:195], v[8:11]
	v_mfma_f32_16x16x32_bf16 v[12:15], v[188:191], v[192:195], v[12:15]
	ds_read_b128 v[128:131], v233 offset:0
	ds_read_b128 v[132:135], v233 offset:1024
	v_mfma_f32_16x16x32_bf16 v[16:19], v[176:179], v[196:199], v[16:19]
	v_mfma_f32_16x16x32_bf16 v[20:23], v[180:183], v[196:199], v[20:23]
	v_mfma_f32_16x16x32_bf16 v[24:27], v[184:187], v[196:199], v[24:27]
	v_mfma_f32_16x16x32_bf16 v[28:31], v[188:191], v[196:199], v[28:31]
	ds_read_b128 v[136:139], v233 offset:2048
	ds_read_b128 v[140:143], v233 offset:3072
	v_mfma_f32_16x16x32_bf16 v[32:35], v[176:179], v[200:203], v[32:35]
	v_mfma_f32_16x16x32_bf16 v[36:39], v[180:183], v[200:203], v[36:39]
	v_mfma_f32_16x16x32_bf16 v[40:43], v[184:187], v[200:203], v[40:43]
	v_mfma_f32_16x16x32_bf16 v[44:47], v[188:191], v[200:203], v[44:47]
	ds_read_b128 v[144:147], v232 offset:0
	ds_read_b128 v[148:151], v232 offset:1024
	v_mfma_f32_16x16x32_bf16 v[48:51], v[176:179], v[204:207], v[48:51]
	v_mfma_f32_16x16x32_bf16 v[52:55], v[180:183], v[204:207], v[52:55]
	v_mfma_f32_16x16x32_bf16 v[56:59], v[184:187], v[204:207], v[56:59]
	v_mfma_f32_16x16x32_bf16 v[60:63], v[188:191], v[204:207], v[60:63]
	ds_read_b128 v[152:155], v232 offset:2048
	ds_read_b128 v[156:159], v232 offset:3072
	v_mfma_f32_16x16x32_bf16 v[64:67], v[176:179], v[208:211], v[64:67]
	v_mfma_f32_16x16x32_bf16 v[68:71], v[180:183], v[208:211], v[68:71]
	v_mfma_f32_16x16x32_bf16 v[72:75], v[184:187], v[208:211], v[72:75]
	v_mfma_f32_16x16x32_bf16 v[76:79], v[188:191], v[208:211], v[76:79]
	ds_read_b128 v[160:163], v232 offset:4096
	v_mfma_f32_16x16x32_bf16 v[80:83], v[176:179], v[212:215], v[80:83]
	v_mfma_f32_16x16x32_bf16 v[84:87], v[180:183], v[212:215], v[84:87]
	v_mfma_f32_16x16x32_bf16 v[88:91], v[184:187], v[212:215], v[88:91]
	v_mfma_f32_16x16x32_bf16 v[92:95], v[188:191], v[212:215], v[92:95]
	ds_read_b128 v[164:167], v232 offset:5120
	v_mfma_f32_16x16x32_bf16 v[96:99], v[176:179], v[216:219], v[96:99]
	v_mfma_f32_16x16x32_bf16 v[100:103], v[180:183], v[216:219], v[100:103]
	v_mfma_f32_16x16x32_bf16 v[104:107], v[184:187], v[216:219], v[104:107]
	v_mfma_f32_16x16x32_bf16 v[108:111], v[188:191], v[216:219], v[108:111]
	ds_read_b128 v[168:171], v232 offset:6144
	s_add_u32 s98, s98, 24576
	s_cmp_eq_u32 s98, 73728
	s_cselect_b32 s98, 0, s98
	v_mfma_f32_16x16x32_bf16 v[112:115], v[176:179], v[220:223], v[112:115]
	v_mfma_f32_16x16x32_bf16 v[116:119], v[180:183], v[220:223], v[116:119]
	v_mfma_f32_16x16x32_bf16 v[120:123], v[184:187], v[220:223], v[120:123]
	v_mfma_f32_16x16x32_bf16 v[124:127], v[188:191], v[220:223], v[124:127]
	ds_read_b128 v[172:175], v232 offset:7168
	s_cmp_eq_u32 s10, 0
	s_cbranch_scc0 .Lg8_hi3
	s_setprio 0
.Lg8_hi3:
	s_waitcnt vmcnt(0)
	s_waitcnt lgkmcnt(0)
	s_barrier
	v_add_u32_e32 v232, s98, v230
	v_add_u32_e32 v233, s98, v231
	s_setprio 1
	v_mfma_f32_16x16x32_bf16 v[0:3], v[128:131], v[144:147], v[0:3]
	v_mfma_f32_16x16x32_bf16 v[4:7], v[132:135], v[144:147], v[4:7]
	v_mfma_f32_16x16x32_bf16 v[8:11], v[136:139], v[144:147], v[8:11]
	v_mfma_f32_16x16x32_bf16 v[12:15], v[140:143], v[144:147], v[12:15]
	ds_read_b128 v[176:179], v233 offset:0
	ds_read_b128 v[180:183], v233 offset:1024
	v_mfma_f32_16x16x32_bf16 v[16:19], v[128:131], v[148:151], v[16:19]
	v_mfma_f32_16x16x32_bf16 v[20:23], v[132:135], v[148:151], v[20:23]
	v_mfma_f32_16x16x32_bf16 v[24:27], v[136:139], v[148:151], v[24:27]
	v_mfma_f32_16x16x32_bf16 v[28:31], v[140:143], v[148:151], v[28:31]
	ds_read_b128 v[184:187], v233 offset:2048
	ds_read_b128 v[188:191], v233 offset:3072
	v_mfma_f32_16x16x32_bf16 v[32:35], v[128:131], v[152:155], v[32:35]
	v_mfma_f32_16x16x32_bf16 v[36:39], v[132:135], v[152:155], v[36:39]
	v_mfma_f32_16x16x32_bf16 v[40:43], v[136:139], v[152:155], v[40:43]
	v_mfma_f32_16x16x32_bf16 v[44:47], v[140:143], v[152:155], v[44:47]
	ds_read_b128 v[192:195], v232 offset:0
	ds_read_b128 v[196:199], v232 offset:1024
	v_mfma_f32_16x16x32_bf16 v[48:51], v[128:131], v[156:159], v[48:51]
	v_mfma_f32_16x16x32_bf16 v[52:55], v[132:135], v[156:159], v[52:55]
	v_mfma_f32_16x16x32_bf16 v[56:59], v[136:139], v[156:159], v[56:59]
	v_mfma_f32_16x16x32_bf16 v[60:63], v[140:143], v[156:159], v[60:63]
	ds_read_b128 v[200:203], v232 offset:2048
	ds_read_b128 v[204:207], v232 offset:3072
	v_mfma_f32_16x16x32_bf16 v[64:67], v[128:131], v[160:163], v[64:67]
	v_mfma_f32_16x16x32_bf16 v[68:71], v[132:135], v[160:163], v[68:71]
	v_mfma_f32_16x16x32_bf16 v[72:75], v[136:139], v[160:163], v[72:75]
	v_mfma_f32_16x16x32_bf16 v[76:79], v[140:143], v[160:163], v[76:79]
	ds_read_b128 v[208:211], v232 offset:4096
	v_mfma_f32_16x16x32_bf16 v[80:83], v[128:131], v[164:167], v[80:83]
	v_mfma_f32_16x16x32_bf16 v[84:87], v[132:135], v[164:167], v[84:87]
	v_mfma_f32_16x16x32_bf16 v[88:91], v[136:139], v[164:167], v[88:91]
	v_mfma_f32_16x16x32_bf16 v[92:95], v[140:143], v[164:167], v[92:95]
	ds_read_b128 v[212:215], v232 offset:5120
	v_mfma_f32_16x16x32_bf16 v[96:99], v[128:131], v[168:171], v[96:99]
	v_mfma_f32_16x16x32_bf16 v[100:103], v[132:135], v[168:171], v[100:103]
	v_mfma_f32_16x16x32_bf16 v[104:107], v[136:139], v[168:171], v[104:107]
	v_mfma_f32_16x16x32_bf16 v[108:111], v[140:143], v[168:171], v[108:111]
	ds_read_b128 v[216:219], v232 offset:6144
	s_add_u32 s98, s98, 24576
	s_cmp_eq_u32 s98, 73728
	s_cselect_b32 s98, 0, s98
	v_mfma_f32_16x16x32_bf16 v[112:115], v[128:131], v[172:175], v[112:115]
	v_mfma_f32_16x16x32_bf16 v[116:119], v[132:135], v[172:175], v[116:119]
	v_mfma_f32_16x16x32_bf16 v[120:123], v[136:139], v[172:175], v[120:123]
	v_mfma_f32_16x16x32_bf16 v[124:127], v[140:143], v[172:175], v[124:127]
	ds_read_b128 v[220:223], v232 offset:7168
	s_cmp_eq_u32 s10, 0
	s_cbranch_scc0 .Lg8_hi4
	s_setprio 0
; template <class Epi>
; DI void gemm_tile(char* smem, const bf16_t* __restrict__ A0, int lda0, int ksplit, const bf16_t* __restrict__ A1, int lda1,
;                   const bf16_t* __restrict__ Bt, int K, int row0, int col0, const Epi& epi, int tid) {
;     ...
; #pragma unroll
;   for (int m = 0; m < 8; ++m)
; #pragma unroll
;     for (int n = 0; n < 4; ++n) epi(row0 + wr * 128 + m * 16 + fr, col0 + wc * 64 + n * 16 + fq * 4, acc[m][n]);
.Lg8_hi4:
	s_waitcnt lgkmcnt(0)
	s_barrier
	s_setprio 1
	v_mfma_f32_16x16x32_bf16 v[0:3], v[176:179], v[192:195], v[0:3]
	v_mfma_f32_16x16x32_bf16 v[4:7], v[180:183], v[192:195], v[4:7]
	v_mfma_f32_16x16x32_bf16 v[8:11], v[184:187], v[192:195], v[8:11]
	v_mfma_f32_16x16x32_bf16 v[12:15], v[188:191], v[192:195], v[12:15]
	v_mfma_f32_16x16x32_bf16 v[16:19], v[176:179], v[196:199], v[16:19]
	v_mfma_f32_16x16x32_bf16 v[20:23], v[180:183], v[196:199], v[20:23]
	v_mfma_f32_16x16x32_bf16 v[24:27], v[184:187], v[196:199], v[24:27]
	v_mfma_f32_16x16x32_bf16 v[28:31], v[188:191], v[196:199], v[28:31]
	v_mfma_f32_16x16x32_bf16 v[32:35], v[176:179], v[200:203], v[32:35]
	v_mfma_f32_16x16x32_bf16 v[36:39], v[180:183], v[200:203], v[36:39]
	v_mfma_f32_16x16x32_bf16 v[40:43], v[184:187], v[200:203], v[40:43]
	v_mfma_f32_16x16x32_bf16 v[44:47], v[188:191], v[200:203], v[44:47]
	v_mfma_f32_16x16x32_bf16 v[48:51], v[176:179], v[204:207], v[48:51]
	v_mfma_f32_16x16x32_bf16 v[52:55], v[180:183], v[204:207], v[52:55]
	v_mfma_f32_16x16x32_bf16 v[56:59], v[184:187], v[204:207], v[56:59]
	v_mfma_f32_16x16x32_bf16 v[60:63], v[188:191], v[204:207], v[60:63]
	v_mfma_f32_16x16x32_bf16 v[64:67], v[176:179], v[208:211], v[64:67]
	v_mfma_f32_16x16x32_bf16 v[68:71], v[180:183], v[208:211], v[68:71]
	v_mfma_f32_16x16x32_bf16 v[72:75], v[184:187], v[208:211], v[72:75]
	v_mfma_f32_16x16x32_bf16 v[76:79], v[188:191], v[208:211], v[76:79]
	v_mfma_f32_16x16x32_bf16 v[80:83], v[176:179], v[212:215], v[80:83]
	v_mfma_f32_16x16x32_bf16 v[84:87], v[180:183], v[212:215], v[84:87]
	v_mfma_f32_16x16x32_bf16 v[88:91], v[184:187], v[212:215], v[88:91]
	v_mfma_f32_16x16x32_bf16 v[92:95], v[188:191], v[212:215], v[92:95]
	v_mfma_f32_16x16x32_bf16 v[96:99], v[176:179], v[216:219], v[96:99]
	v_mfma_f32_16x16x32_bf16 v[100:103], v[180:183], v[216:219], v[100:103]
	v_mfma_f32_16x16x32_bf16 v[104:107], v[184:187], v[216:219], v[104:107]
	v_mfma_f32_16x16x32_bf16 v[108:111], v[188:191], v[216:219], v[108:111]
	v_mfma_f32_16x16x32_bf16 v[112:115], v[176:179], v[220:223], v[112:115]
	v_mfma_f32_16x16x32_bf16 v[116:119], v[180:183], v[220:223], v[116:119]
	v_mfma_f32_16x16x32_bf16 v[120:123], v[184:187], v[220:223], v[120:123]
	v_mfma_f32_16x16x32_bf16 v[124:127], v[188:191], v[220:223], v[124:127]
	s_cmp_eq_u32 s10, 0
	s_cbranch_scc0 .Lg8_hi5
	s_setprio 0
.Lg8_hi5:
	s_branch .Lg8_epi
.Lg8_epi:
	s_nop 7
	s_nop 7
	s_mul_i32 s12, s18, 8192
	s_lshl_b32 s11, s13, 1
	s_add_u32 s12, s12, s11
	s_add_u32 s12, s12, 0x7800000
	s_add_u32 s4, s92, s12
	s_addc_u32 s5, s93, 0
	v_max_f32_e32 v0, 0, v0
	v_max_f32_e32 v1, 0, v1
	v_max_f32_e32 v2, 0, v2
	v_max_f32_e32 v3, 0, v3
	v_pk_mul_f32 v[0:1], v[0:1], v[0:1]
	v_pk_mul_f32 v[2:3], v[2:3], v[2:3]
	v_cvt_pk_bf16_f32 v128, v0, v1
	v_cvt_pk_bf16_f32 v129, v2, v3
	ds_write_b64 v236, v[128:129]
	v_max_f32_e32 v4, 0, v4
	v_max_f32_e32 v5, 0, v5
	v_max_f32_e32 v6, 0, v6
	v_max_f32_e32 v7, 0, v7
	v_pk_mul_f32 v[4:5], v[4:5], v[4:5]
	v_pk_mul_f32 v[6:7], v[6:7], v[6:7]
	v_cvt_pk_bf16_f32 v130, v4, v5
	v_cvt_pk_bf16_f32 v131, v6, v7
	ds_write_b64 v236, v[130:131] offset:32
	v_max_f32_e32 v8, 0, v8
	v_max_f32_e32 v9, 0, v9
	v_max_f32_e32 v10, 0, v10
	v_max_f32_e32 v11, 0, v11
	v_pk_mul_f32 v[8:9], v[8:9], v[8:9]
	v_pk_mul_f32 v[10:11], v[10:11], v[10:11]
	v_cvt_pk_bf16_f32 v132, v8, v9
	v_cvt_pk_bf16_f32 v133, v10, v11
	ds_write_b64 v236, v[132:133] offset:64
	v_max_f32_e32 v12, 0, v12
	v_max_f32_e32 v13, 0, v13
	v_max_f32_e32 v14, 0, v14
	v_max_f32_e32 v15, 0, v15
	v_pk_mul_f32 v[12:13], v[12:13], v[12:13]
	v_pk_mul_f32 v[14:15], v[14:15], v[14:15]
	v_cvt_pk_bf16_f32 v134, v12, v13
	v_cvt_pk_bf16_f32 v135, v14, v15
	ds_write_b64 v236, v[134:135] offset:96
	v_max_f32_e32 v16, 0, v16
	v_max_f32_e32 v17, 0, v17
	v_max_f32_e32 v18, 0, v18
	v_max_f32_e32 v19, 0, v19
	v_pk_mul_f32 v[16:17], v[16:17], v[16:17]
	v_pk_mul_f32 v[18:19], v[18:19], v[18:19]
	v_cvt_pk_bf16_f32 v136, v16, v17
	v_cvt_pk_bf16_f32 v137, v18, v19
	ds_write_b64 v236, v[136:137] offset:2304
	v_max_f32_e32 v20, 0, v20
	v_max_f32_e32 v21, 0, v21
	v_max_f32_e32 v22, 0, v22
	v_max_f32_e32 v23, 0, v23
	v_pk_mul_f32 v[20:21], v[20:21], v[20:21]
	v_pk_mul_f32 v[22:23], v[22:23], v[22:23]
	v_cvt_pk_bf16_f32 v138, v20, v21
	v_cvt_pk_bf16_f32 v139, v22, v23
	ds_write_b64 v236, v[138:139] offset:2336
	v_max_f32_e32 v24, 0, v24
	v_max_f32_e32 v25, 0, v25
	v_max_f32_e32 v26, 0, v26
	v_max_f32_e32 v27, 0, v27
	v_pk_mul_f32 v[24:25], v[24:25], v[24:25]
	v_pk_mul_f32 v[26:27], v[26:27], v[26:27]
	v_cvt_pk_bf16_f32 v140, v24, v25
	v_cvt_pk_bf16_f32 v141, v26, v27
	ds_write_b64 v236, v[140:141] offset:2368
	v_max_f32_e32 v28, 0, v28
	v_max_f32_e32 v29, 0, v29
	v_max_f32_e32 v30, 0, v30
	v_max_f32_e32 v31, 0, v31
	v_pk_mul_f32 v[28:29], v[28:29], v[28:29]
	v_pk_mul_f32 v[30:31], v[30:31], v[30:31]
	v_cvt_pk_bf16_f32 v142, v28, v29
	v_cvt_pk_bf16_f32 v143, v30, v31
	ds_write_b64 v236, v[142:143] offset:2400
	v_max_f32_e32 v32, 0, v32
	v_max_f32_e32 v33, 0, v33
	v_max_f32_e32 v34, 0, v34
	v_max_f32_e32 v35, 0, v35
	v_pk_mul_f32 v[32:33], v[32:33], v[32:33]
	v_pk_mul_f32 v[34:35], v[34:35], v[34:35]
	v_cvt_pk_bf16_f32 v144, v32, v33
	v_cvt_pk_bf16_f32 v145, v34, v35
	ds_write_b64 v236, v[144:145] offset:4608
	v_max_f32_e32 v36, 0, v36
	v_max_f32_e32 v37, 0, v37
	v_max_f32_e32 v38, 0, v38
	v_max_f32_e32 v39, 0, v39
	v_pk_mul_f32 v[36:37], v[36:37], v[36:37]
	v_pk_mul_f32 v[38:39], v[38:39], v[38:39]
	v_cvt_pk_bf16_f32 v146, v36, v37
	v_cvt_pk_bf16_f32 v147, v38, v39
	ds_write_b64 v236, v[146:147] offset:4640
	v_max_f32_e32 v40, 0, v40
	v_max_f32_e32 v41, 0, v41
	v_max_f32_e32 v42, 0, v42
	v_max_f32_e32 v43, 0, v43
	v_pk_mul_f32 v[40:41], v[40:41], v[40:41]
	v_pk_mul_f32 v[42:43], v[42:43], v[42:43]
	v_cvt_pk_bf16_f32 v148, v40, v41
	v_cvt_pk_bf16_f32 v149, v42, v43
	ds_write_b64 v236, v[148:149] offset:4672
	v_max_f32_e32 v44, 0, v44
	v_max_f32_e32 v45, 0, v45
	v_max_f32_e32 v46, 0, v46
	v_max_f32_e32 v47, 0, v47
	v_pk_mul_f32 v[44:45], v[44:45], v[44:45]
	v_pk_mul_f32 v[46:47], v[46:47], v[46:47]
	v_cvt_pk_bf16_f32 v150, v44, v45
	v_cvt_pk_bf16_f32 v151, v46, v47
	ds_write_b64 v236, v[150:151] offset:4704
	v_max_f32_e32 v48, 0, v48
	v_max_f32_e32 v49, 0, v49
	v_max_f32_e32 v50, 0, v50
	v_max_f32_e32 v51, 0, v51
	v_pk_mul_f32 v[48:49], v[48:49], v[48:49]
	v_pk_mul_f32 v[50:51], v[50:51], v[50:51]
	v_cvt_pk_bf16_f32 v152, v48, v49
	v_cvt_pk_bf16_f32 v153, v50, v51
	ds_write_b64 v236, v[152:153] offset:6912
	v_max_f32_e32 v52, 0, v52
	v_max_f32_e32 v53, 0, v53
	v_max_f32_e32 v54, 0, v54
	v_max_f32_e32 v55, 0, v55
	v_pk_mul_f32 v[52:53], v[52:53], v[52:53]
	v_pk_mul_f32 v[54:55], v[54:55], v[54:55]
	v_cvt_pk_bf16_f32 v154, v52, v53
	v_cvt_pk_bf16_f32 v155, v54, v55
	ds_write_b64 v236, v[154:155] offset:6944
	v_max_f32_e32 v56, 0, v56
	v_max_f32_e32 v57, 0, v57
	v_max_f32_e32 v58, 0, v58
	v_max_f32_e32 v59, 0, v59
	v_pk_mul_f32 v[56:57], v[56:57], v[56:57]
	v_pk_mul_f32 v[58:59], v[58:59], v[58:59]
	v_cvt_pk_bf16_f32 v156, v56, v57
	v_cvt_pk_bf16_f32 v157, v58, v59
	ds_write_b64 v236, v[156:157] offset:6976
	v_max_f32_e32 v60, 0, v60
	v_max_f32_e32 v61, 0, v61
	v_max_f32_e32 v62, 0, v62
	v_max_f32_e32 v63, 0, v63
	v_pk_mul_f32 v[60:61], v[60:61], v[60:61]
	v_pk_mul_f32 v[62:63], v[62:63], v[62:63]
	v_cvt_pk_bf16_f32 v158, v60, v61
	v_cvt_pk_bf16_f32 v159, v62, v63
	ds_write_b64 v236, v[158:159] offset:7008
	v_max_f32_e32 v64, 0, v64
	v_max_f32_e32 v65, 0, v65
	v_max_f32_e32 v66, 0, v66
	v_max_f32_e32 v67, 0, v67
	v_pk_mul_f32 v[64:65], v[64:65], v[64:65]
	v_pk_mul_f32 v[66:67], v[66:67], v[66:67]
	v_cvt_pk_bf16_f32 v128, v64, v65
	v_cvt_pk_bf16_f32 v129, v66, v67
	ds_write_b64 v236, v[128:129] offset:9216
	v_max_f32_e32 v68, 0, v68
	v_max_f32_e32 v69, 0, v69
	v_max_f32_e32 v70, 0, v70
	v_max_f32_e32 v71, 0, v71
	v_pk_mul_f32 v[68:69], v[68:69], v[68:69]
	v_pk_mul_f32 v[70:71], v[70:71], v[70:71]
	v_cvt_pk_bf16_f32 v130, v68, v69
	v_cvt_pk_bf16_f32 v131, v70, v71
	ds_write_b64 v236, v[130:131] offset:9248
	v_max_f32_e32 v72, 0, v72
	v_max_f32_e32 v73, 0, v73
	v_max_f32_e32 v74, 0, v74
	v_max_f32_e32 v75, 0, v75
	v_pk_mul_f32 v[72:73], v[72:73], v[72:73]
	v_pk_mul_f32 v[74:75], v[74:75], v[74:75]
	v_cvt_pk_bf16_f32 v132, v72, v73
	v_cvt_pk_bf16_f32 v133, v74, v75
	ds_write_b64 v236, v[132:133] offset:9280
	v_max_f32_e32 v76, 0, v76
	v_max_f32_e32 v77, 0, v77
	v_max_f32_e32 v78, 0, v78
	v_max_f32_e32 v79, 0, v79
	v_pk_mul_f32 v[76:77], v[76:77], v[76:77]
	v_pk_mul_f32 v[78:79], v[78:79], v[78:79]
	v_cvt_pk_bf16_f32 v134, v76, v77
	v_cvt_pk_bf16_f32 v135, v78, v79
	ds_write_b64 v236, v[134:135] offset:9312
	v_max_f32_e32 v80, 0, v80
	v_max_f32_e32 v81, 0, v81
	v_max_f32_e32 v82, 0, v82
	v_max_f32_e32 v83, 0, v83
	v_pk_mul_f32 v[80:81], v[80:81], v[80:81]
	v_pk_mul_f32 v[82:83], v[82:83], v[82:83]
	v_cvt_pk_bf16_f32 v136, v80, v81
	v_cvt_pk_bf16_f32 v137, v82, v83
	ds_write_b64 v236, v[136:137] offset:11520
	v_max_f32_e32 v84, 0, v84
	v_max_f32_e32 v85, 0, v85
	v_max_f32_e32 v86, 0, v86
	v_max_f32_e32 v87, 0, v87
	v_pk_mul_f32 v[84:85], v[84:85], v[84:85]
	v_pk_mul_f32 v[86:87], v[86:87], v[86:87]
	v_cvt_pk_bf16_f32 v138, v84, v85
	v_cvt_pk_bf16_f32 v139, v86, v87
	ds_write_b64 v236, v[138:139] offset:11552
	v_max_f32_e32 v88, 0, v88
	v_max_f32_e32 v89, 0, v89
	v_max_f32_e32 v90, 0, v90
	v_max_f32_e32 v91, 0, v91
	v_pk_mul_f32 v[88:89], v[88:89], v[88:89]
	v_pk_mul_f32 v[90:91], v[90:91], v[90:91]
	v_cvt_pk_bf16_f32 v140, v88, v89
	v_cvt_pk_bf16_f32 v141, v90, v91
	ds_write_b64 v236, v[140:141] offset:11584
	v_max_f32_e32 v92, 0, v92
	v_max_f32_e32 v93, 0, v93
	v_max_f32_e32 v94, 0, v94
	v_max_f32_e32 v95, 0, v95
	v_pk_mul_f32 v[92:93], v[92:93], v[92:93]
	v_pk_mul_f32 v[94:95], v[94:95], v[94:95]
	v_cvt_pk_bf16_f32 v142, v92, v93
	v_cvt_pk_bf16_f32 v143, v94, v95
	ds_write_b64 v236, v[142:143] offset:11616
	v_max_f32_e32 v96, 0, v96
	v_max_f32_e32 v97, 0, v97
	v_max_f32_e32 v98, 0, v98
	v_max_f32_e32 v99, 0, v99
	v_pk_mul_f32 v[96:97], v[96:97], v[96:97]
	v_pk_mul_f32 v[98:99], v[98:99], v[98:99]
	v_cvt_pk_bf16_f32 v144, v96, v97
	v_cvt_pk_bf16_f32 v145, v98, v99
	ds_write_b64 v236, v[144:145] offset:13824
	v_max_f32_e32 v100, 0, v100
	v_max_f32_e32 v101, 0, v101
	v_max_f32_e32 v102, 0, v102
	v_max_f32_e32 v103, 0, v103
	v_pk_mul_f32 v[100:101], v[100:101], v[100:101]
	v_pk_mul_f32 v[102:103], v[102:103], v[102:103]
	v_cvt_pk_bf16_f32 v146, v100, v101
	v_cvt_pk_bf16_f32 v147, v102, v103
	ds_write_b64 v236, v[146:147] offset:13856
	v_max_f32_e32 v104, 0, v104
	v_max_f32_e32 v105, 0, v105
	v_max_f32_e32 v106, 0, v106
	v_max_f32_e32 v107, 0, v107
	v_pk_mul_f32 v[104:105], v[104:105], v[104:105]
	v_pk_mul_f32 v[106:107], v[106:107], v[106:107]
	v_cvt_pk_bf16_f32 v148, v104, v105
	v_cvt_pk_bf16_f32 v149, v106, v107
	ds_write_b64 v236, v[148:149] offset:13888
	v_max_f32_e32 v108, 0, v108
	v_max_f32_e32 v109, 0, v109
	v_max_f32_e32 v110, 0, v110
	v_max_f32_e32 v111, 0, v111
	v_pk_mul_f32 v[108:109], v[108:109], v[108:109]
	v_pk_mul_f32 v[110:111], v[110:111], v[110:111]
	v_cvt_pk_bf16_f32 v150, v108, v109
	v_cvt_pk_bf16_f32 v151, v110, v111
	ds_write_b64 v236, v[150:151] offset:13920
	v_max_f32_e32 v112, 0, v112
	v_max_f32_e32 v113, 0, v113
	v_max_f32_e32 v114, 0, v114
	v_max_f32_e32 v115, 0, v115
	v_pk_mul_f32 v[112:113], v[112:113], v[112:113]
	v_pk_mul_f32 v[114:115], v[114:115], v[114:115]
	v_cvt_pk_bf16_f32 v152, v112, v113
	v_cvt_pk_bf16_f32 v153, v114, v115
	ds_write_b64 v236, v[152:153] offset:16128
	v_max_f32_e32 v116, 0, v116
	v_max_f32_e32 v117, 0, v117
	v_max_f32_e32 v118, 0, v118
	v_max_f32_e32 v119, 0, v119
	v_pk_mul_f32 v[116:117], v[116:117], v[116:117]
	v_pk_mul_f32 v[118:119], v[118:119], v[118:119]
	v_cvt_pk_bf16_f32 v154, v116, v117
	v_cvt_pk_bf16_f32 v155, v118, v119
	ds_write_b64 v236, v[154:155] offset:16160
	v_max_f32_e32 v120, 0, v120
	v_max_f32_e32 v121, 0, v121
	v_max_f32_e32 v122, 0, v122
	v_max_f32_e32 v123, 0, v123
	v_pk_mul_f32 v[120:121], v[120:121], v[120:121]
	v_pk_mul_f32 v[122:123], v[122:123], v[122:123]
	v_cvt_pk_bf16_f32 v156, v120, v121
	v_cvt_pk_bf16_f32 v157, v122, v123
	ds_write_b64 v236, v[156:157] offset:16192
	v_max_f32_e32 v124, 0, v124
	v_max_f32_e32 v125, 0, v125
	v_max_f32_e32 v126, 0, v126
	v_max_f32_e32 v127, 0, v127
	v_pk_mul_f32 v[124:125], v[124:125], v[124:125]
	v_pk_mul_f32 v[126:127], v[126:127], v[126:127]
	v_cvt_pk_bf16_f32 v158, v124, v125
	v_cvt_pk_bf16_f32 v159, v126, v127
	ds_write_b64 v236, v[158:159] offset:16224
	s_waitcnt lgkmcnt(0)
; DI unsigned pack2(float lo, float hi) { const f32x2c v = {lo, hi}; return __builtin_bit_cast(unsigned, __builtin_convertvector(v, bf16x2c)); }
; template <class Epi>
; DI void gemm_tile(char* smem, const bf16_t* __restrict__ A0, int lda0, int ksplit, const bf16_t* __restrict__ A1, int lda1,
;                   const bf16_t* __restrict__ Bt, int K, int row0, int col0, const Epi& epi, int tid) {
;     ...
; #pragma unroll
;   for (int m = 0; m < 8; ++m)
; #pragma unroll
;     for (int n = 0; n < 4; ++n) epi(row0 + wr * 128 + m * 16 + fr, col0 + wc * 64 + n * 16 + fq * 4, acc[m][n]);
; }
; DI void st_bf16x4(bf16_t* o, f32x4 v) { u32x2 q; q.x = pack2(v[0], v[1]); q.y = pack2(v[2], v[3]); *(u32x2*)o = q; }
	ds_read_b128 v[128:131], v237
	ds_read_b128 v[132:135], v237 offset:1152
	ds_read_b128 v[136:139], v237 offset:2304
	ds_read_b128 v[140:143], v237 offset:3456
	ds_read_b128 v[144:147], v237 offset:4608
	ds_read_b128 v[148:151], v237 offset:5760
	ds_read_b128 v[152:155], v237 offset:6912
	ds_read_b128 v[156:159], v237 offset:8064
	ds_read_b128 v[160:163], v237 offset:9216
	ds_read_b128 v[164:167], v237 offset:10368
	ds_read_b128 v[168:171], v237 offset:11520
	ds_read_b128 v[172:175], v237 offset:12672
	ds_read_b128 v[176:179], v237 offset:13824
	ds_read_b128 v[180:183], v237 offset:14976
	ds_read_b128 v[184:187], v237 offset:16128
	ds_read_b128 v[188:191], v237 offset:17280
	s_waitcnt lgkmcnt(15)
	global_store_dwordx4 v238, v[128:131], s[4:5] nt
	s_add_u32 s4, s4, 0x10000
	s_addc_u32 s5, s5, 0
	s_waitcnt lgkmcnt(14)
	global_store_dwordx4 v238, v[132:135], s[4:5] nt
	s_add_u32 s4, s4, 0x10000
	s_addc_u32 s5, s5, 0
	s_waitcnt lgkmcnt(13)
	global_store_dwordx4 v238, v[136:139], s[4:5] nt
	s_add_u32 s4, s4, 0x10000
	s_addc_u32 s5, s5, 0
	s_waitcnt lgkmcnt(12)
	global_store_dwordx4 v238, v[140:143], s[4:5] nt
	s_add_u32 s4, s4, 0x10000
	s_addc_u32 s5, s5, 0
	s_waitcnt lgkmcnt(11)
	global_store_dwordx4 v238, v[144:147], s[4:5] nt
	s_add_u32 s4, s4, 0x10000
	s_addc_u32 s5, s5, 0
	s_waitcnt lgkmcnt(10)
	global_store_dwordx4 v238, v[148:151], s[4:5] nt
	s_add_u32 s4, s4, 0x10000
	s_addc_u32 s5, s5, 0
	s_waitcnt lgkmcnt(9)
	global_store_dwordx4 v238, v[152:155], s[4:5] nt
	s_add_u32 s4, s4, 0x10000
	s_addc_u32 s5, s5, 0
	s_waitcnt lgkmcnt(8)
	global_store_dwordx4 v238, v[156:159], s[4:5] nt
	s_add_u32 s4, s4, 0x10000
	s_addc_u32 s5, s5, 0
	s_waitcnt lgkmcnt(7)
	global_store_dwordx4 v238, v[160:163], s[4:5] nt
	s_add_u32 s4, s4, 0x10000
	s_addc_u32 s5, s5, 0
	s_waitcnt lgkmcnt(6)
	global_store_dwordx4 v238, v[164:167], s[4:5] nt
	s_add_u32 s4, s4, 0x10000
	s_addc_u32 s5, s5, 0
	s_waitcnt lgkmcnt(5)
	global_store_dwordx4 v238, v[168:171], s[4:5] nt
	s_add_u32 s4, s4, 0x10000
	s_addc_u32 s5, s5, 0
	s_waitcnt lgkmcnt(4)
	global_store_dwordx4 v238, v[172:175], s[4:5] nt
	s_add_u32 s4, s4, 0x10000
	s_addc_u32 s5, s5, 0
	s_waitcnt lgkmcnt(3)
	global_store_dwordx4 v238, v[176:179], s[4:5] nt
	s_add_u32 s4, s4, 0x10000
	s_addc_u32 s5, s5, 0
	s_waitcnt lgkmcnt(2)
	global_store_dwordx4 v238, v[180:183], s[4:5] nt
	s_add_u32 s4, s4, 0x10000
	s_addc_u32 s5, s5, 0
	s_waitcnt lgkmcnt(1)
	global_store_dwordx4 v238, v[184:187], s[4:5] nt
	s_add_u32 s4, s4, 0x10000
	s_addc_u32 s5, s5, 0
	s_waitcnt lgkmcnt(0)
	global_store_dwordx4 v238, v[188:191], s[4:5] nt
	s_nop 1
	s_add_u32 s17, s17, 64
	s_branch .Lg8_tile

; template <class Epi>
; DI void gemm_tile(char* smem, const bf16_t* __restrict__ A0, int lda0, int ksplit, const bf16_t* __restrict__ A1, int lda1,
;                   const bf16_t* __restrict__ Bt, int K, int row0, int col0, const Epi& epi, int tid) {
;   constexpr int BK = 32, PITCH = 40, BUF = (256 + 128) * PITCH;
;   bf16_t* sbase = (bf16_t*)smem;
;   const int lane = tid & 63, wid = tid >> 6, wr = wid >> 1, wc = wid & 1, fr = lane & 15, fq = lane >> 4;
;   f32x4 acc[8][4];
; #pragma unroll
;   for (int m = 0; m < 8; ++m)
; #pragma unroll
;     for (int n = 0; n < 4; ++n) acc[m][n] = (f32x4){0.f, 0.f, 0.f, 0.f};
;   u32x4 ra[2][4], rb[2][2];
;   const int nk = K / BK;
;   const int sr = tid >> 2, scv = tid & 3;
; template <class Epi>
; DI void gemm_phase(char* smem, const bf16_t* A0, int lda0, int ksplit, const bf16_t* A1, int lda1, const bf16_t* Bt, int K, int nN, const Epi& epi, int tid) {
;   const int G = gridDim.x;
;   if ((G & 7) == 0) {
;     const int x = blockIdx.x & 7, l = blockIdx.x >> 3, L = G >> 3, per = 8 * nN, tot = 2 * per;
;     for (int q = l; q < tot; q += L) { const int rgl = q / per, rem = q % per, ct = rem >> 3, rt = (x * 2 + rgl) * 8 + (rem & 7);
;       gemm_tile(smem, A0, lda0, ksplit, A1, lda1, Bt, K, rt * 256, ct * 128, epi, tid); }
.LBB0_929:
	s_cmp_gt_i32 s94, 9
	s_cselect_b64 s[0:1], -1, 0
	s_cmp_lt_i32 s95, 10
	s_cselect_b64 s[2:3], -1, 0
	s_or_b64 s[0:1], s[0:1], s[2:3]
	s_and_b64 vcc, exec, s[0:1]
	s_cbranch_vccnz .LBB0_957
	s_load_dword s12, s[74:75], 0x180
	s_add_u32 s0, s92, 0x7800000
	s_addc_u32 s1, s93, 0
	s_add_u32 s2, s92, 0x1bc0000
	s_addc_u32 s3, s93, 0
	s_waitcnt lgkmcnt(0)
	s_and_b32 s14, s72, 0xffffffc0
	v_mbcnt_hi_u32_b32 v195, -1, v194
	s_and_b32 s13, s12, 7
	s_cmp_lg_u32 s13, 0
	s_waitcnt vmcnt(16)
	v_add_u32_e32 v196, s14, v195
	v_mbcnt_lo_u32_b32 v240, -1, 0
	v_mbcnt_hi_u32_b32 v240, -1, v240
	s_lshr_b32 s10, s72, 6
	s_lshl_b32 s101, s10, 10
	v_and_b32_e32 v241, 15, v240
	v_lshrrev_b32_e32 v242, 4, v240
	v_bfe_u32 v243, v240, 3, 1
	v_mul_u32_u24_e32 v243, 3, v243
	v_xor_b32_e32 v243, v242, v243
	v_lshlrev_b32_e32 v243, 4, v243
	v_lshl_add_u32 v243, v241, 6, v243
	s_lshr_b32 s9, s10, 1
	s_lshl_b32 s9, s9, 13
	v_add_u32_e32 v230, s9, v243
	s_and_b32 s9, s10, 1
	s_lshl_b32 s9, s9, 12
	s_add_u32 s9, s9, 16384
	v_add_u32_e32 v231, s9, v243
	s_lshr_b32 s9, s10, 1
	s_lshl_b32 s9, s9, 7
	v_add_u32_e32 v244, s9, v241
	s_and_b32 s9, s10, 1
	s_lshl_b32 s9, s9, 6
	v_lshl_add_u32 v245, v242, 2, s9
	s_movk_i32 s9, 0x1000
	v_mul_lo_u32 v246, v244, s9
	v_lshl_add_u32 v234, v245, 2, v246
	v_lshrrev_b32_e32 v241, 2, v240
	s_lshl_b32 s9, s10, 4
	v_add_u32_e32 v241, s9, v241
	v_bfe_u32 v242, v240, 5, 1
	v_mul_u32_u24_e32 v242, 3, v242
	v_and_b32_e32 v243, 3, v240
	v_xor_b32_e32 v243, v243, v242
	v_lshlrev_b32_e32 v243, 4, v243
	s_mov_b32 s9, 8192
	v_mad_u32_u24 v224, v241, s9, v243
	v_add_u32_e32 v225, 0x80000, v224
	v_add_u32_e32 v226, 0x100000, v224
	v_add_u32_e32 v227, 0x180000, v224
	s_mov_b32 s9, 8192
	v_mad_u32_u24 v228, v241, s9, v243
	v_add_u32_e32 v229, 0x80000, v228
	s_load_dwordx2 s[6:7], s[74:75], 0x168
	v_mbcnt_lo_u32_b32 v240, -1, 0
	v_mbcnt_hi_u32_b32 v240, -1, v240
	s_lshr_b32 s10, s72, 6
	s_mul_i32 s9, s10, 17408
	v_and_b32_e32 v241, 15, v240
	v_lshrrev_b32_e32 v242, 4, v240
	v_mul_u32_u24_e32 v243, 0x110, v241
	v_lshl_add_u32 v243, v242, 4, v243
	v_add_u32_e32 v245, s9, v243
	v_mul_u32_u24_e32 v243, 0x110, v242
	v_lshl_add_u32 v243, v241, 4, v243
	v_add_u32_e32 v246, s9, v243
	s_lshr_b32 s9, s10, 1
	s_lshl_b32 s9, s9, 7
	v_add_u32_e32 v243, s9, v242
	v_lshlrev_b32_e32 v243, 12, v243
	s_and_b32 s9, s10, 1
	s_lshl_b32 s9, s9, 8
	v_lshl_add_u32 v244, v241, 4, s9
	v_add_u32_e32 v247, v243, v244
	s_cmpk_gt_u32 s96, 0xff
	s_cselect_b32 s8, 1, 0
	s_cmpk_gt_u32 s96, 0xff
	s_cbranch_scc0 .Lg9_prio
	s_setprio 1

; #define LWRITE(S, buf) do { bf16_t* sA_ = sbase + (buf) * BUF; bf16_t* sB_ = sA_ + 256 * PITCH; \
;     _Pragma("unroll") for (int i_ = 0; i_ < 4; ++i_) *(u32x4*)(sA_ + (sr + i_ * 64) * PITCH + scv * 8) = ra[S][i_]; \
;     _Pragma("unroll") for (int i_ = 0; i_ < 2; ++i_) *(u32x4*)(sB_ + (sr + i_ * 64) * PITCH + scv * 8) = rb[S][i_]; } while (0)
; template <class Epi>
; DI void gemm_tile(char* smem, const bf16_t* __restrict__ A0, int lda0, int ksplit, const bf16_t* __restrict__ A1, int lda1,
;                   const bf16_t* __restrict__ Bt, int K, int row0, int col0, const Epi& epi, int tid) {
;     ...
;   __syncthreads();
;   {
;     const int last = nk - 1;
;     GLOAD(0, 0);
;     __builtin_amdgcn_sched_barrier(0);
;     GLOAD(1, 1);
;     __builtin_amdgcn_sched_barrier(0);
;     LWRITE(0, 0);
;     __builtin_amdgcn_sched_barrier(0);
;     GLOAD(0, (2 < last ? 2 : last));
;     __builtin_amdgcn_sched_barrier(0);
;     __syncthreads();
;     for (int kt = 0; kt < nk; kt += 2) {
;       LWRITE(1, 1);
;       __builtin_amdgcn_sched_barrier(0);
;       GLOAD(1, (kt + 3 < last ? kt + 3 : last));
;       __builtin_amdgcn_sched_barrier(0);
;       COMPUTE(0);
;       __syncthreads();
;       LWRITE(0, 0);
;       __builtin_amdgcn_sched_barrier(0);
;       GLOAD(0, (kt + 4 < last ? kt + 4 : last));
;       __builtin_amdgcn_sched_barrier(0);
;       COMPUTE(1);
;       __syncthreads();
;     }
.Lg9_kloop:
	s_waitcnt vmcnt(6)
	s_waitcnt lgkmcnt(0)
	s_barrier
	v_add_u32_e32 v232, s98, v230
	v_add_u32_e32 v233, s98, v231
	s_add_u32 s9, s17, s101
	s_setprio 1
	v_mfma_f32_16x16x32_bf16 v[0:3], v[128:131], v[144:147], v[0:3]
	v_mfma_f32_16x16x32_bf16 v[4:7], v[132:135], v[144:147], v[4:7]
	v_mfma_f32_16x16x32_bf16 v[8:11], v[136:139], v[144:147], v[8:11]
	v_mfma_f32_16x16x32_bf16 v[12:15], v[140:143], v[144:147], v[12:15]
	ds_read_b128 v[176:179], v233 offset:0
	ds_read_b128 v[180:183], v233 offset:1024
	s_add_u32 m0, s9, 0
	s_nop 0
	global_load_lds_dwordx4 v224, s[0:1]
	v_mfma_f32_16x16x32_bf16 v[16:19], v[128:131], v[148:151], v[16:19]
	v_mfma_f32_16x16x32_bf16 v[20:23], v[132:135], v[148:151], v[20:23]
	v_mfma_f32_16x16x32_bf16 v[24:27], v[136:139], v[148:151], v[24:27]
	v_mfma_f32_16x16x32_bf16 v[28:31], v[140:143], v[148:151], v[28:31]
	ds_read_b128 v[184:187], v233 offset:2048
	ds_read_b128 v[188:191], v233 offset:3072
	s_add_u32 m0, s9, 4096
	s_nop 0
	global_load_lds_dwordx4 v225, s[0:1]
	v_mfma_f32_16x16x32_bf16 v[32:35], v[128:131], v[152:155], v[32:35]
	v_mfma_f32_16x16x32_bf16 v[36:39], v[132:135], v[152:155], v[36:39]
	v_mfma_f32_16x16x32_bf16 v[40:43], v[136:139], v[152:155], v[40:43]
	v_mfma_f32_16x16x32_bf16 v[44:47], v[140:143], v[152:155], v[44:47]
	ds_read_b128 v[192:195], v232 offset:0
	ds_read_b128 v[196:199], v232 offset:1024
	s_add_u32 m0, s9, 8192
	s_nop 0
	global_load_lds_dwordx4 v226, s[0:1]
	v_mfma_f32_16x16x32_bf16 v[48:51], v[128:131], v[156:159], v[48:51]
	v_mfma_f32_16x16x32_bf16 v[52:55], v[132:135], v[156:159], v[52:55]
	v_mfma_f32_16x16x32_bf16 v[56:59], v[136:139], v[156:159], v[56:59]
	v_mfma_f32_16x16x32_bf16 v[60:63], v[140:143], v[156:159], v[60:63]
	ds_read_b128 v[200:203], v232 offset:2048
	ds_read_b128 v[204:207], v232 offset:3072
	s_add_u32 m0, s9, 12288
	s_nop 0
	global_load_lds_dwordx4 v227, s[0:1]
	v_mfma_f32_16x16x32_bf16 v[64:67], v[128:131], v[160:163], v[64:67]
	v_mfma_f32_16x16x32_bf16 v[68:71], v[132:135], v[160:163], v[68:71]
	v_mfma_f32_16x16x32_bf16 v[72:75], v[136:139], v[160:163], v[72:75]
	v_mfma_f32_16x16x32_bf16 v[76:79], v[140:143], v[160:163], v[76:79]
	ds_read_b128 v[208:211], v232 offset:4096
	s_add_u32 m0, s9, 16384
	s_nop 0
	global_load_lds_dwordx4 v228, s[2:3]
	v_mfma_f32_16x16x32_bf16 v[80:83], v[128:131], v[164:167], v[80:83]
	v_mfma_f32_16x16x32_bf16 v[84:87], v[132:135], v[164:167], v[84:87]
	v_mfma_f32_16x16x32_bf16 v[88:91], v[136:139], v[164:167], v[88:91]
	v_mfma_f32_16x16x32_bf16 v[92:95], v[140:143], v[164:167], v[92:95]
	ds_read_b128 v[212:215], v232 offset:5120
	s_add_u32 m0, s9, 20480
	s_nop 0
	global_load_lds_dwordx4 v229, s[2:3]
	v_mfma_f32_16x16x32_bf16 v[96:99], v[128:131], v[168:171], v[96:99]
	v_mfma_f32_16x16x32_bf16 v[100:103], v[132:135], v[168:171], v[100:103]
	v_mfma_f32_16x16x32_bf16 v[104:107], v[136:139], v[168:171], v[104:107]
	v_mfma_f32_16x16x32_bf16 v[108:111], v[140:143], v[168:171], v[108:111]
	ds_read_b128 v[216:219], v232 offset:6144
	s_add_u32 s0, s0, 64
	s_addc_u32 s1, s1, 0
	s_add_u32 s2, s2, 64
	s_addc_u32 s3, s3, 0
	s_add_u32 s100, s100, 1
	s_add_u32 s17, s17, 24576
	s_cmp_eq_u32 s17, 73728
	s_cselect_b32 s17, 0, s17
	s_add_u32 s98, s98, 24576
	s_cmp_eq_u32 s98, 73728
	s_cselect_b32 s98, 0, s98
	v_mfma_f32_16x16x32_bf16 v[112:115], v[128:131], v[172:175], v[112:115]
	v_mfma_f32_16x16x32_bf16 v[116:119], v[132:135], v[172:175], v[116:119]
	v_mfma_f32_16x16x32_bf16 v[120:123], v[136:139], v[172:175], v[120:123]
	v_mfma_f32_16x16x32_bf16 v[124:127], v[140:143], v[172:175], v[124:127]
	ds_read_b128 v[220:223], v232 offset:7168
	s_cmp_eq_u32 s8, 0
	s_cbranch_scc0 .Lg9_hi0
	s_setprio 0
.Lg9_hi0:
	s_waitcnt vmcnt(6)
	s_waitcnt lgkmcnt(0)
	s_barrier
	v_add_u32_e32 v232, s98, v230
	v_add_u32_e32 v233, s98, v231
	s_add_u32 s9, s17, s101
	s_setprio 1
	v_mfma_f32_16x16x32_bf16 v[0:3], v[176:179], v[192:195], v[0:3]
	v_mfma_f32_16x16x32_bf16 v[4:7], v[180:183], v[192:195], v[4:7]
	v_mfma_f32_16x16x32_bf16 v[8:11], v[184:187], v[192:195], v[8:11]
	v_mfma_f32_16x16x32_bf16 v[12:15], v[188:191], v[192:195], v[12:15]
	ds_read_b128 v[128:131], v233 offset:0
	ds_read_b128 v[132:135], v233 offset:1024
	s_add_u32 m0, s9, 0
	s_nop 0
	global_load_lds_dwordx4 v224, s[0:1]
	v_mfma_f32_16x16x32_bf16 v[16:19], v[176:179], v[196:199], v[16:19]
	v_mfma_f32_16x16x32_bf16 v[20:23], v[180:183], v[196:199], v[20:23]
	v_mfma_f32_16x16x32_bf16 v[24:27], v[184:187], v[196:199], v[24:27]
	v_mfma_f32_16x16x32_bf16 v[28:31], v[188:191], v[196:199], v[28:31]
	ds_read_b128 v[136:139], v233 offset:2048
	ds_read_b128 v[140:143], v233 offset:3072
	s_add_u32 m0, s9, 4096
	s_nop 0
	global_load_lds_dwordx4 v225, s[0:1]
	v_mfma_f32_16x16x32_bf16 v[32:35], v[176:179], v[200:203], v[32:35]
	v_mfma_f32_16x16x32_bf16 v[36:39], v[180:183], v[200:203], v[36:39]
	v_mfma_f32_16x16x32_bf16 v[40:43], v[184:187], v[200:203], v[40:43]
	v_mfma_f32_16x16x32_bf16 v[44:47], v[188:191], v[200:203], v[44:47]
	ds_read_b128 v[144:147], v232 offset:0
	ds_read_b128 v[148:151], v232 offset:1024
	s_add_u32 m0, s9, 8192
	s_nop 0
	global_load_lds_dwordx4 v226, s[0:1]
	v_mfma_f32_16x16x32_bf16 v[48:51], v[176:179], v[204:207], v[48:51]
	v_mfma_f32_16x16x32_bf16 v[52:55], v[180:183], v[204:207], v[52:55]
	v_mfma_f32_16x16x32_bf16 v[56:59], v[184:187], v[204:207], v[56:59]
	v_mfma_f32_16x16x32_bf16 v[60:63], v[188:191], v[204:207], v[60:63]
	ds_read_b128 v[152:155], v232 offset:2048
	ds_read_b128 v[156:159], v232 offset:3072
	s_add_u32 m0, s9, 12288
	s_nop 0
	global_load_lds_dwordx4 v227, s[0:1]
	v_mfma_f32_16x16x32_bf16 v[64:67], v[176:179], v[208:211], v[64:67]
	v_mfma_f32_16x16x32_bf16 v[68:71], v[180:183], v[208:211], v[68:71]
; #define LWRITE(S, buf) do { bf16_t* sA_ = sbase + (buf) * BUF; bf16_t* sB_ = sA_ + 256 * PITCH; \
;     _Pragma("unroll") for (int i_ = 0; i_ < 4; ++i_) *(u32x4*)(sA_ + (sr + i_ * 64) * PITCH + scv * 8) = ra[S][i_]; \
;     _Pragma("unroll") for (int i_ = 0; i_ < 2; ++i_) *(u32x4*)(sB_ + (sr + i_ * 64) * PITCH + scv * 8) = rb[S][i_]; } while (0)
; template <class Epi>
; DI void gemm_tile(char* smem, const bf16_t* __restrict__ A0, int lda0, int ksplit, const bf16_t* __restrict__ A1, int lda1,
;                   const bf16_t* __restrict__ Bt, int K, int row0, int col0, const Epi& epi, int tid) {
;     ...
;   __syncthreads();
;   {
;     const int last = nk - 1;
;     GLOAD(0, 0);
;     __builtin_amdgcn_sched_barrier(0);
;     GLOAD(1, 1);
;     __builtin_amdgcn_sched_barrier(0);
;     LWRITE(0, 0);
;     __builtin_amdgcn_sched_barrier(0);
;     GLOAD(0, (2 < last ? 2 : last));
;     __builtin_amdgcn_sched_barrier(0);
;     __syncthreads();
;     for (int kt = 0; kt < nk; kt += 2) {
;       LWRITE(1, 1);
;       __builtin_amdgcn_sched_barrier(0);
;       GLOAD(1, (kt + 3 < last ? kt + 3 : last));
;       __builtin_amdgcn_sched_barrier(0);
;       COMPUTE(0);
;       __syncthreads();
;       LWRITE(0, 0);
;       __builtin_amdgcn_sched_barrier(0);
;       GLOAD(0, (kt + 4 < last ? kt + 4 : last));
;       __builtin_amdgcn_sched_barrier(0);
;       COMPUTE(1);
;       __syncthreads();
;     }
	v_mfma_f32_16x16x32_bf16 v[72:75], v[184:187], v[208:211], v[72:75]
	v_mfma_f32_16x16x32_bf16 v[76:79], v[188:191], v[208:211], v[76:79]
	ds_read_b128 v[160:163], v232 offset:4096
	s_add_u32 m0, s9, 16384
	s_nop 0
	global_load_lds_dwordx4 v228, s[2:3]
	v_mfma_f32_16x16x32_bf16 v[80:83], v[176:179], v[212:215], v[80:83]
	v_mfma_f32_16x16x32_bf16 v[84:87], v[180:183], v[212:215], v[84:87]
	v_mfma_f32_16x16x32_bf16 v[88:91], v[184:187], v[212:215], v[88:91]
	v_mfma_f32_16x16x32_bf16 v[92:95], v[188:191], v[212:215], v[92:95]
	ds_read_b128 v[164:167], v232 offset:5120
	s_add_u32 m0, s9, 20480
	s_nop 0
	global_load_lds_dwordx4 v229, s[2:3]
	v_mfma_f32_16x16x32_bf16 v[96:99], v[176:179], v[216:219], v[96:99]
	v_mfma_f32_16x16x32_bf16 v[100:103], v[180:183], v[216:219], v[100:103]
	v_mfma_f32_16x16x32_bf16 v[104:107], v[184:187], v[216:219], v[104:107]
	v_mfma_f32_16x16x32_bf16 v[108:111], v[188:191], v[216:219], v[108:111]
	ds_read_b128 v[168:171], v232 offset:6144
	s_add_u32 s0, s0, 64
	s_addc_u32 s1, s1, 0
	s_add_u32 s2, s2, 64
	s_addc_u32 s3, s3, 0
	s_add_u32 s100, s100, 1
	s_add_u32 s17, s17, 24576
	s_cmp_eq_u32 s17, 73728
	s_cselect_b32 s17, 0, s17
	s_add_u32 s98, s98, 24576
	s_cmp_eq_u32 s98, 73728
	s_cselect_b32 s98, 0, s98
	v_mfma_f32_16x16x32_bf16 v[112:115], v[176:179], v[220:223], v[112:115]
	v_mfma_f32_16x16x32_bf16 v[116:119], v[180:183], v[220:223], v[116:119]
	v_mfma_f32_16x16x32_bf16 v[120:123], v[184:187], v[220:223], v[120:123]
	v_mfma_f32_16x16x32_bf16 v[124:127], v[188:191], v[220:223], v[124:127]
	ds_read_b128 v[172:175], v232 offset:7168
	s_cmp_eq_u32 s8, 0
	s_cbranch_scc0 .Lg9_hi1
	s_setprio 0
.Lg9_hi1:
	s_add_u32 s99, s99, 2
	s_cmp_lt_u32 s99, 124
	s_cbranch_scc1 .Lg9_kloop
	s_waitcnt vmcnt(6)
	s_waitcnt lgkmcnt(0)
	s_barrier
	v_add_u32_e32 v232, s98, v230
	v_add_u32_e32 v233, s98, v231
	s_add_u32 s9, s17, s101
	s_setprio 1
	v_mfma_f32_16x16x32_bf16 v[0:3], v[128:131], v[144:147], v[0:3]
	v_mfma_f32_16x16x32_bf16 v[4:7], v[132:135], v[144:147], v[4:7]
	v_mfma_f32_16x16x32_bf16 v[8:11], v[136:139], v[144:147], v[8:11]
	v_mfma_f32_16x16x32_bf16 v[12:15], v[140:143], v[144:147], v[12:15]
	ds_read_b128 v[176:179], v233 offset:0
	ds_read_b128 v[180:183], v233 offset:1024
	s_add_u32 m0, s9, 0
	s_nop 0
	global_load_lds_dwordx4 v224, s[0:1]
	v_mfma_f32_16x16x32_bf16 v[16:19], v[128:131], v[148:151], v[16:19]
	v_mfma_f32_16x16x32_bf16 v[20:23], v[132:135], v[148:151], v[20:23]
	v_mfma_f32_16x16x32_bf16 v[24:27], v[136:139], v[148:151], v[24:27]
	v_mfma_f32_16x16x32_bf16 v[28:31], v[140:143], v[148:151], v[28:31]
	ds_read_b128 v[184:187], v233 offset:2048
	ds_read_b128 v[188:191], v233 offset:3072
	s_add_u32 m0, s9, 4096
	s_nop 0
	global_load_lds_dwordx4 v225, s[0:1]
	v_mfma_f32_16x16x32_bf16 v[32:35], v[128:131], v[152:155], v[32:35]
	v_mfma_f32_16x16x32_bf16 v[36:39], v[132:135], v[152:155], v[36:39]
	v_mfma_f32_16x16x32_bf16 v[40:43], v[136:139], v[152:155], v[40:43]
	v_mfma_f32_16x16x32_bf16 v[44:47], v[140:143], v[152:155], v[44:47]
	ds_read_b128 v[192:195], v232 offset:0
	ds_read_b128 v[196:199], v232 offset:1024
	s_add_u32 m0, s9, 8192
	s_nop 0
	global_load_lds_dwordx4 v226, s[0:1]
	v_mfma_f32_16x16x32_bf16 v[48:51], v[128:131], v[156:159], v[48:51]
	v_mfma_f32_16x16x32_bf16 v[52:55], v[132:135], v[156:159], v[52:55]
	v_mfma_f32_16x16x32_bf16 v[56:59], v[136:139], v[156:159], v[56:59]
	v_mfma_f32_16x16x32_bf16 v[60:63], v[140:143], v[156:159], v[60:63]
	ds_read_b128 v[200:203], v232 offset:2048
	ds_read_b128 v[204:207], v232 offset:3072
	s_add_u32 m0, s9, 12288
	s_nop 0
	global_load_lds_dwordx4 v227, s[0:1]
	v_mfma_f32_16x16x32_bf16 v[64:67], v[128:131], v[160:163], v[64:67]
	v_mfma_f32_16x16x32_bf16 v[68:71], v[132:135], v[160:163], v[68:71]
	v_mfma_f32_16x16x32_bf16 v[72:75], v[136:139], v[160:163], v[72:75]
	v_mfma_f32_16x16x32_bf16 v[76:79], v[140:143], v[160:163], v[76:79]
	ds_read_b128 v[208:211], v232 offset:4096
	s_add_u32 m0, s9, 16384
	s_nop 0
	global_load_lds_dwordx4 v228, s[2:3]
	v_mfma_f32_16x16x32_bf16 v[80:83], v[128:131], v[164:167], v[80:83]
	v_mfma_f32_16x16x32_bf16 v[84:87], v[132:135], v[164:167], v[84:87]
	v_mfma_f32_16x16x32_bf16 v[88:91], v[136:139], v[164:167], v[88:91]
	v_mfma_f32_16x16x32_bf16 v[92:95], v[140:143], v[164:167], v[92:95]
	ds_read_b128 v[212:215], v232 offset:5120
	s_add_u32 m0, s9, 20480
	s_nop 0
	global_load_lds_dwordx4 v229, s[2:3]
	v_mfma_f32_16x16x32_bf16 v[96:99], v[128:131], v[168:171], v[96:99]
	v_mfma_f32_16x16x32_bf16 v[100:103], v[132:135], v[168:171], v[100:103]
	v_mfma_f32_16x16x32_bf16 v[104:107], v[136:139], v[168:171], v[104:107]
	v_mfma_f32_16x16x32_bf16 v[108:111], v[140:143], v[168:171], v[108:111]
	ds_read_b128 v[216:219], v232 offset:6144
	s_add_u32 s0, s0, 64
	s_addc_u32 s1, s1, 0
	s_add_u32 s2, s2, 64
	s_addc_u32 s3, s3, 0
	s_add_u32 s100, s100, 1
	s_add_u32 s17, s17, 24576
	s_cmp_eq_u32 s17, 73728
	s_cselect_b32 s17, 0, s17
	s_add_u32 s98, s98, 24576
	s_cmp_eq_u32 s98, 73728
	s_cselect_b32 s98, 0, s98
	v_mfma_f32_16x16x32_bf16 v[112:115], v[128:131], v[172:175], v[112:115]
	v_mfma_f32_16x16x32_bf16 v[116:119], v[132:135], v[172:175], v[116:119]
	v_mfma_f32_16x16x32_bf16 v[120:123], v[136:139], v[172:175], v[120:123]
	v_mfma_f32_16x16x32_bf16 v[124:127], v[140:143], v[172:175], v[124:127]
	ds_read_b128 v[220:223], v232 offset:7168
	s_cmp_eq_u32 s8, 0
	s_cbranch_scc0 .Lg9_hi2
	s_setprio 0
; #define LWRITE(S, buf) do { bf16_t* sA_ = sbase + (buf) * BUF; bf16_t* sB_ = sA_ + 256 * PITCH; \
;     _Pragma("unroll") for (int i_ = 0; i_ < 4; ++i_) *(u32x4*)(sA_ + (sr + i_ * 64) * PITCH + scv * 8) = ra[S][i_]; \
;     _Pragma("unroll") for (int i_ = 0; i_ < 2; ++i_) *(u32x4*)(sB_ + (sr + i_ * 64) * PITCH + scv * 8) = rb[S][i_]; } while (0)
; template <class Epi>
; DI void gemm_tile(char* smem, const bf16_t* __restrict__ A0, int lda0, int ksplit, const bf16_t* __restrict__ A1, int lda1,
;                   const bf16_t* __restrict__ Bt, int K, int row0, int col0, const Epi& epi, int tid) {
;     ...
;   __syncthreads();
;   {
;     const int last = nk - 1;
;     GLOAD(0, 0);
;     __builtin_amdgcn_sched_barrier(0);
;     GLOAD(1, 1);
;     __builtin_amdgcn_sched_barrier(0);
;     LWRITE(0, 0);
;     __builtin_amdgcn_sched_barrier(0);
;     GLOAD(0, (2 < last ? 2 : last));
;     __builtin_amdgcn_sched_barrier(0);
;     __syncthreads();
;     for (int kt = 0; kt < nk; kt += 2) {
;       LWRITE(1, 1);
;       __builtin_amdgcn_sched_barrier(0);
;       GLOAD(1, (kt + 3 < last ? kt + 3 : last));
;       __builtin_amdgcn_sched_barrier(0);
;       COMPUTE(0);
;       __syncthreads();
;       LWRITE(0, 0);
;       __builtin_amdgcn_sched_barrier(0);
;       GLOAD(0, (kt + 4 < last ? kt + 4 : last));
;       __builtin_amdgcn_sched_barrier(0);
;       COMPUTE(1);
;       __syncthreads();
;     }
.Lg9_hi2:
	s_waitcnt vmcnt(6)
	s_waitcnt lgkmcnt(0)
	s_barrier
	v_add_u32_e32 v232, s98, v230
	v_add_u32_e32 v233, s98, v231
	s_setprio 1
	v_mfma_f32_16x16x32_bf16 v[0:3], v[176:179], v[192:195], v[0:3]
	v_mfma_f32_16x16x32_bf16 v[4:7], v[180:183], v[192:195], v[4:7]
	v_mfma_f32_16x16x32_bf16 v[8:11], v[184:187], v[192:195], v[8:11]
	v_mfma_f32_16x16x32_bf16 v[12:15], v[188:191], v[192:195], v[12:15]
	ds_read_b128 v[128:131], v233 offset:0
	ds_read_b128 v[132:135], v233 offset:1024
	v_mfma_f32_16x16x32_bf16 v[16:19], v[176:179], v[196:199], v[16:19]
	v_mfma_f32_16x16x32_bf16 v[20:23], v[180:183], v[196:199], v[20:23]
	v_mfma_f32_16x16x32_bf16 v[24:27], v[184:187], v[196:199], v[24:27]
	v_mfma_f32_16x16x32_bf16 v[28:31], v[188:191], v[196:199], v[28:31]
	ds_read_b128 v[136:139], v233 offset:2048
	ds_read_b128 v[140:143], v233 offset:3072
	v_mfma_f32_16x16x32_bf16 v[32:35], v[176:179], v[200:203], v[32:35]
	v_mfma_f32_16x16x32_bf16 v[36:39], v[180:183], v[200:203], v[36:39]
	v_mfma_f32_16x16x32_bf16 v[40:43], v[184:187], v[200:203], v[40:43]
	v_mfma_f32_16x16x32_bf16 v[44:47], v[188:191], v[200:203], v[44:47]
	ds_read_b128 v[144:147], v232 offset:0
	ds_read_b128 v[148:151], v232 offset:1024
	v_mfma_f32_16x16x32_bf16 v[48:51], v[176:179], v[204:207], v[48:51]
	v_mfma_f32_16x16x32_bf16 v[52:55], v[180:183], v[204:207], v[52:55]
	v_mfma_f32_16x16x32_bf16 v[56:59], v[184:187], v[204:207], v[56:59]
	v_mfma_f32_16x16x32_bf16 v[60:63], v[188:191], v[204:207], v[60:63]
	ds_read_b128 v[152:155], v232 offset:2048
	ds_read_b128 v[156:159], v232 offset:3072
	v_mfma_f32_16x16x32_bf16 v[64:67], v[176:179], v[208:211], v[64:67]
	v_mfma_f32_16x16x32_bf16 v[68:71], v[180:183], v[208:211], v[68:71]
	v_mfma_f32_16x16x32_bf16 v[72:75], v[184:187], v[208:211], v[72:75]
	v_mfma_f32_16x16x32_bf16 v[76:79], v[188:191], v[208:211], v[76:79]
	ds_read_b128 v[160:163], v232 offset:4096
	v_mfma_f32_16x16x32_bf16 v[80:83], v[176:179], v[212:215], v[80:83]
	v_mfma_f32_16x16x32_bf16 v[84:87], v[180:183], v[212:215], v[84:87]
	v_mfma_f32_16x16x32_bf16 v[88:91], v[184:187], v[212:215], v[88:91]
	v_mfma_f32_16x16x32_bf16 v[92:95], v[188:191], v[212:215], v[92:95]
	ds_read_b128 v[164:167], v232 offset:5120
	v_mfma_f32_16x16x32_bf16 v[96:99], v[176:179], v[216:219], v[96:99]
	v_mfma_f32_16x16x32_bf16 v[100:103], v[180:183], v[216:219], v[100:103]
	v_mfma_f32_16x16x32_bf16 v[104:107], v[184:187], v[216:219], v[104:107]
	v_mfma_f32_16x16x32_bf16 v[108:111], v[188:191], v[216:219], v[108:111]
	ds_read_b128 v[168:171], v232 offset:6144
	s_add_u32 s98, s98, 24576
	s_cmp_eq_u32 s98, 73728
	s_cselect_b32 s98, 0, s98
	v_mfma_f32_16x16x32_bf16 v[112:115], v[176:179], v[220:223], v[112:115]
	v_mfma_f32_16x16x32_bf16 v[116:119], v[180:183], v[220:223], v[116:119]
	v_mfma_f32_16x16x32_bf16 v[120:123], v[184:187], v[220:223], v[120:123]
	v_mfma_f32_16x16x32_bf16 v[124:127], v[188:191], v[220:223], v[124:127]
	ds_read_b128 v[172:175], v232 offset:7168
	s_cmp_eq_u32 s8, 0
	s_cbranch_scc0 .Lg9_hi3
	s_setprio 0
.Lg9_hi3:
	s_waitcnt vmcnt(0)
	s_waitcnt lgkmcnt(0)
	s_barrier
	v_add_u32_e32 v232, s98, v230
	v_add_u32_e32 v233, s98, v231
	s_setprio 1
	v_mfma_f32_16x16x32_bf16 v[0:3], v[128:131], v[144:147], v[0:3]
	v_mfma_f32_16x16x32_bf16 v[4:7], v[132:135], v[144:147], v[4:7]
	v_mfma_f32_16x16x32_bf16 v[8:11], v[136:139], v[144:147], v[8:11]
	v_mfma_f32_16x16x32_bf16 v[12:15], v[140:143], v[144:147], v[12:15]
	ds_read_b128 v[176:179], v233 offset:0
	ds_read_b128 v[180:183], v233 offset:1024
	v_mfma_f32_16x16x32_bf16 v[16:19], v[128:131], v[148:151], v[16:19]
	v_mfma_f32_16x16x32_bf16 v[20:23], v[132:135], v[148:151], v[20:23]
	v_mfma_f32_16x16x32_bf16 v[24:27], v[136:139], v[148:151], v[24:27]
	v_mfma_f32_16x16x32_bf16 v[28:31], v[140:143], v[148:151], v[28:31]
	ds_read_b128 v[184:187], v233 offset:2048
	ds_read_b128 v[188:191], v233 offset:3072
	v_mfma_f32_16x16x32_bf16 v[32:35], v[128:131], v[152:155], v[32:35]
	v_mfma_f32_16x16x32_bf16 v[36:39], v[132:135], v[152:155], v[36:39]
	v_mfma_f32_16x16x32_bf16 v[40:43], v[136:139], v[152:155], v[40:43]
	v_mfma_f32_16x16x32_bf16 v[44:47], v[140:143], v[152:155], v[44:47]
	ds_read_b128 v[192:195], v232 offset:0
	ds_read_b128 v[196:199], v232 offset:1024
	v_mfma_f32_16x16x32_bf16 v[48:51], v[128:131], v[156:159], v[48:51]
	v_mfma_f32_16x16x32_bf16 v[52:55], v[132:135], v[156:159], v[52:55]
	v_mfma_f32_16x16x32_bf16 v[56:59], v[136:139], v[156:159], v[56:59]
	v_mfma_f32_16x16x32_bf16 v[60:63], v[140:143], v[156:159], v[60:63]
	ds_read_b128 v[200:203], v232 offset:2048
	ds_read_b128 v[204:207], v232 offset:3072
	v_mfma_f32_16x16x32_bf16 v[64:67], v[128:131], v[160:163], v[64:67]
	v_mfma_f32_16x16x32_bf16 v[68:71], v[132:135], v[160:163], v[68:71]
	v_mfma_f32_16x16x32_bf16 v[72:75], v[136:139], v[160:163], v[72:75]
	v_mfma_f32_16x16x32_bf16 v[76:79], v[140:143], v[160:163], v[76:79]
	ds_read_b128 v[208:211], v232 offset:4096
	v_mfma_f32_16x16x32_bf16 v[80:83], v[128:131], v[164:167], v[80:83]
	v_mfma_f32_16x16x32_bf16 v[84:87], v[132:135], v[164:167], v[84:87]
	v_mfma_f32_16x16x32_bf16 v[88:91], v[136:139], v[164:167], v[88:91]
	v_mfma_f32_16x16x32_bf16 v[92:95], v[140:143], v[164:167], v[92:95]
	ds_read_b128 v[212:215], v232 offset:5120
	v_mfma_f32_16x16x32_bf16 v[96:99], v[128:131], v[168:171], v[96:99]
	v_mfma_f32_16x16x32_bf16 v[100:103], v[132:135], v[168:171], v[100:103]
	v_mfma_f32_16x16x32_bf16 v[104:107], v[136:139], v[168:171], v[104:107]
	v_mfma_f32_16x16x32_bf16 v[108:111], v[140:143], v[168:171], v[108:111]
	ds_read_b128 v[216:219], v232 offset:6144
	s_add_u32 s98, s98, 24576
	s_cmp_eq_u32 s98, 73728
	s_cselect_b32 s98, 0, s98
	v_mfma_f32_16x16x32_bf16 v[112:115], v[128:131], v[172:175], v[112:115]
	v_mfma_f32_16x16x32_bf16 v[116:119], v[132:135], v[172:175], v[116:119]
	v_mfma_f32_16x16x32_bf16 v[120:123], v[136:139], v[172:175], v[120:123]
	v_mfma_f32_16x16x32_bf16 v[124:127], v[140:143], v[172:175], v[124:127]
	ds_read_b128 v[220:223], v232 offset:7168
	s_cmp_eq_u32 s8, 0
	s_cbranch_scc0 .Lg9_hi4
	s_setprio 0
; #define LWRITE(S, buf) do { bf16_t* sA_ = sbase + (buf) * BUF; bf16_t* sB_ = sA_ + 256 * PITCH; \
;     _Pragma("unroll") for (int i_ = 0; i_ < 4; ++i_) *(u32x4*)(sA_ + (sr + i_ * 64) * PITCH + scv * 8) = ra[S][i_]; \
;     _Pragma("unroll") for (int i_ = 0; i_ < 2; ++i_) *(u32x4*)(sB_ + (sr + i_ * 64) * PITCH + scv * 8) = rb[S][i_]; } while (0)
; template <class Epi>
; DI void gemm_tile(char* smem, const bf16_t* __restrict__ A0, int lda0, int ksplit, const bf16_t* __restrict__ A1, int lda1,
;                   const bf16_t* __restrict__ Bt, int K, int row0, int col0, const Epi& epi, int tid) {
;     ...
;     for (int kt = 0; kt < nk; kt += 2) {
;       LWRITE(1, 1);
;       __builtin_amdgcn_sched_barrier(0);
;       GLOAD(1, (kt + 3 < last ? kt + 3 : last));
;       __builtin_amdgcn_sched_barrier(0);
;       COMPUTE(0);
;       __syncthreads();
;       LWRITE(0, 0);
;       __builtin_amdgcn_sched_barrier(0);
;       GLOAD(0, (kt + 4 < last ? kt + 4 : last));
;       __builtin_amdgcn_sched_barrier(0);
;       COMPUTE(1);
;       __syncthreads();
;     }
.Lg9_hi4:
	s_waitcnt lgkmcnt(0)
	s_barrier
	s_setprio 1
	v_mfma_f32_16x16x32_bf16 v[0:3], v[176:179], v[192:195], v[0:3]
	v_mfma_f32_16x16x32_bf16 v[4:7], v[180:183], v[192:195], v[4:7]
	v_mfma_f32_16x16x32_bf16 v[8:11], v[184:187], v[192:195], v[8:11]
	v_mfma_f32_16x16x32_bf16 v[12:15], v[188:191], v[192:195], v[12:15]
	v_mfma_f32_16x16x32_bf16 v[16:19], v[176:179], v[196:199], v[16:19]
	v_mfma_f32_16x16x32_bf16 v[20:23], v[180:183], v[196:199], v[20:23]
	v_mfma_f32_16x16x32_bf16 v[24:27], v[184:187], v[196:199], v[24:27]
	v_mfma_f32_16x16x32_bf16 v[28:31], v[188:191], v[196:199], v[28:31]
	v_mfma_f32_16x16x32_bf16 v[32:35], v[176:179], v[200:203], v[32:35]
	v_mfma_f32_16x16x32_bf16 v[36:39], v[180:183], v[200:203], v[36:39]
	v_mfma_f32_16x16x32_bf16 v[40:43], v[184:187], v[200:203], v[40:43]
	v_mfma_f32_16x16x32_bf16 v[44:47], v[188:191], v[200:203], v[44:47]
	v_mfma_f32_16x16x32_bf16 v[48:51], v[176:179], v[204:207], v[48:51]
	v_mfma_f32_16x16x32_bf16 v[52:55], v[180:183], v[204:207], v[52:55]
	v_mfma_f32_16x16x32_bf16 v[56:59], v[184:187], v[204:207], v[56:59]
	v_mfma_f32_16x16x32_bf16 v[60:63], v[188:191], v[204:207], v[60:63]
	v_mfma_f32_16x16x32_bf16 v[64:67], v[176:179], v[208:211], v[64:67]
	v_mfma_f32_16x16x32_bf16 v[68:71], v[180:183], v[208:211], v[68:71]
	v_mfma_f32_16x16x32_bf16 v[72:75], v[184:187], v[208:211], v[72:75]
	v_mfma_f32_16x16x32_bf16 v[76:79], v[188:191], v[208:211], v[76:79]
	v_mfma_f32_16x16x32_bf16 v[80:83], v[176:179], v[212:215], v[80:83]
	v_mfma_f32_16x16x32_bf16 v[84:87], v[180:183], v[212:215], v[84:87]
	v_mfma_f32_16x16x32_bf16 v[88:91], v[184:187], v[212:215], v[88:91]
	v_mfma_f32_16x16x32_bf16 v[92:95], v[188:191], v[212:215], v[92:95]
	v_mfma_f32_16x16x32_bf16 v[96:99], v[176:179], v[216:219], v[96:99]
	v_mfma_f32_16x16x32_bf16 v[100:103], v[180:183], v[216:219], v[100:103]
	v_mfma_f32_16x16x32_bf16 v[104:107], v[184:187], v[216:219], v[104:107]
	v_mfma_f32_16x16x32_bf16 v[108:111], v[188:191], v[216:219], v[108:111]
	v_mfma_f32_16x16x32_bf16 v[112:115], v[176:179], v[220:223], v[112:115]
	v_mfma_f32_16x16x32_bf16 v[116:119], v[180:183], v[220:223], v[116:119]
	v_mfma_f32_16x16x32_bf16 v[120:123], v[184:187], v[220:223], v[120:123]
	v_mfma_f32_16x16x32_bf16 v[124:127], v[188:191], v[220:223], v[124:127]
	s_cmp_eq_u32 s8, 0
	s_cbranch_scc0 .Lg9_hi5
	s_setprio 0
.Lg9_hi5:
	s_branch .Lg9_epi
.Lg9_epi:
	s_nop 7
	s_nop 7
	s_lshl_b32 s10, s16, 12
	s_lshl_b32 s9, s11, 2
	s_add_u32 s10, s10, s9
	s_add_u32 s4, s6, s10
	s_addc_u32 s5, s7, 0
	s_lshl_b32 s10, s16, 12
	s_lshl_b32 s9, s11, 2
	s_add_u32 s10, s10, s9
	s_add_u32 s0, s6, s10
	s_addc_u32 s1, s7, 0
	ds_write_b128 v245, v[0:3]
	ds_write_b128 v245, v[4:7] offset:64
	ds_write_b128 v245, v[8:11] offset:128
	ds_write_b128 v245, v[12:15] offset:192
	ds_write_b128 v245, v[16:19] offset:4352
	ds_write_b128 v245, v[20:23] offset:4416
	ds_write_b128 v245, v[24:27] offset:4480
	ds_write_b128 v245, v[28:31] offset:4544
	ds_write_b128 v245, v[32:35] offset:8704
	ds_write_b128 v245, v[36:39] offset:8768
	ds_write_b128 v245, v[40:43] offset:8832
	ds_write_b128 v245, v[44:47] offset:8896
	ds_write_b128 v245, v[48:51] offset:13056
	ds_write_b128 v245, v[52:55] offset:13120
	ds_write_b128 v245, v[56:59] offset:13184
	ds_write_b128 v245, v[60:63] offset:13248
	global_load_dwordx4 v[128:131], v247, s[0:1]
	s_add_u32 s0, s0, 0x4000
	s_addc_u32 s1, s1, 0
	global_load_dwordx4 v[132:135], v247, s[0:1]
	s_add_u32 s0, s0, 0x4000
	s_addc_u32 s1, s1, 0
	global_load_dwordx4 v[136:139], v247, s[0:1]
	s_add_u32 s0, s0, 0x4000
	s_addc_u32 s1, s1, 0
	global_load_dwordx4 v[140:143], v247, s[0:1]
	s_add_u32 s0, s0, 0x4000
	s_addc_u32 s1, s1, 0
	global_load_dwordx4 v[144:147], v247, s[0:1]
	s_add_u32 s0, s0, 0x4000
	s_addc_u32 s1, s1, 0
	global_load_dwordx4 v[148:151], v247, s[0:1]
	s_add_u32 s0, s0, 0x4000
	s_addc_u32 s1, s1, 0
	global_load_dwordx4 v[152:155], v247, s[0:1]
	s_add_u32 s0, s0, 0x4000
	s_addc_u32 s1, s1, 0
	global_load_dwordx4 v[156:159], v247, s[0:1]
	s_add_u32 s0, s0, 0x4000
	s_addc_u32 s1, s1, 0
	s_waitcnt lgkmcnt(0)
	ds_read_b128 v[160:163], v246
	ds_read_b128 v[164:167], v246 offset:1088
	ds_read_b128 v[168:171], v246 offset:2176
	ds_read_b128 v[172:175], v246 offset:3264
	ds_read_b128 v[176:179], v246 offset:4352
	ds_read_b128 v[180:183], v246 offset:5440
	ds_read_b128 v[184:187], v246 offset:6528
	ds_read_b128 v[188:191], v246 offset:7616
	s_waitcnt vmcnt(7) lgkmcnt(7)
	v_pk_add_f32 v[128:129], v[128:129], v[160:161]
	v_pk_add_f32 v[130:131], v[130:131], v[162:163]
	global_store_dwordx4 v247, v[128:131], s[4:5] nt
	s_add_u32 s4, s4, 0x4000
	s_addc_u32 s5, s5, 0
	s_waitcnt vmcnt(7) lgkmcnt(6)
	v_pk_add_f32 v[132:133], v[132:133], v[164:165]
	v_pk_add_f32 v[134:135], v[134:135], v[166:167]
	global_store_dwordx4 v247, v[132:135], s[4:5] nt
	s_add_u32 s4, s4, 0x4000
	s_addc_u32 s5, s5, 0
	s_waitcnt vmcnt(7) lgkmcnt(5)
	v_pk_add_f32 v[136:137], v[136:137], v[168:169]
	v_pk_add_f32 v[138:139], v[138:139], v[170:171]
	global_store_dwordx4 v247, v[136:139], s[4:5] nt
	s_add_u32 s4, s4, 0x4000
	s_addc_u32 s5, s5, 0
	s_waitcnt vmcnt(7) lgkmcnt(4)
	v_pk_add_f32 v[140:141], v[140:141], v[172:173]
	v_pk_add_f32 v[142:143], v[142:143], v[174:175]
	global_store_dwordx4 v247, v[140:143], s[4:5] nt
	s_add_u32 s4, s4, 0x4000
	s_addc_u32 s5, s5, 0
	s_waitcnt vmcnt(7) lgkmcnt(3)
	v_pk_add_f32 v[144:145], v[144:145], v[176:177]
	v_pk_add_f32 v[146:147], v[146:147], v[178:179]
	global_store_dwordx4 v247, v[144:147], s[4:5] nt
	s_add_u32 s4, s4, 0x4000
	s_addc_u32 s5, s5, 0
	s_waitcnt vmcnt(7) lgkmcnt(2)
	v_pk_add_f32 v[148:149], v[148:149], v[180:181]
	v_pk_add_f32 v[150:151], v[150:151], v[182:183]
	global_store_dwordx4 v247, v[148:151], s[4:5] nt
	s_add_u32 s4, s4, 0x4000
	s_addc_u32 s5, s5, 0
	s_waitcnt vmcnt(7) lgkmcnt(1)
	v_pk_add_f32 v[152:153], v[152:153], v[184:185]
	v_pk_add_f32 v[154:155], v[154:155], v[186:187]
	global_store_dwordx4 v247, v[152:155], s[4:5] nt
	s_add_u32 s4, s4, 0x4000
	s_addc_u32 s5, s5, 0
	s_waitcnt vmcnt(7) lgkmcnt(0)
	v_pk_add_f32 v[156:157], v[156:157], v[188:189]
	v_pk_add_f32 v[158:159], v[158:159], v[190:191]
	global_store_dwordx4 v247, v[156:159], s[4:5] nt
	s_add_u32 s4, s4, 0x4000
	s_addc_u32 s5, s5, 0
	s_nop 1
	global_load_dwordx4 v[128:131], v247, s[0:1]
	s_add_u32 s0, s0, 0x4000
	s_addc_u32 s1, s1, 0
	global_load_dwordx4 v[132:135], v247, s[0:1]
	s_add_u32 s0, s0, 0x4000
	s_addc_u32 s1, s1, 0
	global_load_dwordx4 v[136:139], v247, s[0:1]
	s_add_u32 s0, s0, 0x4000
	s_addc_u32 s1, s1, 0
	global_load_dwordx4 v[140:143], v247, s[0:1]
	s_add_u32 s0, s0, 0x4000
	s_addc_u32 s1, s1, 0
	global_load_dwordx4 v[144:147], v247, s[0:1]
	s_add_u32 s0, s0, 0x4000
	s_addc_u32 s1, s1, 0
	global_load_dwordx4 v[148:151], v247, s[0:1]
	s_add_u32 s0, s0, 0x4000
	s_addc_u32 s1, s1, 0
	global_load_dwordx4 v[152:155], v247, s[0:1]
	s_add_u32 s0, s0, 0x4000
	s_addc_u32 s1, s1, 0
	global_load_dwordx4 v[156:159], v247, s[0:1]
	s_add_u32 s0, s0, 0x4000
	s_addc_u32 s1, s1, 0
	ds_read_b128 v[160:163], v246 offset:8704
	ds_read_b128 v[164:167], v246 offset:9792
	ds_read_b128 v[168:171], v246 offset:10880
	ds_read_b128 v[172:175], v246 offset:11968
	ds_read_b128 v[176:179], v246 offset:13056
	ds_read_b128 v[180:183], v246 offset:14144
	ds_read_b128 v[184:187], v246 offset:15232
	ds_read_b128 v[188:191], v246 offset:16320
	s_waitcnt vmcnt(7) lgkmcnt(7)
	v_pk_add_f32 v[128:129], v[128:129], v[160:161]
	v_pk_add_f32 v[130:131], v[130:131], v[162:163]
	global_store_dwordx4 v247, v[128:131], s[4:5] nt
	s_add_u32 s4, s4, 0x4000
	s_addc_u32 s5, s5, 0
	s_waitcnt vmcnt(7) lgkmcnt(6)
	v_pk_add_f32 v[132:133], v[132:133], v[164:165]
	v_pk_add_f32 v[134:135], v[134:135], v[166:167]
	global_store_dwordx4 v247, v[132:135], s[4:5] nt
	s_add_u32 s4, s4, 0x4000
	s_addc_u32 s5, s5, 0
	s_waitcnt vmcnt(7) lgkmcnt(5)
	v_pk_add_f32 v[136:137], v[136:137], v[168:169]
	v_pk_add_f32 v[138:139], v[138:139], v[170:171]
	global_store_dwordx4 v247, v[136:139], s[4:5] nt
	s_add_u32 s4, s4, 0x4000
	s_addc_u32 s5, s5, 0
	s_waitcnt vmcnt(7) lgkmcnt(4)
	v_pk_add_f32 v[140:141], v[140:141], v[172:173]
	v_pk_add_f32 v[142:143], v[142:143], v[174:175]
	global_store_dwordx4 v247, v[140:143], s[4:5] nt
	s_add_u32 s4, s4, 0x4000
	s_addc_u32 s5, s5, 0
	s_waitcnt vmcnt(7) lgkmcnt(3)
	v_pk_add_f32 v[144:145], v[144:145], v[176:177]
	v_pk_add_f32 v[146:147], v[146:147], v[178:179]
	global_store_dwordx4 v247, v[144:147], s[4:5] nt
	s_add_u32 s4, s4, 0x4000
	s_addc_u32 s5, s5, 0
	s_waitcnt vmcnt(7) lgkmcnt(2)
	v_pk_add_f32 v[148:149], v[148:149], v[180:181]
	v_pk_add_f32 v[150:151], v[150:151], v[182:183]
	global_store_dwordx4 v247, v[148:151], s[4:5] nt
	s_add_u32 s4, s4, 0x4000
	s_addc_u32 s5, s5, 0
	s_waitcnt vmcnt(7) lgkmcnt(1)
	v_pk_add_f32 v[152:153], v[152:153], v[184:185]
	v_pk_add_f32 v[154:155], v[154:155], v[186:187]
	global_store_dwordx4 v247, v[152:155], s[4:5] nt
	s_add_u32 s4, s4, 0x4000
	s_addc_u32 s5, s5, 0
	s_waitcnt vmcnt(7) lgkmcnt(0)
	v_pk_add_f32 v[156:157], v[156:157], v[188:189]
	v_pk_add_f32 v[158:159], v[158:159], v[190:191]
	global_store_dwordx4 v247, v[156:159], s[4:5] nt
	s_add_u32 s4, s4, 0x4000
	s_addc_u32 s5, s5, 0
	s_nop 1
	s_waitcnt lgkmcnt(0)
	ds_write_b128 v245, v[64:67]
	ds_write_b128 v245, v[68:71] offset:64
	ds_write_b128 v245, v[72:75] offset:128
	ds_write_b128 v245, v[76:79] offset:192
	ds_write_b128 v245, v[80:83] offset:4352
	ds_write_b128 v245, v[84:87] offset:4416
	ds_write_b128 v245, v[88:91] offset:4480
	ds_write_b128 v245, v[92:95] offset:4544
	ds_write_b128 v245, v[96:99] offset:8704
	ds_write_b128 v245, v[100:103] offset:8768
	ds_write_b128 v245, v[104:107] offset:8832
	ds_write_b128 v245, v[108:111] offset:8896
	ds_write_b128 v245, v[112:115] offset:13056
	ds_write_b128 v245, v[116:119] offset:13120
	ds_write_b128 v245, v[120:123] offset:13184
	ds_write_b128 v245, v[124:127] offset:13248
	global_load_dwordx4 v[128:131], v247, s[0:1]
	s_add_u32 s0, s0, 0x4000
	s_addc_u32 s1, s1, 0
	global_load_dwordx4 v[132:135], v247, s[0:1]
	s_add_u32 s0, s0, 0x4000
	s_addc_u32 s1, s1, 0
	global_load_dwordx4 v[136:139], v247, s[0:1]
	s_add_u32 s0, s0, 0x4000
	s_addc_u32 s1, s1, 0
	global_load_dwordx4 v[140:143], v247, s[0:1]
	s_add_u32 s0, s0, 0x4000
	s_addc_u32 s1, s1, 0
	global_load_dwordx4 v[144:147], v247, s[0:1]
	s_add_u32 s0, s0, 0x4000
	s_addc_u32 s1, s1, 0
	global_load_dwordx4 v[148:151], v247, s[0:1]
	s_add_u32 s0, s0, 0x4000
	s_addc_u32 s1, s1, 0
	global_load_dwordx4 v[152:155], v247, s[0:1]
	s_add_u32 s0, s0, 0x4000
	s_addc_u32 s1, s1, 0
	global_load_dwordx4 v[156:159], v247, s[0:1]
	s_add_u32 s0, s0, 0x4000
	s_addc_u32 s1, s1, 0
	s_waitcnt lgkmcnt(0)
	ds_read_b128 v[160:163], v246
	ds_read_b128 v[164:167], v246 offset:1088
	ds_read_b128 v[168:171], v246 offset:2176
	ds_read_b128 v[172:175], v246 offset:3264
	ds_read_b128 v[176:179], v246 offset:4352
	ds_read_b128 v[180:183], v246 offset:5440
	ds_read_b128 v[184:187], v246 offset:6528
	ds_read_b128 v[188:191], v246 offset:7616
	s_waitcnt vmcnt(7) lgkmcnt(7)
	v_pk_add_f32 v[128:129], v[128:129], v[160:161]
	v_pk_add_f32 v[130:131], v[130:131], v[162:163]
	global_store_dwordx4 v247, v[128:131], s[4:5] nt
	s_add_u32 s4, s4, 0x4000
	s_addc_u32 s5, s5, 0
	s_waitcnt vmcnt(7) lgkmcnt(6)
	v_pk_add_f32 v[132:133], v[132:133], v[164:165]
	v_pk_add_f32 v[134:135], v[134:135], v[166:167]
	global_store_dwordx4 v247, v[132:135], s[4:5] nt
	s_add_u32 s4, s4, 0x4000
	s_addc_u32 s5, s5, 0
	s_waitcnt vmcnt(7) lgkmcnt(5)
	v_pk_add_f32 v[136:137], v[136:137], v[168:169]
	v_pk_add_f32 v[138:139], v[138:139], v[170:171]
	global_store_dwordx4 v247, v[136:139], s[4:5] nt
	s_add_u32 s4, s4, 0x4000
	s_addc_u32 s5, s5, 0
	s_waitcnt vmcnt(7) lgkmcnt(4)
	v_pk_add_f32 v[140:141], v[140:141], v[172:173]
	v_pk_add_f32 v[142:143], v[142:143], v[174:175]
	global_store_dwordx4 v247, v[140:143], s[4:5] nt
	s_add_u32 s4, s4, 0x4000
	s_addc_u32 s5, s5, 0
	s_waitcnt vmcnt(7) lgkmcnt(3)
	v_pk_add_f32 v[144:145], v[144:145], v[176:177]
	v_pk_add_f32 v[146:147], v[146:147], v[178:179]
	global_store_dwordx4 v247, v[144:147], s[4:5] nt
	s_add_u32 s4, s4, 0x4000
	s_addc_u32 s5, s5, 0
	s_waitcnt vmcnt(7) lgkmcnt(2)
	v_pk_add_f32 v[148:149], v[148:149], v[180:181]
	v_pk_add_f32 v[150:151], v[150:151], v[182:183]
	global_store_dwordx4 v247, v[148:151], s[4:5] nt
	s_add_u32 s4, s4, 0x4000
	s_addc_u32 s5, s5, 0
	s_waitcnt vmcnt(7) lgkmcnt(1)
	v_pk_add_f32 v[152:153], v[152:153], v[184:185]
	v_pk_add_f32 v[154:155], v[154:155], v[186:187]
	global_store_dwordx4 v247, v[152:155], s[4:5] nt
	s_add_u32 s4, s4, 0x4000
	s_addc_u32 s5, s5, 0
	s_waitcnt vmcnt(7) lgkmcnt(0)
	v_pk_add_f32 v[156:157], v[156:157], v[188:189]
	v_pk_add_f32 v[158:159], v[158:159], v[190:191]
	global_store_dwordx4 v247, v[156:159], s[4:5] nt
	s_add_u32 s4, s4, 0x4000
	s_addc_u32 s5, s5, 0
	s_nop 1
	global_load_dwordx4 v[128:131], v247, s[0:1]
	s_add_u32 s0, s0, 0x4000
	s_addc_u32 s1, s1, 0
	global_load_dwordx4 v[132:135], v247, s[0:1]
	s_add_u32 s0, s0, 0x4000
	s_addc_u32 s1, s1, 0
	global_load_dwordx4 v[136:139], v247, s[0:1]
	s_add_u32 s0, s0, 0x4000
	s_addc_u32 s1, s1, 0
	global_load_dwordx4 v[140:143], v247, s[0:1]
	s_add_u32 s0, s0, 0x4000
	s_addc_u32 s1, s1, 0
	global_load_dwordx4 v[144:147], v247, s[0:1]
	s_add_u32 s0, s0, 0x4000
	s_addc_u32 s1, s1, 0
	global_load_dwordx4 v[148:151], v247, s[0:1]
	s_add_u32 s0, s0, 0x4000
	s_addc_u32 s1, s1, 0
	global_load_dwordx4 v[152:155], v247, s[0:1]
	s_add_u32 s0, s0, 0x4000
	s_addc_u32 s1, s1, 0
	global_load_dwordx4 v[156:159], v247, s[0:1]
	s_add_u32 s0, s0, 0x4000
	s_addc_u32 s1, s1, 0
	ds_read_b128 v[160:163], v246 offset:8704
	ds_read_b128 v[164:167], v246 offset:9792
	ds_read_b128 v[168:171], v246 offset:10880
	ds_read_b128 v[172:175], v246 offset:11968
	ds_read_b128 v[176:179], v246 offset:13056
	ds_read_b128 v[180:183], v246 offset:14144
	ds_read_b128 v[184:187], v246 offset:15232
	ds_read_b128 v[188:191], v246 offset:16320
	s_waitcnt vmcnt(7) lgkmcnt(7)
	v_pk_add_f32 v[128:129], v[128:129], v[160:161]
	v_pk_add_f32 v[130:131], v[130:131], v[162:163]
	global_store_dwordx4 v247, v[128:131], s[4:5] nt
	s_add_u32 s4, s4, 0x4000
	s_addc_u32 s5, s5, 0
	s_waitcnt vmcnt(7) lgkmcnt(6)
	v_pk_add_f32 v[132:133], v[132:133], v[164:165]
	v_pk_add_f32 v[134:135], v[134:135], v[166:167]
	global_store_dwordx4 v247, v[132:135], s[4:5] nt
	s_add_u32 s4, s4, 0x4000
	s_addc_u32 s5, s5, 0
	s_waitcnt vmcnt(7) lgkmcnt(5)
	v_pk_add_f32 v[136:137], v[136:137], v[168:169]
	v_pk_add_f32 v[138:139], v[138:139], v[170:171]
	global_store_dwordx4 v247, v[136:139], s[4:5] nt
	s_add_u32 s4, s4, 0x4000
	s_addc_u32 s5, s5, 0
	s_waitcnt vmcnt(7) lgkmcnt(4)
	v_pk_add_f32 v[140:141], v[140:141], v[172:173]
	v_pk_add_f32 v[142:143], v[142:143], v[174:175]
	global_store_dwordx4 v247, v[140:143], s[4:5] nt
	s_add_u32 s4, s4, 0x4000
	s_addc_u32 s5, s5, 0
	s_waitcnt vmcnt(7) lgkmcnt(3)
	v_pk_add_f32 v[144:145], v[144:145], v[176:177]
	v_pk_add_f32 v[146:147], v[146:147], v[178:179]
	global_store_dwordx4 v247, v[144:147], s[4:5] nt
	s_add_u32 s4, s4, 0x4000
	s_addc_u32 s5, s5, 0
	s_waitcnt vmcnt(7) lgkmcnt(2)
	v_pk_add_f32 v[148:149], v[148:149], v[180:181]
	v_pk_add_f32 v[150:151], v[150:151], v[182:183]
	global_store_dwordx4 v247, v[148:151], s[4:5] nt
	s_add_u32 s4, s4, 0x4000
	s_addc_u32 s5, s5, 0
	s_waitcnt vmcnt(7) lgkmcnt(1)
	v_pk_add_f32 v[152:153], v[152:153], v[184:185]
	v_pk_add_f32 v[154:155], v[154:155], v[186:187]
	global_store_dwordx4 v247, v[152:155], s[4:5] nt
	s_add_u32 s4, s4, 0x4000
	s_addc_u32 s5, s5, 0
	s_waitcnt vmcnt(7) lgkmcnt(0)
	v_pk_add_f32 v[156:157], v[156:157], v[188:189]
	v_pk_add_f32 v[158:159], v[158:159], v[190:191]
	global_store_dwordx4 v247, v[156:159], s[4:5] nt
	s_add_u32 s4, s4, 0x4000
	s_addc_u32 s5, s5, 0
	s_nop 1
	s_add_u32 s15, s15, 64
	s_branch .Lg9_tile

; template <class Epi>
; DI void gemm_tile(char* smem, const bf16_t* __restrict__ A0, int lda0, int ksplit, const bf16_t* __restrict__ A1, int lda1,
;                   const bf16_t* __restrict__ Bt, int K, int row0, int col0, const Epi& epi, int tid) {
;   constexpr int BK = 32, PITCH = 40, BUF = (256 + 128) * PITCH;
;   bf16_t* sbase = (bf16_t*)smem;
;   const int lane = tid & 63, wid = tid >> 6, wr = wid >> 1, wc = wid & 1, fr = lane & 15, fq = lane >> 4;
;   f32x4 acc[8][4];
; #pragma unroll
;   for (int m = 0; m < 8; ++m)
; #pragma unroll
;     for (int n = 0; n < 4; ++n) acc[m][n] = (f32x4){0.f, 0.f, 0.f, 0.f};
;   u32x4 ra[2][4], rb[2][2];
;   const int nk = K / BK;
;   const int sr = tid >> 2, scv = tid & 3;
; template <class Epi>
; DI void gemm_phase(char* smem, const bf16_t* A0, int lda0, int ksplit, const bf16_t* A1, int lda1, const bf16_t* Bt, int K, int nN, const Epi& epi, int tid) {
;   const int G = gridDim.x;
;   if ((G & 7) == 0) {
;     const int x = blockIdx.x & 7, l = blockIdx.x >> 3, L = G >> 3, per = 8 * nN, tot = 2 * per;
;     for (int q = l; q < tot; q += L) { const int rgl = q / per, rem = q % per, ct = rem >> 3, rt = (x * 2 + rgl) * 8 + (rem & 7);
;       gemm_tile(smem, A0, lda0, ksplit, A1, lda1, Bt, K, rt * 256, ct * 128, epi, tid); }
.LBB0_975:
	s_cmp_gt_i32 s94, 11
	s_cselect_b64 s[0:1], -1, 0
	s_cmp_lt_i32 s95, 12
	s_cselect_b64 s[2:3], -1, 0
	s_or_b64 s[0:1], s[0:1], s[2:3]
	s_and_b64 vcc, exec, s[0:1]
	s_cbranch_vccnz .LBB0_1259
	s_load_dword s34, s[74:75], 0x180
	s_add_u32 s0, s92, 0x3800000
	s_addc_u32 s1, s93, 0
	s_add_u32 s10, s92, 0x2bc0000
	s_addc_u32 s11, s93, 0
	s_and_b32 s36, s72, 0xffffffc0
	v_mbcnt_hi_u32_b32 v195, -1, v194
	s_waitcnt lgkmcnt(0)
	s_and_b32 s35, s34, 7
	s_cmp_lg_u32 s35, 0
	s_waitcnt vmcnt(16)
	v_add_u32_e32 v196, s36, v195
	v_mbcnt_lo_u32_b32 v240, -1, 0
	v_mbcnt_hi_u32_b32 v240, -1, v240
	s_lshr_b32 s26, s72, 6
	s_lshl_b32 s99, s26, 10
	v_and_b32_e32 v241, 15, v240
	v_lshrrev_b32_e32 v242, 4, v240
	v_bfe_u32 v243, v240, 3, 1
	v_mul_u32_u24_e32 v243, 3, v243
	v_xor_b32_e32 v243, v242, v243
	v_lshlrev_b32_e32 v243, 4, v243
	v_lshl_add_u32 v243, v241, 6, v243
	s_lshr_b32 s25, s26, 1
	s_lshl_b32 s25, s25, 13
	v_add_u32_e32 v230, s25, v243
	s_and_b32 s25, s26, 1
	s_lshl_b32 s25, s25, 12
	s_add_u32 s25, s25, 16384
	v_add_u32_e32 v231, s25, v243
	s_lshr_b32 s25, s26, 1
	s_lshl_b32 s25, s25, 7
	v_add_u32_e32 v244, s25, v241
	s_and_b32 s25, s26, 1
	s_lshl_b32 s25, s25, 6
	v_lshl_add_u32 v245, v242, 2, s25
	s_movk_i32 s25, 1024
	v_mul_lo_u32 v246, v244, s25
	v_lshl_add_u32 v234, v245, 1, v246
	s_movk_i32 s25, 4160
	v_mul_lo_u32 v246, v244, s25
	v_lshl_add_u32 v235, v245, 1, v246
	s_mul_i32 s25, s26, 18432
	v_mul_u32_u24_e32 v246, 144, v241
	v_lshl_add_u32 v246, v242, 3, v246
	v_add_u32_e32 v236, s25, v246
	v_lshrrev_b32_e32 v246, 3, v240
	v_mul_u32_u24_e32 v246, 144, v246
	v_and_b32_e32 v247, 7, v240
	v_lshl_add_u32 v246, v247, 4, v246
	v_add_u32_e32 v237, s25, v246
	s_lshr_b32 s25, s26, 1
	s_lshl_b32 s25, s25, 7
	v_lshrrev_b32_e32 v246, 3, v240
	v_add_u32_e32 v246, s25, v246
	s_and_b32 s25, s26, 1
	s_lshl_b32 s25, s25, 6
	v_lshl_add_u32 v248, v247, 3, s25
	s_movk_i32 s25, 1024
	v_mul_lo_u32 v247, v246, s25
	v_lshl_add_u32 v238, v248, 1, v247
	s_movk_i32 s25, 4160
	v_mul_lo_u32 v247, v246, s25
	v_lshl_add_u32 v239, v248, 1, v247
	v_lshrrev_b32_e32 v241, 2, v240
	s_lshl_b32 s25, s26, 4
	v_add_u32_e32 v241, s25, v241
	v_bfe_u32 v242, v240, 5, 1
	v_mul_u32_u24_e32 v242, 3, v242
	v_and_b32_e32 v243, 3, v240
	v_xor_b32_e32 v243, v243, v242
	v_lshlrev_b32_e32 v243, 4, v243
	s_mov_b32 s25, 2048
	v_mad_u32_u24 v224, v241, s25, v243
	v_add_u32_e32 v225, 0x20000, v224
	v_add_u32_e32 v226, 0x40000, v224
	v_add_u32_e32 v227, 0x60000, v224
	s_mov_b32 s25, 2048
	v_mad_u32_u24 v228, v241, s25, v243
	v_add_u32_e32 v229, 0x20000, v228
	s_cmpk_gt_u32 s96, 0xff
	s_cselect_b32 s24, 1, 0
	s_cmpk_gt_u32 s96, 0xff
	s_cbranch_scc0 .Lg11_prio
	s_setprio 1

; #define LWRITE(S, buf) do { bf16_t* sA_ = sbase + (buf) * BUF; bf16_t* sB_ = sA_ + 256 * PITCH; \
;     _Pragma("unroll") for (int i_ = 0; i_ < 4; ++i_) *(u32x4*)(sA_ + (sr + i_ * 64) * PITCH + scv * 8) = ra[S][i_]; \
;     _Pragma("unroll") for (int i_ = 0; i_ < 2; ++i_) *(u32x4*)(sB_ + (sr + i_ * 64) * PITCH + scv * 8) = rb[S][i_]; } while (0)
; template <class Epi>
; DI void gemm_tile(char* smem, const bf16_t* __restrict__ A0, int lda0, int ksplit, const bf16_t* __restrict__ A1, int lda1,
;                   const bf16_t* __restrict__ Bt, int K, int row0, int col0, const Epi& epi, int tid) {
;     ...
;   __syncthreads();
;   {
;     const int last = nk - 1;
;     GLOAD(0, 0);
;     __builtin_amdgcn_sched_barrier(0);
;     GLOAD(1, 1);
;     __builtin_amdgcn_sched_barrier(0);
;     LWRITE(0, 0);
;     __builtin_amdgcn_sched_barrier(0);
;     GLOAD(0, (2 < last ? 2 : last));
;     __builtin_amdgcn_sched_barrier(0);
;     __syncthreads();
;     for (int kt = 0; kt < nk; kt += 2) {
;       LWRITE(1, 1);
;       __builtin_amdgcn_sched_barrier(0);
;       GLOAD(1, (kt + 3 < last ? kt + 3 : last));
;       __builtin_amdgcn_sched_barrier(0);
;       COMPUTE(0);
;       __syncthreads();
;       LWRITE(0, 0);
;       __builtin_amdgcn_sched_barrier(0);
;       GLOAD(0, (kt + 4 < last ? kt + 4 : last));
;       __builtin_amdgcn_sched_barrier(0);
;       COMPUTE(1);
;       __syncthreads();
;     }
.Lg11_kloop:
	s_waitcnt vmcnt(6)
	s_waitcnt lgkmcnt(0)
	s_barrier
	v_add_u32_e32 v232, s30, v230
	v_add_u32_e32 v233, s30, v231
	s_add_u32 s25, s29, s99
	s_setprio 1
	v_mfma_f32_16x16x32_bf16 v[0:3], v[128:131], v[144:147], v[0:3]
	v_mfma_f32_16x16x32_bf16 v[4:7], v[132:135], v[144:147], v[4:7]
	v_mfma_f32_16x16x32_bf16 v[8:11], v[136:139], v[144:147], v[8:11]
	v_mfma_f32_16x16x32_bf16 v[12:15], v[140:143], v[144:147], v[12:15]
	ds_read_b128 v[176:179], v233 offset:0
	ds_read_b128 v[180:183], v233 offset:1024
	s_add_u32 m0, s25, 0
	s_nop 0
	global_load_lds_dwordx4 v224, s[0:1]
	v_mfma_f32_16x16x32_bf16 v[16:19], v[128:131], v[148:151], v[16:19]
	v_mfma_f32_16x16x32_bf16 v[20:23], v[132:135], v[148:151], v[20:23]
	v_mfma_f32_16x16x32_bf16 v[24:27], v[136:139], v[148:151], v[24:27]
	v_mfma_f32_16x16x32_bf16 v[28:31], v[140:143], v[148:151], v[28:31]
	ds_read_b128 v[184:187], v233 offset:2048
	ds_read_b128 v[188:191], v233 offset:3072
	s_add_u32 m0, s25, 4096
	s_nop 0
	global_load_lds_dwordx4 v225, s[0:1]
	v_mfma_f32_16x16x32_bf16 v[32:35], v[128:131], v[152:155], v[32:35]
	v_mfma_f32_16x16x32_bf16 v[36:39], v[132:135], v[152:155], v[36:39]
	v_mfma_f32_16x16x32_bf16 v[40:43], v[136:139], v[152:155], v[40:43]
	v_mfma_f32_16x16x32_bf16 v[44:47], v[140:143], v[152:155], v[44:47]
	ds_read_b128 v[192:195], v232 offset:0
	ds_read_b128 v[196:199], v232 offset:1024
	s_add_u32 m0, s25, 8192
	s_nop 0
	global_load_lds_dwordx4 v226, s[0:1]
	v_mfma_f32_16x16x32_bf16 v[48:51], v[128:131], v[156:159], v[48:51]
	v_mfma_f32_16x16x32_bf16 v[52:55], v[132:135], v[156:159], v[52:55]
	v_mfma_f32_16x16x32_bf16 v[56:59], v[136:139], v[156:159], v[56:59]
	v_mfma_f32_16x16x32_bf16 v[60:63], v[140:143], v[156:159], v[60:63]
	ds_read_b128 v[200:203], v232 offset:2048
	ds_read_b128 v[204:207], v232 offset:3072
	s_add_u32 m0, s25, 12288
	s_nop 0
	global_load_lds_dwordx4 v227, s[0:1]
	v_mfma_f32_16x16x32_bf16 v[64:67], v[128:131], v[160:163], v[64:67]
	v_mfma_f32_16x16x32_bf16 v[68:71], v[132:135], v[160:163], v[68:71]
	v_mfma_f32_16x16x32_bf16 v[72:75], v[136:139], v[160:163], v[72:75]
	v_mfma_f32_16x16x32_bf16 v[76:79], v[140:143], v[160:163], v[76:79]
	ds_read_b128 v[208:211], v232 offset:4096
	s_add_u32 m0, s25, 16384
	s_nop 0
	global_load_lds_dwordx4 v228, s[2:3]
	v_mfma_f32_16x16x32_bf16 v[80:83], v[128:131], v[164:167], v[80:83]
	v_mfma_f32_16x16x32_bf16 v[84:87], v[132:135], v[164:167], v[84:87]
	v_mfma_f32_16x16x32_bf16 v[88:91], v[136:139], v[164:167], v[88:91]
	v_mfma_f32_16x16x32_bf16 v[92:95], v[140:143], v[164:167], v[92:95]
	ds_read_b128 v[212:215], v232 offset:5120
	s_add_u32 m0, s25, 20480
	s_nop 0
	global_load_lds_dwordx4 v229, s[2:3]
	v_mfma_f32_16x16x32_bf16 v[96:99], v[128:131], v[168:171], v[96:99]
	v_mfma_f32_16x16x32_bf16 v[100:103], v[132:135], v[168:171], v[100:103]
	v_mfma_f32_16x16x32_bf16 v[104:107], v[136:139], v[168:171], v[104:107]
	v_mfma_f32_16x16x32_bf16 v[108:111], v[140:143], v[168:171], v[108:111]
	ds_read_b128 v[216:219], v232 offset:6144
	s_add_u32 s0, s0, 64
	s_addc_u32 s1, s1, 0
	s_add_u32 s2, s2, 64
	s_addc_u32 s3, s3, 0
	s_add_u32 s98, s98, 1
	s_add_u32 s29, s29, 24576
	s_cmp_eq_u32 s29, 73728
	s_cselect_b32 s29, 0, s29
	s_add_u32 s30, s30, 24576
	s_cmp_eq_u32 s30, 73728
	s_cselect_b32 s30, 0, s30
	v_mfma_f32_16x16x32_bf16 v[112:115], v[128:131], v[172:175], v[112:115]
	v_mfma_f32_16x16x32_bf16 v[116:119], v[132:135], v[172:175], v[116:119]
	v_mfma_f32_16x16x32_bf16 v[120:123], v[136:139], v[172:175], v[120:123]
	v_mfma_f32_16x16x32_bf16 v[124:127], v[140:143], v[172:175], v[124:127]
	ds_read_b128 v[220:223], v232 offset:7168
	s_cmp_eq_u32 s24, 0
	s_cbranch_scc0 .Lg11_hi0
	s_setprio 0
.Lg11_hi0:
	s_waitcnt vmcnt(6)
	s_waitcnt lgkmcnt(0)
	s_barrier
	v_add_u32_e32 v232, s30, v230
	v_add_u32_e32 v233, s30, v231
	s_add_u32 s25, s29, s99
	s_setprio 1
	v_mfma_f32_16x16x32_bf16 v[0:3], v[176:179], v[192:195], v[0:3]
	v_mfma_f32_16x16x32_bf16 v[4:7], v[180:183], v[192:195], v[4:7]
	v_mfma_f32_16x16x32_bf16 v[8:11], v[184:187], v[192:195], v[8:11]
	v_mfma_f32_16x16x32_bf16 v[12:15], v[188:191], v[192:195], v[12:15]
	ds_read_b128 v[128:131], v233 offset:0
	ds_read_b128 v[132:135], v233 offset:1024
	s_add_u32 m0, s25, 0
	s_nop 0
	global_load_lds_dwordx4 v224, s[0:1]
	v_mfma_f32_16x16x32_bf16 v[16:19], v[176:179], v[196:199], v[16:19]
	v_mfma_f32_16x16x32_bf16 v[20:23], v[180:183], v[196:199], v[20:23]
	v_mfma_f32_16x16x32_bf16 v[24:27], v[184:187], v[196:199], v[24:27]
	v_mfma_f32_16x16x32_bf16 v[28:31], v[188:191], v[196:199], v[28:31]
	ds_read_b128 v[136:139], v233 offset:2048
	ds_read_b128 v[140:143], v233 offset:3072
	s_add_u32 m0, s25, 4096
	s_nop 0
	global_load_lds_dwordx4 v225, s[0:1]
	v_mfma_f32_16x16x32_bf16 v[32:35], v[176:179], v[200:203], v[32:35]
	v_mfma_f32_16x16x32_bf16 v[36:39], v[180:183], v[200:203], v[36:39]
	v_mfma_f32_16x16x32_bf16 v[40:43], v[184:187], v[200:203], v[40:43]
	v_mfma_f32_16x16x32_bf16 v[44:47], v[188:191], v[200:203], v[44:47]
	ds_read_b128 v[144:147], v232 offset:0
	ds_read_b128 v[148:151], v232 offset:1024
	s_add_u32 m0, s25, 8192
	s_nop 0
	global_load_lds_dwordx4 v226, s[0:1]
	v_mfma_f32_16x16x32_bf16 v[48:51], v[176:179], v[204:207], v[48:51]
	v_mfma_f32_16x16x32_bf16 v[52:55], v[180:183], v[204:207], v[52:55]
	v_mfma_f32_16x16x32_bf16 v[56:59], v[184:187], v[204:207], v[56:59]
	v_mfma_f32_16x16x32_bf16 v[60:63], v[188:191], v[204:207], v[60:63]
	ds_read_b128 v[152:155], v232 offset:2048
	ds_read_b128 v[156:159], v232 offset:3072
	s_add_u32 m0, s25, 12288
	s_nop 0
	global_load_lds_dwordx4 v227, s[0:1]
	v_mfma_f32_16x16x32_bf16 v[64:67], v[176:179], v[208:211], v[64:67]
; #define LWRITE(S, buf) do { bf16_t* sA_ = sbase + (buf) * BUF; bf16_t* sB_ = sA_ + 256 * PITCH; \
;     _Pragma("unroll") for (int i_ = 0; i_ < 4; ++i_) *(u32x4*)(sA_ + (sr + i_ * 64) * PITCH + scv * 8) = ra[S][i_]; \
;     _Pragma("unroll") for (int i_ = 0; i_ < 2; ++i_) *(u32x4*)(sB_ + (sr + i_ * 64) * PITCH + scv * 8) = rb[S][i_]; } while (0)
; template <class Epi>
; DI void gemm_tile(char* smem, const bf16_t* __restrict__ A0, int lda0, int ksplit, const bf16_t* __restrict__ A1, int lda1,
;                   const bf16_t* __restrict__ Bt, int K, int row0, int col0, const Epi& epi, int tid) {
;     ...
;   __syncthreads();
;   {
;     const int last = nk - 1;
;     GLOAD(0, 0);
;     __builtin_amdgcn_sched_barrier(0);
;     GLOAD(1, 1);
;     __builtin_amdgcn_sched_barrier(0);
;     LWRITE(0, 0);
;     __builtin_amdgcn_sched_barrier(0);
;     GLOAD(0, (2 < last ? 2 : last));
;     __builtin_amdgcn_sched_barrier(0);
;     __syncthreads();
;     for (int kt = 0; kt < nk; kt += 2) {
;       LWRITE(1, 1);
;       __builtin_amdgcn_sched_barrier(0);
;       GLOAD(1, (kt + 3 < last ? kt + 3 : last));
;       __builtin_amdgcn_sched_barrier(0);
;       COMPUTE(0);
;       __syncthreads();
;       LWRITE(0, 0);
;       __builtin_amdgcn_sched_barrier(0);
;       GLOAD(0, (kt + 4 < last ? kt + 4 : last));
;       __builtin_amdgcn_sched_barrier(0);
;       COMPUTE(1);
;       __syncthreads();
;     }
	v_mfma_f32_16x16x32_bf16 v[68:71], v[180:183], v[208:211], v[68:71]
	v_mfma_f32_16x16x32_bf16 v[72:75], v[184:187], v[208:211], v[72:75]
	v_mfma_f32_16x16x32_bf16 v[76:79], v[188:191], v[208:211], v[76:79]
	ds_read_b128 v[160:163], v232 offset:4096
	s_add_u32 m0, s25, 16384
	s_nop 0
	global_load_lds_dwordx4 v228, s[2:3]
	v_mfma_f32_16x16x32_bf16 v[80:83], v[176:179], v[212:215], v[80:83]
	v_mfma_f32_16x16x32_bf16 v[84:87], v[180:183], v[212:215], v[84:87]
	v_mfma_f32_16x16x32_bf16 v[88:91], v[184:187], v[212:215], v[88:91]
	v_mfma_f32_16x16x32_bf16 v[92:95], v[188:191], v[212:215], v[92:95]
	ds_read_b128 v[164:167], v232 offset:5120
	s_add_u32 m0, s25, 20480
	s_nop 0
	global_load_lds_dwordx4 v229, s[2:3]
	v_mfma_f32_16x16x32_bf16 v[96:99], v[176:179], v[216:219], v[96:99]
	v_mfma_f32_16x16x32_bf16 v[100:103], v[180:183], v[216:219], v[100:103]
	v_mfma_f32_16x16x32_bf16 v[104:107], v[184:187], v[216:219], v[104:107]
	v_mfma_f32_16x16x32_bf16 v[108:111], v[188:191], v[216:219], v[108:111]
	ds_read_b128 v[168:171], v232 offset:6144
	s_add_u32 s0, s0, 64
	s_addc_u32 s1, s1, 0
	s_add_u32 s2, s2, 64
	s_addc_u32 s3, s3, 0
	s_add_u32 s98, s98, 1
	s_add_u32 s29, s29, 24576
	s_cmp_eq_u32 s29, 73728
	s_cselect_b32 s29, 0, s29
	s_add_u32 s30, s30, 24576
	s_cmp_eq_u32 s30, 73728
	s_cselect_b32 s30, 0, s30
	v_mfma_f32_16x16x32_bf16 v[112:115], v[176:179], v[220:223], v[112:115]
	v_mfma_f32_16x16x32_bf16 v[116:119], v[180:183], v[220:223], v[116:119]
	v_mfma_f32_16x16x32_bf16 v[120:123], v[184:187], v[220:223], v[120:123]
	v_mfma_f32_16x16x32_bf16 v[124:127], v[188:191], v[220:223], v[124:127]
	ds_read_b128 v[172:175], v232 offset:7168
	s_cmp_eq_u32 s24, 0
	s_cbranch_scc0 .Lg11_hi1
	s_setprio 0
.Lg11_hi1:
	s_add_u32 s31, s31, 2
	s_cmp_lt_u32 s31, 28
	s_cbranch_scc1 .Lg11_kloop
	s_waitcnt vmcnt(6)
	s_waitcnt lgkmcnt(0)
	s_barrier
	v_add_u32_e32 v232, s30, v230
	v_add_u32_e32 v233, s30, v231
	s_add_u32 s25, s29, s99
	s_setprio 1
	v_mfma_f32_16x16x32_bf16 v[0:3], v[128:131], v[144:147], v[0:3]
	v_mfma_f32_16x16x32_bf16 v[4:7], v[132:135], v[144:147], v[4:7]
	v_mfma_f32_16x16x32_bf16 v[8:11], v[136:139], v[144:147], v[8:11]
	v_mfma_f32_16x16x32_bf16 v[12:15], v[140:143], v[144:147], v[12:15]
	ds_read_b128 v[176:179], v233 offset:0
	ds_read_b128 v[180:183], v233 offset:1024
	s_add_u32 m0, s25, 0
	s_nop 0
	global_load_lds_dwordx4 v224, s[0:1]
	v_mfma_f32_16x16x32_bf16 v[16:19], v[128:131], v[148:151], v[16:19]
	v_mfma_f32_16x16x32_bf16 v[20:23], v[132:135], v[148:151], v[20:23]
	v_mfma_f32_16x16x32_bf16 v[24:27], v[136:139], v[148:151], v[24:27]
	v_mfma_f32_16x16x32_bf16 v[28:31], v[140:143], v[148:151], v[28:31]
	ds_read_b128 v[184:187], v233 offset:2048
	ds_read_b128 v[188:191], v233 offset:3072
	s_add_u32 m0, s25, 4096
	s_nop 0
	global_load_lds_dwordx4 v225, s[0:1]
	v_mfma_f32_16x16x32_bf16 v[32:35], v[128:131], v[152:155], v[32:35]
	v_mfma_f32_16x16x32_bf16 v[36:39], v[132:135], v[152:155], v[36:39]
	v_mfma_f32_16x16x32_bf16 v[40:43], v[136:139], v[152:155], v[40:43]
	v_mfma_f32_16x16x32_bf16 v[44:47], v[140:143], v[152:155], v[44:47]
	ds_read_b128 v[192:195], v232 offset:0
	ds_read_b128 v[196:199], v232 offset:1024
	s_add_u32 m0, s25, 8192
	s_nop 0
	global_load_lds_dwordx4 v226, s[0:1]
	v_mfma_f32_16x16x32_bf16 v[48:51], v[128:131], v[156:159], v[48:51]
	v_mfma_f32_16x16x32_bf16 v[52:55], v[132:135], v[156:159], v[52:55]
	v_mfma_f32_16x16x32_bf16 v[56:59], v[136:139], v[156:159], v[56:59]
	v_mfma_f32_16x16x32_bf16 v[60:63], v[140:143], v[156:159], v[60:63]
	ds_read_b128 v[200:203], v232 offset:2048
	ds_read_b128 v[204:207], v232 offset:3072
	s_add_u32 m0, s25, 12288
	s_nop 0
	global_load_lds_dwordx4 v227, s[0:1]
	v_mfma_f32_16x16x32_bf16 v[64:67], v[128:131], v[160:163], v[64:67]
	v_mfma_f32_16x16x32_bf16 v[68:71], v[132:135], v[160:163], v[68:71]
	v_mfma_f32_16x16x32_bf16 v[72:75], v[136:139], v[160:163], v[72:75]
	v_mfma_f32_16x16x32_bf16 v[76:79], v[140:143], v[160:163], v[76:79]
	ds_read_b128 v[208:211], v232 offset:4096
	s_add_u32 m0, s25, 16384
	s_nop 0
	global_load_lds_dwordx4 v228, s[2:3]
	v_mfma_f32_16x16x32_bf16 v[80:83], v[128:131], v[164:167], v[80:83]
	v_mfma_f32_16x16x32_bf16 v[84:87], v[132:135], v[164:167], v[84:87]
	v_mfma_f32_16x16x32_bf16 v[88:91], v[136:139], v[164:167], v[88:91]
	v_mfma_f32_16x16x32_bf16 v[92:95], v[140:143], v[164:167], v[92:95]
	ds_read_b128 v[212:215], v232 offset:5120
	s_add_u32 m0, s25, 20480
	s_nop 0
	global_load_lds_dwordx4 v229, s[2:3]
	v_mfma_f32_16x16x32_bf16 v[96:99], v[128:131], v[168:171], v[96:99]
	v_mfma_f32_16x16x32_bf16 v[100:103], v[132:135], v[168:171], v[100:103]
	v_mfma_f32_16x16x32_bf16 v[104:107], v[136:139], v[168:171], v[104:107]
	v_mfma_f32_16x16x32_bf16 v[108:111], v[140:143], v[168:171], v[108:111]
	ds_read_b128 v[216:219], v232 offset:6144
	s_add_u32 s0, s0, 64
	s_addc_u32 s1, s1, 0
	s_add_u32 s2, s2, 64
	s_addc_u32 s3, s3, 0
	s_add_u32 s98, s98, 1
	s_add_u32 s29, s29, 24576
	s_cmp_eq_u32 s29, 73728
	s_cselect_b32 s29, 0, s29
	s_add_u32 s30, s30, 24576
	s_cmp_eq_u32 s30, 73728
	s_cselect_b32 s30, 0, s30
	v_mfma_f32_16x16x32_bf16 v[112:115], v[128:131], v[172:175], v[112:115]
	v_mfma_f32_16x16x32_bf16 v[116:119], v[132:135], v[172:175], v[116:119]
	v_mfma_f32_16x16x32_bf16 v[120:123], v[136:139], v[172:175], v[120:123]
	v_mfma_f32_16x16x32_bf16 v[124:127], v[140:143], v[172:175], v[124:127]
	ds_read_b128 v[220:223], v232 offset:7168
	s_cmp_eq_u32 s24, 0
	s_cbranch_scc0 .Lg11_hi2
	s_setprio 0
; #define LWRITE(S, buf) do { bf16_t* sA_ = sbase + (buf) * BUF; bf16_t* sB_ = sA_ + 256 * PITCH; \
;     _Pragma("unroll") for (int i_ = 0; i_ < 4; ++i_) *(u32x4*)(sA_ + (sr + i_ * 64) * PITCH + scv * 8) = ra[S][i_]; \
;     _Pragma("unroll") for (int i_ = 0; i_ < 2; ++i_) *(u32x4*)(sB_ + (sr + i_ * 64) * PITCH + scv * 8) = rb[S][i_]; } while (0)
; template <class Epi>
; DI void gemm_tile(char* smem, const bf16_t* __restrict__ A0, int lda0, int ksplit, const bf16_t* __restrict__ A1, int lda1,
;                   const bf16_t* __restrict__ Bt, int K, int row0, int col0, const Epi& epi, int tid) {
;     ...
;   __syncthreads();
;   {
;     const int last = nk - 1;
;     GLOAD(0, 0);
;     __builtin_amdgcn_sched_barrier(0);
;     GLOAD(1, 1);
;     __builtin_amdgcn_sched_barrier(0);
;     LWRITE(0, 0);
;     __builtin_amdgcn_sched_barrier(0);
;     GLOAD(0, (2 < last ? 2 : last));
;     __builtin_amdgcn_sched_barrier(0);
;     __syncthreads();
;     for (int kt = 0; kt < nk; kt += 2) {
;       LWRITE(1, 1);
;       __builtin_amdgcn_sched_barrier(0);
;       GLOAD(1, (kt + 3 < last ? kt + 3 : last));
;       __builtin_amdgcn_sched_barrier(0);
;       COMPUTE(0);
;       __syncthreads();
;       LWRITE(0, 0);
;       __builtin_amdgcn_sched_barrier(0);
;       GLOAD(0, (kt + 4 < last ? kt + 4 : last));
;       __builtin_amdgcn_sched_barrier(0);
;       COMPUTE(1);
;       __syncthreads();
;     }
.Lg11_hi2:
	s_waitcnt vmcnt(6)
	s_waitcnt lgkmcnt(0)
	s_barrier
	v_add_u32_e32 v232, s30, v230
	v_add_u32_e32 v233, s30, v231
	s_setprio 1
	v_mfma_f32_16x16x32_bf16 v[0:3], v[176:179], v[192:195], v[0:3]
	v_mfma_f32_16x16x32_bf16 v[4:7], v[180:183], v[192:195], v[4:7]
	v_mfma_f32_16x16x32_bf16 v[8:11], v[184:187], v[192:195], v[8:11]
	v_mfma_f32_16x16x32_bf16 v[12:15], v[188:191], v[192:195], v[12:15]
	ds_read_b128 v[128:131], v233 offset:0
	ds_read_b128 v[132:135], v233 offset:1024
	v_mfma_f32_16x16x32_bf16 v[16:19], v[176:179], v[196:199], v[16:19]
	v_mfma_f32_16x16x32_bf16 v[20:23], v[180:183], v[196:199], v[20:23]
	v_mfma_f32_16x16x32_bf16 v[24:27], v[184:187], v[196:199], v[24:27]
	v_mfma_f32_16x16x32_bf16 v[28:31], v[188:191], v[196:199], v[28:31]
	ds_read_b128 v[136:139], v233 offset:2048
	ds_read_b128 v[140:143], v233 offset:3072
	v_mfma_f32_16x16x32_bf16 v[32:35], v[176:179], v[200:203], v[32:35]
	v_mfma_f32_16x16x32_bf16 v[36:39], v[180:183], v[200:203], v[36:39]
	v_mfma_f32_16x16x32_bf16 v[40:43], v[184:187], v[200:203], v[40:43]
	v_mfma_f32_16x16x32_bf16 v[44:47], v[188:191], v[200:203], v[44:47]
	ds_read_b128 v[144:147], v232 offset:0
	ds_read_b128 v[148:151], v232 offset:1024
	v_mfma_f32_16x16x32_bf16 v[48:51], v[176:179], v[204:207], v[48:51]
	v_mfma_f32_16x16x32_bf16 v[52:55], v[180:183], v[204:207], v[52:55]
	v_mfma_f32_16x16x32_bf16 v[56:59], v[184:187], v[204:207], v[56:59]
	v_mfma_f32_16x16x32_bf16 v[60:63], v[188:191], v[204:207], v[60:63]
	ds_read_b128 v[152:155], v232 offset:2048
	ds_read_b128 v[156:159], v232 offset:3072
	v_mfma_f32_16x16x32_bf16 v[64:67], v[176:179], v[208:211], v[64:67]
	v_mfma_f32_16x16x32_bf16 v[68:71], v[180:183], v[208:211], v[68:71]
	v_mfma_f32_16x16x32_bf16 v[72:75], v[184:187], v[208:211], v[72:75]
	v_mfma_f32_16x16x32_bf16 v[76:79], v[188:191], v[208:211], v[76:79]
	ds_read_b128 v[160:163], v232 offset:4096
	v_mfma_f32_16x16x32_bf16 v[80:83], v[176:179], v[212:215], v[80:83]
	v_mfma_f32_16x16x32_bf16 v[84:87], v[180:183], v[212:215], v[84:87]
	v_mfma_f32_16x16x32_bf16 v[88:91], v[184:187], v[212:215], v[88:91]
	v_mfma_f32_16x16x32_bf16 v[92:95], v[188:191], v[212:215], v[92:95]
	ds_read_b128 v[164:167], v232 offset:5120
	v_mfma_f32_16x16x32_bf16 v[96:99], v[176:179], v[216:219], v[96:99]
	v_mfma_f32_16x16x32_bf16 v[100:103], v[180:183], v[216:219], v[100:103]
	v_mfma_f32_16x16x32_bf16 v[104:107], v[184:187], v[216:219], v[104:107]
	v_mfma_f32_16x16x32_bf16 v[108:111], v[188:191], v[216:219], v[108:111]
	ds_read_b128 v[168:171], v232 offset:6144
	s_add_u32 s30, s30, 24576
	s_cmp_eq_u32 s30, 73728
	s_cselect_b32 s30, 0, s30
	v_mfma_f32_16x16x32_bf16 v[112:115], v[176:179], v[220:223], v[112:115]
	v_mfma_f32_16x16x32_bf16 v[116:119], v[180:183], v[220:223], v[116:119]
	v_mfma_f32_16x16x32_bf16 v[120:123], v[184:187], v[220:223], v[120:123]
	v_mfma_f32_16x16x32_bf16 v[124:127], v[188:191], v[220:223], v[124:127]
	ds_read_b128 v[172:175], v232 offset:7168
	s_cmp_eq_u32 s24, 0
	s_cbranch_scc0 .Lg11_hi3
	s_setprio 0
.Lg11_hi3:
	s_waitcnt vmcnt(0)
	s_waitcnt lgkmcnt(0)
	s_barrier
	v_add_u32_e32 v232, s30, v230
	v_add_u32_e32 v233, s30, v231
	s_setprio 1
	v_mfma_f32_16x16x32_bf16 v[0:3], v[128:131], v[144:147], v[0:3]
	v_mfma_f32_16x16x32_bf16 v[4:7], v[132:135], v[144:147], v[4:7]
	v_mfma_f32_16x16x32_bf16 v[8:11], v[136:139], v[144:147], v[8:11]
	v_mfma_f32_16x16x32_bf16 v[12:15], v[140:143], v[144:147], v[12:15]
	ds_read_b128 v[176:179], v233 offset:0
	ds_read_b128 v[180:183], v233 offset:1024
	v_mfma_f32_16x16x32_bf16 v[16:19], v[128:131], v[148:151], v[16:19]
	v_mfma_f32_16x16x32_bf16 v[20:23], v[132:135], v[148:151], v[20:23]
	v_mfma_f32_16x16x32_bf16 v[24:27], v[136:139], v[148:151], v[24:27]
	v_mfma_f32_16x16x32_bf16 v[28:31], v[140:143], v[148:151], v[28:31]
	ds_read_b128 v[184:187], v233 offset:2048
	ds_read_b128 v[188:191], v233 offset:3072
	v_mfma_f32_16x16x32_bf16 v[32:35], v[128:131], v[152:155], v[32:35]
	v_mfma_f32_16x16x32_bf16 v[36:39], v[132:135], v[152:155], v[36:39]
	v_mfma_f32_16x16x32_bf16 v[40:43], v[136:139], v[152:155], v[40:43]
	v_mfma_f32_16x16x32_bf16 v[44:47], v[140:143], v[152:155], v[44:47]
	ds_read_b128 v[192:195], v232 offset:0
	ds_read_b128 v[196:199], v232 offset:1024
	v_mfma_f32_16x16x32_bf16 v[48:51], v[128:131], v[156:159], v[48:51]
	v_mfma_f32_16x16x32_bf16 v[52:55], v[132:135], v[156:159], v[52:55]
	v_mfma_f32_16x16x32_bf16 v[56:59], v[136:139], v[156:159], v[56:59]
	v_mfma_f32_16x16x32_bf16 v[60:63], v[140:143], v[156:159], v[60:63]
	ds_read_b128 v[200:203], v232 offset:2048
	ds_read_b128 v[204:207], v232 offset:3072
	v_mfma_f32_16x16x32_bf16 v[64:67], v[128:131], v[160:163], v[64:67]
	v_mfma_f32_16x16x32_bf16 v[68:71], v[132:135], v[160:163], v[68:71]
	v_mfma_f32_16x16x32_bf16 v[72:75], v[136:139], v[160:163], v[72:75]
	v_mfma_f32_16x16x32_bf16 v[76:79], v[140:143], v[160:163], v[76:79]
	ds_read_b128 v[208:211], v232 offset:4096
	v_mfma_f32_16x16x32_bf16 v[80:83], v[128:131], v[164:167], v[80:83]
	v_mfma_f32_16x16x32_bf16 v[84:87], v[132:135], v[164:167], v[84:87]
	v_mfma_f32_16x16x32_bf16 v[88:91], v[136:139], v[164:167], v[88:91]
	v_mfma_f32_16x16x32_bf16 v[92:95], v[140:143], v[164:167], v[92:95]
	ds_read_b128 v[212:215], v232 offset:5120
	v_mfma_f32_16x16x32_bf16 v[96:99], v[128:131], v[168:171], v[96:99]
	v_mfma_f32_16x16x32_bf16 v[100:103], v[132:135], v[168:171], v[100:103]
	v_mfma_f32_16x16x32_bf16 v[104:107], v[136:139], v[168:171], v[104:107]
	v_mfma_f32_16x16x32_bf16 v[108:111], v[140:143], v[168:171], v[108:111]
	ds_read_b128 v[216:219], v232 offset:6144
	s_add_u32 s30, s30, 24576
	s_cmp_eq_u32 s30, 73728
	s_cselect_b32 s30, 0, s30
	v_mfma_f32_16x16x32_bf16 v[112:115], v[128:131], v[172:175], v[112:115]
	v_mfma_f32_16x16x32_bf16 v[116:119], v[132:135], v[172:175], v[116:119]
	v_mfma_f32_16x16x32_bf16 v[120:123], v[136:139], v[172:175], v[120:123]
	v_mfma_f32_16x16x32_bf16 v[124:127], v[140:143], v[172:175], v[124:127]
	ds_read_b128 v[220:223], v232 offset:7168
	s_cmp_eq_u32 s24, 0
	s_cbranch_scc0 .Lg11_hi4
	s_setprio 0
; #define LWRITE(S, buf) do { bf16_t* sA_ = sbase + (buf) * BUF; bf16_t* sB_ = sA_ + 256 * PITCH; \
;     _Pragma("unroll") for (int i_ = 0; i_ < 4; ++i_) *(u32x4*)(sA_ + (sr + i_ * 64) * PITCH + scv * 8) = ra[S][i_]; \
;     _Pragma("unroll") for (int i_ = 0; i_ < 2; ++i_) *(u32x4*)(sB_ + (sr + i_ * 64) * PITCH + scv * 8) = rb[S][i_]; } while (0)
; template <class Epi>
; DI void gemm_tile(char* smem, const bf16_t* __restrict__ A0, int lda0, int ksplit, const bf16_t* __restrict__ A1, int lda1,
;                   const bf16_t* __restrict__ Bt, int K, int row0, int col0, const Epi& epi, int tid) {
;     ...
;     for (int kt = 0; kt < nk; kt += 2) {
;       LWRITE(1, 1);
;       __builtin_amdgcn_sched_barrier(0);
;       GLOAD(1, (kt + 3 < last ? kt + 3 : last));
;       __builtin_amdgcn_sched_barrier(0);
;       COMPUTE(0);
;       __syncthreads();
;       LWRITE(0, 0);
;       __builtin_amdgcn_sched_barrier(0);
;       GLOAD(0, (kt + 4 < last ? kt + 4 : last));
;       __builtin_amdgcn_sched_barrier(0);
;       COMPUTE(1);
;       __syncthreads();
;     }
.Lg11_hi4:
	s_waitcnt lgkmcnt(0)
	s_barrier
	s_setprio 1
	v_mfma_f32_16x16x32_bf16 v[0:3], v[176:179], v[192:195], v[0:3]
	v_mfma_f32_16x16x32_bf16 v[4:7], v[180:183], v[192:195], v[4:7]
	v_mfma_f32_16x16x32_bf16 v[8:11], v[184:187], v[192:195], v[8:11]
	v_mfma_f32_16x16x32_bf16 v[12:15], v[188:191], v[192:195], v[12:15]
	v_mfma_f32_16x16x32_bf16 v[16:19], v[176:179], v[196:199], v[16:19]
	v_mfma_f32_16x16x32_bf16 v[20:23], v[180:183], v[196:199], v[20:23]
	v_mfma_f32_16x16x32_bf16 v[24:27], v[184:187], v[196:199], v[24:27]
	v_mfma_f32_16x16x32_bf16 v[28:31], v[188:191], v[196:199], v[28:31]
	v_mfma_f32_16x16x32_bf16 v[32:35], v[176:179], v[200:203], v[32:35]
	v_mfma_f32_16x16x32_bf16 v[36:39], v[180:183], v[200:203], v[36:39]
	v_mfma_f32_16x16x32_bf16 v[40:43], v[184:187], v[200:203], v[40:43]
	v_mfma_f32_16x16x32_bf16 v[44:47], v[188:191], v[200:203], v[44:47]
	v_mfma_f32_16x16x32_bf16 v[48:51], v[176:179], v[204:207], v[48:51]
	v_mfma_f32_16x16x32_bf16 v[52:55], v[180:183], v[204:207], v[52:55]
	v_mfma_f32_16x16x32_bf16 v[56:59], v[184:187], v[204:207], v[56:59]
	v_mfma_f32_16x16x32_bf16 v[60:63], v[188:191], v[204:207], v[60:63]
	v_mfma_f32_16x16x32_bf16 v[64:67], v[176:179], v[208:211], v[64:67]
	v_mfma_f32_16x16x32_bf16 v[68:71], v[180:183], v[208:211], v[68:71]
	v_mfma_f32_16x16x32_bf16 v[72:75], v[184:187], v[208:211], v[72:75]
	v_mfma_f32_16x16x32_bf16 v[76:79], v[188:191], v[208:211], v[76:79]
	v_mfma_f32_16x16x32_bf16 v[80:83], v[176:179], v[212:215], v[80:83]
	v_mfma_f32_16x16x32_bf16 v[84:87], v[180:183], v[212:215], v[84:87]
	v_mfma_f32_16x16x32_bf16 v[88:91], v[184:187], v[212:215], v[88:91]
	v_mfma_f32_16x16x32_bf16 v[92:95], v[188:191], v[212:215], v[92:95]
	v_mfma_f32_16x16x32_bf16 v[96:99], v[176:179], v[216:219], v[96:99]
	v_mfma_f32_16x16x32_bf16 v[100:103], v[180:183], v[216:219], v[100:103]
	v_mfma_f32_16x16x32_bf16 v[104:107], v[184:187], v[216:219], v[104:107]
	v_mfma_f32_16x16x32_bf16 v[108:111], v[188:191], v[216:219], v[108:111]
	v_mfma_f32_16x16x32_bf16 v[112:115], v[176:179], v[220:223], v[112:115]
	v_mfma_f32_16x16x32_bf16 v[116:119], v[180:183], v[220:223], v[116:119]
	v_mfma_f32_16x16x32_bf16 v[120:123], v[184:187], v[220:223], v[120:123]
	v_mfma_f32_16x16x32_bf16 v[124:127], v[188:191], v[220:223], v[124:127]
	s_cmp_eq_u32 s24, 0
	s_cbranch_scc0 .Lg11_hi5
	s_setprio 0
.Lg11_hi5:
	s_branch .Lg11_epi
; DI unsigned pack2(float lo, float hi) { const f32x2c v = {lo, hi}; return __builtin_bit_cast(unsigned, __builtin_convertvector(v, bf16x2c)); }
; template <class Epi>
; DI void gemm_tile(char* smem, const bf16_t* __restrict__ A0, int lda0, int ksplit, const bf16_t* __restrict__ A1, int lda1,
;                   const bf16_t* __restrict__ Bt, int K, int row0, int col0, const Epi& epi, int tid) {
;     ...
; #pragma unroll
;   for (int m = 0; m < 8; ++m)
; #pragma unroll
;     for (int n = 0; n < 4; ++n) epi(row0 + wr * 128 + m * 16 + fr, col0 + wc * 64 + n * 16 + fq * 4, acc[m][n]);
; }
; DI void st_bf16x4(bf16_t* o, f32x4 v) { u32x2 q; q.x = pack2(v[0], v[1]); q.y = pack2(v[2], v[3]); *(u32x2*)o = q; }
;   DI void operator()(int row, int col, f32x4 v) const {
;     if (col < n0) st_bf16x4(o0 + (size_t)row * ld0 + col, v);
;     else { const int c = col - n0; if (c < n1) st_bf16x4(o1 + (size_t)row * ld1 + c, v); }
;   }
.Lg11_epi:
	s_nop 7
	s_nop 7
	s_cmpk_ge_u32 s27, 512
	s_cbranch_scc1 .Lg11_eo1
	s_mul_i32 s26, s28, 1024
	s_lshl_b32 s25, s27, 1
	s_add_u32 s26, s26, s25
	s_add_u32 s26, s26, 0x7800000
	s_add_u32 s4, s92, s26
	s_addc_u32 s5, s93, 0
	v_cvt_pk_bf16_f32 v128, v0, v1
	v_cvt_pk_bf16_f32 v129, v2, v3
	ds_write_b64 v236, v[128:129]
	v_cvt_pk_bf16_f32 v130, v4, v5
	v_cvt_pk_bf16_f32 v131, v6, v7
	ds_write_b64 v236, v[130:131] offset:32
	v_cvt_pk_bf16_f32 v132, v8, v9
	v_cvt_pk_bf16_f32 v133, v10, v11
	ds_write_b64 v236, v[132:133] offset:64
	v_cvt_pk_bf16_f32 v134, v12, v13
	v_cvt_pk_bf16_f32 v135, v14, v15
	ds_write_b64 v236, v[134:135] offset:96
	v_cvt_pk_bf16_f32 v136, v16, v17
	v_cvt_pk_bf16_f32 v137, v18, v19
	ds_write_b64 v236, v[136:137] offset:2304
	v_cvt_pk_bf16_f32 v138, v20, v21
	v_cvt_pk_bf16_f32 v139, v22, v23
	ds_write_b64 v236, v[138:139] offset:2336
	v_cvt_pk_bf16_f32 v140, v24, v25
	v_cvt_pk_bf16_f32 v141, v26, v27
	ds_write_b64 v236, v[140:141] offset:2368
	v_cvt_pk_bf16_f32 v142, v28, v29
	v_cvt_pk_bf16_f32 v143, v30, v31
	ds_write_b64 v236, v[142:143] offset:2400
	v_cvt_pk_bf16_f32 v144, v32, v33
	v_cvt_pk_bf16_f32 v145, v34, v35
	ds_write_b64 v236, v[144:145] offset:4608
	v_cvt_pk_bf16_f32 v146, v36, v37
	v_cvt_pk_bf16_f32 v147, v38, v39
	ds_write_b64 v236, v[146:147] offset:4640
	v_cvt_pk_bf16_f32 v148, v40, v41
	v_cvt_pk_bf16_f32 v149, v42, v43
	ds_write_b64 v236, v[148:149] offset:4672
	v_cvt_pk_bf16_f32 v150, v44, v45
	v_cvt_pk_bf16_f32 v151, v46, v47
	ds_write_b64 v236, v[150:151] offset:4704
	v_cvt_pk_bf16_f32 v152, v48, v49
	v_cvt_pk_bf16_f32 v153, v50, v51
	ds_write_b64 v236, v[152:153] offset:6912
	v_cvt_pk_bf16_f32 v154, v52, v53
	v_cvt_pk_bf16_f32 v155, v54, v55
	ds_write_b64 v236, v[154:155] offset:6944
	v_cvt_pk_bf16_f32 v156, v56, v57
	v_cvt_pk_bf16_f32 v157, v58, v59
	ds_write_b64 v236, v[156:157] offset:6976
	v_cvt_pk_bf16_f32 v158, v60, v61
	v_cvt_pk_bf16_f32 v159, v62, v63
	ds_write_b64 v236, v[158:159] offset:7008
	v_cvt_pk_bf16_f32 v128, v64, v65
	v_cvt_pk_bf16_f32 v129, v66, v67
	ds_write_b64 v236, v[128:129] offset:9216
	v_cvt_pk_bf16_f32 v130, v68, v69
	v_cvt_pk_bf16_f32 v131, v70, v71
	ds_write_b64 v236, v[130:131] offset:9248
	v_cvt_pk_bf16_f32 v132, v72, v73
	v_cvt_pk_bf16_f32 v133, v74, v75
	ds_write_b64 v236, v[132:133] offset:9280
	v_cvt_pk_bf16_f32 v134, v76, v77
	v_cvt_pk_bf16_f32 v135, v78, v79
	ds_write_b64 v236, v[134:135] offset:9312
	v_cvt_pk_bf16_f32 v136, v80, v81
	v_cvt_pk_bf16_f32 v137, v82, v83
	ds_write_b64 v236, v[136:137] offset:11520
	v_cvt_pk_bf16_f32 v138, v84, v85
	v_cvt_pk_bf16_f32 v139, v86, v87
	ds_write_b64 v236, v[138:139] offset:11552
	v_cvt_pk_bf16_f32 v140, v88, v89
	v_cvt_pk_bf16_f32 v141, v90, v91
	ds_write_b64 v236, v[140:141] offset:11584
	v_cvt_pk_bf16_f32 v142, v92, v93
	v_cvt_pk_bf16_f32 v143, v94, v95
	ds_write_b64 v236, v[142:143] offset:11616
	v_cvt_pk_bf16_f32 v144, v96, v97
	v_cvt_pk_bf16_f32 v145, v98, v99
	ds_write_b64 v236, v[144:145] offset:13824
	v_cvt_pk_bf16_f32 v146, v100, v101
	v_cvt_pk_bf16_f32 v147, v102, v103
	ds_write_b64 v236, v[146:147] offset:13856
	v_cvt_pk_bf16_f32 v148, v104, v105
	v_cvt_pk_bf16_f32 v149, v106, v107
	ds_write_b64 v236, v[148:149] offset:13888
	v_cvt_pk_bf16_f32 v150, v108, v109
	v_cvt_pk_bf16_f32 v151, v110, v111
	ds_write_b64 v236, v[150:151] offset:13920
	v_cvt_pk_bf16_f32 v152, v112, v113
	v_cvt_pk_bf16_f32 v153, v114, v115
	ds_write_b64 v236, v[152:153] offset:16128
	v_cvt_pk_bf16_f32 v154, v116, v117
	v_cvt_pk_bf16_f32 v155, v118, v119
	ds_write_b64 v236, v[154:155] offset:16160
	v_cvt_pk_bf16_f32 v156, v120, v121
	v_cvt_pk_bf16_f32 v157, v122, v123
	ds_write_b64 v236, v[156:157] offset:16192
	v_cvt_pk_bf16_f32 v158, v124, v125
	v_cvt_pk_bf16_f32 v159, v126, v127
	ds_write_b64 v236, v[158:159] offset:16224
	s_waitcnt lgkmcnt(0)
	ds_read_b128 v[128:131], v237
	ds_read_b128 v[132:135], v237 offset:1152
	ds_read_b128 v[136:139], v237 offset:2304
	ds_read_b128 v[140:143], v237 offset:3456
	ds_read_b128 v[144:147], v237 offset:4608
	ds_read_b128 v[148:151], v237 offset:5760
	ds_read_b128 v[152:155], v237 offset:6912
	ds_read_b128 v[156:159], v237 offset:8064
	ds_read_b128 v[160:163], v237 offset:9216
	ds_read_b128 v[164:167], v237 offset:10368
	ds_read_b128 v[168:171], v237 offset:11520
	ds_read_b128 v[172:175], v237 offset:12672
	ds_read_b128 v[176:179], v237 offset:13824
	ds_read_b128 v[180:183], v237 offset:14976
	ds_read_b128 v[184:187], v237 offset:16128
	ds_read_b128 v[188:191], v237 offset:17280
	s_waitcnt lgkmcnt(15)
	global_store_dwordx4 v238, v[128:131], s[4:5] nt
	s_add_u32 s4, s4, 0x2000
	s_addc_u32 s5, s5, 0
	s_waitcnt lgkmcnt(14)
	global_store_dwordx4 v238, v[132:135], s[4:5] nt
	s_add_u32 s4, s4, 0x2000
	s_addc_u32 s5, s5, 0
	s_waitcnt lgkmcnt(13)
	global_store_dwordx4 v238, v[136:139], s[4:5] nt
	s_add_u32 s4, s4, 0x2000
	s_addc_u32 s5, s5, 0
	s_waitcnt lgkmcnt(12)
	global_store_dwordx4 v238, v[140:143], s[4:5] nt
	s_add_u32 s4, s4, 0x2000
	s_addc_u32 s5, s5, 0
	s_waitcnt lgkmcnt(11)
	global_store_dwordx4 v238, v[144:147], s[4:5] nt
	s_add_u32 s4, s4, 0x2000
	s_addc_u32 s5, s5, 0
	s_waitcnt lgkmcnt(10)
	global_store_dwordx4 v238, v[148:151], s[4:5] nt
	s_add_u32 s4, s4, 0x2000
	s_addc_u32 s5, s5, 0
	s_waitcnt lgkmcnt(9)
	global_store_dwordx4 v238, v[152:155], s[4:5] nt
	s_add_u32 s4, s4, 0x2000
	s_addc_u32 s5, s5, 0
	s_waitcnt lgkmcnt(8)
	global_store_dwordx4 v238, v[156:159], s[4:5] nt
	s_add_u32 s4, s4, 0x2000
	s_addc_u32 s5, s5, 0
	s_waitcnt lgkmcnt(7)
	global_store_dwordx4 v238, v[160:163], s[4:5] nt
	s_add_u32 s4, s4, 0x2000
	s_addc_u32 s5, s5, 0
	s_waitcnt lgkmcnt(6)
	global_store_dwordx4 v238, v[164:167], s[4:5] nt
	s_add_u32 s4, s4, 0x2000
	s_addc_u32 s5, s5, 0
	s_waitcnt lgkmcnt(5)
	global_store_dwordx4 v238, v[168:171], s[4:5] nt
	s_add_u32 s4, s4, 0x2000
	s_addc_u32 s5, s5, 0
	s_waitcnt lgkmcnt(4)
	global_store_dwordx4 v238, v[172:175], s[4:5] nt
	s_add_u32 s4, s4, 0x2000
	s_addc_u32 s5, s5, 0
	s_waitcnt lgkmcnt(3)
	global_store_dwordx4 v238, v[176:179], s[4:5] nt
	s_add_u32 s4, s4, 0x2000
	s_addc_u32 s5, s5, 0
	s_waitcnt lgkmcnt(2)
	global_store_dwordx4 v238, v[180:183], s[4:5] nt
	s_add_u32 s4, s4, 0x2000
	s_addc_u32 s5, s5, 0
	s_waitcnt lgkmcnt(1)
	global_store_dwordx4 v238, v[184:187], s[4:5] nt
	s_add_u32 s4, s4, 0x2000
	s_addc_u32 s5, s5, 0
	s_waitcnt lgkmcnt(0)
	global_store_dwordx4 v238, v[188:191], s[4:5] nt
	s_nop 1
	s_branch .Lg11_enext

; #define PH(k) case k: if (ONLY_PHASE >= 0 && ONLY_PHASE != k) break;
; template <class Epi>
; DI void gemm_tile(char* smem, const bf16_t* __restrict__ A0, int lda0, int ksplit, const bf16_t* __restrict__ A1, int lda1,
;                   const bf16_t* __restrict__ Bt, int K, int row0, int col0, const Epi& epi, int tid) {
;   constexpr int BK = 32, PITCH = 40, BUF = (256 + 128) * PITCH;
;   bf16_t* sbase = (bf16_t*)smem;
;   const int lane = tid & 63, wid = tid >> 6, wr = wid >> 1, wc = wid & 1, fr = lane & 15, fq = lane >> 4;
;   f32x4 acc[8][4];
; #pragma unroll
;   for (int m = 0; m < 8; ++m)
; #pragma unroll
;     for (int n = 0; n < 4; ++n) acc[m][n] = (f32x4){0.f, 0.f, 0.f, 0.f};
;   u32x4 ra[2][4], rb[2][2];
;   const int nk = K / BK;
;   const int sr = tid >> 2, scv = tid & 3;
; template <int ph> DI void run_phase(const Ctx& c, char* smem) {
;     ...
;     PH(14) gemm_phase(smem, (const bf16_t*)(ws + OFF_YG), 512, 1 << 30, XN, 1024, (const bf16_t*)(ws + OFF_WGLU), 512, 4,
;                         EpiGlu{(const bf16_t*)(ws + OFF_YG), p.s5_glu_b, (bf16_t*)(ws + OFF_S5Y)}, TIDX); break;
.LBB0_1816:
	s_cmp_gt_i32 s94, 14
	s_cselect_b64 s[0:1], -1, 0
	s_cmp_lt_i32 s95, 15
	s_cselect_b64 s[2:3], -1, 0
	s_or_b64 s[0:1], s[0:1], s[2:3]
	v_readlane_b32 s36, v252, 8
	s_and_b64 vcc, exec, s[0:1]
	v_readlane_b32 s40, v252, 12
	v_readlane_b32 s41, v252, 13
	v_readlane_b32 s42, v252, 14
	v_readlane_b32 s43, v252, 15
	v_readlane_b32 s37, v252, 9
	v_readlane_b32 s38, v252, 10
	v_readlane_b32 s39, v252, 11
	v_readlane_b32 s44, v252, 16
	v_readlane_b32 s45, v252, 17
	v_readlane_b32 s46, v252, 18
	v_readlane_b32 s47, v252, 19
	v_readlane_b32 s48, v252, 20
	v_readlane_b32 s49, v252, 21
	v_readlane_b32 s50, v252, 22
	v_readlane_b32 s51, v252, 23
	s_cbranch_vccnz .LBB0_1844
	s_add_u32 s2, s92, 0x1da00000
	s_waitcnt lgkmcnt(0)
	s_load_dword s14, s[74:75], 0x180
	s_addc_u32 s3, s93, 0
	s_add_u32 s0, s92, 0x3400000
	s_addc_u32 s1, s93, 0
	s_add_u32 s4, s92, 0x11a00000
	s_addc_u32 s5, s93, 0
	s_and_b32 s16, s72, 0xffffffc0
	v_mbcnt_hi_u32_b32 v195, -1, v194
	s_waitcnt lgkmcnt(0)
	s_and_b32 s15, s14, 7
	s_cmp_lg_u32 s15, 0
	s_waitcnt vmcnt(16)
	v_add_u32_e32 v196, s16, v195
	v_mbcnt_lo_u32_b32 v240, -1, 0
	v_mbcnt_hi_u32_b32 v240, -1, v240
	s_lshr_b32 s12, s72, 6
	s_lshl_b32 s101, s12, 10
	v_and_b32_e32 v241, 15, v240
	v_lshrrev_b32_e32 v242, 4, v240
	v_bfe_u32 v243, v240, 3, 1
	v_mul_u32_u24_e32 v243, 3, v243
	v_xor_b32_e32 v243, v242, v243
	v_lshlrev_b32_e32 v243, 4, v243
	v_lshl_add_u32 v243, v241, 6, v243
	s_lshr_b32 s11, s12, 1
	s_lshl_b32 s11, s11, 13
	v_add_u32_e32 v230, s11, v243
	s_and_b32 s11, s12, 1
	s_lshl_b32 s11, s11, 12
	s_add_u32 s11, s11, 16384
	v_add_u32_e32 v231, s11, v243
	s_lshr_b32 s11, s12, 1
	s_lshl_b32 s11, s11, 7
	v_add_u32_e32 v244, s11, v241
	s_and_b32 s11, s12, 1
	s_lshl_b32 s11, s11, 6
	v_lshl_add_u32 v245, v242, 2, s11
	s_movk_i32 s11, 0x1000
	v_mul_lo_u32 v246, v244, s11
	v_lshl_add_u32 v234, v245, 2, v246
	v_lshrrev_b32_e32 v241, 2, v240
	s_lshl_b32 s11, s12, 4
	v_add_u32_e32 v241, s11, v241
	v_bfe_u32 v242, v240, 5, 1
	v_mul_u32_u24_e32 v242, 3, v242
	v_and_b32_e32 v243, 3, v240
	v_xor_b32_e32 v243, v243, v242
	v_lshlrev_b32_e32 v243, 4, v243
	s_mov_b32 s11, 1024
	v_mad_u32_u24 v224, v241, s11, v243
	v_add_u32_e32 v225, 0x10000, v224
	v_add_u32_e32 v226, 0x20000, v224
	v_add_u32_e32 v227, 0x30000, v224
	s_mov_b32 s11, 1024
	v_mad_u32_u24 v228, v241, s11, v243
	v_add_u32_e32 v229, 0x10000, v228
	s_load_dwordx2 s[6:7], s[74:75], 0x118
	v_mbcnt_lo_u32_b32 v240, -1, 0
	v_mbcnt_hi_u32_b32 v240, -1, v240
	s_lshr_b32 s12, s72, 6
	s_mul_i32 s11, s12, 17408
	v_and_b32_e32 v241, 15, v240
	v_lshrrev_b32_e32 v242, 4, v240
	v_mul_u32_u24_e32 v243, 0x110, v241
	v_lshl_add_u32 v243, v242, 4, v243
	v_add_u32_e32 v245, s11, v243
	v_mul_u32_u24_e32 v243, 0x110, v242
	v_lshl_add_u32 v243, v241, 4, v243
	v_add_u32_e32 v246, s11, v243
	s_lshr_b32 s11, s12, 1
	s_lshl_b32 s11, s11, 7
	v_add_u32_e32 v243, s11, v242
	v_lshlrev_b32_e32 v243, 12, v243
	s_and_b32 s11, s12, 1
	s_lshl_b32 s11, s11, 8
	v_lshl_add_u32 v244, v241, 4, s11
	v_add_u32_e32 v247, v243, v244
	v_lshrrev_b32_e32 v243, 2, v243
	v_lshrrev_b32_e32 v235, 1, v244
	v_add_u32_e32 v235, v243, v235
	v_mov_b32_e32 v234, v244
	s_cmpk_gt_u32 s96, 0xff
	s_cselect_b32 s10, 1, 0
	s_cmpk_gt_u32 s96, 0xff
	s_cbranch_scc0 .Lg14_prio
	s_setprio 1

; #define LWRITE(S, buf) do { bf16_t* sA_ = sbase + (buf) * BUF; bf16_t* sB_ = sA_ + 256 * PITCH; \
;     _Pragma("unroll") for (int i_ = 0; i_ < 4; ++i_) *(u32x4*)(sA_ + (sr + i_ * 64) * PITCH + scv * 8) = ra[S][i_]; \
;     _Pragma("unroll") for (int i_ = 0; i_ < 2; ++i_) *(u32x4*)(sB_ + (sr + i_ * 64) * PITCH + scv * 8) = rb[S][i_]; } while (0)
; template <class Epi>
; DI void gemm_tile(char* smem, const bf16_t* __restrict__ A0, int lda0, int ksplit, const bf16_t* __restrict__ A1, int lda1,
;                   const bf16_t* __restrict__ Bt, int K, int row0, int col0, const Epi& epi, int tid) {
;     ...
;     for (int kt = 0; kt < nk; kt += 2) {
;       LWRITE(1, 1);
;       __builtin_amdgcn_sched_barrier(0);
;       GLOAD(1, (kt + 3 < last ? kt + 3 : last));
;       __builtin_amdgcn_sched_barrier(0);
;       COMPUTE(0);
;       __syncthreads();
;       LWRITE(0, 0);
;       __builtin_amdgcn_sched_barrier(0);
;       GLOAD(0, (kt + 4 < last ? kt + 4 : last));
;       __builtin_amdgcn_sched_barrier(0);
;       COMPUTE(1);
;       __syncthreads();
;     }
.Lg14_hi1:
	s_add_u32 s99, s99, 2
	s_cmp_lt_u32 s99, 12
	s_cbranch_scc1 .Lg14_kloop
	s_waitcnt vmcnt(6)
	s_waitcnt lgkmcnt(0)
	s_barrier
	v_add_u32_e32 v232, s98, v230
	v_add_u32_e32 v233, s98, v231
	s_add_u32 s11, s19, s101
	s_setprio 1
	v_mfma_f32_16x16x32_bf16 v[0:3], v[128:131], v[144:147], v[0:3]
	v_mfma_f32_16x16x32_bf16 v[4:7], v[132:135], v[144:147], v[4:7]
	v_mfma_f32_16x16x32_bf16 v[8:11], v[136:139], v[144:147], v[8:11]
	v_mfma_f32_16x16x32_bf16 v[12:15], v[140:143], v[144:147], v[12:15]
	ds_read_b128 v[176:179], v233 offset:0
	ds_read_b128 v[180:183], v233 offset:1024
	s_add_u32 m0, s11, 0
	s_nop 0
	global_load_lds_dwordx4 v224, s[0:1]
	v_mfma_f32_16x16x32_bf16 v[16:19], v[128:131], v[148:151], v[16:19]
	v_mfma_f32_16x16x32_bf16 v[20:23], v[132:135], v[148:151], v[20:23]
	v_mfma_f32_16x16x32_bf16 v[24:27], v[136:139], v[148:151], v[24:27]
	v_mfma_f32_16x16x32_bf16 v[28:31], v[140:143], v[148:151], v[28:31]
	ds_read_b128 v[184:187], v233 offset:2048
	ds_read_b128 v[188:191], v233 offset:3072
	s_add_u32 m0, s11, 4096
	s_nop 0
	global_load_lds_dwordx4 v225, s[0:1]
	v_mfma_f32_16x16x32_bf16 v[32:35], v[128:131], v[152:155], v[32:35]
	v_mfma_f32_16x16x32_bf16 v[36:39], v[132:135], v[152:155], v[36:39]
	v_mfma_f32_16x16x32_bf16 v[40:43], v[136:139], v[152:155], v[40:43]
	v_mfma_f32_16x16x32_bf16 v[44:47], v[140:143], v[152:155], v[44:47]
	ds_read_b128 v[192:195], v232 offset:0
	ds_read_b128 v[196:199], v232 offset:1024
	s_add_u32 m0, s11, 8192
	s_nop 0
	global_load_lds_dwordx4 v226, s[0:1]
	v_mfma_f32_16x16x32_bf16 v[48:51], v[128:131], v[156:159], v[48:51]
	v_mfma_f32_16x16x32_bf16 v[52:55], v[132:135], v[156:159], v[52:55]
	v_mfma_f32_16x16x32_bf16 v[56:59], v[136:139], v[156:159], v[56:59]
	v_mfma_f32_16x16x32_bf16 v[60:63], v[140:143], v[156:159], v[60:63]
	ds_read_b128 v[200:203], v232 offset:2048
	ds_read_b128 v[204:207], v232 offset:3072
	s_add_u32 m0, s11, 12288
	s_nop 0
	global_load_lds_dwordx4 v227, s[0:1]
	v_mfma_f32_16x16x32_bf16 v[64:67], v[128:131], v[160:163], v[64:67]
	v_mfma_f32_16x16x32_bf16 v[68:71], v[132:135], v[160:163], v[68:71]
	v_mfma_f32_16x16x32_bf16 v[72:75], v[136:139], v[160:163], v[72:75]
	v_mfma_f32_16x16x32_bf16 v[76:79], v[140:143], v[160:163], v[76:79]
	ds_read_b128 v[208:211], v232 offset:4096
	s_add_u32 m0, s11, 16384
	s_nop 0
	global_load_lds_dwordx4 v228, s[2:3]
	v_mfma_f32_16x16x32_bf16 v[80:83], v[128:131], v[164:167], v[80:83]
	v_mfma_f32_16x16x32_bf16 v[84:87], v[132:135], v[164:167], v[84:87]
	v_mfma_f32_16x16x32_bf16 v[88:91], v[136:139], v[164:167], v[88:91]
	v_mfma_f32_16x16x32_bf16 v[92:95], v[140:143], v[164:167], v[92:95]
	ds_read_b128 v[212:215], v232 offset:5120
	s_add_u32 m0, s11, 20480
	s_nop 0
	global_load_lds_dwordx4 v229, s[2:3]
	v_mfma_f32_16x16x32_bf16 v[96:99], v[128:131], v[168:171], v[96:99]
	v_mfma_f32_16x16x32_bf16 v[100:103], v[132:135], v[168:171], v[100:103]
	v_mfma_f32_16x16x32_bf16 v[104:107], v[136:139], v[168:171], v[104:107]
	v_mfma_f32_16x16x32_bf16 v[108:111], v[140:143], v[168:171], v[108:111]
	ds_read_b128 v[216:219], v232 offset:6144
	s_add_u32 s0, s0, 64
	s_addc_u32 s1, s1, 0
	s_add_u32 s2, s2, 64
	s_addc_u32 s3, s3, 0
	s_add_u32 s100, s100, 1
	s_add_u32 s19, s19, 24576
	s_cmp_eq_u32 s19, 73728
	s_cselect_b32 s19, 0, s19
	s_add_u32 s98, s98, 24576
	s_cmp_eq_u32 s98, 73728
	s_cselect_b32 s98, 0, s98
	v_mfma_f32_16x16x32_bf16 v[112:115], v[128:131], v[172:175], v[112:115]
	v_mfma_f32_16x16x32_bf16 v[116:119], v[132:135], v[172:175], v[116:119]
	v_mfma_f32_16x16x32_bf16 v[120:123], v[136:139], v[172:175], v[120:123]
	v_mfma_f32_16x16x32_bf16 v[124:127], v[140:143], v[172:175], v[124:127]
	ds_read_b128 v[220:223], v232 offset:7168
	s_cmp_eq_u32 s10, 0
	s_cbranch_scc0 .Lg14_hi2
	s_setprio 0

.Lg14_hi5:
	s_branch .Lg14_epi
.Lg14_epi:
	s_nop 7
	s_nop 7
	s_lshl_b32 s12, s18, 10
	s_lshl_b32 s11, s13, 1
	s_add_u32 s12, s12, s11
	s_add_u32 s12, s12, 0x11a00000
	s_add_u32 s4, s92, s12
	s_addc_u32 s5, s93, 0
	s_lshl_b32 s12, s18, 10
	s_lshl_b32 s11, s13, 1
	s_add_u32 s12, s12, s11
	s_add_u32 s12, s12, 0x1da00000
	s_add_u32 s0, s92, s12
	s_addc_u32 s1, s93, 0
	s_lshl_b32 s12, s13, 2
	s_add_u32 s2, s6, s12
	s_addc_u32 s3, s7, 0
	global_load_dwordx4 v[192:195], v234, s[2:3]
	ds_write_b128 v245, v[0:3]
	ds_write_b128 v245, v[4:7] offset:64
	ds_write_b128 v245, v[8:11] offset:128
	ds_write_b128 v245, v[12:15] offset:192
	ds_write_b128 v245, v[16:19] offset:4352
	ds_write_b128 v245, v[20:23] offset:4416
	ds_write_b128 v245, v[24:27] offset:4480
	ds_write_b128 v245, v[28:31] offset:4544
	ds_write_b128 v245, v[32:35] offset:8704
	ds_write_b128 v245, v[36:39] offset:8768
	ds_write_b128 v245, v[40:43] offset:8832
	ds_write_b128 v245, v[44:47] offset:8896
	ds_write_b128 v245, v[48:51] offset:13056
	ds_write_b128 v245, v[52:55] offset:13120
	ds_write_b128 v245, v[56:59] offset:13184
	ds_write_b128 v245, v[60:63] offset:13248
	global_load_dwordx2 v[128:129], v235, s[0:1]
	s_add_u32 s0, s0, 0x1000
	s_addc_u32 s1, s1, 0
	global_load_dwordx2 v[130:131], v235, s[0:1]
	s_add_u32 s0, s0, 0x1000
	s_addc_u32 s1, s1, 0
	global_load_dwordx2 v[132:133], v235, s[0:1]
	s_add_u32 s0, s0, 0x1000
	s_addc_u32 s1, s1, 0
	global_load_dwordx2 v[134:135], v235, s[0:1]
	s_add_u32 s0, s0, 0x1000
	s_addc_u32 s1, s1, 0
	global_load_dwordx2 v[136:137], v235, s[0:1]
	s_add_u32 s0, s0, 0x1000
	s_addc_u32 s1, s1, 0
	global_load_dwordx2 v[138:139], v235, s[0:1]
	s_add_u32 s0, s0, 0x1000
	s_addc_u32 s1, s1, 0
	global_load_dwordx2 v[140:141], v235, s[0:1]
	s_add_u32 s0, s0, 0x1000
	s_addc_u32 s1, s1, 0
	global_load_dwordx2 v[142:143], v235, s[0:1]
	s_add_u32 s0, s0, 0x1000
	s_addc_u32 s1, s1, 0
	s_waitcnt lgkmcnt(0)
	ds_read_b128 v[160:163], v246
	ds_read_b128 v[164:167], v246 offset:1088
	ds_read_b128 v[168:171], v246 offset:2176
	ds_read_b128 v[172:175], v246 offset:3264
	ds_read_b128 v[176:179], v246 offset:4352
	ds_read_b128 v[180:183], v246 offset:5440
	ds_read_b128 v[184:187], v246 offset:6528
	ds_read_b128 v[188:191], v246 offset:7616
	s_waitcnt vmcnt(7) lgkmcnt(7)
	v_add_f32_e32 v160, v160, v192
	v_add_f32_e32 v161, v161, v193
	v_add_f32_e32 v162, v162, v194
	v_add_f32_e32 v163, v163, v195
	v_mul_f32_e32 v160, 0xbfb8aa3b, v160
	v_mul_f32_e32 v161, 0xbfb8aa3b, v161
	v_mul_f32_e32 v162, 0xbfb8aa3b, v162
	v_mul_f32_e32 v163, 0xbfb8aa3b, v163
	v_exp_f32_e32 v160, v160
	v_exp_f32_e32 v161, v161
	v_exp_f32_e32 v162, v162
	v_exp_f32_e32 v163, v163
	v_lshlrev_b32_e32 v144, 16, v128
	v_and_b32_e32 v145, 0xffff0000, v128
	v_lshlrev_b32_e32 v146, 16, v129
	v_and_b32_e32 v147, 0xffff0000, v129
	v_add_f32_e32 v160, 1.0, v160
	v_add_f32_e32 v161, 1.0, v161
	v_add_f32_e32 v162, 1.0, v162
	v_add_f32_e32 v163, 1.0, v163
	v_rcp_f32_e32 v160, v160
	v_rcp_f32_e32 v161, v161
	v_rcp_f32_e32 v162, v162
	v_rcp_f32_e32 v163, v163
	s_nop 0
	v_mul_f32_e32 v160, v144, v160
	v_mul_f32_e32 v161, v145, v161
	v_mul_f32_e32 v162, v146, v162
	v_mul_f32_e32 v163, v147, v163
	v_cvt_pk_bf16_f32 v128, v160, v161
	v_cvt_pk_bf16_f32 v129, v162, v163
	global_store_dwordx2 v235, v[128:129], s[4:5]
	s_add_u32 s4, s4, 0x1000
	s_addc_u32 s5, s5, 0
	s_waitcnt vmcnt(7) lgkmcnt(6)
	v_add_f32_e32 v164, v164, v192
	v_add_f32_e32 v165, v165, v193
	v_add_f32_e32 v166, v166, v194
	v_add_f32_e32 v167, v167, v195
	v_mul_f32_e32 v164, 0xbfb8aa3b, v164
	v_mul_f32_e32 v165, 0xbfb8aa3b, v165
	v_mul_f32_e32 v166, 0xbfb8aa3b, v166
	v_mul_f32_e32 v167, 0xbfb8aa3b, v167
	v_exp_f32_e32 v164, v164
	v_exp_f32_e32 v165, v165
	v_exp_f32_e32 v166, v166
	v_exp_f32_e32 v167, v167
	v_lshlrev_b32_e32 v148, 16, v130
	v_and_b32_e32 v149, 0xffff0000, v130
	v_lshlrev_b32_e32 v150, 16, v131
	v_and_b32_e32 v151, 0xffff0000, v131
	v_add_f32_e32 v164, 1.0, v164
	v_add_f32_e32 v165, 1.0, v165
	v_add_f32_e32 v166, 1.0, v166
	v_add_f32_e32 v167, 1.0, v167
	v_rcp_f32_e32 v164, v164
	v_rcp_f32_e32 v165, v165
	v_rcp_f32_e32 v166, v166
	v_rcp_f32_e32 v167, v167
	s_nop 0
	v_mul_f32_e32 v164, v148, v164
	v_mul_f32_e32 v165, v149, v165
	v_mul_f32_e32 v166, v150, v166
	v_mul_f32_e32 v167, v151, v167
	v_cvt_pk_bf16_f32 v130, v164, v165
	v_cvt_pk_bf16_f32 v131, v166, v167
	global_store_dwordx2 v235, v[130:131], s[4:5]
	s_add_u32 s4, s4, 0x1000
	s_addc_u32 s5, s5, 0
	s_waitcnt vmcnt(7) lgkmcnt(5)
	v_add_f32_e32 v168, v168, v192
	v_add_f32_e32 v169, v169, v193
	v_add_f32_e32 v170, v170, v194
	v_add_f32_e32 v171, v171, v195
	v_mul_f32_e32 v168, 0xbfb8aa3b, v168
	v_mul_f32_e32 v169, 0xbfb8aa3b, v169
	v_mul_f32_e32 v170, 0xbfb8aa3b, v170
	v_mul_f32_e32 v171, 0xbfb8aa3b, v171
	v_exp_f32_e32 v168, v168
	v_exp_f32_e32 v169, v169
	v_exp_f32_e32 v170, v170
	v_exp_f32_e32 v171, v171
	v_lshlrev_b32_e32 v144, 16, v132
	v_and_b32_e32 v145, 0xffff0000, v132
	v_lshlrev_b32_e32 v146, 16, v133
	v_and_b32_e32 v147, 0xffff0000, v133
	v_add_f32_e32 v168, 1.0, v168
	v_add_f32_e32 v169, 1.0, v169
	v_add_f32_e32 v170, 1.0, v170
	v_add_f32_e32 v171, 1.0, v171
	v_rcp_f32_e32 v168, v168
	v_rcp_f32_e32 v169, v169
	v_rcp_f32_e32 v170, v170
	v_rcp_f32_e32 v171, v171
	s_nop 0
	v_mul_f32_e32 v168, v144, v168
	v_mul_f32_e32 v169, v145, v169
	v_mul_f32_e32 v170, v146, v170
	v_mul_f32_e32 v171, v147, v171
	v_cvt_pk_bf16_f32 v132, v168, v169
	v_cvt_pk_bf16_f32 v133, v170, v171
	global_store_dwordx2 v235, v[132:133], s[4:5]
	s_add_u32 s4, s4, 0x1000
	s_addc_u32 s5, s5, 0
	s_waitcnt vmcnt(7) lgkmcnt(4)
	v_add_f32_e32 v172, v172, v192
	v_add_f32_e32 v173, v173, v193
	v_add_f32_e32 v174, v174, v194
	v_add_f32_e32 v175, v175, v195
	v_mul_f32_e32 v172, 0xbfb8aa3b, v172
	v_mul_f32_e32 v173, 0xbfb8aa3b, v173
	v_mul_f32_e32 v174, 0xbfb8aa3b, v174
	v_mul_f32_e32 v175, 0xbfb8aa3b, v175
	v_exp_f32_e32 v172, v172
	v_exp_f32_e32 v173, v173
	v_exp_f32_e32 v174, v174
	v_exp_f32_e32 v175, v175
	v_lshlrev_b32_e32 v148, 16, v134
	v_and_b32_e32 v149, 0xffff0000, v134
	v_lshlrev_b32_e32 v150, 16, v135
	v_and_b32_e32 v151, 0xffff0000, v135
	v_add_f32_e32 v172, 1.0, v172
	v_add_f32_e32 v173, 1.0, v173
	v_add_f32_e32 v174, 1.0, v174
	v_add_f32_e32 v175, 1.0, v175
	v_rcp_f32_e32 v172, v172
	v_rcp_f32_e32 v173, v173
	v_rcp_f32_e32 v174, v174
	v_rcp_f32_e32 v175, v175
	s_nop 0
	v_mul_f32_e32 v172, v148, v172
	v_mul_f32_e32 v173, v149, v173
	v_mul_f32_e32 v174, v150, v174
	v_mul_f32_e32 v175, v151, v175
	v_cvt_pk_bf16_f32 v134, v172, v173
	v_cvt_pk_bf16_f32 v135, v174, v175
	global_store_dwordx2 v235, v[134:135], s[4:5]
	s_add_u32 s4, s4, 0x1000
	s_addc_u32 s5, s5, 0
	s_waitcnt vmcnt(7) lgkmcnt(3)
	v_add_f32_e32 v176, v176, v192
	v_add_f32_e32 v177, v177, v193
	v_add_f32_e32 v178, v178, v194
	v_add_f32_e32 v179, v179, v195
	v_mul_f32_e32 v176, 0xbfb8aa3b, v176
	v_mul_f32_e32 v177, 0xbfb8aa3b, v177
	v_mul_f32_e32 v178, 0xbfb8aa3b, v178
	v_mul_f32_e32 v179, 0xbfb8aa3b, v179
	v_exp_f32_e32 v176, v176
	v_exp_f32_e32 v177, v177
	v_exp_f32_e32 v178, v178
	v_exp_f32_e32 v179, v179
	v_lshlrev_b32_e32 v144, 16, v136
	v_and_b32_e32 v145, 0xffff0000, v136
	v_lshlrev_b32_e32 v146, 16, v137
	v_and_b32_e32 v147, 0xffff0000, v137
	v_add_f32_e32 v176, 1.0, v176
	v_add_f32_e32 v177, 1.0, v177
	v_add_f32_e32 v178, 1.0, v178
	v_add_f32_e32 v179, 1.0, v179
	v_rcp_f32_e32 v176, v176
	v_rcp_f32_e32 v177, v177
	v_rcp_f32_e32 v178, v178
	v_rcp_f32_e32 v179, v179
	s_nop 0
	v_mul_f32_e32 v176, v144, v176
	v_mul_f32_e32 v177, v145, v177
	v_mul_f32_e32 v178, v146, v178
	v_mul_f32_e32 v179, v147, v179
	v_cvt_pk_bf16_f32 v136, v176, v177
	v_cvt_pk_bf16_f32 v137, v178, v179
	global_store_dwordx2 v235, v[136:137], s[4:5]
	s_add_u32 s4, s4, 0x1000
	s_addc_u32 s5, s5, 0
	s_waitcnt vmcnt(7) lgkmcnt(2)
	v_add_f32_e32 v180, v180, v192
	v_add_f32_e32 v181, v181, v193
	v_add_f32_e32 v182, v182, v194
	v_add_f32_e32 v183, v183, v195
	v_mul_f32_e32 v180, 0xbfb8aa3b, v180
	v_mul_f32_e32 v181, 0xbfb8aa3b, v181
	v_mul_f32_e32 v182, 0xbfb8aa3b, v182
	v_mul_f32_e32 v183, 0xbfb8aa3b, v183
	v_exp_f32_e32 v180, v180
	v_exp_f32_e32 v181, v181
	v_exp_f32_e32 v182, v182
	v_exp_f32_e32 v183, v183
	v_lshlrev_b32_e32 v148, 16, v138
	v_and_b32_e32 v149, 0xffff0000, v138
	v_lshlrev_b32_e32 v150, 16, v139
	v_and_b32_e32 v151, 0xffff0000, v139
	v_add_f32_e32 v180, 1.0, v180
	v_add_f32_e32 v181, 1.0, v181
	v_add_f32_e32 v182, 1.0, v182
	v_add_f32_e32 v183, 1.0, v183
	v_rcp_f32_e32 v180, v180
	v_rcp_f32_e32 v181, v181
	v_rcp_f32_e32 v182, v182
	v_rcp_f32_e32 v183, v183
	s_nop 0
	v_mul_f32_e32 v180, v148, v180
	v_mul_f32_e32 v181, v149, v181
	v_mul_f32_e32 v182, v150, v182
	v_mul_f32_e32 v183, v151, v183
	v_cvt_pk_bf16_f32 v138, v180, v181
	v_cvt_pk_bf16_f32 v139, v182, v183
	global_store_dwordx2 v235, v[138:139], s[4:5]
	s_add_u32 s4, s4, 0x1000
	s_addc_u32 s5, s5, 0
	s_waitcnt vmcnt(7) lgkmcnt(1)
	v_add_f32_e32 v184, v184, v192
	v_add_f32_e32 v185, v185, v193
	v_add_f32_e32 v186, v186, v194
	v_add_f32_e32 v187, v187, v195
	v_mul_f32_e32 v184, 0xbfb8aa3b, v184
	v_mul_f32_e32 v185, 0xbfb8aa3b, v185
	v_mul_f32_e32 v186, 0xbfb8aa3b, v186
	v_mul_f32_e32 v187, 0xbfb8aa3b, v187
	v_exp_f32_e32 v184, v184
	v_exp_f32_e32 v185, v185
	v_exp_f32_e32 v186, v186
	v_exp_f32_e32 v187, v187
	v_lshlrev_b32_e32 v144, 16, v140
	v_and_b32_e32 v145, 0xffff0000, v140
	v_lshlrev_b32_e32 v146, 16, v141
	v_and_b32_e32 v147, 0xffff0000, v141
	v_add_f32_e32 v184, 1.0, v184
	v_add_f32_e32 v185, 1.0, v185
	v_add_f32_e32 v186, 1.0, v186
	v_add_f32_e32 v187, 1.0, v187
	v_rcp_f32_e32 v184, v184
	v_rcp_f32_e32 v185, v185
	v_rcp_f32_e32 v186, v186
	v_rcp_f32_e32 v187, v187
	s_nop 0
	v_mul_f32_e32 v184, v144, v184
	v_mul_f32_e32 v185, v145, v185
	v_mul_f32_e32 v186, v146, v186
	v_mul_f32_e32 v187, v147, v187
	v_cvt_pk_bf16_f32 v140, v184, v185
	v_cvt_pk_bf16_f32 v141, v186, v187
	global_store_dwordx2 v235, v[140:141], s[4:5]
	s_add_u32 s4, s4, 0x1000
	s_addc_u32 s5, s5, 0
	s_waitcnt vmcnt(7) lgkmcnt(0)
	v_add_f32_e32 v188, v188, v192
	v_add_f32_e32 v189, v189, v193
	v_add_f32_e32 v190, v190, v194
	v_add_f32_e32 v191, v191, v195
	v_mul_f32_e32 v188, 0xbfb8aa3b, v188
	v_mul_f32_e32 v189, 0xbfb8aa3b, v189
	v_mul_f32_e32 v190, 0xbfb8aa3b, v190
	v_mul_f32_e32 v191, 0xbfb8aa3b, v191
	v_exp_f32_e32 v188, v188
	v_exp_f32_e32 v189, v189
	v_exp_f32_e32 v190, v190
	v_exp_f32_e32 v191, v191
	v_lshlrev_b32_e32 v148, 16, v142
	v_and_b32_e32 v149, 0xffff0000, v142
	v_lshlrev_b32_e32 v150, 16, v143
	v_and_b32_e32 v151, 0xffff0000, v143
	v_add_f32_e32 v188, 1.0, v188
	v_add_f32_e32 v189, 1.0, v189
	v_add_f32_e32 v190, 1.0, v190
	v_add_f32_e32 v191, 1.0, v191
	v_rcp_f32_e32 v188, v188
	v_rcp_f32_e32 v189, v189
	v_rcp_f32_e32 v190, v190
	v_rcp_f32_e32 v191, v191
	s_nop 0
	v_mul_f32_e32 v188, v148, v188
	v_mul_f32_e32 v189, v149, v189
	v_mul_f32_e32 v190, v150, v190
	v_mul_f32_e32 v191, v151, v191
	v_cvt_pk_bf16_f32 v142, v188, v189
	v_cvt_pk_bf16_f32 v143, v190, v191
	global_store_dwordx2 v235, v[142:143], s[4:5]
	s_add_u32 s4, s4, 0x1000
	s_addc_u32 s5, s5, 0
	s_nop 1
	global_load_dwordx2 v[128:129], v235, s[0:1]
	s_add_u32 s0, s0, 0x1000
	s_addc_u32 s1, s1, 0
	global_load_dwordx2 v[130:131], v235, s[0:1]
	s_add_u32 s0, s0, 0x1000
	s_addc_u32 s1, s1, 0
	global_load_dwordx2 v[132:133], v235, s[0:1]
	s_add_u32 s0, s0, 0x1000
	s_addc_u32 s1, s1, 0
	global_load_dwordx2 v[134:135], v235, s[0:1]
	s_add_u32 s0, s0, 0x1000
	s_addc_u32 s1, s1, 0
	global_load_dwordx2 v[136:137], v235, s[0:1]
	s_add_u32 s0, s0, 0x1000
	s_addc_u32 s1, s1, 0
	global_load_dwordx2 v[138:139], v235, s[0:1]
	s_add_u32 s0, s0, 0x1000
	s_addc_u32 s1, s1, 0
	global_load_dwordx2 v[140:141], v235, s[0:1]
	s_add_u32 s0, s0, 0x1000
	s_addc_u32 s1, s1, 0
	global_load_dwordx2 v[142:143], v235, s[0:1]
	s_add_u32 s0, s0, 0x1000
	s_addc_u32 s1, s1, 0
	ds_read_b128 v[160:163], v246 offset:8704
	ds_read_b128 v[164:167], v246 offset:9792
	ds_read_b128 v[168:171], v246 offset:10880
	ds_read_b128 v[172:175], v246 offset:11968
	ds_read_b128 v[176:179], v246 offset:13056
	ds_read_b128 v[180:183], v246 offset:14144
	ds_read_b128 v[184:187], v246 offset:15232
	ds_read_b128 v[188:191], v246 offset:16320
	s_waitcnt vmcnt(7) lgkmcnt(7)
	v_add_f32_e32 v160, v160, v192
	v_add_f32_e32 v161, v161, v193
	v_add_f32_e32 v162, v162, v194
	v_add_f32_e32 v163, v163, v195
	v_mul_f32_e32 v160, 0xbfb8aa3b, v160
	v_mul_f32_e32 v161, 0xbfb8aa3b, v161
	v_mul_f32_e32 v162, 0xbfb8aa3b, v162
	v_mul_f32_e32 v163, 0xbfb8aa3b, v163
	v_exp_f32_e32 v160, v160
	v_exp_f32_e32 v161, v161
	v_exp_f32_e32 v162, v162
	v_exp_f32_e32 v163, v163
	v_lshlrev_b32_e32 v144, 16, v128
	v_and_b32_e32 v145, 0xffff0000, v128
	v_lshlrev_b32_e32 v146, 16, v129
	v_and_b32_e32 v147, 0xffff0000, v129
	v_add_f32_e32 v160, 1.0, v160
	v_add_f32_e32 v161, 1.0, v161
	v_add_f32_e32 v162, 1.0, v162
	v_add_f32_e32 v163, 1.0, v163
	v_rcp_f32_e32 v160, v160
	v_rcp_f32_e32 v161, v161
	v_rcp_f32_e32 v162, v162
	v_rcp_f32_e32 v163, v163
	s_nop 0
	v_mul_f32_e32 v160, v144, v160
	v_mul_f32_e32 v161, v145, v161
	v_mul_f32_e32 v162, v146, v162
	v_mul_f32_e32 v163, v147, v163
	v_cvt_pk_bf16_f32 v128, v160, v161
	v_cvt_pk_bf16_f32 v129, v162, v163
	global_store_dwordx2 v235, v[128:129], s[4:5]
	s_add_u32 s4, s4, 0x1000
	s_addc_u32 s5, s5, 0
	s_waitcnt vmcnt(7) lgkmcnt(6)
	v_add_f32_e32 v164, v164, v192
	v_add_f32_e32 v165, v165, v193
	v_add_f32_e32 v166, v166, v194
	v_add_f32_e32 v167, v167, v195
	v_mul_f32_e32 v164, 0xbfb8aa3b, v164
	v_mul_f32_e32 v165, 0xbfb8aa3b, v165
	v_mul_f32_e32 v166, 0xbfb8aa3b, v166
	v_mul_f32_e32 v167, 0xbfb8aa3b, v167
	v_exp_f32_e32 v164, v164
	v_exp_f32_e32 v165, v165
	v_exp_f32_e32 v166, v166
	v_exp_f32_e32 v167, v167
	v_lshlrev_b32_e32 v148, 16, v130
	v_and_b32_e32 v149, 0xffff0000, v130
	v_lshlrev_b32_e32 v150, 16, v131
	v_and_b32_e32 v151, 0xffff0000, v131
	v_add_f32_e32 v164, 1.0, v164
	v_add_f32_e32 v165, 1.0, v165
	v_add_f32_e32 v166, 1.0, v166
	v_add_f32_e32 v167, 1.0, v167
	v_rcp_f32_e32 v164, v164
	v_rcp_f32_e32 v165, v165
	v_rcp_f32_e32 v166, v166
	v_rcp_f32_e32 v167, v167
	s_nop 0
	v_mul_f32_e32 v164, v148, v164
	v_mul_f32_e32 v165, v149, v165
	v_mul_f32_e32 v166, v150, v166
	v_mul_f32_e32 v167, v151, v167
	v_cvt_pk_bf16_f32 v130, v164, v165
	v_cvt_pk_bf16_f32 v131, v166, v167
	global_store_dwordx2 v235, v[130:131], s[4:5]
	s_add_u32 s4, s4, 0x1000
	s_addc_u32 s5, s5, 0
	s_waitcnt vmcnt(7) lgkmcnt(5)
	v_add_f32_e32 v168, v168, v192
	v_add_f32_e32 v169, v169, v193
	v_add_f32_e32 v170, v170, v194
	v_add_f32_e32 v171, v171, v195
	v_mul_f32_e32 v168, 0xbfb8aa3b, v168
	v_mul_f32_e32 v169, 0xbfb8aa3b, v169
	v_mul_f32_e32 v170, 0xbfb8aa3b, v170
	v_mul_f32_e32 v171, 0xbfb8aa3b, v171
	v_exp_f32_e32 v168, v168
	v_exp_f32_e32 v169, v169
	v_exp_f32_e32 v170, v170
	v_exp_f32_e32 v171, v171
	v_lshlrev_b32_e32 v144, 16, v132
	v_and_b32_e32 v145, 0xffff0000, v132
	v_lshlrev_b32_e32 v146, 16, v133
	v_and_b32_e32 v147, 0xffff0000, v133
	v_add_f32_e32 v168, 1.0, v168
	v_add_f32_e32 v169, 1.0, v169
	v_add_f32_e32 v170, 1.0, v170
	v_add_f32_e32 v171, 1.0, v171
	v_rcp_f32_e32 v168, v168
	v_rcp_f32_e32 v169, v169
	v_rcp_f32_e32 v170, v170
	v_rcp_f32_e32 v171, v171
	s_nop 0
	v_mul_f32_e32 v168, v144, v168
	v_mul_f32_e32 v169, v145, v169
	v_mul_f32_e32 v170, v146, v170
	v_mul_f32_e32 v171, v147, v171
	v_cvt_pk_bf16_f32 v132, v168, v169
	v_cvt_pk_bf16_f32 v133, v170, v171
	global_store_dwordx2 v235, v[132:133], s[4:5]
	s_add_u32 s4, s4, 0x1000
	s_addc_u32 s5, s5, 0
	s_waitcnt vmcnt(7) lgkmcnt(4)
	v_add_f32_e32 v172, v172, v192
	v_add_f32_e32 v173, v173, v193
	v_add_f32_e32 v174, v174, v194
	v_add_f32_e32 v175, v175, v195
	v_mul_f32_e32 v172, 0xbfb8aa3b, v172
	v_mul_f32_e32 v173, 0xbfb8aa3b, v173
	v_mul_f32_e32 v174, 0xbfb8aa3b, v174
	v_mul_f32_e32 v175, 0xbfb8aa3b, v175
	v_exp_f32_e32 v172, v172
	v_exp_f32_e32 v173, v173
	v_exp_f32_e32 v174, v174
	v_exp_f32_e32 v175, v175
	v_lshlrev_b32_e32 v148, 16, v134
	v_and_b32_e32 v149, 0xffff0000, v134
	v_lshlrev_b32_e32 v150, 16, v135
	v_and_b32_e32 v151, 0xffff0000, v135
	v_add_f32_e32 v172, 1.0, v172
	v_add_f32_e32 v173, 1.0, v173
	v_add_f32_e32 v174, 1.0, v174
	v_add_f32_e32 v175, 1.0, v175
	v_rcp_f32_e32 v172, v172
	v_rcp_f32_e32 v173, v173
	v_rcp_f32_e32 v174, v174
	v_rcp_f32_e32 v175, v175
	s_nop 0
	v_mul_f32_e32 v172, v148, v172
	v_mul_f32_e32 v173, v149, v173
	v_mul_f32_e32 v174, v150, v174
	v_mul_f32_e32 v175, v151, v175
	v_cvt_pk_bf16_f32 v134, v172, v173
	v_cvt_pk_bf16_f32 v135, v174, v175
	global_store_dwordx2 v235, v[134:135], s[4:5]
	s_add_u32 s4, s4, 0x1000
	s_addc_u32 s5, s5, 0
	s_waitcnt vmcnt(7) lgkmcnt(3)
	v_add_f32_e32 v176, v176, v192
	v_add_f32_e32 v177, v177, v193
	v_add_f32_e32 v178, v178, v194
	v_add_f32_e32 v179, v179, v195
	v_mul_f32_e32 v176, 0xbfb8aa3b, v176
	v_mul_f32_e32 v177, 0xbfb8aa3b, v177
	v_mul_f32_e32 v178, 0xbfb8aa3b, v178
	v_mul_f32_e32 v179, 0xbfb8aa3b, v179
	v_exp_f32_e32 v176, v176
	v_exp_f32_e32 v177, v177
	v_exp_f32_e32 v178, v178
	v_exp_f32_e32 v179, v179
	v_lshlrev_b32_e32 v144, 16, v136
	v_and_b32_e32 v145, 0xffff0000, v136
	v_lshlrev_b32_e32 v146, 16, v137
	v_and_b32_e32 v147, 0xffff0000, v137
	v_add_f32_e32 v176, 1.0, v176
	v_add_f32_e32 v177, 1.0, v177
	v_add_f32_e32 v178, 1.0, v178
	v_add_f32_e32 v179, 1.0, v179
	v_rcp_f32_e32 v176, v176
	v_rcp_f32_e32 v177, v177
	v_rcp_f32_e32 v178, v178
	v_rcp_f32_e32 v179, v179
	s_nop 0
	v_mul_f32_e32 v176, v144, v176
	v_mul_f32_e32 v177, v145, v177
	v_mul_f32_e32 v178, v146, v178
	v_mul_f32_e32 v179, v147, v179
	v_cvt_pk_bf16_f32 v136, v176, v177
	v_cvt_pk_bf16_f32 v137, v178, v179
	global_store_dwordx2 v235, v[136:137], s[4:5]
	s_add_u32 s4, s4, 0x1000
	s_addc_u32 s5, s5, 0
	s_waitcnt vmcnt(7) lgkmcnt(2)
	v_add_f32_e32 v180, v180, v192
	v_add_f32_e32 v181, v181, v193
	v_add_f32_e32 v182, v182, v194
	v_add_f32_e32 v183, v183, v195
	v_mul_f32_e32 v180, 0xbfb8aa3b, v180
	v_mul_f32_e32 v181, 0xbfb8aa3b, v181
	v_mul_f32_e32 v182, 0xbfb8aa3b, v182
	v_mul_f32_e32 v183, 0xbfb8aa3b, v183
	v_exp_f32_e32 v180, v180
	v_exp_f32_e32 v181, v181
	v_exp_f32_e32 v182, v182
	v_exp_f32_e32 v183, v183
	v_lshlrev_b32_e32 v148, 16, v138
	v_and_b32_e32 v149, 0xffff0000, v138
	v_lshlrev_b32_e32 v150, 16, v139
	v_and_b32_e32 v151, 0xffff0000, v139
	v_add_f32_e32 v180, 1.0, v180
	v_add_f32_e32 v181, 1.0, v181
	v_add_f32_e32 v182, 1.0, v182
	v_add_f32_e32 v183, 1.0, v183
	v_rcp_f32_e32 v180, v180
	v_rcp_f32_e32 v181, v181
	v_rcp_f32_e32 v182, v182
	v_rcp_f32_e32 v183, v183
	s_nop 0
	v_mul_f32_e32 v180, v148, v180
	v_mul_f32_e32 v181, v149, v181
	v_mul_f32_e32 v182, v150, v182
	v_mul_f32_e32 v183, v151, v183
	v_cvt_pk_bf16_f32 v138, v180, v181
	v_cvt_pk_bf16_f32 v139, v182, v183
	global_store_dwordx2 v235, v[138:139], s[4:5]
	s_add_u32 s4, s4, 0x1000
	s_addc_u32 s5, s5, 0
	s_waitcnt vmcnt(7) lgkmcnt(1)
	v_add_f32_e32 v184, v184, v192
	v_add_f32_e32 v185, v185, v193
	v_add_f32_e32 v186, v186, v194
	v_add_f32_e32 v187, v187, v195
	v_mul_f32_e32 v184, 0xbfb8aa3b, v184
	v_mul_f32_e32 v185, 0xbfb8aa3b, v185
	v_mul_f32_e32 v186, 0xbfb8aa3b, v186
	v_mul_f32_e32 v187, 0xbfb8aa3b, v187
	v_exp_f32_e32 v184, v184
	v_exp_f32_e32 v185, v185
	v_exp_f32_e32 v186, v186
	v_exp_f32_e32 v187, v187
	v_lshlrev_b32_e32 v144, 16, v140
	v_and_b32_e32 v145, 0xffff0000, v140
	v_lshlrev_b32_e32 v146, 16, v141
	v_and_b32_e32 v147, 0xffff0000, v141
	v_add_f32_e32 v184, 1.0, v184
	v_add_f32_e32 v185, 1.0, v185
	v_add_f32_e32 v186, 1.0, v186
	v_add_f32_e32 v187, 1.0, v187
	v_rcp_f32_e32 v184, v184
	v_rcp_f32_e32 v185, v185
	v_rcp_f32_e32 v186, v186
	v_rcp_f32_e32 v187, v187
	s_nop 0
	v_mul_f32_e32 v184, v144, v184
	v_mul_f32_e32 v185, v145, v185
	v_mul_f32_e32 v186, v146, v186
	v_mul_f32_e32 v187, v147, v187
	v_cvt_pk_bf16_f32 v140, v184, v185
	v_cvt_pk_bf16_f32 v141, v186, v187
	global_store_dwordx2 v235, v[140:141], s[4:5]
	s_add_u32 s4, s4, 0x1000
	s_addc_u32 s5, s5, 0
	s_waitcnt vmcnt(7) lgkmcnt(0)
	v_add_f32_e32 v188, v188, v192
	v_add_f32_e32 v189, v189, v193
	v_add_f32_e32 v190, v190, v194
	v_add_f32_e32 v191, v191, v195
	v_mul_f32_e32 v188, 0xbfb8aa3b, v188
	v_mul_f32_e32 v189, 0xbfb8aa3b, v189
	v_mul_f32_e32 v190, 0xbfb8aa3b, v190
	v_mul_f32_e32 v191, 0xbfb8aa3b, v191
	v_exp_f32_e32 v188, v188
	v_exp_f32_e32 v189, v189
	v_exp_f32_e32 v190, v190
	v_exp_f32_e32 v191, v191
	v_lshlrev_b32_e32 v148, 16, v142
	v_and_b32_e32 v149, 0xffff0000, v142
	v_lshlrev_b32_e32 v150, 16, v143
	v_and_b32_e32 v151, 0xffff0000, v143
	v_add_f32_e32 v188, 1.0, v188
	v_add_f32_e32 v189, 1.0, v189
	v_add_f32_e32 v190, 1.0, v190
	v_add_f32_e32 v191, 1.0, v191
	v_rcp_f32_e32 v188, v188
	v_rcp_f32_e32 v189, v189
	v_rcp_f32_e32 v190, v190
	v_rcp_f32_e32 v191, v191
	s_nop 0
	v_mul_f32_e32 v188, v148, v188
	v_mul_f32_e32 v189, v149, v189
	v_mul_f32_e32 v190, v150, v190
	v_mul_f32_e32 v191, v151, v191
	v_cvt_pk_bf16_f32 v142, v188, v189
	v_cvt_pk_bf16_f32 v143, v190, v191
	global_store_dwordx2 v235, v[142:143], s[4:5]
	s_add_u32 s4, s4, 0x1000
	s_addc_u32 s5, s5, 0
	s_nop 1
	s_waitcnt lgkmcnt(0)
	ds_write_b128 v245, v[64:67]
	ds_write_b128 v245, v[68:71] offset:64
	ds_write_b128 v245, v[72:75] offset:128
	ds_write_b128 v245, v[76:79] offset:192
	ds_write_b128 v245, v[80:83] offset:4352
	ds_write_b128 v245, v[84:87] offset:4416
	ds_write_b128 v245, v[88:91] offset:4480
	ds_write_b128 v245, v[92:95] offset:4544
	ds_write_b128 v245, v[96:99] offset:8704
	ds_write_b128 v245, v[100:103] offset:8768
	ds_write_b128 v245, v[104:107] offset:8832
	ds_write_b128 v245, v[108:111] offset:8896
	ds_write_b128 v245, v[112:115] offset:13056
	ds_write_b128 v245, v[116:119] offset:13120
	ds_write_b128 v245, v[120:123] offset:13184
	ds_write_b128 v245, v[124:127] offset:13248
	global_load_dwordx2 v[128:129], v235, s[0:1]
	s_add_u32 s0, s0, 0x1000
	s_addc_u32 s1, s1, 0
	global_load_dwordx2 v[130:131], v235, s[0:1]
	s_add_u32 s0, s0, 0x1000
	s_addc_u32 s1, s1, 0
	global_load_dwordx2 v[132:133], v235, s[0:1]
	s_add_u32 s0, s0, 0x1000
	s_addc_u32 s1, s1, 0
	global_load_dwordx2 v[134:135], v235, s[0:1]
	s_add_u32 s0, s0, 0x1000
	s_addc_u32 s1, s1, 0
	global_load_dwordx2 v[136:137], v235, s[0:1]
	s_add_u32 s0, s0, 0x1000
	s_addc_u32 s1, s1, 0
	global_load_dwordx2 v[138:139], v235, s[0:1]
	s_add_u32 s0, s0, 0x1000
	s_addc_u32 s1, s1, 0
	global_load_dwordx2 v[140:141], v235, s[0:1]
	s_add_u32 s0, s0, 0x1000
	s_addc_u32 s1, s1, 0
	global_load_dwordx2 v[142:143], v235, s[0:1]
	s_add_u32 s0, s0, 0x1000
	s_addc_u32 s1, s1, 0
	s_waitcnt lgkmcnt(0)
	ds_read_b128 v[160:163], v246
	ds_read_b128 v[164:167], v246 offset:1088
	ds_read_b128 v[168:171], v246 offset:2176
	ds_read_b128 v[172:175], v246 offset:3264
	ds_read_b128 v[176:179], v246 offset:4352
	ds_read_b128 v[180:183], v246 offset:5440
	ds_read_b128 v[184:187], v246 offset:6528
	ds_read_b128 v[188:191], v246 offset:7616
	s_waitcnt vmcnt(7) lgkmcnt(7)
	v_add_f32_e32 v160, v160, v192
	v_add_f32_e32 v161, v161, v193
	v_add_f32_e32 v162, v162, v194
	v_add_f32_e32 v163, v163, v195
	v_mul_f32_e32 v160, 0xbfb8aa3b, v160
	v_mul_f32_e32 v161, 0xbfb8aa3b, v161
	v_mul_f32_e32 v162, 0xbfb8aa3b, v162
	v_mul_f32_e32 v163, 0xbfb8aa3b, v163
	v_exp_f32_e32 v160, v160
	v_exp_f32_e32 v161, v161
	v_exp_f32_e32 v162, v162
	v_exp_f32_e32 v163, v163
	v_lshlrev_b32_e32 v144, 16, v128
	v_and_b32_e32 v145, 0xffff0000, v128
	v_lshlrev_b32_e32 v146, 16, v129
	v_and_b32_e32 v147, 0xffff0000, v129
	v_add_f32_e32 v160, 1.0, v160
	v_add_f32_e32 v161, 1.0, v161
	v_add_f32_e32 v162, 1.0, v162
	v_add_f32_e32 v163, 1.0, v163
	v_rcp_f32_e32 v160, v160
	v_rcp_f32_e32 v161, v161
	v_rcp_f32_e32 v162, v162
	v_rcp_f32_e32 v163, v163
	s_nop 0
	v_mul_f32_e32 v160, v144, v160
	v_mul_f32_e32 v161, v145, v161
	v_mul_f32_e32 v162, v146, v162
	v_mul_f32_e32 v163, v147, v163
	v_cvt_pk_bf16_f32 v128, v160, v161
	v_cvt_pk_bf16_f32 v129, v162, v163
	global_store_dwordx2 v235, v[128:129], s[4:5]
	s_add_u32 s4, s4, 0x1000
	s_addc_u32 s5, s5, 0
	s_waitcnt vmcnt(7) lgkmcnt(6)
	v_add_f32_e32 v164, v164, v192
	v_add_f32_e32 v165, v165, v193
	v_add_f32_e32 v166, v166, v194
	v_add_f32_e32 v167, v167, v195
	v_mul_f32_e32 v164, 0xbfb8aa3b, v164
	v_mul_f32_e32 v165, 0xbfb8aa3b, v165
	v_mul_f32_e32 v166, 0xbfb8aa3b, v166
	v_mul_f32_e32 v167, 0xbfb8aa3b, v167
	v_exp_f32_e32 v164, v164
	v_exp_f32_e32 v165, v165
	v_exp_f32_e32 v166, v166
	v_exp_f32_e32 v167, v167
	v_lshlrev_b32_e32 v148, 16, v130
	v_and_b32_e32 v149, 0xffff0000, v130
	v_lshlrev_b32_e32 v150, 16, v131
	v_and_b32_e32 v151, 0xffff0000, v131
	v_add_f32_e32 v164, 1.0, v164
	v_add_f32_e32 v165, 1.0, v165
	v_add_f32_e32 v166, 1.0, v166
	v_add_f32_e32 v167, 1.0, v167
	v_rcp_f32_e32 v164, v164
	v_rcp_f32_e32 v165, v165
	v_rcp_f32_e32 v166, v166
	v_rcp_f32_e32 v167, v167
	s_nop 0
	v_mul_f32_e32 v164, v148, v164
	v_mul_f32_e32 v165, v149, v165
	v_mul_f32_e32 v166, v150, v166
	v_mul_f32_e32 v167, v151, v167
	v_cvt_pk_bf16_f32 v130, v164, v165
	v_cvt_pk_bf16_f32 v131, v166, v167
	global_store_dwordx2 v235, v[130:131], s[4:5]
	s_add_u32 s4, s4, 0x1000
	s_addc_u32 s5, s5, 0
	s_waitcnt vmcnt(7) lgkmcnt(5)
	v_add_f32_e32 v168, v168, v192
	v_add_f32_e32 v169, v169, v193
	v_add_f32_e32 v170, v170, v194
	v_add_f32_e32 v171, v171, v195
	v_mul_f32_e32 v168, 0xbfb8aa3b, v168
	v_mul_f32_e32 v169, 0xbfb8aa3b, v169
	v_mul_f32_e32 v170, 0xbfb8aa3b, v170
	v_mul_f32_e32 v171, 0xbfb8aa3b, v171
	v_exp_f32_e32 v168, v168
	v_exp_f32_e32 v169, v169
	v_exp_f32_e32 v170, v170
	v_exp_f32_e32 v171, v171
	v_lshlrev_b32_e32 v144, 16, v132
	v_and_b32_e32 v145, 0xffff0000, v132
	v_lshlrev_b32_e32 v146, 16, v133
	v_and_b32_e32 v147, 0xffff0000, v133
	v_add_f32_e32 v168, 1.0, v168
	v_add_f32_e32 v169, 1.0, v169
	v_add_f32_e32 v170, 1.0, v170
	v_add_f32_e32 v171, 1.0, v171
	v_rcp_f32_e32 v168, v168
	v_rcp_f32_e32 v169, v169
	v_rcp_f32_e32 v170, v170
	v_rcp_f32_e32 v171, v171
	s_nop 0
	v_mul_f32_e32 v168, v144, v168
	v_mul_f32_e32 v169, v145, v169
	v_mul_f32_e32 v170, v146, v170
	v_mul_f32_e32 v171, v147, v171
	v_cvt_pk_bf16_f32 v132, v168, v169
	v_cvt_pk_bf16_f32 v133, v170, v171
	global_store_dwordx2 v235, v[132:133], s[4:5]
	s_add_u32 s4, s4, 0x1000
	s_addc_u32 s5, s5, 0
	s_waitcnt vmcnt(7) lgkmcnt(4)
	v_add_f32_e32 v172, v172, v192
	v_add_f32_e32 v173, v173, v193
	v_add_f32_e32 v174, v174, v194
	v_add_f32_e32 v175, v175, v195
	v_mul_f32_e32 v172, 0xbfb8aa3b, v172
	v_mul_f32_e32 v173, 0xbfb8aa3b, v173
	v_mul_f32_e32 v174, 0xbfb8aa3b, v174
	v_mul_f32_e32 v175, 0xbfb8aa3b, v175
	v_exp_f32_e32 v172, v172
	v_exp_f32_e32 v173, v173
	v_exp_f32_e32 v174, v174
	v_exp_f32_e32 v175, v175
	v_lshlrev_b32_e32 v148, 16, v134
	v_and_b32_e32 v149, 0xffff0000, v134
	v_lshlrev_b32_e32 v150, 16, v135
	v_and_b32_e32 v151, 0xffff0000, v135
	v_add_f32_e32 v172, 1.0, v172
	v_add_f32_e32 v173, 1.0, v173
	v_add_f32_e32 v174, 1.0, v174
	v_add_f32_e32 v175, 1.0, v175
	v_rcp_f32_e32 v172, v172
	v_rcp_f32_e32 v173, v173
	v_rcp_f32_e32 v174, v174
	v_rcp_f32_e32 v175, v175
	s_nop 0
	v_mul_f32_e32 v172, v148, v172
	v_mul_f32_e32 v173, v149, v173
	v_mul_f32_e32 v174, v150, v174
	v_mul_f32_e32 v175, v151, v175
	v_cvt_pk_bf16_f32 v134, v172, v173
	v_cvt_pk_bf16_f32 v135, v174, v175
	global_store_dwordx2 v235, v[134:135], s[4:5]
	s_add_u32 s4, s4, 0x1000
	s_addc_u32 s5, s5, 0
	s_waitcnt vmcnt(7) lgkmcnt(3)
	v_add_f32_e32 v176, v176, v192
	v_add_f32_e32 v177, v177, v193
	v_add_f32_e32 v178, v178, v194
	v_add_f32_e32 v179, v179, v195
	v_mul_f32_e32 v176, 0xbfb8aa3b, v176
	v_mul_f32_e32 v177, 0xbfb8aa3b, v177
	v_mul_f32_e32 v178, 0xbfb8aa3b, v178
	v_mul_f32_e32 v179, 0xbfb8aa3b, v179
	v_exp_f32_e32 v176, v176
	v_exp_f32_e32 v177, v177
	v_exp_f32_e32 v178, v178
	v_exp_f32_e32 v179, v179
	v_lshlrev_b32_e32 v144, 16, v136
	v_and_b32_e32 v145, 0xffff0000, v136
	v_lshlrev_b32_e32 v146, 16, v137
	v_and_b32_e32 v147, 0xffff0000, v137
	v_add_f32_e32 v176, 1.0, v176
	v_add_f32_e32 v177, 1.0, v177
	v_add_f32_e32 v178, 1.0, v178
	v_add_f32_e32 v179, 1.0, v179
	v_rcp_f32_e32 v176, v176
	v_rcp_f32_e32 v177, v177
	v_rcp_f32_e32 v178, v178
	v_rcp_f32_e32 v179, v179
	s_nop 0
	v_mul_f32_e32 v176, v144, v176
	v_mul_f32_e32 v177, v145, v177
	v_mul_f32_e32 v178, v146, v178
	v_mul_f32_e32 v179, v147, v179
	v_cvt_pk_bf16_f32 v136, v176, v177
	v_cvt_pk_bf16_f32 v137, v178, v179
	global_store_dwordx2 v235, v[136:137], s[4:5]
	s_add_u32 s4, s4, 0x1000
	s_addc_u32 s5, s5, 0
	s_waitcnt vmcnt(7) lgkmcnt(2)
	v_add_f32_e32 v180, v180, v192
	v_add_f32_e32 v181, v181, v193
	v_add_f32_e32 v182, v182, v194
	v_add_f32_e32 v183, v183, v195
	v_mul_f32_e32 v180, 0xbfb8aa3b, v180
	v_mul_f32_e32 v181, 0xbfb8aa3b, v181
	v_mul_f32_e32 v182, 0xbfb8aa3b, v182
	v_mul_f32_e32 v183, 0xbfb8aa3b, v183
	v_exp_f32_e32 v180, v180
	v_exp_f32_e32 v181, v181
	v_exp_f32_e32 v182, v182
	v_exp_f32_e32 v183, v183
	v_lshlrev_b32_e32 v148, 16, v138
	v_and_b32_e32 v149, 0xffff0000, v138
	v_lshlrev_b32_e32 v150, 16, v139
	v_and_b32_e32 v151, 0xffff0000, v139
	v_add_f32_e32 v180, 1.0, v180
	v_add_f32_e32 v181, 1.0, v181
	v_add_f32_e32 v182, 1.0, v182
	v_add_f32_e32 v183, 1.0, v183
	v_rcp_f32_e32 v180, v180
	v_rcp_f32_e32 v181, v181
	v_rcp_f32_e32 v182, v182
	v_rcp_f32_e32 v183, v183
	s_nop 0
	v_mul_f32_e32 v180, v148, v180
	v_mul_f32_e32 v181, v149, v181
	v_mul_f32_e32 v182, v150, v182
	v_mul_f32_e32 v183, v151, v183
	v_cvt_pk_bf16_f32 v138, v180, v181
	v_cvt_pk_bf16_f32 v139, v182, v183
	global_store_dwordx2 v235, v[138:139], s[4:5]
	s_add_u32 s4, s4, 0x1000
	s_addc_u32 s5, s5, 0
	s_waitcnt vmcnt(7) lgkmcnt(1)
	v_add_f32_e32 v184, v184, v192
	v_add_f32_e32 v185, v185, v193
	v_add_f32_e32 v186, v186, v194
	v_add_f32_e32 v187, v187, v195
	v_mul_f32_e32 v184, 0xbfb8aa3b, v184
	v_mul_f32_e32 v185, 0xbfb8aa3b, v185
	v_mul_f32_e32 v186, 0xbfb8aa3b, v186
	v_mul_f32_e32 v187, 0xbfb8aa3b, v187
	v_exp_f32_e32 v184, v184
	v_exp_f32_e32 v185, v185
	v_exp_f32_e32 v186, v186
	v_exp_f32_e32 v187, v187
	v_lshlrev_b32_e32 v144, 16, v140
	v_and_b32_e32 v145, 0xffff0000, v140
	v_lshlrev_b32_e32 v146, 16, v141
	v_and_b32_e32 v147, 0xffff0000, v141
	v_add_f32_e32 v184, 1.0, v184
	v_add_f32_e32 v185, 1.0, v185
	v_add_f32_e32 v186, 1.0, v186
	v_add_f32_e32 v187, 1.0, v187
	v_rcp_f32_e32 v184, v184
	v_rcp_f32_e32 v185, v185
	v_rcp_f32_e32 v186, v186
	v_rcp_f32_e32 v187, v187
	s_nop 0
	v_mul_f32_e32 v184, v144, v184
	v_mul_f32_e32 v185, v145, v185
	v_mul_f32_e32 v186, v146, v186
	v_mul_f32_e32 v187, v147, v187
	v_cvt_pk_bf16_f32 v140, v184, v185
	v_cvt_pk_bf16_f32 v141, v186, v187
	global_store_dwordx2 v235, v[140:141], s[4:5]
	s_add_u32 s4, s4, 0x1000
	s_addc_u32 s5, s5, 0
	s_waitcnt vmcnt(7) lgkmcnt(0)
	v_add_f32_e32 v188, v188, v192
	v_add_f32_e32 v189, v189, v193
	v_add_f32_e32 v190, v190, v194
	v_add_f32_e32 v191, v191, v195
	v_mul_f32_e32 v188, 0xbfb8aa3b, v188
	v_mul_f32_e32 v189, 0xbfb8aa3b, v189
	v_mul_f32_e32 v190, 0xbfb8aa3b, v190
	v_mul_f32_e32 v191, 0xbfb8aa3b, v191
	v_exp_f32_e32 v188, v188
	v_exp_f32_e32 v189, v189
	v_exp_f32_e32 v190, v190
	v_exp_f32_e32 v191, v191
	v_lshlrev_b32_e32 v148, 16, v142
	v_and_b32_e32 v149, 0xffff0000, v142
	v_lshlrev_b32_e32 v150, 16, v143
	v_and_b32_e32 v151, 0xffff0000, v143
	v_add_f32_e32 v188, 1.0, v188
	v_add_f32_e32 v189, 1.0, v189
	v_add_f32_e32 v190, 1.0, v190
	v_add_f32_e32 v191, 1.0, v191
	v_rcp_f32_e32 v188, v188
	v_rcp_f32_e32 v189, v189
	v_rcp_f32_e32 v190, v190
	v_rcp_f32_e32 v191, v191
	s_nop 0
	v_mul_f32_e32 v188, v148, v188
	v_mul_f32_e32 v189, v149, v189
	v_mul_f32_e32 v190, v150, v190
	v_mul_f32_e32 v191, v151, v191
	v_cvt_pk_bf16_f32 v142, v188, v189
	v_cvt_pk_bf16_f32 v143, v190, v191
	global_store_dwordx2 v235, v[142:143], s[4:5]
	s_add_u32 s4, s4, 0x1000
	s_addc_u32 s5, s5, 0
	s_nop 1
	global_load_dwordx2 v[128:129], v235, s[0:1]
	s_add_u32 s0, s0, 0x1000
	s_addc_u32 s1, s1, 0
	global_load_dwordx2 v[130:131], v235, s[0:1]
	s_add_u32 s0, s0, 0x1000
	s_addc_u32 s1, s1, 0
	global_load_dwordx2 v[132:133], v235, s[0:1]
	s_add_u32 s0, s0, 0x1000
	s_addc_u32 s1, s1, 0
	global_load_dwordx2 v[134:135], v235, s[0:1]
	s_add_u32 s0, s0, 0x1000
	s_addc_u32 s1, s1, 0
	global_load_dwordx2 v[136:137], v235, s[0:1]
	s_add_u32 s0, s0, 0x1000
	s_addc_u32 s1, s1, 0
	global_load_dwordx2 v[138:139], v235, s[0:1]
	s_add_u32 s0, s0, 0x1000
	s_addc_u32 s1, s1, 0
	global_load_dwordx2 v[140:141], v235, s[0:1]
	s_add_u32 s0, s0, 0x1000
	s_addc_u32 s1, s1, 0
	global_load_dwordx2 v[142:143], v235, s[0:1]
	s_add_u32 s0, s0, 0x1000
	s_addc_u32 s1, s1, 0
	ds_read_b128 v[160:163], v246 offset:8704
	ds_read_b128 v[164:167], v246 offset:9792
	ds_read_b128 v[168:171], v246 offset:10880
	ds_read_b128 v[172:175], v246 offset:11968
	ds_read_b128 v[176:179], v246 offset:13056
	ds_read_b128 v[180:183], v246 offset:14144
	ds_read_b128 v[184:187], v246 offset:15232
	ds_read_b128 v[188:191], v246 offset:16320
	s_waitcnt vmcnt(7) lgkmcnt(7)
	v_add_f32_e32 v160, v160, v192
	v_add_f32_e32 v161, v161, v193
	v_add_f32_e32 v162, v162, v194
	v_add_f32_e32 v163, v163, v195
	v_mul_f32_e32 v160, 0xbfb8aa3b, v160
	v_mul_f32_e32 v161, 0xbfb8aa3b, v161
	v_mul_f32_e32 v162, 0xbfb8aa3b, v162
	v_mul_f32_e32 v163, 0xbfb8aa3b, v163
	v_exp_f32_e32 v160, v160
	v_exp_f32_e32 v161, v161
	v_exp_f32_e32 v162, v162
	v_exp_f32_e32 v163, v163
	v_lshlrev_b32_e32 v144, 16, v128
	v_and_b32_e32 v145, 0xffff0000, v128
	v_lshlrev_b32_e32 v146, 16, v129
	v_and_b32_e32 v147, 0xffff0000, v129
	v_add_f32_e32 v160, 1.0, v160
	v_add_f32_e32 v161, 1.0, v161
	v_add_f32_e32 v162, 1.0, v162
	v_add_f32_e32 v163, 1.0, v163
	v_rcp_f32_e32 v160, v160
	v_rcp_f32_e32 v161, v161
	v_rcp_f32_e32 v162, v162
	v_rcp_f32_e32 v163, v163
	s_nop 0
	v_mul_f32_e32 v160, v144, v160
	v_mul_f32_e32 v161, v145, v161
	v_mul_f32_e32 v162, v146, v162
	v_mul_f32_e32 v163, v147, v163
	v_cvt_pk_bf16_f32 v128, v160, v161
	v_cvt_pk_bf16_f32 v129, v162, v163
	global_store_dwordx2 v235, v[128:129], s[4:5]
	s_add_u32 s4, s4, 0x1000
	s_addc_u32 s5, s5, 0
	s_waitcnt vmcnt(7) lgkmcnt(6)
	v_add_f32_e32 v164, v164, v192
	v_add_f32_e32 v165, v165, v193
	v_add_f32_e32 v166, v166, v194
	v_add_f32_e32 v167, v167, v195
	v_mul_f32_e32 v164, 0xbfb8aa3b, v164
	v_mul_f32_e32 v165, 0xbfb8aa3b, v165
	v_mul_f32_e32 v166, 0xbfb8aa3b, v166
	v_mul_f32_e32 v167, 0xbfb8aa3b, v167
	v_exp_f32_e32 v164, v164
	v_exp_f32_e32 v165, v165
	v_exp_f32_e32 v166, v166
	v_exp_f32_e32 v167, v167
	v_lshlrev_b32_e32 v148, 16, v130
	v_and_b32_e32 v149, 0xffff0000, v130
	v_lshlrev_b32_e32 v150, 16, v131
	v_and_b32_e32 v151, 0xffff0000, v131
	v_add_f32_e32 v164, 1.0, v164
	v_add_f32_e32 v165, 1.0, v165
	v_add_f32_e32 v166, 1.0, v166
	v_add_f32_e32 v167, 1.0, v167
	v_rcp_f32_e32 v164, v164
	v_rcp_f32_e32 v165, v165
	v_rcp_f32_e32 v166, v166
	v_rcp_f32_e32 v167, v167
	s_nop 0
	v_mul_f32_e32 v164, v148, v164
	v_mul_f32_e32 v165, v149, v165
	v_mul_f32_e32 v166, v150, v166
	v_mul_f32_e32 v167, v151, v167
	v_cvt_pk_bf16_f32 v130, v164, v165
	v_cvt_pk_bf16_f32 v131, v166, v167
	global_store_dwordx2 v235, v[130:131], s[4:5]
	s_add_u32 s4, s4, 0x1000
	s_addc_u32 s5, s5, 0
	s_waitcnt vmcnt(7) lgkmcnt(5)
	v_add_f32_e32 v168, v168, v192
	v_add_f32_e32 v169, v169, v193
	v_add_f32_e32 v170, v170, v194
	v_add_f32_e32 v171, v171, v195
	v_mul_f32_e32 v168, 0xbfb8aa3b, v168
	v_mul_f32_e32 v169, 0xbfb8aa3b, v169
	v_mul_f32_e32 v170, 0xbfb8aa3b, v170
	v_mul_f32_e32 v171, 0xbfb8aa3b, v171
	v_exp_f32_e32 v168, v168
	v_exp_f32_e32 v169, v169
	v_exp_f32_e32 v170, v170
	v_exp_f32_e32 v171, v171
	v_lshlrev_b32_e32 v144, 16, v132
	v_and_b32_e32 v145, 0xffff0000, v132
	v_lshlrev_b32_e32 v146, 16, v133
	v_and_b32_e32 v147, 0xffff0000, v133
	v_add_f32_e32 v168, 1.0, v168
	v_add_f32_e32 v169, 1.0, v169
	v_add_f32_e32 v170, 1.0, v170
	v_add_f32_e32 v171, 1.0, v171
	v_rcp_f32_e32 v168, v168
	v_rcp_f32_e32 v169, v169
	v_rcp_f32_e32 v170, v170
	v_rcp_f32_e32 v171, v171
	s_nop 0
	v_mul_f32_e32 v168, v144, v168
	v_mul_f32_e32 v169, v145, v169
	v_mul_f32_e32 v170, v146, v170
	v_mul_f32_e32 v171, v147, v171
	v_cvt_pk_bf16_f32 v132, v168, v169
	v_cvt_pk_bf16_f32 v133, v170, v171
	global_store_dwordx2 v235, v[132:133], s[4:5]
	s_add_u32 s4, s4, 0x1000
	s_addc_u32 s5, s5, 0
	s_waitcnt vmcnt(7) lgkmcnt(4)
	v_add_f32_e32 v172, v172, v192
	v_add_f32_e32 v173, v173, v193
	v_add_f32_e32 v174, v174, v194
	v_add_f32_e32 v175, v175, v195
	v_mul_f32_e32 v172, 0xbfb8aa3b, v172
	v_mul_f32_e32 v173, 0xbfb8aa3b, v173
	v_mul_f32_e32 v174, 0xbfb8aa3b, v174
	v_mul_f32_e32 v175, 0xbfb8aa3b, v175
	v_exp_f32_e32 v172, v172
	v_exp_f32_e32 v173, v173
	v_exp_f32_e32 v174, v174
	v_exp_f32_e32 v175, v175
	v_lshlrev_b32_e32 v148, 16, v134
	v_and_b32_e32 v149, 0xffff0000, v134
	v_lshlrev_b32_e32 v150, 16, v135
	v_and_b32_e32 v151, 0xffff0000, v135
	v_add_f32_e32 v172, 1.0, v172
	v_add_f32_e32 v173, 1.0, v173
	v_add_f32_e32 v174, 1.0, v174
	v_add_f32_e32 v175, 1.0, v175
	v_rcp_f32_e32 v172, v172
	v_rcp_f32_e32 v173, v173
	v_rcp_f32_e32 v174, v174
	v_rcp_f32_e32 v175, v175
	s_nop 0
	v_mul_f32_e32 v172, v148, v172
	v_mul_f32_e32 v173, v149, v173
	v_mul_f32_e32 v174, v150, v174
	v_mul_f32_e32 v175, v151, v175
	v_cvt_pk_bf16_f32 v134, v172, v173
	v_cvt_pk_bf16_f32 v135, v174, v175
	global_store_dwordx2 v235, v[134:135], s[4:5]
	s_add_u32 s4, s4, 0x1000
	s_addc_u32 s5, s5, 0
	s_waitcnt vmcnt(7) lgkmcnt(3)
	v_add_f32_e32 v176, v176, v192
	v_add_f32_e32 v177, v177, v193
	v_add_f32_e32 v178, v178, v194
	v_add_f32_e32 v179, v179, v195
	v_mul_f32_e32 v176, 0xbfb8aa3b, v176
	v_mul_f32_e32 v177, 0xbfb8aa3b, v177
	v_mul_f32_e32 v178, 0xbfb8aa3b, v178
	v_mul_f32_e32 v179, 0xbfb8aa3b, v179
	v_exp_f32_e32 v176, v176
	v_exp_f32_e32 v177, v177
	v_exp_f32_e32 v178, v178
	v_exp_f32_e32 v179, v179
	v_lshlrev_b32_e32 v144, 16, v136
	v_and_b32_e32 v145, 0xffff0000, v136
	v_lshlrev_b32_e32 v146, 16, v137
	v_and_b32_e32 v147, 0xffff0000, v137
	v_add_f32_e32 v176, 1.0, v176
	v_add_f32_e32 v177, 1.0, v177
	v_add_f32_e32 v178, 1.0, v178
	v_add_f32_e32 v179, 1.0, v179
	v_rcp_f32_e32 v176, v176
	v_rcp_f32_e32 v177, v177
	v_rcp_f32_e32 v178, v178
	v_rcp_f32_e32 v179, v179
	s_nop 0
	v_mul_f32_e32 v176, v144, v176
	v_mul_f32_e32 v177, v145, v177
	v_mul_f32_e32 v178, v146, v178
	v_mul_f32_e32 v179, v147, v179
	v_cvt_pk_bf16_f32 v136, v176, v177
	v_cvt_pk_bf16_f32 v137, v178, v179
	global_store_dwordx2 v235, v[136:137], s[4:5]
	s_add_u32 s4, s4, 0x1000
	s_addc_u32 s5, s5, 0
	s_waitcnt vmcnt(7) lgkmcnt(2)
	v_add_f32_e32 v180, v180, v192
	v_add_f32_e32 v181, v181, v193
	v_add_f32_e32 v182, v182, v194
	v_add_f32_e32 v183, v183, v195
	v_mul_f32_e32 v180, 0xbfb8aa3b, v180
	v_mul_f32_e32 v181, 0xbfb8aa3b, v181
	v_mul_f32_e32 v182, 0xbfb8aa3b, v182
	v_mul_f32_e32 v183, 0xbfb8aa3b, v183
	v_exp_f32_e32 v180, v180
	v_exp_f32_e32 v181, v181
	v_exp_f32_e32 v182, v182
	v_exp_f32_e32 v183, v183
	v_lshlrev_b32_e32 v148, 16, v138
	v_and_b32_e32 v149, 0xffff0000, v138
	v_lshlrev_b32_e32 v150, 16, v139
	v_and_b32_e32 v151, 0xffff0000, v139
	v_add_f32_e32 v180, 1.0, v180
	v_add_f32_e32 v181, 1.0, v181
	v_add_f32_e32 v182, 1.0, v182
	v_add_f32_e32 v183, 1.0, v183
	v_rcp_f32_e32 v180, v180
	v_rcp_f32_e32 v181, v181
	v_rcp_f32_e32 v182, v182
	v_rcp_f32_e32 v183, v183
	s_nop 0
	v_mul_f32_e32 v180, v148, v180
	v_mul_f32_e32 v181, v149, v181
	v_mul_f32_e32 v182, v150, v182
	v_mul_f32_e32 v183, v151, v183
	v_cvt_pk_bf16_f32 v138, v180, v181
	v_cvt_pk_bf16_f32 v139, v182, v183
	global_store_dwordx2 v235, v[138:139], s[4:5]
	s_add_u32 s4, s4, 0x1000
	s_addc_u32 s5, s5, 0
	s_waitcnt vmcnt(7) lgkmcnt(1)
	v_add_f32_e32 v184, v184, v192
	v_add_f32_e32 v185, v185, v193
	v_add_f32_e32 v186, v186, v194
	v_add_f32_e32 v187, v187, v195
	v_mul_f32_e32 v184, 0xbfb8aa3b, v184
	v_mul_f32_e32 v185, 0xbfb8aa3b, v185
	v_mul_f32_e32 v186, 0xbfb8aa3b, v186
	v_mul_f32_e32 v187, 0xbfb8aa3b, v187
	v_exp_f32_e32 v184, v184
	v_exp_f32_e32 v185, v185
	v_exp_f32_e32 v186, v186
	v_exp_f32_e32 v187, v187
	v_lshlrev_b32_e32 v144, 16, v140
	v_and_b32_e32 v145, 0xffff0000, v140
	v_lshlrev_b32_e32 v146, 16, v141
	v_and_b32_e32 v147, 0xffff0000, v141
	v_add_f32_e32 v184, 1.0, v184
	v_add_f32_e32 v185, 1.0, v185
	v_add_f32_e32 v186, 1.0, v186
	v_add_f32_e32 v187, 1.0, v187
	v_rcp_f32_e32 v184, v184
	v_rcp_f32_e32 v185, v185
	v_rcp_f32_e32 v186, v186
	v_rcp_f32_e32 v187, v187
	s_nop 0
	v_mul_f32_e32 v184, v144, v184
	v_mul_f32_e32 v185, v145, v185
	v_mul_f32_e32 v186, v146, v186
	v_mul_f32_e32 v187, v147, v187
	v_cvt_pk_bf16_f32 v140, v184, v185
	v_cvt_pk_bf16_f32 v141, v186, v187
	global_store_dwordx2 v235, v[140:141], s[4:5]
	s_add_u32 s4, s4, 0x1000
	s_addc_u32 s5, s5, 0
	s_waitcnt vmcnt(7) lgkmcnt(0)
	v_add_f32_e32 v188, v188, v192
	v_add_f32_e32 v189, v189, v193
	v_add_f32_e32 v190, v190, v194
	v_add_f32_e32 v191, v191, v195
	v_mul_f32_e32 v188, 0xbfb8aa3b, v188
	v_mul_f32_e32 v189, 0xbfb8aa3b, v189
	v_mul_f32_e32 v190, 0xbfb8aa3b, v190
	v_mul_f32_e32 v191, 0xbfb8aa3b, v191
	v_exp_f32_e32 v188, v188
	v_exp_f32_e32 v189, v189
	v_exp_f32_e32 v190, v190
	v_exp_f32_e32 v191, v191
	v_lshlrev_b32_e32 v148, 16, v142
	v_and_b32_e32 v149, 0xffff0000, v142
	v_lshlrev_b32_e32 v150, 16, v143
	v_and_b32_e32 v151, 0xffff0000, v143
	v_add_f32_e32 v188, 1.0, v188
	v_add_f32_e32 v189, 1.0, v189
	v_add_f32_e32 v190, 1.0, v190
	v_add_f32_e32 v191, 1.0, v191
	v_rcp_f32_e32 v188, v188
	v_rcp_f32_e32 v189, v189
	v_rcp_f32_e32 v190, v190
	v_rcp_f32_e32 v191, v191
	s_nop 0
	v_mul_f32_e32 v188, v148, v188
	v_mul_f32_e32 v189, v149, v189
	v_mul_f32_e32 v190, v150, v190
	v_mul_f32_e32 v191, v151, v191
	v_cvt_pk_bf16_f32 v142, v188, v189
	v_cvt_pk_bf16_f32 v143, v190, v191
	global_store_dwordx2 v235, v[142:143], s[4:5]
	s_add_u32 s4, s4, 0x1000
	s_addc_u32 s5, s5, 0
	s_nop 1
	s_add_u32 s17, s17, 64
	s_branch .Lg14_tile

; #define PH(k) case k: if (ONLY_PHASE >= 0 && ONLY_PHASE != k) break;
; template <class Epi>
; DI void gemm_tile(char* smem, const bf16_t* __restrict__ A0, int lda0, int ksplit, const bf16_t* __restrict__ A1, int lda1,
;                   const bf16_t* __restrict__ Bt, int K, int row0, int col0, const Epi& epi, int tid) {
;   constexpr int BK = 32, PITCH = 40, BUF = (256 + 128) * PITCH;
;   bf16_t* sbase = (bf16_t*)smem;
;   const int lane = tid & 63, wid = tid >> 6, wr = wid >> 1, wc = wid & 1, fr = lane & 15, fq = lane >> 4;
;   f32x4 acc[8][4];
; #pragma unroll
;   for (int m = 0; m < 8; ++m)
; #pragma unroll
;     for (int n = 0; n < 4; ++n) acc[m][n] = (f32x4){0.f, 0.f, 0.f, 0.f};
;   u32x4 ra[2][4], rb[2][2];
;   const int nk = K / BK;
;   const int sr = tid >> 2, scv = tid & 3;
; template <int ph> DI void run_phase(const Ctx& c, char* smem) {
;     ...
;     PH(15) gemm_phase(smem, (const bf16_t*)(ws + OFF_S5Y), 512, 512, (const bf16_t*)(ws + OFF_MLRAW) + 1024, 2080, (const bf16_t*)(ws + OFF_WCDOUT), 1536, 8, EpiResid{p.out, p.out}, TIDX); break;
.LBB0_1844:
	s_cmp_gt_i32 s94, 15
	s_cselect_b64 s[0:1], -1, 0
	s_cmp_lt_i32 s95, 16
	s_cselect_b64 s[2:3], -1, 0
	s_or_b64 s[0:1], s[0:1], s[2:3]
	s_and_b64 vcc, exec, s[0:1]
	s_cbranch_vccnz .LBB0_1872
	s_add_u32 s0, s92, 0x11a00000
	s_load_dword s12, s[74:75], 0x180
	s_addc_u32 s1, s93, 0
	s_add_u32 s6, s92, 0x9800800
	s_addc_u32 s7, s93, 0
	s_add_u32 s2, s92, 0x3100000
	s_addc_u32 s3, s93, 0
	s_and_b32 s8, s72, 0xffffffc0
	v_mbcnt_hi_u32_b32 v195, -1, v194
	s_waitcnt lgkmcnt(0)
	s_and_b32 s10, s12, 7
	s_cmp_lg_u32 s10, 0
	s_waitcnt vmcnt(16)
	v_add_u32_e32 v196, s8, v195
	v_mbcnt_lo_u32_b32 v240, -1, 0
	v_mbcnt_hi_u32_b32 v240, -1, v240
	s_lshr_b32 s20, s72, 6
	s_lshl_b32 s13, s20, 10
	v_and_b32_e32 v241, 15, v240
	v_lshrrev_b32_e32 v242, 4, v240
	v_bfe_u32 v243, v240, 3, 1
	v_mul_u32_u24_e32 v243, 3, v243
	v_xor_b32_e32 v243, v242, v243
	v_lshlrev_b32_e32 v243, 4, v243
	v_lshl_add_u32 v243, v241, 6, v243
	s_lshr_b32 s19, s20, 1
	s_lshl_b32 s19, s19, 13
	v_add_u32_e32 v230, s19, v243
	s_and_b32 s19, s20, 1
	s_lshl_b32 s19, s19, 12
	s_add_u32 s19, s19, 16384
	v_add_u32_e32 v231, s19, v243
	s_lshr_b32 s19, s20, 1
	s_lshl_b32 s19, s19, 7
	v_add_u32_e32 v244, s19, v241
	s_and_b32 s19, s20, 1
	s_lshl_b32 s19, s19, 6
	v_lshl_add_u32 v245, v242, 2, s19
	s_movk_i32 s19, 0x1000
	v_mul_lo_u32 v246, v244, s19
	v_lshl_add_u32 v234, v245, 2, v246
	v_lshrrev_b32_e32 v241, 2, v240
	s_lshl_b32 s19, s20, 4
	v_add_u32_e32 v241, s19, v241
	v_bfe_u32 v242, v240, 5, 1
	v_mul_u32_u24_e32 v242, 3, v242
	v_and_b32_e32 v243, 3, v240
	v_xor_b32_e32 v243, v243, v242
	v_lshlrev_b32_e32 v243, 4, v243
	s_mov_b32 s19, 1024
	v_mad_u32_u24 v224, v241, s19, v243
	v_add_u32_e32 v225, 0x10000, v224
	v_add_u32_e32 v226, 0x20000, v224
	v_add_u32_e32 v227, 0x30000, v224
	s_mov_b32 s19, 4160
	v_mad_u32_u24 v236, v241, s19, v243
	v_add_u32_e32 v237, 0x41000, v236
	v_add_u32_e32 v238, 0x82000, v236
	v_add_u32_e32 v239, 0xc3000, v236
	v_mov_b32_e32 v248, v224
	v_mov_b32_e32 v249, v225
	v_mov_b32_e32 v250, v226
	v_mov_b32_e32 v251, v227
	s_mov_b32 s19, 3072
	v_mad_u32_u24 v228, v241, s19, v243
	v_add_u32_e32 v229, 0x30000, v228
	s_load_dwordx2 s[6:7], s[74:75], 0x168
	v_mbcnt_lo_u32_b32 v240, -1, 0
	v_mbcnt_hi_u32_b32 v240, -1, v240
	s_lshr_b32 s20, s72, 6
	s_mul_i32 s19, s20, 17408
	v_and_b32_e32 v241, 15, v240
	v_lshrrev_b32_e32 v242, 4, v240
	v_mul_u32_u24_e32 v243, 0x110, v241
	v_lshl_add_u32 v243, v242, 4, v243
	v_add_u32_e32 v245, s19, v243
	v_mul_u32_u24_e32 v243, 0x110, v242
	v_lshl_add_u32 v243, v241, 4, v243
	v_add_u32_e32 v246, s19, v243
	s_lshr_b32 s19, s20, 1
	s_lshl_b32 s19, s19, 7
	v_add_u32_e32 v243, s19, v242
	v_lshlrev_b32_e32 v243, 12, v243
	s_and_b32 s19, s20, 1
	s_lshl_b32 s19, s19, 8
	v_lshl_add_u32 v244, v241, 4, s19
	v_add_u32_e32 v247, v243, v244
	s_cmpk_gt_u32 s96, 0xff
	s_cselect_b32 s18, 1, 0
	s_cmpk_gt_u32 s96, 0xff
	s_cbranch_scc0 .Lg15_prio
	s_setprio 1

.Lg15_hi5:
	s_branch .Lg15_epi
.Lg15_sw0:
	s_mul_i32 s20, s98, 4160
	s_add_u32 s20, s20, 0x9800800
	s_add_u32 s0, s92, s20
	s_addc_u32 s1, s93, 0
	v_mov_b32_e32 v224, v236
	v_mov_b32_e32 v225, v237
	v_mov_b32_e32 v226, v238
	v_mov_b32_e32 v227, v239
	s_branch .Lg15_swb0

; #define PH(k) case k: if (ONLY_PHASE >= 0 && ONLY_PHASE != k) break;
; template <class Epi>
; DI void gemm_tile(char* smem, const bf16_t* __restrict__ A0, int lda0, int ksplit, const bf16_t* __restrict__ A1, int lda1,
;                   const bf16_t* __restrict__ Bt, int K, int row0, int col0, const Epi& epi, int tid) {
;   constexpr int BK = 32, PITCH = 40, BUF = (256 + 128) * PITCH;
;   bf16_t* sbase = (bf16_t*)smem;
;   const int lane = tid & 63, wid = tid >> 6, wr = wid >> 1, wc = wid & 1, fr = lane & 15, fq = lane >> 4;
;   f32x4 acc[8][4];
; #pragma unroll
;   for (int m = 0; m < 8; ++m)
; #pragma unroll
;     for (int n = 0; n < 4; ++n) acc[m][n] = (f32x4){0.f, 0.f, 0.f, 0.f};
;   u32x4 ra[2][4], rb[2][2];
;   const int nk = K / BK;
;   const int sr = tid >> 2, scv = tid & 3;
; template <int ph> DI void run_phase(const Ctx& c, char* smem) {
;     ...
;     PH(17) gemm_phase(smem, XN, 1024, 1 << 30, XN, 1024, (const bf16_t*)(ws + OFF_W1) + 4096ull * 1024, 1024, 32, EpiRelu2{(bf16_t*)(ws + OFF_R1)}, TIDX); break;
.LBB0_1890:
	s_cmp_gt_i32 s94, 17
	s_cselect_b64 s[0:1], -1, 0
	s_cmp_lt_i32 s95, 18
	s_cselect_b64 s[2:3], -1, 0
	s_or_b64 s[0:1], s[0:1], s[2:3]
	s_and_b64 vcc, exec, s[0:1]
	s_cbranch_vccnz .LBB0_1918
	s_add_u32 s2, s92, 0x3800000
	s_waitcnt lgkmcnt(0)
	s_load_dword s14, s[74:75], 0x180
	s_addc_u32 s3, s93, 0
	s_add_u32 s4, s92, 0x13c0000
	s_addc_u32 s5, s93, 0
	s_add_u32 s0, s92, 0x7800000
	s_addc_u32 s1, s93, 0
	s_and_b32 s16, s72, 0xffffffc0
	v_mbcnt_hi_u32_b32 v195, -1, v194
	s_waitcnt lgkmcnt(0)
	s_and_b32 s15, s14, 7
	s_cmp_lg_u32 s15, 0
	s_waitcnt vmcnt(16)
	v_add_u32_e32 v196, s16, v195
	v_mbcnt_lo_u32_b32 v240, -1, 0
	v_mbcnt_hi_u32_b32 v240, -1, v240
	s_lshr_b32 s12, s72, 6
	s_lshl_b32 s101, s12, 10
	v_and_b32_e32 v241, 15, v240
	v_lshrrev_b32_e32 v242, 4, v240
	v_bfe_u32 v243, v240, 3, 1
	v_mul_u32_u24_e32 v243, 3, v243
	v_xor_b32_e32 v243, v242, v243
	v_lshlrev_b32_e32 v243, 4, v243
	v_lshl_add_u32 v243, v241, 6, v243
	s_lshr_b32 s11, s12, 1
	s_lshl_b32 s11, s11, 13
	v_add_u32_e32 v230, s11, v243
	s_and_b32 s11, s12, 1
	s_lshl_b32 s11, s11, 12
	s_add_u32 s11, s11, 16384
	v_add_u32_e32 v231, s11, v243
	s_lshr_b32 s11, s12, 1
	s_lshl_b32 s11, s11, 7
	v_add_u32_e32 v244, s11, v241
	s_and_b32 s11, s12, 1
	s_lshl_b32 s11, s11, 6
	v_lshl_add_u32 v245, v242, 2, s11
	s_movk_i32 s11, 0x2000
	v_mul_lo_u32 v246, v244, s11
	v_lshl_add_u32 v234, v245, 1, v246
	s_mul_i32 s11, s12, 18432
	v_mul_u32_u24_e32 v246, 144, v241
	v_lshl_add_u32 v246, v242, 3, v246
	v_add_u32_e32 v236, s11, v246
	v_lshrrev_b32_e32 v246, 3, v240
	v_mul_u32_u24_e32 v246, 144, v246
	v_and_b32_e32 v247, 7, v240
	v_lshl_add_u32 v246, v247, 4, v246
	v_add_u32_e32 v237, s11, v246
	s_lshr_b32 s11, s12, 1
	s_lshl_b32 s11, s11, 7
	v_lshrrev_b32_e32 v246, 3, v240
	v_add_u32_e32 v246, s11, v246
	s_and_b32 s11, s12, 1
	s_lshl_b32 s11, s11, 6
	v_lshl_add_u32 v248, v247, 3, s11
	s_movk_i32 s11, 8192
	v_mul_lo_u32 v247, v246, s11
	v_lshl_add_u32 v238, v248, 1, v247
	v_lshrrev_b32_e32 v241, 2, v240
	s_lshl_b32 s11, s12, 4
	v_add_u32_e32 v241, s11, v241
	v_bfe_u32 v242, v240, 5, 1
	v_mul_u32_u24_e32 v242, 3, v242
	v_and_b32_e32 v243, 3, v240
	v_xor_b32_e32 v243, v243, v242
	v_lshlrev_b32_e32 v243, 4, v243
	s_mov_b32 s11, 2048
	v_mad_u32_u24 v224, v241, s11, v243
	v_add_u32_e32 v225, 0x20000, v224
	v_add_u32_e32 v226, 0x40000, v224
	v_add_u32_e32 v227, 0x60000, v224
	s_mov_b32 s11, 2048
	v_mad_u32_u24 v228, v241, s11, v243
	v_add_u32_e32 v229, 0x20000, v228
	s_cmpk_gt_u32 s96, 0xff
	s_cselect_b32 s10, 1, 0
	s_cmpk_gt_u32 s96, 0xff
	s_cbranch_scc0 .Lg17_prio
	s_setprio 1

.Lg17_hi5:
	s_branch .Lg17_epi
.Lg17_epi:
	s_nop 7
	s_nop 7
	s_mul_i32 s12, s18, 8192
	s_lshl_b32 s11, s13, 1
	s_add_u32 s12, s12, s11
	s_add_u32 s12, s12, 0x7800000
	s_add_u32 s4, s92, s12
	s_addc_u32 s5, s93, 0
	v_max_f32_e32 v0, 0, v0
	v_max_f32_e32 v1, 0, v1
	v_max_f32_e32 v2, 0, v2
	v_max_f32_e32 v3, 0, v3
	v_pk_mul_f32 v[0:1], v[0:1], v[0:1]
	v_pk_mul_f32 v[2:3], v[2:3], v[2:3]
	v_cvt_pk_bf16_f32 v128, v0, v1
	v_cvt_pk_bf16_f32 v129, v2, v3
	ds_write_b64 v236, v[128:129]
	v_max_f32_e32 v4, 0, v4
	v_max_f32_e32 v5, 0, v5
	v_max_f32_e32 v6, 0, v6
	v_max_f32_e32 v7, 0, v7
	v_pk_mul_f32 v[4:5], v[4:5], v[4:5]
	v_pk_mul_f32 v[6:7], v[6:7], v[6:7]
	v_cvt_pk_bf16_f32 v130, v4, v5
	v_cvt_pk_bf16_f32 v131, v6, v7
	ds_write_b64 v236, v[130:131] offset:32
	v_max_f32_e32 v8, 0, v8
	v_max_f32_e32 v9, 0, v9
	v_max_f32_e32 v10, 0, v10
	v_max_f32_e32 v11, 0, v11
	v_pk_mul_f32 v[8:9], v[8:9], v[8:9]
	v_pk_mul_f32 v[10:11], v[10:11], v[10:11]
	v_cvt_pk_bf16_f32 v132, v8, v9
	v_cvt_pk_bf16_f32 v133, v10, v11
	ds_write_b64 v236, v[132:133] offset:64
	v_max_f32_e32 v12, 0, v12
	v_max_f32_e32 v13, 0, v13
	v_max_f32_e32 v14, 0, v14
	v_max_f32_e32 v15, 0, v15
	v_pk_mul_f32 v[12:13], v[12:13], v[12:13]
	v_pk_mul_f32 v[14:15], v[14:15], v[14:15]
	v_cvt_pk_bf16_f32 v134, v12, v13
	v_cvt_pk_bf16_f32 v135, v14, v15
	ds_write_b64 v236, v[134:135] offset:96
	v_max_f32_e32 v16, 0, v16
	v_max_f32_e32 v17, 0, v17
	v_max_f32_e32 v18, 0, v18
	v_max_f32_e32 v19, 0, v19
	v_pk_mul_f32 v[16:17], v[16:17], v[16:17]
	v_pk_mul_f32 v[18:19], v[18:19], v[18:19]
	v_cvt_pk_bf16_f32 v136, v16, v17
	v_cvt_pk_bf16_f32 v137, v18, v19
	ds_write_b64 v236, v[136:137] offset:2304
	v_max_f32_e32 v20, 0, v20
	v_max_f32_e32 v21, 0, v21
	v_max_f32_e32 v22, 0, v22
	v_max_f32_e32 v23, 0, v23
	v_pk_mul_f32 v[20:21], v[20:21], v[20:21]
	v_pk_mul_f32 v[22:23], v[22:23], v[22:23]
	v_cvt_pk_bf16_f32 v138, v20, v21
	v_cvt_pk_bf16_f32 v139, v22, v23
	ds_write_b64 v236, v[138:139] offset:2336
	v_max_f32_e32 v24, 0, v24
	v_max_f32_e32 v25, 0, v25
	v_max_f32_e32 v26, 0, v26
	v_max_f32_e32 v27, 0, v27
	v_pk_mul_f32 v[24:25], v[24:25], v[24:25]
	v_pk_mul_f32 v[26:27], v[26:27], v[26:27]
	v_cvt_pk_bf16_f32 v140, v24, v25
	v_cvt_pk_bf16_f32 v141, v26, v27
	ds_write_b64 v236, v[140:141] offset:2368
	v_max_f32_e32 v28, 0, v28
	v_max_f32_e32 v29, 0, v29
	v_max_f32_e32 v30, 0, v30
	v_max_f32_e32 v31, 0, v31
	v_pk_mul_f32 v[28:29], v[28:29], v[28:29]
	v_pk_mul_f32 v[30:31], v[30:31], v[30:31]
	v_cvt_pk_bf16_f32 v142, v28, v29
	v_cvt_pk_bf16_f32 v143, v30, v31
	ds_write_b64 v236, v[142:143] offset:2400
	v_max_f32_e32 v32, 0, v32
	v_max_f32_e32 v33, 0, v33
	v_max_f32_e32 v34, 0, v34
	v_max_f32_e32 v35, 0, v35
	v_pk_mul_f32 v[32:33], v[32:33], v[32:33]
	v_pk_mul_f32 v[34:35], v[34:35], v[34:35]
	v_cvt_pk_bf16_f32 v144, v32, v33
	v_cvt_pk_bf16_f32 v145, v34, v35
	ds_write_b64 v236, v[144:145] offset:4608
	v_max_f32_e32 v36, 0, v36
	v_max_f32_e32 v37, 0, v37
	v_max_f32_e32 v38, 0, v38
	v_max_f32_e32 v39, 0, v39
	v_pk_mul_f32 v[36:37], v[36:37], v[36:37]
	v_pk_mul_f32 v[38:39], v[38:39], v[38:39]
	v_cvt_pk_bf16_f32 v146, v36, v37
	v_cvt_pk_bf16_f32 v147, v38, v39
	ds_write_b64 v236, v[146:147] offset:4640
	v_max_f32_e32 v40, 0, v40
	v_max_f32_e32 v41, 0, v41
	v_max_f32_e32 v42, 0, v42
	v_max_f32_e32 v43, 0, v43
	v_pk_mul_f32 v[40:41], v[40:41], v[40:41]
	v_pk_mul_f32 v[42:43], v[42:43], v[42:43]
	v_cvt_pk_bf16_f32 v148, v40, v41
	v_cvt_pk_bf16_f32 v149, v42, v43
	ds_write_b64 v236, v[148:149] offset:4672
	v_max_f32_e32 v44, 0, v44
	v_max_f32_e32 v45, 0, v45
	v_max_f32_e32 v46, 0, v46
	v_max_f32_e32 v47, 0, v47
	v_pk_mul_f32 v[44:45], v[44:45], v[44:45]
	v_pk_mul_f32 v[46:47], v[46:47], v[46:47]
	v_cvt_pk_bf16_f32 v150, v44, v45
	v_cvt_pk_bf16_f32 v151, v46, v47
	ds_write_b64 v236, v[150:151] offset:4704
	v_max_f32_e32 v48, 0, v48
	v_max_f32_e32 v49, 0, v49
	v_max_f32_e32 v50, 0, v50
	v_max_f32_e32 v51, 0, v51
	v_pk_mul_f32 v[48:49], v[48:49], v[48:49]
	v_pk_mul_f32 v[50:51], v[50:51], v[50:51]
	v_cvt_pk_bf16_f32 v152, v48, v49
	v_cvt_pk_bf16_f32 v153, v50, v51
	ds_write_b64 v236, v[152:153] offset:6912
	v_max_f32_e32 v52, 0, v52
	v_max_f32_e32 v53, 0, v53
	v_max_f32_e32 v54, 0, v54
	v_max_f32_e32 v55, 0, v55
	v_pk_mul_f32 v[52:53], v[52:53], v[52:53]
	v_pk_mul_f32 v[54:55], v[54:55], v[54:55]
	v_cvt_pk_bf16_f32 v154, v52, v53
	v_cvt_pk_bf16_f32 v155, v54, v55
	ds_write_b64 v236, v[154:155] offset:6944
	v_max_f32_e32 v56, 0, v56
	v_max_f32_e32 v57, 0, v57
	v_max_f32_e32 v58, 0, v58
	v_max_f32_e32 v59, 0, v59
	v_pk_mul_f32 v[56:57], v[56:57], v[56:57]
	v_pk_mul_f32 v[58:59], v[58:59], v[58:59]
	v_cvt_pk_bf16_f32 v156, v56, v57
	v_cvt_pk_bf16_f32 v157, v58, v59
	ds_write_b64 v236, v[156:157] offset:6976
	v_max_f32_e32 v60, 0, v60
	v_max_f32_e32 v61, 0, v61
	v_max_f32_e32 v62, 0, v62
	v_max_f32_e32 v63, 0, v63
	v_pk_mul_f32 v[60:61], v[60:61], v[60:61]
	v_pk_mul_f32 v[62:63], v[62:63], v[62:63]
	v_cvt_pk_bf16_f32 v158, v60, v61
	v_cvt_pk_bf16_f32 v159, v62, v63
	ds_write_b64 v236, v[158:159] offset:7008
	v_max_f32_e32 v64, 0, v64
	v_max_f32_e32 v65, 0, v65
	v_max_f32_e32 v66, 0, v66
	v_max_f32_e32 v67, 0, v67
	v_pk_mul_f32 v[64:65], v[64:65], v[64:65]
	v_pk_mul_f32 v[66:67], v[66:67], v[66:67]
	v_cvt_pk_bf16_f32 v128, v64, v65
	v_cvt_pk_bf16_f32 v129, v66, v67
	ds_write_b64 v236, v[128:129] offset:9216
	v_max_f32_e32 v68, 0, v68
	v_max_f32_e32 v69, 0, v69
	v_max_f32_e32 v70, 0, v70
	v_max_f32_e32 v71, 0, v71
	v_pk_mul_f32 v[68:69], v[68:69], v[68:69]
	v_pk_mul_f32 v[70:71], v[70:71], v[70:71]
	v_cvt_pk_bf16_f32 v130, v68, v69
	v_cvt_pk_bf16_f32 v131, v70, v71
	ds_write_b64 v236, v[130:131] offset:9248
	v_max_f32_e32 v72, 0, v72
	v_max_f32_e32 v73, 0, v73
	v_max_f32_e32 v74, 0, v74
	v_max_f32_e32 v75, 0, v75
	v_pk_mul_f32 v[72:73], v[72:73], v[72:73]
	v_pk_mul_f32 v[74:75], v[74:75], v[74:75]
	v_cvt_pk_bf16_f32 v132, v72, v73
	v_cvt_pk_bf16_f32 v133, v74, v75
	ds_write_b64 v236, v[132:133] offset:9280
	v_max_f32_e32 v76, 0, v76
	v_max_f32_e32 v77, 0, v77
	v_max_f32_e32 v78, 0, v78
	v_max_f32_e32 v79, 0, v79
	v_pk_mul_f32 v[76:77], v[76:77], v[76:77]
	v_pk_mul_f32 v[78:79], v[78:79], v[78:79]
	v_cvt_pk_bf16_f32 v134, v76, v77
	v_cvt_pk_bf16_f32 v135, v78, v79
	ds_write_b64 v236, v[134:135] offset:9312
	v_max_f32_e32 v80, 0, v80
	v_max_f32_e32 v81, 0, v81
	v_max_f32_e32 v82, 0, v82
	v_max_f32_e32 v83, 0, v83
	v_pk_mul_f32 v[80:81], v[80:81], v[80:81]
	v_pk_mul_f32 v[82:83], v[82:83], v[82:83]
	v_cvt_pk_bf16_f32 v136, v80, v81
	v_cvt_pk_bf16_f32 v137, v82, v83
	ds_write_b64 v236, v[136:137] offset:11520
	v_max_f32_e32 v84, 0, v84
	v_max_f32_e32 v85, 0, v85
	v_max_f32_e32 v86, 0, v86
	v_max_f32_e32 v87, 0, v87
	v_pk_mul_f32 v[84:85], v[84:85], v[84:85]
	v_pk_mul_f32 v[86:87], v[86:87], v[86:87]
	v_cvt_pk_bf16_f32 v138, v84, v85
	v_cvt_pk_bf16_f32 v139, v86, v87
	ds_write_b64 v236, v[138:139] offset:11552
	v_max_f32_e32 v88, 0, v88
	v_max_f32_e32 v89, 0, v89
	v_max_f32_e32 v90, 0, v90
	v_max_f32_e32 v91, 0, v91
	v_pk_mul_f32 v[88:89], v[88:89], v[88:89]
	v_pk_mul_f32 v[90:91], v[90:91], v[90:91]
	v_cvt_pk_bf16_f32 v140, v88, v89
	v_cvt_pk_bf16_f32 v141, v90, v91
	ds_write_b64 v236, v[140:141] offset:11584
	v_max_f32_e32 v92, 0, v92
	v_max_f32_e32 v93, 0, v93
	v_max_f32_e32 v94, 0, v94
	v_max_f32_e32 v95, 0, v95
	v_pk_mul_f32 v[92:93], v[92:93], v[92:93]
	v_pk_mul_f32 v[94:95], v[94:95], v[94:95]
	v_cvt_pk_bf16_f32 v142, v92, v93
	v_cvt_pk_bf16_f32 v143, v94, v95
	ds_write_b64 v236, v[142:143] offset:11616
	v_max_f32_e32 v96, 0, v96
	v_max_f32_e32 v97, 0, v97
	v_max_f32_e32 v98, 0, v98
	v_max_f32_e32 v99, 0, v99
	v_pk_mul_f32 v[96:97], v[96:97], v[96:97]
	v_pk_mul_f32 v[98:99], v[98:99], v[98:99]
	v_cvt_pk_bf16_f32 v144, v96, v97
	v_cvt_pk_bf16_f32 v145, v98, v99
	ds_write_b64 v236, v[144:145] offset:13824
	v_max_f32_e32 v100, 0, v100
	v_max_f32_e32 v101, 0, v101
	v_max_f32_e32 v102, 0, v102
	v_max_f32_e32 v103, 0, v103
	v_pk_mul_f32 v[100:101], v[100:101], v[100:101]
	v_pk_mul_f32 v[102:103], v[102:103], v[102:103]
	v_cvt_pk_bf16_f32 v146, v100, v101
	v_cvt_pk_bf16_f32 v147, v102, v103
	ds_write_b64 v236, v[146:147] offset:13856
	v_max_f32_e32 v104, 0, v104
	v_max_f32_e32 v105, 0, v105
	v_max_f32_e32 v106, 0, v106
	v_max_f32_e32 v107, 0, v107
	v_pk_mul_f32 v[104:105], v[104:105], v[104:105]
	v_pk_mul_f32 v[106:107], v[106:107], v[106:107]
	v_cvt_pk_bf16_f32 v148, v104, v105
	v_cvt_pk_bf16_f32 v149, v106, v107
	ds_write_b64 v236, v[148:149] offset:13888
	v_max_f32_e32 v108, 0, v108
	v_max_f32_e32 v109, 0, v109
	v_max_f32_e32 v110, 0, v110
	v_max_f32_e32 v111, 0, v111
	v_pk_mul_f32 v[108:109], v[108:109], v[108:109]
	v_pk_mul_f32 v[110:111], v[110:111], v[110:111]
	v_cvt_pk_bf16_f32 v150, v108, v109
	v_cvt_pk_bf16_f32 v151, v110, v111
	ds_write_b64 v236, v[150:151] offset:13920
	v_max_f32_e32 v112, 0, v112
	v_max_f32_e32 v113, 0, v113
	v_max_f32_e32 v114, 0, v114
	v_max_f32_e32 v115, 0, v115
	v_pk_mul_f32 v[112:113], v[112:113], v[112:113]
	v_pk_mul_f32 v[114:115], v[114:115], v[114:115]
	v_cvt_pk_bf16_f32 v152, v112, v113
	v_cvt_pk_bf16_f32 v153, v114, v115
	ds_write_b64 v236, v[152:153] offset:16128
	v_max_f32_e32 v116, 0, v116
	v_max_f32_e32 v117, 0, v117
	v_max_f32_e32 v118, 0, v118
	v_max_f32_e32 v119, 0, v119
	v_pk_mul_f32 v[116:117], v[116:117], v[116:117]
	v_pk_mul_f32 v[118:119], v[118:119], v[118:119]
	v_cvt_pk_bf16_f32 v154, v116, v117
	v_cvt_pk_bf16_f32 v155, v118, v119
	ds_write_b64 v236, v[154:155] offset:16160
	v_max_f32_e32 v120, 0, v120
	v_max_f32_e32 v121, 0, v121
	v_max_f32_e32 v122, 0, v122
	v_max_f32_e32 v123, 0, v123
	v_pk_mul_f32 v[120:121], v[120:121], v[120:121]
	v_pk_mul_f32 v[122:123], v[122:123], v[122:123]
	v_cvt_pk_bf16_f32 v156, v120, v121
	v_cvt_pk_bf16_f32 v157, v122, v123
	ds_write_b64 v236, v[156:157] offset:16192
	v_max_f32_e32 v124, 0, v124
	v_max_f32_e32 v125, 0, v125
	v_max_f32_e32 v126, 0, v126
	v_max_f32_e32 v127, 0, v127
	v_pk_mul_f32 v[124:125], v[124:125], v[124:125]
	v_pk_mul_f32 v[126:127], v[126:127], v[126:127]
	v_cvt_pk_bf16_f32 v158, v124, v125
	v_cvt_pk_bf16_f32 v159, v126, v127
	ds_write_b64 v236, v[158:159] offset:16224
	s_waitcnt lgkmcnt(0)
	ds_read_b128 v[128:131], v237
	ds_read_b128 v[132:135], v237 offset:1152
	ds_read_b128 v[136:139], v237 offset:2304
	ds_read_b128 v[140:143], v237 offset:3456
	ds_read_b128 v[144:147], v237 offset:4608
	ds_read_b128 v[148:151], v237 offset:5760
	ds_read_b128 v[152:155], v237 offset:6912
	ds_read_b128 v[156:159], v237 offset:8064
	ds_read_b128 v[160:163], v237 offset:9216
	ds_read_b128 v[164:167], v237 offset:10368
	ds_read_b128 v[168:171], v237 offset:11520
	ds_read_b128 v[172:175], v237 offset:12672
	ds_read_b128 v[176:179], v237 offset:13824
	ds_read_b128 v[180:183], v237 offset:14976
	ds_read_b128 v[184:187], v237 offset:16128
	ds_read_b128 v[188:191], v237 offset:17280
	s_waitcnt lgkmcnt(15)
	global_store_dwordx4 v238, v[128:131], s[4:5] nt
	s_add_u32 s4, s4, 0x10000
	s_addc_u32 s5, s5, 0
	s_waitcnt lgkmcnt(14)
	global_store_dwordx4 v238, v[132:135], s[4:5] nt
	s_add_u32 s4, s4, 0x10000
	s_addc_u32 s5, s5, 0
	s_waitcnt lgkmcnt(13)
	global_store_dwordx4 v238, v[136:139], s[4:5] nt
	s_add_u32 s4, s4, 0x10000
	s_addc_u32 s5, s5, 0
	s_waitcnt lgkmcnt(12)
	global_store_dwordx4 v238, v[140:143], s[4:5] nt
	s_add_u32 s4, s4, 0x10000
	s_addc_u32 s5, s5, 0
	s_waitcnt lgkmcnt(11)
	global_store_dwordx4 v238, v[144:147], s[4:5] nt
	s_add_u32 s4, s4, 0x10000
	s_addc_u32 s5, s5, 0
	s_waitcnt lgkmcnt(10)
	global_store_dwordx4 v238, v[148:151], s[4:5] nt
	s_add_u32 s4, s4, 0x10000
	s_addc_u32 s5, s5, 0
	s_waitcnt lgkmcnt(9)
	global_store_dwordx4 v238, v[152:155], s[4:5] nt
	s_add_u32 s4, s4, 0x10000
	s_addc_u32 s5, s5, 0
	s_waitcnt lgkmcnt(8)
	global_store_dwordx4 v238, v[156:159], s[4:5] nt
	s_add_u32 s4, s4, 0x10000
	s_addc_u32 s5, s5, 0
	s_waitcnt lgkmcnt(7)
	global_store_dwordx4 v238, v[160:163], s[4:5] nt
	s_add_u32 s4, s4, 0x10000
	s_addc_u32 s5, s5, 0
	s_waitcnt lgkmcnt(6)
	global_store_dwordx4 v238, v[164:167], s[4:5] nt
	s_add_u32 s4, s4, 0x10000
	s_addc_u32 s5, s5, 0
	s_waitcnt lgkmcnt(5)
	global_store_dwordx4 v238, v[168:171], s[4:5] nt
	s_add_u32 s4, s4, 0x10000
	s_addc_u32 s5, s5, 0
	s_waitcnt lgkmcnt(4)
	global_store_dwordx4 v238, v[172:175], s[4:5] nt
	s_add_u32 s4, s4, 0x10000
	s_addc_u32 s5, s5, 0
	s_waitcnt lgkmcnt(3)
	global_store_dwordx4 v238, v[176:179], s[4:5] nt
	s_add_u32 s4, s4, 0x10000
	s_addc_u32 s5, s5, 0
	s_waitcnt lgkmcnt(2)
	global_store_dwordx4 v238, v[180:183], s[4:5] nt
	s_add_u32 s4, s4, 0x10000
	s_addc_u32 s5, s5, 0
	s_waitcnt lgkmcnt(1)
	global_store_dwordx4 v238, v[184:187], s[4:5] nt
	s_add_u32 s4, s4, 0x10000
	s_addc_u32 s5, s5, 0
	s_waitcnt lgkmcnt(0)
	global_store_dwordx4 v238, v[188:191], s[4:5] nt
	s_nop 1
	s_add_u32 s17, s17, 64
	s_branch .Lg17_tile

; #define PH(k) case k: if (ONLY_PHASE >= 0 && ONLY_PHASE != k) break;
; template <class Epi>
; DI void gemm_tile(char* smem, const bf16_t* __restrict__ A0, int lda0, int ksplit, const bf16_t* __restrict__ A1, int lda1,
;                   const bf16_t* __restrict__ Bt, int K, int row0, int col0, const Epi& epi, int tid) {
;   constexpr int BK = 32, PITCH = 40, BUF = (256 + 128) * PITCH;
;   bf16_t* sbase = (bf16_t*)smem;
;   const int lane = tid & 63, wid = tid >> 6, wr = wid >> 1, wc = wid & 1, fr = lane & 15, fq = lane >> 4;
;   f32x4 acc[8][4];
; #pragma unroll
;   for (int m = 0; m < 8; ++m)
; #pragma unroll
;     for (int n = 0; n < 4; ++n) acc[m][n] = (f32x4){0.f, 0.f, 0.f, 0.f};
;   u32x4 ra[2][4], rb[2][2];
;   const int nk = K / BK;
;   const int sr = tid >> 2, scv = tid & 3;
; template <int ph> DI void run_phase(const Ctx& c, char* smem) {
;     ...
;     PH(18) gemm_phase(smem, (const bf16_t*)(ws + OFF_R1), 4096, 1 << 30, XN, 1024, (const bf16_t*)(ws + OFF_W2) + 4096ull * 1024, 4096, 8, EpiResid{p.out, p.out}, TIDX); break;
.LBB0_1918:
	s_cmp_gt_i32 s94, 18
	s_cselect_b64 s[0:1], -1, 0
	s_cmp_lt_i32 s95, 19
	s_cselect_b64 s[2:3], -1, 0
	s_or_b64 s[0:1], s[0:1], s[2:3]
	s_and_b64 vcc, exec, s[0:1]
	s_cbranch_vccnz .LBB0_1946
	s_load_dword s12, s[74:75], 0x180
	s_add_u32 s0, s92, 0x7800000
	s_addc_u32 s1, s93, 0
	s_add_u32 s2, s92, 0x23c0000
	s_addc_u32 s3, s93, 0
	s_waitcnt lgkmcnt(0)
	s_and_b32 s14, s72, 0xffffffc0
	v_mbcnt_hi_u32_b32 v195, -1, v194
	s_and_b32 s13, s12, 7
	s_cmp_lg_u32 s13, 0
	s_waitcnt vmcnt(16)
	v_add_u32_e32 v196, s14, v195
	v_mbcnt_lo_u32_b32 v240, -1, 0
	v_mbcnt_hi_u32_b32 v240, -1, v240
	s_lshr_b32 s10, s72, 6
	s_lshl_b32 s101, s10, 10
	v_and_b32_e32 v241, 15, v240
	v_lshrrev_b32_e32 v242, 4, v240
	v_bfe_u32 v243, v240, 3, 1
	v_mul_u32_u24_e32 v243, 3, v243
	v_xor_b32_e32 v243, v242, v243
	v_lshlrev_b32_e32 v243, 4, v243
	v_lshl_add_u32 v243, v241, 6, v243
	s_lshr_b32 s9, s10, 1
	s_lshl_b32 s9, s9, 13
	v_add_u32_e32 v230, s9, v243
	s_and_b32 s9, s10, 1
	s_lshl_b32 s9, s9, 12
	s_add_u32 s9, s9, 16384
	v_add_u32_e32 v231, s9, v243
	s_lshr_b32 s9, s10, 1
	s_lshl_b32 s9, s9, 7
	v_add_u32_e32 v244, s9, v241
	s_and_b32 s9, s10, 1
	s_lshl_b32 s9, s9, 6
	v_lshl_add_u32 v245, v242, 2, s9
	s_movk_i32 s9, 0x1000
	v_mul_lo_u32 v246, v244, s9
	v_lshl_add_u32 v234, v245, 2, v246
	v_lshrrev_b32_e32 v241, 2, v240
	s_lshl_b32 s9, s10, 4
	v_add_u32_e32 v241, s9, v241
	v_bfe_u32 v242, v240, 5, 1
	v_mul_u32_u24_e32 v242, 3, v242
	v_and_b32_e32 v243, 3, v240
	v_xor_b32_e32 v243, v243, v242
	v_lshlrev_b32_e32 v243, 4, v243
	s_mov_b32 s9, 8192
	v_mad_u32_u24 v224, v241, s9, v243
	v_add_u32_e32 v225, 0x80000, v224
	v_add_u32_e32 v226, 0x100000, v224
	v_add_u32_e32 v227, 0x180000, v224
	s_mov_b32 s9, 8192
	v_mad_u32_u24 v228, v241, s9, v243
	v_add_u32_e32 v229, 0x80000, v228
	s_load_dwordx2 s[6:7], s[74:75], 0x168
	v_mbcnt_lo_u32_b32 v240, -1, 0
	v_mbcnt_hi_u32_b32 v240, -1, v240
	s_lshr_b32 s10, s72, 6
	s_mul_i32 s9, s10, 17408
	v_and_b32_e32 v241, 15, v240
	v_lshrrev_b32_e32 v242, 4, v240
	v_mul_u32_u24_e32 v243, 0x110, v241
	v_lshl_add_u32 v243, v242, 4, v243
	v_add_u32_e32 v245, s9, v243
	v_mul_u32_u24_e32 v243, 0x110, v242
	v_lshl_add_u32 v243, v241, 4, v243
	v_add_u32_e32 v246, s9, v243
	s_lshr_b32 s9, s10, 1
	s_lshl_b32 s9, s9, 7
	v_add_u32_e32 v243, s9, v242
	v_lshlrev_b32_e32 v243, 12, v243
	s_and_b32 s9, s10, 1
	s_lshl_b32 s9, s9, 8
	v_lshl_add_u32 v244, v241, 4, s9
	v_add_u32_e32 v247, v243, v244
	s_cmpk_gt_u32 s96, 0xff
	s_cselect_b32 s8, 1, 0
	s_cmpk_gt_u32 s96, 0xff
	s_cbranch_scc0 .Lg18_prio
	s_setprio 1

.Lg18_hi5:
	s_branch .Lg18_epi
.Lg18_epi:
	s_nop 7
	s_nop 7
	s_lshl_b32 s10, s16, 12
	s_lshl_b32 s9, s11, 2
	s_add_u32 s10, s10, s9
	s_add_u32 s4, s6, s10
	s_addc_u32 s5, s7, 0
	s_lshl_b32 s10, s16, 12
	s_lshl_b32 s9, s11, 2
	s_add_u32 s10, s10, s9
	s_add_u32 s0, s6, s10
	s_addc_u32 s1, s7, 0
	ds_write_b128 v245, v[0:3]
	ds_write_b128 v245, v[4:7] offset:64
	ds_write_b128 v245, v[8:11] offset:128
	ds_write_b128 v245, v[12:15] offset:192
	ds_write_b128 v245, v[16:19] offset:4352
	ds_write_b128 v245, v[20:23] offset:4416
	ds_write_b128 v245, v[24:27] offset:4480
	ds_write_b128 v245, v[28:31] offset:4544
	ds_write_b128 v245, v[32:35] offset:8704
	ds_write_b128 v245, v[36:39] offset:8768
	ds_write_b128 v245, v[40:43] offset:8832
	ds_write_b128 v245, v[44:47] offset:8896
	ds_write_b128 v245, v[48:51] offset:13056
	ds_write_b128 v245, v[52:55] offset:13120
	ds_write_b128 v245, v[56:59] offset:13184
	ds_write_b128 v245, v[60:63] offset:13248
	global_load_dwordx4 v[128:131], v247, s[0:1]
	s_add_u32 s0, s0, 0x4000
	s_addc_u32 s1, s1, 0
	global_load_dwordx4 v[132:135], v247, s[0:1]
	s_add_u32 s0, s0, 0x4000
	s_addc_u32 s1, s1, 0
	global_load_dwordx4 v[136:139], v247, s[0:1]
	s_add_u32 s0, s0, 0x4000
	s_addc_u32 s1, s1, 0
	global_load_dwordx4 v[140:143], v247, s[0:1]
	s_add_u32 s0, s0, 0x4000
	s_addc_u32 s1, s1, 0
	global_load_dwordx4 v[144:147], v247, s[0:1]
	s_add_u32 s0, s0, 0x4000
	s_addc_u32 s1, s1, 0
	global_load_dwordx4 v[148:151], v247, s[0:1]
	s_add_u32 s0, s0, 0x4000
	s_addc_u32 s1, s1, 0
	global_load_dwordx4 v[152:155], v247, s[0:1]
	s_add_u32 s0, s0, 0x4000
	s_addc_u32 s1, s1, 0
	global_load_dwordx4 v[156:159], v247, s[0:1]
	s_add_u32 s0, s0, 0x4000
	s_addc_u32 s1, s1, 0
	s_waitcnt lgkmcnt(0)
	ds_read_b128 v[160:163], v246
	ds_read_b128 v[164:167], v246 offset:1088
	ds_read_b128 v[168:171], v246 offset:2176
	ds_read_b128 v[172:175], v246 offset:3264
	ds_read_b128 v[176:179], v246 offset:4352
	ds_read_b128 v[180:183], v246 offset:5440
	ds_read_b128 v[184:187], v246 offset:6528
	ds_read_b128 v[188:191], v246 offset:7616
	s_waitcnt vmcnt(7) lgkmcnt(7)
	v_pk_add_f32 v[128:129], v[128:129], v[160:161]
	v_pk_add_f32 v[130:131], v[130:131], v[162:163]
	global_store_dwordx4 v247, v[128:131], s[4:5] nt
	s_add_u32 s4, s4, 0x4000
	s_addc_u32 s5, s5, 0
	s_waitcnt vmcnt(7) lgkmcnt(6)
	v_pk_add_f32 v[132:133], v[132:133], v[164:165]
	v_pk_add_f32 v[134:135], v[134:135], v[166:167]
	global_store_dwordx4 v247, v[132:135], s[4:5] nt
	s_add_u32 s4, s4, 0x4000
	s_addc_u32 s5, s5, 0
	s_waitcnt vmcnt(7) lgkmcnt(5)
	v_pk_add_f32 v[136:137], v[136:137], v[168:169]
	v_pk_add_f32 v[138:139], v[138:139], v[170:171]
	global_store_dwordx4 v247, v[136:139], s[4:5] nt
	s_add_u32 s4, s4, 0x4000
	s_addc_u32 s5, s5, 0
	s_waitcnt vmcnt(7) lgkmcnt(4)
	v_pk_add_f32 v[140:141], v[140:141], v[172:173]
	v_pk_add_f32 v[142:143], v[142:143], v[174:175]
	global_store_dwordx4 v247, v[140:143], s[4:5] nt
	s_add_u32 s4, s4, 0x4000
	s_addc_u32 s5, s5, 0
	s_waitcnt vmcnt(7) lgkmcnt(3)
	v_pk_add_f32 v[144:145], v[144:145], v[176:177]
	v_pk_add_f32 v[146:147], v[146:147], v[178:179]
	global_store_dwordx4 v247, v[144:147], s[4:5] nt
	s_add_u32 s4, s4, 0x4000
	s_addc_u32 s5, s5, 0
	s_waitcnt vmcnt(7) lgkmcnt(2)
	v_pk_add_f32 v[148:149], v[148:149], v[180:181]
	v_pk_add_f32 v[150:151], v[150:151], v[182:183]
	global_store_dwordx4 v247, v[148:151], s[4:5] nt
	s_add_u32 s4, s4, 0x4000
	s_addc_u32 s5, s5, 0
	s_waitcnt vmcnt(7) lgkmcnt(1)
	v_pk_add_f32 v[152:153], v[152:153], v[184:185]
	v_pk_add_f32 v[154:155], v[154:155], v[186:187]
	global_store_dwordx4 v247, v[152:155], s[4:5] nt
	s_add_u32 s4, s4, 0x4000
	s_addc_u32 s5, s5, 0
	s_waitcnt vmcnt(7) lgkmcnt(0)
	v_pk_add_f32 v[156:157], v[156:157], v[188:189]
	v_pk_add_f32 v[158:159], v[158:159], v[190:191]
	global_store_dwordx4 v247, v[156:159], s[4:5] nt
	s_add_u32 s4, s4, 0x4000
	s_addc_u32 s5, s5, 0
	s_nop 1
	global_load_dwordx4 v[128:131], v247, s[0:1]
	s_add_u32 s0, s0, 0x4000
	s_addc_u32 s1, s1, 0
	global_load_dwordx4 v[132:135], v247, s[0:1]
	s_add_u32 s0, s0, 0x4000
	s_addc_u32 s1, s1, 0
	global_load_dwordx4 v[136:139], v247, s[0:1]
	s_add_u32 s0, s0, 0x4000
	s_addc_u32 s1, s1, 0
	global_load_dwordx4 v[140:143], v247, s[0:1]
	s_add_u32 s0, s0, 0x4000
	s_addc_u32 s1, s1, 0
	global_load_dwordx4 v[144:147], v247, s[0:1]
	s_add_u32 s0, s0, 0x4000
	s_addc_u32 s1, s1, 0
	global_load_dwordx4 v[148:151], v247, s[0:1]
	s_add_u32 s0, s0, 0x4000
	s_addc_u32 s1, s1, 0
	global_load_dwordx4 v[152:155], v247, s[0:1]
	s_add_u32 s0, s0, 0x4000
	s_addc_u32 s1, s1, 0
	global_load_dwordx4 v[156:159], v247, s[0:1]
	s_add_u32 s0, s0, 0x4000
	s_addc_u32 s1, s1, 0
	ds_read_b128 v[160:163], v246 offset:8704
	ds_read_b128 v[164:167], v246 offset:9792
	ds_read_b128 v[168:171], v246 offset:10880
	ds_read_b128 v[172:175], v246 offset:11968
	ds_read_b128 v[176:179], v246 offset:13056
	ds_read_b128 v[180:183], v246 offset:14144
	ds_read_b128 v[184:187], v246 offset:15232
	ds_read_b128 v[188:191], v246 offset:16320
	s_waitcnt vmcnt(7) lgkmcnt(7)
	v_pk_add_f32 v[128:129], v[128:129], v[160:161]
	v_pk_add_f32 v[130:131], v[130:131], v[162:163]
	global_store_dwordx4 v247, v[128:131], s[4:5] nt
	s_add_u32 s4, s4, 0x4000
	s_addc_u32 s5, s5, 0
	s_waitcnt vmcnt(7) lgkmcnt(6)
	v_pk_add_f32 v[132:133], v[132:133], v[164:165]
	v_pk_add_f32 v[134:135], v[134:135], v[166:167]
	global_store_dwordx4 v247, v[132:135], s[4:5] nt
	s_add_u32 s4, s4, 0x4000
	s_addc_u32 s5, s5, 0
	s_waitcnt vmcnt(7) lgkmcnt(5)
	v_pk_add_f32 v[136:137], v[136:137], v[168:169]
	v_pk_add_f32 v[138:139], v[138:139], v[170:171]
	global_store_dwordx4 v247, v[136:139], s[4:5] nt
	s_add_u32 s4, s4, 0x4000
	s_addc_u32 s5, s5, 0
	s_waitcnt vmcnt(7) lgkmcnt(4)
	v_pk_add_f32 v[140:141], v[140:141], v[172:173]
	v_pk_add_f32 v[142:143], v[142:143], v[174:175]
	global_store_dwordx4 v247, v[140:143], s[4:5] nt
	s_add_u32 s4, s4, 0x4000
	s_addc_u32 s5, s5, 0
	s_waitcnt vmcnt(7) lgkmcnt(3)
	v_pk_add_f32 v[144:145], v[144:145], v[176:177]
	v_pk_add_f32 v[146:147], v[146:147], v[178:179]
	global_store_dwordx4 v247, v[144:147], s[4:5] nt
	s_add_u32 s4, s4, 0x4000
	s_addc_u32 s5, s5, 0
	s_waitcnt vmcnt(7) lgkmcnt(2)
	v_pk_add_f32 v[148:149], v[148:149], v[180:181]
	v_pk_add_f32 v[150:151], v[150:151], v[182:183]
	global_store_dwordx4 v247, v[148:151], s[4:5] nt
	s_add_u32 s4, s4, 0x4000
	s_addc_u32 s5, s5, 0
	s_waitcnt vmcnt(7) lgkmcnt(1)
	v_pk_add_f32 v[152:153], v[152:153], v[184:185]
	v_pk_add_f32 v[154:155], v[154:155], v[186:187]
	global_store_dwordx4 v247, v[152:155], s[4:5] nt
	s_add_u32 s4, s4, 0x4000
	s_addc_u32 s5, s5, 0
	s_waitcnt vmcnt(7) lgkmcnt(0)
	v_pk_add_f32 v[156:157], v[156:157], v[188:189]
	v_pk_add_f32 v[158:159], v[158:159], v[190:191]
	global_store_dwordx4 v247, v[156:159], s[4:5] nt
	s_add_u32 s4, s4, 0x4000
	s_addc_u32 s5, s5, 0
	s_nop 1
	s_waitcnt lgkmcnt(0)
	ds_write_b128 v245, v[64:67]
	ds_write_b128 v245, v[68:71] offset:64
	ds_write_b128 v245, v[72:75] offset:128
	ds_write_b128 v245, v[76:79] offset:192
	ds_write_b128 v245, v[80:83] offset:4352
	ds_write_b128 v245, v[84:87] offset:4416
	ds_write_b128 v245, v[88:91] offset:4480
	ds_write_b128 v245, v[92:95] offset:4544
	ds_write_b128 v245, v[96:99] offset:8704
	ds_write_b128 v245, v[100:103] offset:8768
	ds_write_b128 v245, v[104:107] offset:8832
	ds_write_b128 v245, v[108:111] offset:8896
	ds_write_b128 v245, v[112:115] offset:13056
	ds_write_b128 v245, v[116:119] offset:13120
	ds_write_b128 v245, v[120:123] offset:13184
	ds_write_b128 v245, v[124:127] offset:13248
	global_load_dwordx4 v[128:131], v247, s[0:1]
	s_add_u32 s0, s0, 0x4000
	s_addc_u32 s1, s1, 0
	global_load_dwordx4 v[132:135], v247, s[0:1]
	s_add_u32 s0, s0, 0x4000
	s_addc_u32 s1, s1, 0
	global_load_dwordx4 v[136:139], v247, s[0:1]
	s_add_u32 s0, s0, 0x4000
	s_addc_u32 s1, s1, 0
	global_load_dwordx4 v[140:143], v247, s[0:1]
	s_add_u32 s0, s0, 0x4000
	s_addc_u32 s1, s1, 0
	global_load_dwordx4 v[144:147], v247, s[0:1]
	s_add_u32 s0, s0, 0x4000
	s_addc_u32 s1, s1, 0
	global_load_dwordx4 v[148:151], v247, s[0:1]
	s_add_u32 s0, s0, 0x4000
	s_addc_u32 s1, s1, 0
	global_load_dwordx4 v[152:155], v247, s[0:1]
	s_add_u32 s0, s0, 0x4000
	s_addc_u32 s1, s1, 0
	global_load_dwordx4 v[156:159], v247, s[0:1]
	s_add_u32 s0, s0, 0x4000
	s_addc_u32 s1, s1, 0
	s_waitcnt lgkmcnt(0)
	ds_read_b128 v[160:163], v246
	ds_read_b128 v[164:167], v246 offset:1088
	ds_read_b128 v[168:171], v246 offset:2176
	ds_read_b128 v[172:175], v246 offset:3264
	ds_read_b128 v[176:179], v246 offset:4352
	ds_read_b128 v[180:183], v246 offset:5440
	ds_read_b128 v[184:187], v246 offset:6528
	ds_read_b128 v[188:191], v246 offset:7616
	s_waitcnt vmcnt(7) lgkmcnt(7)
	v_pk_add_f32 v[128:129], v[128:129], v[160:161]
	v_pk_add_f32 v[130:131], v[130:131], v[162:163]
	global_store_dwordx4 v247, v[128:131], s[4:5] nt
	s_add_u32 s4, s4, 0x4000
	s_addc_u32 s5, s5, 0
	s_waitcnt vmcnt(7) lgkmcnt(6)
	v_pk_add_f32 v[132:133], v[132:133], v[164:165]
	v_pk_add_f32 v[134:135], v[134:135], v[166:167]
	global_store_dwordx4 v247, v[132:135], s[4:5] nt
	s_add_u32 s4, s4, 0x4000
	s_addc_u32 s5, s5, 0
	s_waitcnt vmcnt(7) lgkmcnt(5)
	v_pk_add_f32 v[136:137], v[136:137], v[168:169]
	v_pk_add_f32 v[138:139], v[138:139], v[170:171]
	global_store_dwordx4 v247, v[136:139], s[4:5] nt
	s_add_u32 s4, s4, 0x4000
	s_addc_u32 s5, s5, 0
	s_waitcnt vmcnt(7) lgkmcnt(4)
	v_pk_add_f32 v[140:141], v[140:141], v[172:173]
	v_pk_add_f32 v[142:143], v[142:143], v[174:175]
	global_store_dwordx4 v247, v[140:143], s[4:5] nt
	s_add_u32 s4, s4, 0x4000
	s_addc_u32 s5, s5, 0
	s_waitcnt vmcnt(7) lgkmcnt(3)
	v_pk_add_f32 v[144:145], v[144:145], v[176:177]
	v_pk_add_f32 v[146:147], v[146:147], v[178:179]
	global_store_dwordx4 v247, v[144:147], s[4:5] nt
	s_add_u32 s4, s4, 0x4000
	s_addc_u32 s5, s5, 0
	s_waitcnt vmcnt(7) lgkmcnt(2)
	v_pk_add_f32 v[148:149], v[148:149], v[180:181]
	v_pk_add_f32 v[150:151], v[150:151], v[182:183]
	global_store_dwordx4 v247, v[148:151], s[4:5] nt
	s_add_u32 s4, s4, 0x4000
	s_addc_u32 s5, s5, 0
	s_waitcnt vmcnt(7) lgkmcnt(1)
	v_pk_add_f32 v[152:153], v[152:153], v[184:185]
	v_pk_add_f32 v[154:155], v[154:155], v[186:187]
	global_store_dwordx4 v247, v[152:155], s[4:5] nt
	s_add_u32 s4, s4, 0x4000
	s_addc_u32 s5, s5, 0
	s_waitcnt vmcnt(7) lgkmcnt(0)
	v_pk_add_f32 v[156:157], v[156:157], v[188:189]
	v_pk_add_f32 v[158:159], v[158:159], v[190:191]
	global_store_dwordx4 v247, v[156:159], s[4:5] nt
	s_add_u32 s4, s4, 0x4000
	s_addc_u32 s5, s5, 0
	s_nop 1
	global_load_dwordx4 v[128:131], v247, s[0:1]
	s_add_u32 s0, s0, 0x4000
	s_addc_u32 s1, s1, 0
	global_load_dwordx4 v[132:135], v247, s[0:1]
	s_add_u32 s0, s0, 0x4000
	s_addc_u32 s1, s1, 0
	global_load_dwordx4 v[136:139], v247, s[0:1]
	s_add_u32 s0, s0, 0x4000
	s_addc_u32 s1, s1, 0
	global_load_dwordx4 v[140:143], v247, s[0:1]
	s_add_u32 s0, s0, 0x4000
	s_addc_u32 s1, s1, 0
	global_load_dwordx4 v[144:147], v247, s[0:1]
	s_add_u32 s0, s0, 0x4000
	s_addc_u32 s1, s1, 0
	global_load_dwordx4 v[148:151], v247, s[0:1]
	s_add_u32 s0, s0, 0x4000
	s_addc_u32 s1, s1, 0
	global_load_dwordx4 v[152:155], v247, s[0:1]
	s_add_u32 s0, s0, 0x4000
	s_addc_u32 s1, s1, 0
	global_load_dwordx4 v[156:159], v247, s[0:1]
	s_add_u32 s0, s0, 0x4000
	s_addc_u32 s1, s1, 0
	ds_read_b128 v[160:163], v246 offset:8704
	ds_read_b128 v[164:167], v246 offset:9792
	ds_read_b128 v[168:171], v246 offset:10880
	ds_read_b128 v[172:175], v246 offset:11968
	ds_read_b128 v[176:179], v246 offset:13056
	ds_read_b128 v[180:183], v246 offset:14144
	ds_read_b128 v[184:187], v246 offset:15232
	ds_read_b128 v[188:191], v246 offset:16320
	s_waitcnt vmcnt(7) lgkmcnt(7)
	v_pk_add_f32 v[128:129], v[128:129], v[160:161]
	v_pk_add_f32 v[130:131], v[130:131], v[162:163]
	global_store_dwordx4 v247, v[128:131], s[4:5] nt
	s_add_u32 s4, s4, 0x4000
	s_addc_u32 s5, s5, 0
	s_waitcnt vmcnt(7) lgkmcnt(6)
	v_pk_add_f32 v[132:133], v[132:133], v[164:165]
	v_pk_add_f32 v[134:135], v[134:135], v[166:167]
	global_store_dwordx4 v247, v[132:135], s[4:5] nt
	s_add_u32 s4, s4, 0x4000
	s_addc_u32 s5, s5, 0
	s_waitcnt vmcnt(7) lgkmcnt(5)
	v_pk_add_f32 v[136:137], v[136:137], v[168:169]
	v_pk_add_f32 v[138:139], v[138:139], v[170:171]
	global_store_dwordx4 v247, v[136:139], s[4:5] nt
	s_add_u32 s4, s4, 0x4000
	s_addc_u32 s5, s5, 0
	s_waitcnt vmcnt(7) lgkmcnt(4)
	v_pk_add_f32 v[140:141], v[140:141], v[172:173]
	v_pk_add_f32 v[142:143], v[142:143], v[174:175]
	global_store_dwordx4 v247, v[140:143], s[4:5] nt
	s_add_u32 s4, s4, 0x4000
	s_addc_u32 s5, s5, 0
	s_waitcnt vmcnt(7) lgkmcnt(3)
	v_pk_add_f32 v[144:145], v[144:145], v[176:177]
	v_pk_add_f32 v[146:147], v[146:147], v[178:179]
	global_store_dwordx4 v247, v[144:147], s[4:5] nt
	s_add_u32 s4, s4, 0x4000
	s_addc_u32 s5, s5, 0
	s_waitcnt vmcnt(7) lgkmcnt(2)
	v_pk_add_f32 v[148:149], v[148:149], v[180:181]
	v_pk_add_f32 v[150:151], v[150:151], v[182:183]
	global_store_dwordx4 v247, v[148:151], s[4:5] nt
	s_add_u32 s4, s4, 0x4000
	s_addc_u32 s5, s5, 0
	s_waitcnt vmcnt(7) lgkmcnt(1)
	v_pk_add_f32 v[152:153], v[152:153], v[184:185]
	v_pk_add_f32 v[154:155], v[154:155], v[186:187]
	global_store_dwordx4 v247, v[152:155], s[4:5] nt
	s_add_u32 s4, s4, 0x4000
	s_addc_u32 s5, s5, 0
	s_waitcnt vmcnt(7) lgkmcnt(0)
	v_pk_add_f32 v[156:157], v[156:157], v[188:189]
	v_pk_add_f32 v[158:159], v[158:159], v[190:191]
	global_store_dwordx4 v247, v[156:159], s[4:5] nt
	s_add_u32 s4, s4, 0x4000
	s_addc_u32 s5, s5, 0
	s_nop 1
	s_add_u32 s15, s15, 64
	s_branch .Lg18_tile
